# GEMM main loops: per-phase s_setprio flips replaced by one static priority raise for waves 0-3 per tile main loop (timing-only change)
# speedup vs baseline: 1.0068x; 1.0054x over previous
; #define PG8_STAGE(bufoff, gbase, voff) do { _Pragma("unroll") for (int _i = 0; _i < 2; ++_i) \
;     __builtin_amdgcn_global_load_lds((const unsigned*)((const char*)(gbase) + (voff)[_i]), (PG8_LAS unsigned*)(lds + (bufoff) + ldsw + _i * 8192), 16, 0, 0); } while (0)
; #define PG8_LDA(dst, b, h) do { _Pragma("unroll") for (int m = 0; m < 4; ++m) _Pragma("unroll") for (int k = 0; k < 2; ++k) dst[m][k] = *(const PG8_LAS bf16x8*)(lds + PG8_SA(b, h) + aoff + m * 2048 + k * 1024); } while (0)
; #define PG8_LDB(dst, b, h) do { _Pragma("unroll") for (int n = 0; n < 2; ++n) _Pragma("unroll") for (int k = 0; k < 2; ++k) dst[n][k] = *(const PG8_LAS bf16x8*)(lds + PG8_SB(b, h) + boff + n * 2048 + k * 1024); } while (0)
; #define PG8_MMA(ai, bj, At, Bt) do { __builtin_amdgcn_s_setprio(1); _Pragma("unroll") for (int m = 0; m < 4; ++m) _Pragma("unroll") for (int n = 0; n < 2; ++n) _Pragma("unroll") for (int k = 0; k < 2; ++k) \
;     acc[ai][bj][m][n] = __builtin_amdgcn_mfma_f32_16x16x32_bf16(Bt[n][k], At[m][k], acc[ai][bj][m][n], 0, 0, 0); __builtin_amdgcn_s_setprio(0); } while (0)
; #define PG8_WAIT_V(n) asm volatile("s_waitcnt vmcnt(" #n ")" ::: "memory")
; #define PG8_BAR __builtin_amdgcn_s_barrier()
; template <class Epi, bool SEQ>
; DEV void gemm_phase(PG8_LAS unsigned char* lds, const Gemm g, const Epi& E) {
;     ...
;     const bool has_next = next_unit<SEQ>(g, ui + 1, G, cblk, nxt);
;     const char* nA = has_next ? PG8_ABASE(nxt) : cA; const char* nB = has_next ? PG8_BBASE(nxt) : cB;
;     for (int t = 0; t < nt; t += 2) {
;       const bool last = (t == nt - 2);
;       const char* a1 = cA + (size_t)(t + 1) * kstep;
;       const char* a2 = last ? nA : cA + (size_t)(t + 2) * kstep; const char* b2 = last ? nB : cB + (size_t)(t + 2) * kstep;
;       const char* a3 = a2 + kstep; const char* b3 = b2 + kstep;
;       PG8_LDB(B0, 0, 0); PG8_LDB(B1, 0, 1); PG8_SCHED; PG8_LDA(At, 0, 0); PG8_STAGE(PG8_SA(1, 1), a1 + hstepA, voffA);
;       PG8_WAIT_V(8); PG8_WAIT_L(0); PG8_BAR; PG8_MMA(0, 0, At, B0); PG8_MMA(0, 1, At, B1); PG8_BAR; PG8_SCHED;
;     ...
; #pragma unroll
;       for (int a = 0; a < 2; ++a)
; #pragma unroll
;         for (int b = 0; b < 2; ++b)
; #pragma unroll
;           for (int m = 0; m < 4; ++m)
; #pragma unroll
;             for (int n = 0; n < 2; ++n) acc[a][b][m][n] = (f32x4){0.f, 0.f, 0.f, 0.f};
;     }
;     cur = nxt; cA = nA; cB = nB; ++ui;
.LBB0_129:
	s_ashr_i32 s39, s38, 31
	s_lshl_b64 s[8:9], s[38:39], 19
	s_add_u32 s64, s24, s8
	s_addc_u32 s65, s25, s9
	s_and_b64 s[8:9], s[62:63], exec
	s_cselect_b32 s39, s65, s3
	s_cselect_b32 s43, s64, s2
	s_ashr_i32 s61, s60, 31
	s_lshl_b64 s[8:9], s[60:61], 19
	s_add_u32 s66, s0, s8
	s_addc_u32 s67, s1, s9
	s_and_b64 s[8:9], s[62:63], exec
	s_cselect_b32 s44, s67, s5
	s_cselect_b32 s45, s66, s4
	s_add_u32 s2, s2, 0x40080
	s_addc_u32 s3, s3, 0
	s_add_u32 s46, s4, 0x100
	v_mov_b32_e32 v0, 0
	s_addc_u32 s47, s5, 0
	s_mov_b32 s48, -2
	v_mov_b32_e32 v1, v0
	v_mov_b32_e32 v2, v0
	v_mov_b32_e32 v3, v0
	v_mov_b32_e32 v4, v0
	v_mov_b32_e32 v5, v0
	v_mov_b32_e32 v6, v0
	v_mov_b32_e32 v7, v0
	v_mov_b32_e32 v16, v0
	v_mov_b32_e32 v17, v0
	v_mov_b32_e32 v18, v0
	v_mov_b32_e32 v19, v0
	v_mov_b32_e32 v20, v0
	v_mov_b32_e32 v21, v0
	v_mov_b32_e32 v22, v0
	v_mov_b32_e32 v23, v0
	v_mov_b32_e32 v32, v0
	v_mov_b32_e32 v33, v0
	v_mov_b32_e32 v34, v0
	v_mov_b32_e32 v35, v0
	v_mov_b32_e32 v36, v0
	v_mov_b32_e32 v37, v0
	v_mov_b32_e32 v38, v0
	v_mov_b32_e32 v39, v0
	v_mov_b32_e32 v48, v0
	v_mov_b32_e32 v49, v0
	v_mov_b32_e32 v50, v0
	v_mov_b32_e32 v51, v0
	v_mov_b32_e32 v52, v0
	v_mov_b32_e32 v53, v0
	v_mov_b32_e32 v54, v0
	v_mov_b32_e32 v55, v0
	v_mov_b32_e32 v8, v0
	v_mov_b32_e32 v9, v0
	v_mov_b32_e32 v10, v0
	v_mov_b32_e32 v11, v0
	v_mov_b32_e32 v12, v0
	v_mov_b32_e32 v13, v0
	v_mov_b32_e32 v14, v0
	v_mov_b32_e32 v15, v0
	v_mov_b32_e32 v24, v0
	v_mov_b32_e32 v25, v0
	v_mov_b32_e32 v26, v0
	v_mov_b32_e32 v27, v0
	v_mov_b32_e32 v28, v0
	v_mov_b32_e32 v29, v0
	v_mov_b32_e32 v30, v0
	v_mov_b32_e32 v31, v0
	v_mov_b32_e32 v40, v0
	v_mov_b32_e32 v41, v0
	v_mov_b32_e32 v42, v0
	v_mov_b32_e32 v43, v0
	v_mov_b32_e32 v44, v0
	v_mov_b32_e32 v45, v0
	v_mov_b32_e32 v46, v0
	v_mov_b32_e32 v47, v0
	v_mov_b32_e32 v56, v0
	v_mov_b32_e32 v57, v0
	v_mov_b32_e32 v58, v0
	v_mov_b32_e32 v59, v0
	v_mov_b32_e32 v60, v0
	v_mov_b32_e32 v61, v0
	v_mov_b32_e32 v62, v0
	v_mov_b32_e32 v63, v0
	v_mov_b32_e32 v64, v0
	v_mov_b32_e32 v65, v0
	v_mov_b32_e32 v66, v0
	v_mov_b32_e32 v67, v0
	v_mov_b32_e32 v68, v0
	v_mov_b32_e32 v69, v0
	v_mov_b32_e32 v70, v0
	v_mov_b32_e32 v71, v0
	v_mov_b32_e32 v80, v0
	v_mov_b32_e32 v81, v0
	v_mov_b32_e32 v82, v0
	v_mov_b32_e32 v83, v0
	v_mov_b32_e32 v84, v0
	v_mov_b32_e32 v85, v0
	v_mov_b32_e32 v86, v0
	v_mov_b32_e32 v87, v0
	v_mov_b32_e32 v96, v0
	v_mov_b32_e32 v97, v0
	v_mov_b32_e32 v98, v0
	v_mov_b32_e32 v99, v0
	v_mov_b32_e32 v100, v0
	v_mov_b32_e32 v101, v0
	v_mov_b32_e32 v102, v0
	v_mov_b32_e32 v103, v0
	v_mov_b32_e32 v116, v0
	v_mov_b32_e32 v117, v0
	v_mov_b32_e32 v118, v0
	v_mov_b32_e32 v119, v0
	v_mov_b32_e32 v124, v0
	v_mov_b32_e32 v125, v0
	v_mov_b32_e32 v126, v0
	v_mov_b32_e32 v127, v0
	v_mov_b32_e32 v72, v0
	v_mov_b32_e32 v73, v0
	v_mov_b32_e32 v74, v0
	v_mov_b32_e32 v75, v0
	v_mov_b32_e32 v76, v0
	v_mov_b32_e32 v77, v0
	v_mov_b32_e32 v78, v0
	v_mov_b32_e32 v79, v0
	v_mov_b32_e32 v88, v0
	v_mov_b32_e32 v89, v0
	v_mov_b32_e32 v90, v0
	v_mov_b32_e32 v91, v0
	v_mov_b32_e32 v92, v0
	v_mov_b32_e32 v93, v0
	v_mov_b32_e32 v94, v0
	v_mov_b32_e32 v95, v0
	v_mov_b32_e32 v104, v0
	v_mov_b32_e32 v105, v0
	v_mov_b32_e32 v106, v0
	v_mov_b32_e32 v107, v0
	v_mov_b32_e32 v112, v0
	v_mov_b32_e32 v113, v0
	v_mov_b32_e32 v114, v0
	v_mov_b32_e32 v115, v0
	v_mov_b32_e32 v136, v0
	v_mov_b32_e32 v137, v0
	v_mov_b32_e32 v138, v0
	v_mov_b32_e32 v139, v0
	v_mov_b32_e32 v144, v0
	v_mov_b32_e32 v145, v0
	v_mov_b32_e32 v146, v0
	v_mov_b32_e32 v147, v0
	v_readfirstlane_b32 s98, v171
	s_nop 3
	s_lshr_b32 s98, s98, 6
	s_cmp_lt_u32 s98, 4
	s_cbranch_scc0 .Lprio_130
	s_setprio 1
.Lprio_130:
.LBB0_130:
	s_add_u32 s4, s2, 0xfffc0080
	s_addc_u32 s5, s3, -1
	s_add_i32 s49, 0, 0x10000
	s_cmp_eq_u32 s48, 12
	s_cselect_b32 s9, s39, s5
	s_cselect_b32 s8, s43, s4
	s_cselect_b32 s5, s44, s47
	s_cselect_b32 s4, s45, s46
	s_add_i32 s52, 0, 0x14000
	v_add_u32_e32 v132, s49, v179
	v_add_u32_e32 v156, s52, v179
	ds_read_b128 v[108:111], v132
	ds_read_b128 v[120:123], v132 offset:1024
	ds_read_b128 v[128:131], v132 offset:2048
	ds_read_b128 v[132:135], v132 offset:3072
	ds_read_b128 v[140:143], v156
	ds_read_b128 v[148:151], v156 offset:1024
	ds_read_b128 v[152:155], v156 offset:2048
	ds_read_b128 v[156:159], v156 offset:3072
	v_lshl_add_u64 v[166:167], s[2:3], 0, v[162:163]
	s_add_i32 m0, s14, 0xc000
	ds_read_b128 v[180:183], v219
	ds_read_b128 v[184:187], v219 offset:1024
	ds_read_b128 v[188:191], v219 offset:2048
	ds_read_b128 v[192:195], v219 offset:3072
	ds_read_b128 v[196:199], v219 offset:4096
	ds_read_b128 v[220:223], v219 offset:5120
	ds_read_b128 v[224:227], v219 offset:6144
	ds_read_b128 v[228:231], v219 offset:7168
	global_load_lds_dwordx4 v[166:167], off
	v_lshl_add_u64 v[166:167], s[2:3], 0, v[164:165]
	s_add_i32 m0, s14, 0xe000
	s_nop 0
	global_load_lds_dwordx4 v[166:167], off
	s_waitcnt vmcnt(8)
	s_waitcnt lgkmcnt(0)
	s_barrier
; #define PG8_STAGE(bufoff, gbase, voff) do { _Pragma("unroll") for (int _i = 0; _i < 2; ++_i) \
;     __builtin_amdgcn_global_load_lds((const unsigned*)((const char*)(gbase) + (voff)[_i]), (PG8_LAS unsigned*)(lds + (bufoff) + ldsw + _i * 8192), 16, 0, 0); } while (0)
; #define PG8_LDA(dst, b, h) do { _Pragma("unroll") for (int m = 0; m < 4; ++m) _Pragma("unroll") for (int k = 0; k < 2; ++k) dst[m][k] = *(const PG8_LAS bf16x8*)(lds + PG8_SA(b, h) + aoff + m * 2048 + k * 1024); } while (0)
; #define PG8_LDB(dst, b, h) do { _Pragma("unroll") for (int n = 0; n < 2; ++n) _Pragma("unroll") for (int k = 0; k < 2; ++k) dst[n][k] = *(const PG8_LAS bf16x8*)(lds + PG8_SB(b, h) + boff + n * 2048 + k * 1024); } while (0)
; #define PG8_MMA(ai, bj, At, Bt) do { __builtin_amdgcn_s_setprio(1); _Pragma("unroll") for (int m = 0; m < 4; ++m) _Pragma("unroll") for (int n = 0; n < 2; ++n) _Pragma("unroll") for (int k = 0; k < 2; ++k) \
;     acc[ai][bj][m][n] = __builtin_amdgcn_mfma_f32_16x16x32_bf16(Bt[n][k], At[m][k], acc[ai][bj][m][n], 0, 0, 0); __builtin_amdgcn_s_setprio(0); } while (0)
; #define PG8_WAIT_V(n) asm volatile("s_waitcnt vmcnt(" #n ")" ::: "memory")
; #define PG8_WAIT_L(n) asm volatile("s_waitcnt lgkmcnt(" #n ")" ::: "memory")
; #define PG8_BAR __builtin_amdgcn_s_barrier()
; #define PG8_SCHED __builtin_amdgcn_sched_barrier(0)
; template <class Epi, bool SEQ>
; DEV void gemm_phase(PG8_LAS unsigned char* lds, const Gemm g, const Epi& E) {
;     ...
;       PG8_LDB(B0, 0, 0); PG8_LDB(B1, 0, 1); PG8_SCHED; PG8_LDA(At, 0, 0); PG8_STAGE(PG8_SA(1, 1), a1 + hstepA, voffA);
;       PG8_WAIT_V(8); PG8_WAIT_L(0); PG8_BAR; PG8_MMA(0, 0, At, B0); PG8_MMA(0, 1, At, B1); PG8_BAR; PG8_SCHED;
;       PG8_LDA(At, 0, 1); PG8_STAGE(PG8_SB(0, 0), b2, voffB); PG8_STAGE(PG8_SB(0, 1), b2 + hstepB, voffB); PG8_STAGE(PG8_SA(0, 0), a2, voffA);
;       PG8_WAIT_V(8); PG8_WAIT_L(0); PG8_BAR; PG8_MMA(1, 0, At, B0); PG8_MMA(1, 1, At, B1); PG8_BAR; PG8_SCHED;
	s_waitcnt lgkmcnt(0)
	v_mfma_f32_16x16x32_bf16 v[144:147], v[108:111], v[180:183], v[144:147]
	v_mfma_f32_16x16x32_bf16 v[136:139], v[128:131], v[180:183], v[136:139]
	v_mfma_f32_16x16x32_bf16 v[112:115], v[108:111], v[188:191], v[112:115]
	v_mfma_f32_16x16x32_bf16 v[104:107], v[128:131], v[188:191], v[104:107]
	v_mfma_f32_16x16x32_bf16 v[92:95], v[108:111], v[196:199], v[92:95]
	v_mfma_f32_16x16x32_bf16 v[88:91], v[128:131], v[196:199], v[88:91]
	v_mfma_f32_16x16x32_bf16 v[76:79], v[108:111], v[224:227], v[76:79]
	v_mfma_f32_16x16x32_bf16 v[72:75], v[128:131], v[224:227], v[72:75]
	v_mfma_f32_16x16x32_bf16 v[144:147], v[120:123], v[184:187], v[144:147]
	v_mfma_f32_16x16x32_bf16 v[136:139], v[132:135], v[184:187], v[136:139]
	v_mfma_f32_16x16x32_bf16 v[112:115], v[120:123], v[192:195], v[112:115]
	v_mfma_f32_16x16x32_bf16 v[104:107], v[132:135], v[192:195], v[104:107]
	v_mfma_f32_16x16x32_bf16 v[92:95], v[120:123], v[220:223], v[92:95]
	v_mfma_f32_16x16x32_bf16 v[88:91], v[132:135], v[220:223], v[88:91]
	v_mfma_f32_16x16x32_bf16 v[76:79], v[120:123], v[228:231], v[76:79]
	v_mfma_f32_16x16x32_bf16 v[72:75], v[132:135], v[228:231], v[72:75]
	v_mfma_f32_16x16x32_bf16 v[124:127], v[140:143], v[180:183], v[124:127]
	v_mfma_f32_16x16x32_bf16 v[116:119], v[152:155], v[180:183], v[116:119]
	v_mfma_f32_16x16x32_bf16 v[100:103], v[140:143], v[188:191], v[100:103]
	v_mfma_f32_16x16x32_bf16 v[96:99], v[152:155], v[188:191], v[96:99]
	v_mfma_f32_16x16x32_bf16 v[84:87], v[140:143], v[196:199], v[84:87]
	v_mfma_f32_16x16x32_bf16 v[80:83], v[152:155], v[196:199], v[80:83]
	v_mfma_f32_16x16x32_bf16 v[68:71], v[140:143], v[224:227], v[68:71]
	v_mfma_f32_16x16x32_bf16 v[64:67], v[152:155], v[224:227], v[64:67]
	v_mfma_f32_16x16x32_bf16 v[124:127], v[148:151], v[184:187], v[124:127]
	v_mfma_f32_16x16x32_bf16 v[116:119], v[156:159], v[184:187], v[116:119]
	v_mfma_f32_16x16x32_bf16 v[100:103], v[148:151], v[192:195], v[100:103]
	v_mfma_f32_16x16x32_bf16 v[96:99], v[156:159], v[192:195], v[96:99]
	v_mfma_f32_16x16x32_bf16 v[84:87], v[148:151], v[220:223], v[84:87]
	v_mfma_f32_16x16x32_bf16 v[80:83], v[156:159], v[220:223], v[80:83]
	v_mfma_f32_16x16x32_bf16 v[68:71], v[148:151], v[228:231], v[68:71]
	v_mfma_f32_16x16x32_bf16 v[64:67], v[156:159], v[228:231], v[64:67]
	s_barrier
	s_add_i32 s49, s49, s13
	v_lshl_add_u64 v[166:167], s[4:5], 0, v[168:169]
	s_mov_b32 m0, s49
	ds_read_b128 v[180:183], v219 offset:16384
	ds_read_b128 v[184:187], v219 offset:17408
	ds_read_b128 v[188:191], v219 offset:18432
	ds_read_b128 v[192:195], v219 offset:19456
	ds_read_b128 v[196:199], v219 offset:20480
	ds_read_b128 v[220:223], v219 offset:21504
	ds_read_b128 v[224:227], v219 offset:22528
	ds_read_b128 v[228:231], v219 offset:23552
	global_load_lds_dwordx4 v[166:167], off
	s_add_i32 m0, s49, 0x2000
	s_add_u32 s50, s4, 0x40000
	v_lshl_add_u64 v[232:233], s[4:5], 0, v[160:161]
	s_addc_u32 s51, s5, 0
	s_add_i32 s49, s52, s13
	global_load_lds_dwordx4 v[232:233], off
	v_lshl_add_u64 v[234:235], s[50:51], 0, v[168:169]
	s_mov_b32 m0, s49
	v_lshl_add_u64 v[236:237], s[8:9], 0, v[160:161]
	global_load_lds_dwordx4 v[234:235], off
	v_lshl_add_u64 v[234:235], s[50:51], 0, v[160:161]
	s_add_i32 m0, s49, 0x2000
	s_nop 0
	global_load_lds_dwordx4 v[234:235], off
	v_lshl_add_u64 v[234:235], s[8:9], 0, v[168:169]
	s_mov_b32 m0, s14
	s_nop 0
	global_load_lds_dwordx4 v[234:235], off
	s_mov_b32 m0, s15
	s_nop 0
	global_load_lds_dwordx4 v[236:237], off
	s_waitcnt vmcnt(8)
	s_waitcnt lgkmcnt(0)
	s_barrier
	s_waitcnt lgkmcnt(0)
	v_mfma_f32_16x16x32_bf16 v[60:63], v[108:111], v[180:183], v[60:63]
	v_mfma_f32_16x16x32_bf16 v[56:59], v[128:131], v[180:183], v[56:59]
	v_mfma_f32_16x16x32_bf16 v[44:47], v[108:111], v[188:191], v[44:47]
	v_mfma_f32_16x16x32_bf16 v[40:43], v[128:131], v[188:191], v[40:43]
	v_mfma_f32_16x16x32_bf16 v[28:31], v[108:111], v[196:199], v[28:31]
	v_mfma_f32_16x16x32_bf16 v[24:27], v[128:131], v[196:199], v[24:27]
	v_mfma_f32_16x16x32_bf16 v[12:15], v[108:111], v[224:227], v[12:15]
	v_mfma_f32_16x16x32_bf16 v[8:11], v[128:131], v[224:227], v[8:11]
	v_mfma_f32_16x16x32_bf16 v[60:63], v[120:123], v[184:187], v[60:63]
	v_mfma_f32_16x16x32_bf16 v[56:59], v[132:135], v[184:187], v[56:59]
	v_mfma_f32_16x16x32_bf16 v[44:47], v[120:123], v[192:195], v[44:47]
	v_mfma_f32_16x16x32_bf16 v[40:43], v[132:135], v[192:195], v[40:43]
	v_mfma_f32_16x16x32_bf16 v[28:31], v[120:123], v[220:223], v[28:31]
	v_mfma_f32_16x16x32_bf16 v[24:27], v[132:135], v[220:223], v[24:27]
	v_mfma_f32_16x16x32_bf16 v[12:15], v[120:123], v[228:231], v[12:15]
	v_mfma_f32_16x16x32_bf16 v[8:11], v[132:135], v[228:231], v[8:11]
	v_mfma_f32_16x16x32_bf16 v[52:55], v[140:143], v[180:183], v[52:55]
	v_mfma_f32_16x16x32_bf16 v[48:51], v[152:155], v[180:183], v[48:51]
	v_mfma_f32_16x16x32_bf16 v[36:39], v[140:143], v[188:191], v[36:39]
	v_mfma_f32_16x16x32_bf16 v[32:35], v[152:155], v[188:191], v[32:35]
	v_mfma_f32_16x16x32_bf16 v[20:23], v[140:143], v[196:199], v[20:23]
	v_mfma_f32_16x16x32_bf16 v[16:19], v[152:155], v[196:199], v[16:19]
	v_mfma_f32_16x16x32_bf16 v[4:7], v[140:143], v[224:227], v[4:7]
	v_mfma_f32_16x16x32_bf16 v[0:3], v[152:155], v[224:227], v[0:3]
	v_mfma_f32_16x16x32_bf16 v[52:55], v[148:151], v[184:187], v[52:55]
	v_mfma_f32_16x16x32_bf16 v[48:51], v[156:159], v[184:187], v[48:51]
	v_mfma_f32_16x16x32_bf16 v[36:39], v[148:151], v[192:195], v[36:39]
	v_mfma_f32_16x16x32_bf16 v[32:35], v[156:159], v[192:195], v[32:35]
	v_mfma_f32_16x16x32_bf16 v[20:23], v[148:151], v[220:223], v[20:23]
	v_mfma_f32_16x16x32_bf16 v[16:19], v[156:159], v[220:223], v[16:19]
	v_mfma_f32_16x16x32_bf16 v[4:7], v[148:151], v[228:231], v[4:7]
	v_mfma_f32_16x16x32_bf16 v[0:3], v[156:159], v[228:231], v[0:3]
	s_barrier
; #define PG8_STAGE(bufoff, gbase, voff) do { _Pragma("unroll") for (int _i = 0; _i < 2; ++_i) \
;     __builtin_amdgcn_global_load_lds((const unsigned*)((const char*)(gbase) + (voff)[_i]), (PG8_LAS unsigned*)(lds + (bufoff) + ldsw + _i * 8192), 16, 0, 0); } while (0)
; #define PG8_LDA(dst, b, h) do { _Pragma("unroll") for (int m = 0; m < 4; ++m) _Pragma("unroll") for (int k = 0; k < 2; ++k) dst[m][k] = *(const PG8_LAS bf16x8*)(lds + PG8_SA(b, h) + aoff + m * 2048 + k * 1024); } while (0)
; #define PG8_LDB(dst, b, h) do { _Pragma("unroll") for (int n = 0; n < 2; ++n) _Pragma("unroll") for (int k = 0; k < 2; ++k) dst[n][k] = *(const PG8_LAS bf16x8*)(lds + PG8_SB(b, h) + boff + n * 2048 + k * 1024); } while (0)
; #define PG8_MMA(ai, bj, At, Bt) do { __builtin_amdgcn_s_setprio(1); _Pragma("unroll") for (int m = 0; m < 4; ++m) _Pragma("unroll") for (int n = 0; n < 2; ++n) _Pragma("unroll") for (int k = 0; k < 2; ++k) \
;     acc[ai][bj][m][n] = __builtin_amdgcn_mfma_f32_16x16x32_bf16(Bt[n][k], At[m][k], acc[ai][bj][m][n], 0, 0, 0); __builtin_amdgcn_s_setprio(0); } while (0)
; #define PG8_WAIT_V(n) asm volatile("s_waitcnt vmcnt(" #n ")" ::: "memory")
; #define PG8_WAIT_L(n) asm volatile("s_waitcnt lgkmcnt(" #n ")" ::: "memory")
; #define PG8_BAR __builtin_amdgcn_s_barrier()
; #define PG8_SCHED __builtin_amdgcn_sched_barrier(0)
; template <class Epi, bool SEQ>
; DEV void gemm_phase(PG8_LAS unsigned char* lds, const Gemm g, const Epi& E) {
;     ...
;       PG8_LDB(B0, 1, 0); PG8_LDB(B1, 1, 1); PG8_SCHED; PG8_LDA(At, 1, 0); PG8_STAGE(PG8_SA(0, 1), a2 + hstepA, voffA);
;       PG8_WAIT_V(8); PG8_WAIT_L(0); PG8_BAR; PG8_MMA(0, 0, At, B0); PG8_MMA(0, 1, At, B1); PG8_BAR; PG8_SCHED;
;       PG8_LDA(At, 1, 1); PG8_STAGE(PG8_SB(1, 0), b3, voffB); PG8_STAGE(PG8_SB(1, 1), b3 + hstepB, voffB); PG8_STAGE(PG8_SA(1, 0), a3, voffA);
	s_add_i32 s49, 0, 0x18000
	s_add_i32 s50, 0, 0x1c000
	v_add_u32_e32 v132, s49, v179
	v_add_u32_e32 v156, s50, v179
	ds_read_b128 v[108:111], v132
	ds_read_b128 v[120:123], v132 offset:1024
	ds_read_b128 v[128:131], v132 offset:2048
	ds_read_b128 v[132:135], v132 offset:3072
	ds_read_b128 v[140:143], v156
	ds_read_b128 v[148:151], v156 offset:1024
	ds_read_b128 v[152:155], v156 offset:2048
	ds_read_b128 v[156:159], v156 offset:3072
	s_add_u32 s8, s8, 0x40000
	s_addc_u32 s9, s9, 0
	s_mov_b32 m0, s16
	v_lshl_add_u64 v[238:239], s[8:9], 0, v[168:169]
	ds_read_b128 v[180:183], v219 offset:32768
	ds_read_b128 v[184:187], v219 offset:33792
	ds_read_b128 v[188:191], v219 offset:34816
	ds_read_b128 v[192:195], v219 offset:35840
	ds_read_b128 v[196:199], v219 offset:36864
	ds_read_b128 v[220:223], v219 offset:37888
	ds_read_b128 v[224:227], v219 offset:38912
	ds_read_b128 v[228:231], v219 offset:39936
	global_load_lds_dwordx4 v[238:239], off
	v_lshl_add_u64 v[238:239], s[8:9], 0, v[160:161]
	s_mov_b32 m0, s17
	s_nop 0
	global_load_lds_dwordx4 v[238:239], off
	s_waitcnt vmcnt(8)
	s_waitcnt lgkmcnt(0)
	s_barrier
	s_waitcnt lgkmcnt(0)
	v_mfma_f32_16x16x32_bf16 v[144:147], v[108:111], v[180:183], v[144:147]
	v_mfma_f32_16x16x32_bf16 v[136:139], v[128:131], v[180:183], v[136:139]
	v_mfma_f32_16x16x32_bf16 v[112:115], v[108:111], v[188:191], v[112:115]
	v_mfma_f32_16x16x32_bf16 v[104:107], v[128:131], v[188:191], v[104:107]
	v_mfma_f32_16x16x32_bf16 v[92:95], v[108:111], v[196:199], v[92:95]
	v_mfma_f32_16x16x32_bf16 v[88:91], v[128:131], v[196:199], v[88:91]
	v_mfma_f32_16x16x32_bf16 v[76:79], v[108:111], v[224:227], v[76:79]
	v_mfma_f32_16x16x32_bf16 v[72:75], v[128:131], v[224:227], v[72:75]
	v_mfma_f32_16x16x32_bf16 v[144:147], v[120:123], v[184:187], v[144:147]
	v_mfma_f32_16x16x32_bf16 v[136:139], v[132:135], v[184:187], v[136:139]
	v_mfma_f32_16x16x32_bf16 v[112:115], v[120:123], v[192:195], v[112:115]
	v_mfma_f32_16x16x32_bf16 v[104:107], v[132:135], v[192:195], v[104:107]
	v_mfma_f32_16x16x32_bf16 v[92:95], v[120:123], v[220:223], v[92:95]
	v_mfma_f32_16x16x32_bf16 v[88:91], v[132:135], v[220:223], v[88:91]
	v_mfma_f32_16x16x32_bf16 v[76:79], v[120:123], v[228:231], v[76:79]
	v_mfma_f32_16x16x32_bf16 v[72:75], v[132:135], v[228:231], v[72:75]
	v_mfma_f32_16x16x32_bf16 v[124:127], v[140:143], v[180:183], v[124:127]
	v_mfma_f32_16x16x32_bf16 v[116:119], v[152:155], v[180:183], v[116:119]
	v_mfma_f32_16x16x32_bf16 v[100:103], v[140:143], v[188:191], v[100:103]
	v_mfma_f32_16x16x32_bf16 v[96:99], v[152:155], v[188:191], v[96:99]
	v_mfma_f32_16x16x32_bf16 v[84:87], v[140:143], v[196:199], v[84:87]
	v_mfma_f32_16x16x32_bf16 v[80:83], v[152:155], v[196:199], v[80:83]
	v_mfma_f32_16x16x32_bf16 v[68:71], v[140:143], v[224:227], v[68:71]
	v_mfma_f32_16x16x32_bf16 v[64:67], v[152:155], v[224:227], v[64:67]
	v_mfma_f32_16x16x32_bf16 v[124:127], v[148:151], v[184:187], v[124:127]
	v_mfma_f32_16x16x32_bf16 v[116:119], v[156:159], v[184:187], v[116:119]
	v_mfma_f32_16x16x32_bf16 v[100:103], v[148:151], v[192:195], v[100:103]
	v_mfma_f32_16x16x32_bf16 v[96:99], v[156:159], v[192:195], v[96:99]
	v_mfma_f32_16x16x32_bf16 v[84:87], v[148:151], v[220:223], v[84:87]
	v_mfma_f32_16x16x32_bf16 v[80:83], v[156:159], v[220:223], v[80:83]
	v_mfma_f32_16x16x32_bf16 v[68:71], v[148:151], v[228:231], v[68:71]
	v_mfma_f32_16x16x32_bf16 v[64:67], v[156:159], v[228:231], v[64:67]
	s_barrier
	s_add_i32 s8, s49, s13
	v_lshl_add_u64 v[166:167], v[166:167], 0, s[10:11]
	s_mov_b32 m0, s8
	ds_read_b128 v[180:183], v219 offset:49152
	ds_read_b128 v[184:187], v219 offset:50176
	ds_read_b128 v[188:191], v219 offset:51200
	ds_read_b128 v[192:195], v219 offset:52224
	ds_read_b128 v[196:199], v219 offset:53248
	ds_read_b128 v[220:223], v219 offset:54272
	ds_read_b128 v[224:227], v219 offset:55296
	ds_read_b128 v[228:231], v219 offset:56320
	global_load_lds_dwordx4 v[166:167], off
	s_add_i32 m0, s8, 0x2000
	s_add_u32 s4, s4, 0x40080
	v_lshl_add_u64 v[166:167], v[232:233], 0, s[10:11]
	s_addc_u32 s5, s5, 0
	s_add_i32 s8, s50, s13
	global_load_lds_dwordx4 v[166:167], off
	v_lshl_add_u64 v[166:167], s[4:5], 0, v[168:169]
	s_mov_b32 m0, s8
	s_nop 0
	global_load_lds_dwordx4 v[166:167], off
	v_lshl_add_u64 v[166:167], s[4:5], 0, v[160:161]
	s_add_i32 m0, s8, 0x2000
	s_nop 0
	global_load_lds_dwordx4 v[166:167], off
	v_lshl_add_u64 v[166:167], v[234:235], 0, s[10:11]
	s_mov_b32 m0, s20
	s_nop 0
	global_load_lds_dwordx4 v[166:167], off
	v_lshl_add_u64 v[166:167], v[236:237], 0, s[10:11]
	s_mov_b32 m0, s21
	s_nop 0
	global_load_lds_dwordx4 v[166:167], off
	s_waitcnt vmcnt(8)
	s_waitcnt lgkmcnt(0)
	s_barrier
; DEV float bflo(unsigned w) { return __uint_as_float(w << 16); }
; DEV float bfhi(unsigned w) { return __uint_as_float(w & 0xffff0000u); }
; DEV float sigmoidf_(float x) { return 1.0f / (1.0f + __expf(-x)); }
; #define PG8_WAIT_V(n) asm volatile("s_waitcnt vmcnt(" #n ")" ::: "memory")
; #define PG8_WAIT_L(n) asm volatile("s_waitcnt lgkmcnt(" #n ")" ::: "memory")
; #define PG8_BAR __builtin_amdgcn_s_barrier()
; #define PG8_SCHED __builtin_amdgcn_sched_barrier(0)
; template <class Epi, bool SEQ>
; DEV void gemm_phase(PG8_LAS unsigned char* lds, const Gemm g, const Epi& E) {
;     ...
;       PG8_WAIT_V(8); PG8_WAIT_L(0); PG8_BAR; PG8_MMA(1, 0, At, B0); PG8_MMA(1, 1, At, B1); PG8_BAR; PG8_SCHED;
;     }
;     if (wr == 0) PG8_BAR;
;     bool keep = false;
;     if constexpr (Epi::KEEP) keep = E.rescale(acc, cur, wr, wc, fr, fq);
;     if (!keep) E(acc, cur, wr, wc, fr, fq);
;   DEV void operator()(const f32x4 (&acc)[2][2][4][2], const Unit& u, int wr, int wc, int fr, int fq) const {
;     const int row0 = u.pm * BM + wr * 64 + fr, col0 = u.pn * BM + wc * 32 + 4 * fq;
; #pragma unroll
;     for (int ai = 0; ai < 2; ++ai)
; #pragma unroll
;       for (int mp = 0; mp < 2; ++mp) {
;         f32x4 xv[2][2][2]; u32x2 pw[2][2][2];
; #pragma unroll
;         for (int mm = 0; mm < 2; ++mm)
; #pragma unroll
;           for (int bj = 0; bj < 2; ++bj)
; #pragma unroll
;             for (int n = 0; n < 2; ++n) {
;               const size_t o = (size_t)(row0 + ai * HALF + (mp * 2 + mm) * 16) * D + col0 + bj * HALF + n * 16;
;               pw[mm][bj][n] = *(const u32x2*)(PROJ + o);
;               xv[mm][bj][n] = *(const f32x4*)(X + o);
;             }
; #pragma unroll
;         for (int mm = 0; mm < 2; ++mm)
; #pragma unroll
;           for (int bj = 0; bj < 2; ++bj)
; #pragma unroll
;             for (int n = 0; n < 2; ++n) {
;               const size_t o = (size_t)(row0 + ai * HALF + (mp * 2 + mm) * 16) * D + col0 + bj * HALF + n * 16;
;               const f32x4 v = acc[ai][bj][mp * 2 + mm][n];
;               f32x4 x = xv[mm][bj][n]; const u32x2 w = pw[mm][bj][n];
;               x[0] += sigmoidf_(v[0]) * bflo(w.x); x[1] += sigmoidf_(v[1]) * bfhi(w.x); x[2] += sigmoidf_(v[2]) * bflo(w.y); x[3] += sigmoidf_(v[3]) * bfhi(w.y);
;               *(f32x4*)(X + o) = x;
;             }
	s_waitcnt lgkmcnt(0)
	v_mfma_f32_16x16x32_bf16 v[60:63], v[108:111], v[180:183], v[60:63]
	v_mfma_f32_16x16x32_bf16 v[56:59], v[128:131], v[180:183], v[56:59]
	v_mfma_f32_16x16x32_bf16 v[44:47], v[108:111], v[188:191], v[44:47]
	v_mfma_f32_16x16x32_bf16 v[40:43], v[128:131], v[188:191], v[40:43]
	v_mfma_f32_16x16x32_bf16 v[28:31], v[108:111], v[196:199], v[28:31]
	v_mfma_f32_16x16x32_bf16 v[24:27], v[128:131], v[196:199], v[24:27]
	v_mfma_f32_16x16x32_bf16 v[12:15], v[108:111], v[224:227], v[12:15]
	v_mfma_f32_16x16x32_bf16 v[8:11], v[128:131], v[224:227], v[8:11]
	v_mfma_f32_16x16x32_bf16 v[60:63], v[120:123], v[184:187], v[60:63]
	v_mfma_f32_16x16x32_bf16 v[56:59], v[132:135], v[184:187], v[56:59]
	v_mfma_f32_16x16x32_bf16 v[44:47], v[120:123], v[192:195], v[44:47]
	v_mfma_f32_16x16x32_bf16 v[40:43], v[132:135], v[192:195], v[40:43]
	v_mfma_f32_16x16x32_bf16 v[28:31], v[120:123], v[220:223], v[28:31]
	v_mfma_f32_16x16x32_bf16 v[24:27], v[132:135], v[220:223], v[24:27]
	v_mfma_f32_16x16x32_bf16 v[12:15], v[120:123], v[228:231], v[12:15]
	v_mfma_f32_16x16x32_bf16 v[8:11], v[132:135], v[228:231], v[8:11]
	v_mfma_f32_16x16x32_bf16 v[52:55], v[140:143], v[180:183], v[52:55]
	v_mfma_f32_16x16x32_bf16 v[48:51], v[152:155], v[180:183], v[48:51]
	v_mfma_f32_16x16x32_bf16 v[36:39], v[140:143], v[188:191], v[36:39]
	v_mfma_f32_16x16x32_bf16 v[32:35], v[152:155], v[188:191], v[32:35]
	v_mfma_f32_16x16x32_bf16 v[20:23], v[140:143], v[196:199], v[20:23]
	v_mfma_f32_16x16x32_bf16 v[16:19], v[152:155], v[196:199], v[16:19]
	v_mfma_f32_16x16x32_bf16 v[4:7], v[140:143], v[224:227], v[4:7]
	v_mfma_f32_16x16x32_bf16 v[0:3], v[152:155], v[224:227], v[0:3]
	v_mfma_f32_16x16x32_bf16 v[52:55], v[148:151], v[184:187], v[52:55]
	v_mfma_f32_16x16x32_bf16 v[48:51], v[156:159], v[184:187], v[48:51]
	v_mfma_f32_16x16x32_bf16 v[36:39], v[148:151], v[192:195], v[36:39]
	v_mfma_f32_16x16x32_bf16 v[32:35], v[156:159], v[192:195], v[32:35]
	v_mfma_f32_16x16x32_bf16 v[20:23], v[148:151], v[220:223], v[20:23]
	v_mfma_f32_16x16x32_bf16 v[16:19], v[156:159], v[220:223], v[16:19]
	v_mfma_f32_16x16x32_bf16 v[4:7], v[148:151], v[228:231], v[4:7]
	v_mfma_f32_16x16x32_bf16 v[0:3], v[156:159], v[228:231], v[0:3]
	s_barrier
	s_add_i32 s48, s48, 2
	s_add_u32 s2, s2, 0x100
	s_addc_u32 s3, s3, 0
	s_add_u32 s46, s46, 0x100
	s_addc_u32 s47, s47, 0
	s_cmp_gt_u32 s48, 13
	s_cbranch_scc0 .LBB0_130
	s_and_b64 vcc, exec, s[18:19]
	s_cbranch_vccz .LBB0_133
	s_barrier
.LBB0_133:
	s_setprio 0
	v_lshl_add_u32 v166, s27, 8, v177
	v_lshl_or_b32 v167, s42, 8, v218
	s_mov_b64 s[56:57], s[22:23]
	s_mov_b64 s[58:59], s[40:41]
	s_mov_b64 s[68:69], s[22:23]
	s_mov_b32 s70, 0xbfb8aa3b
	s_mov_b32 s71, 0xbfb8aa3b
	v_lshlrev_b32_e32 v156, 11, v166
	v_lshl_add_u32 v167, v167, 1, v156
	v_lshlrev_b32_e32 v166, 1, v167
	global_load_dwordx2 v[232:233], v167, s[58:59]
	global_load_dwordx4 v[180:183], v166, s[56:57]
	global_load_dwordx2 v[234:235], v167, s[58:59] offset:32
	global_load_dwordx4 v[184:187], v166, s[56:57] offset:64
	global_load_dwordx2 v[236:237], v167, s[58:59] offset:256
	global_load_dwordx4 v[188:191], v166, s[56:57] offset:512
	global_load_dwordx2 v[238:239], v167, s[58:59] offset:288
	global_load_dwordx4 v[192:195], v166, s[56:57] offset:576
	s_add_u32 s56, s56, 0x10000
	s_addc_u32 s57, s57, 0
	s_add_u32 s58, s58, 0x8000
	s_addc_u32 s59, s59, 0
	global_load_dwordx2 v[148:149], v167, s[58:59]
	global_load_dwordx4 v[196:199], v166, s[56:57]
	global_load_dwordx2 v[150:151], v167, s[58:59] offset:32
	global_load_dwordx4 v[220:223], v166, s[56:57] offset:64
	global_load_dwordx2 v[152:153], v167, s[58:59] offset:256
	global_load_dwordx4 v[224:227], v166, s[56:57] offset:512
	global_load_dwordx2 v[154:155], v167, s[58:59] offset:288
	global_load_dwordx4 v[228:231], v166, s[56:57] offset:576
	s_add_u32 s56, s56, 0x10000
	s_addc_u32 s57, s57, 0
	s_add_u32 s58, s58, 0x8000
	s_addc_u32 s59, s59, 0
	s_waitcnt vmcnt(14)
	v_pk_mul_f32 v[128:129], v[144:145], s[70:71]
	v_pk_mul_f32 v[130:131], v[146:147], s[70:71]
	v_lshlrev_b32_e32 v140, 16, v232
	v_exp_f32_e32 v128, v128
	v_exp_f32_e32 v129, v129
	v_exp_f32_e32 v130, v130
	v_exp_f32_e32 v131, v131
	v_and_b32_e32 v141, 0xffff0000, v232
	v_pk_add_f32 v[128:129], v[128:129], 1.0 op_sel_hi:[1,0]
	v_pk_add_f32 v[130:131], v[130:131], 1.0 op_sel_hi:[1,0]
	v_rcp_f32_e32 v132, v128
	v_rcp_f32_e32 v133, v129
	v_rcp_f32_e32 v134, v130
	v_rcp_f32_e32 v135, v131
	v_lshlrev_b32_e32 v142, 16, v233
	v_and_b32_e32 v143, 0xffff0000, v233
	v_pk_fma_f32 v[128:129], v[128:129], v[132:133], 1.0 op_sel_hi:[1,1,0] neg_lo:[1,0,0] neg_hi:[1,0,0]
	v_pk_fma_f32 v[130:131], v[130:131], v[134:135], 1.0 op_sel_hi:[1,1,0] neg_lo:[1,0,0] neg_hi:[1,0,0]
	v_pk_fma_f32 v[132:133], v[128:129], v[132:133], v[132:133]
	v_pk_fma_f32 v[134:135], v[130:131], v[134:135], v[134:135]
	v_pk_fma_f32 v[180:181], v[132:133], v[140:141], v[180:181]
	v_pk_fma_f32 v[182:183], v[134:135], v[142:143], v[182:183]
	global_store_dwordx4 v166, v[180:183], s[68:69]
	global_load_dwordx2 v[232:233], v167, s[58:59]
	global_load_dwordx4 v[180:183], v166, s[56:57]
	s_waitcnt vmcnt(15)
; DEV float bflo(unsigned w) { return __uint_as_float(w << 16); }
; DEV float bfhi(unsigned w) { return __uint_as_float(w & 0xffff0000u); }
; DEV float sigmoidf_(float x) { return 1.0f / (1.0f + __expf(-x)); }
;   DEV void operator()(const f32x4 (&acc)[2][2][4][2], const Unit& u, int wr, int wc, int fr, int fq) const {
;     const int row0 = u.pm * BM + wr * 64 + fr, col0 = u.pn * BM + wc * 32 + 4 * fq;
; #pragma unroll
;     for (int ai = 0; ai < 2; ++ai)
; #pragma unroll
;       for (int mp = 0; mp < 2; ++mp) {
;         f32x4 xv[2][2][2]; u32x2 pw[2][2][2];
; #pragma unroll
;         for (int mm = 0; mm < 2; ++mm)
; #pragma unroll
;           for (int bj = 0; bj < 2; ++bj)
; #pragma unroll
;             for (int n = 0; n < 2; ++n) {
;               const size_t o = (size_t)(row0 + ai * HALF + (mp * 2 + mm) * 16) * D + col0 + bj * HALF + n * 16;
;               pw[mm][bj][n] = *(const u32x2*)(PROJ + o);
;               xv[mm][bj][n] = *(const f32x4*)(X + o);
;             }
; #pragma unroll
;         for (int mm = 0; mm < 2; ++mm)
; #pragma unroll
;           for (int bj = 0; bj < 2; ++bj)
; #pragma unroll
;             for (int n = 0; n < 2; ++n) {
;               const size_t o = (size_t)(row0 + ai * HALF + (mp * 2 + mm) * 16) * D + col0 + bj * HALF + n * 16;
;               const f32x4 v = acc[ai][bj][mp * 2 + mm][n];
;               f32x4 x = xv[mm][bj][n]; const u32x2 w = pw[mm][bj][n];
;               x[0] += sigmoidf_(v[0]) * bflo(w.x); x[1] += sigmoidf_(v[1]) * bfhi(w.x); x[2] += sigmoidf_(v[2]) * bflo(w.y); x[3] += sigmoidf_(v[3]) * bfhi(w.y);
;               *(f32x4*)(X + o) = x;
;             }
;         asm volatile("" ::: "memory");
;       }
;   }
	v_pk_mul_f32 v[128:129], v[136:137], s[70:71]
	v_pk_mul_f32 v[130:131], v[138:139], s[70:71]
	v_lshlrev_b32_e32 v140, 16, v234
	v_exp_f32_e32 v128, v128
	v_exp_f32_e32 v129, v129
	v_exp_f32_e32 v130, v130
	v_exp_f32_e32 v131, v131
	v_and_b32_e32 v141, 0xffff0000, v234
	v_pk_add_f32 v[128:129], v[128:129], 1.0 op_sel_hi:[1,0]
	v_pk_add_f32 v[130:131], v[130:131], 1.0 op_sel_hi:[1,0]
	v_rcp_f32_e32 v132, v128
	v_rcp_f32_e32 v133, v129
	v_rcp_f32_e32 v134, v130
	v_rcp_f32_e32 v135, v131
	v_lshlrev_b32_e32 v142, 16, v235
	v_and_b32_e32 v143, 0xffff0000, v235
	v_pk_fma_f32 v[128:129], v[128:129], v[132:133], 1.0 op_sel_hi:[1,1,0] neg_lo:[1,0,0] neg_hi:[1,0,0]
	v_pk_fma_f32 v[130:131], v[130:131], v[134:135], 1.0 op_sel_hi:[1,1,0] neg_lo:[1,0,0] neg_hi:[1,0,0]
	v_pk_fma_f32 v[132:133], v[128:129], v[132:133], v[132:133]
	v_pk_fma_f32 v[134:135], v[130:131], v[134:135], v[134:135]
	v_pk_fma_f32 v[184:185], v[132:133], v[140:141], v[184:185]
	v_pk_fma_f32 v[186:187], v[134:135], v[142:143], v[186:187]
	global_store_dwordx4 v166, v[184:187], s[68:69] offset:64
	global_load_dwordx2 v[234:235], v167, s[58:59] offset:32
	global_load_dwordx4 v[184:187], v166, s[56:57] offset:64
	s_waitcnt vmcnt(16)
	v_pk_mul_f32 v[128:129], v[124:125], s[70:71]
	v_pk_mul_f32 v[130:131], v[126:127], s[70:71]
	v_lshlrev_b32_e32 v140, 16, v236
	v_exp_f32_e32 v128, v128
	v_exp_f32_e32 v129, v129
	v_exp_f32_e32 v130, v130
	v_exp_f32_e32 v131, v131
	v_and_b32_e32 v141, 0xffff0000, v236
	v_pk_add_f32 v[128:129], v[128:129], 1.0 op_sel_hi:[1,0]
	v_pk_add_f32 v[130:131], v[130:131], 1.0 op_sel_hi:[1,0]
	v_rcp_f32_e32 v132, v128
	v_rcp_f32_e32 v133, v129
	v_rcp_f32_e32 v134, v130
	v_rcp_f32_e32 v135, v131
	v_lshlrev_b32_e32 v142, 16, v237
	v_and_b32_e32 v143, 0xffff0000, v237
	v_pk_fma_f32 v[128:129], v[128:129], v[132:133], 1.0 op_sel_hi:[1,1,0] neg_lo:[1,0,0] neg_hi:[1,0,0]
	v_pk_fma_f32 v[130:131], v[130:131], v[134:135], 1.0 op_sel_hi:[1,1,0] neg_lo:[1,0,0] neg_hi:[1,0,0]
	v_pk_fma_f32 v[132:133], v[128:129], v[132:133], v[132:133]
	v_pk_fma_f32 v[134:135], v[130:131], v[134:135], v[134:135]
	v_pk_fma_f32 v[188:189], v[132:133], v[140:141], v[188:189]
	v_pk_fma_f32 v[190:191], v[134:135], v[142:143], v[190:191]
	global_store_dwordx4 v166, v[188:191], s[68:69] offset:512
	global_load_dwordx2 v[236:237], v167, s[58:59] offset:256
	global_load_dwordx4 v[188:191], v166, s[56:57] offset:512
	s_waitcnt vmcnt(17)
	v_pk_mul_f32 v[128:129], v[116:117], s[70:71]
	v_pk_mul_f32 v[130:131], v[118:119], s[70:71]
	v_lshlrev_b32_e32 v140, 16, v238
	v_exp_f32_e32 v128, v128
	v_exp_f32_e32 v129, v129
	v_exp_f32_e32 v130, v130
	v_exp_f32_e32 v131, v131
	v_and_b32_e32 v141, 0xffff0000, v238
	v_pk_add_f32 v[128:129], v[128:129], 1.0 op_sel_hi:[1,0]
	v_pk_add_f32 v[130:131], v[130:131], 1.0 op_sel_hi:[1,0]
	v_rcp_f32_e32 v132, v128
	v_rcp_f32_e32 v133, v129
	v_rcp_f32_e32 v134, v130
	v_rcp_f32_e32 v135, v131
	v_lshlrev_b32_e32 v142, 16, v239
	v_and_b32_e32 v143, 0xffff0000, v239
	v_pk_fma_f32 v[128:129], v[128:129], v[132:133], 1.0 op_sel_hi:[1,1,0] neg_lo:[1,0,0] neg_hi:[1,0,0]
	v_pk_fma_f32 v[130:131], v[130:131], v[134:135], 1.0 op_sel_hi:[1,1,0] neg_lo:[1,0,0] neg_hi:[1,0,0]
	v_pk_fma_f32 v[132:133], v[128:129], v[132:133], v[132:133]
	v_pk_fma_f32 v[134:135], v[130:131], v[134:135], v[134:135]
	v_pk_fma_f32 v[192:193], v[132:133], v[140:141], v[192:193]
	v_pk_fma_f32 v[194:195], v[134:135], v[142:143], v[194:195]
	global_store_dwordx4 v166, v[192:195], s[68:69] offset:576
	s_add_u32 s68, s68, 0x10000
	s_addc_u32 s69, s69, 0
	global_load_dwordx2 v[238:239], v167, s[58:59] offset:288
	global_load_dwordx4 v[192:195], v166, s[56:57] offset:576
	s_add_u32 s56, s56, 0x10000
	s_addc_u32 s57, s57, 0
	s_add_u32 s58, s58, 0x8000
	s_addc_u32 s59, s59, 0
	s_waitcnt vmcnt(18)
	v_pk_mul_f32 v[128:129], v[112:113], s[70:71]
	v_pk_mul_f32 v[130:131], v[114:115], s[70:71]
	v_lshlrev_b32_e32 v140, 16, v148
	v_exp_f32_e32 v128, v128
	v_exp_f32_e32 v129, v129
	v_exp_f32_e32 v130, v130
	v_exp_f32_e32 v131, v131
	v_and_b32_e32 v141, 0xffff0000, v148
	v_pk_add_f32 v[128:129], v[128:129], 1.0 op_sel_hi:[1,0]
	v_pk_add_f32 v[130:131], v[130:131], 1.0 op_sel_hi:[1,0]
	v_rcp_f32_e32 v132, v128
	v_rcp_f32_e32 v133, v129
	v_rcp_f32_e32 v134, v130
	v_rcp_f32_e32 v135, v131
	v_lshlrev_b32_e32 v142, 16, v149
	v_and_b32_e32 v143, 0xffff0000, v149
	v_pk_fma_f32 v[128:129], v[128:129], v[132:133], 1.0 op_sel_hi:[1,1,0] neg_lo:[1,0,0] neg_hi:[1,0,0]
	v_pk_fma_f32 v[130:131], v[130:131], v[134:135], 1.0 op_sel_hi:[1,1,0] neg_lo:[1,0,0] neg_hi:[1,0,0]
	v_pk_fma_f32 v[132:133], v[128:129], v[132:133], v[132:133]
	v_pk_fma_f32 v[134:135], v[130:131], v[134:135], v[134:135]
	v_pk_fma_f32 v[196:197], v[132:133], v[140:141], v[196:197]
	v_pk_fma_f32 v[198:199], v[134:135], v[142:143], v[198:199]
	global_store_dwordx4 v166, v[196:199], s[68:69]
	global_load_dwordx2 v[148:149], v167, s[58:59]
	global_load_dwordx4 v[196:199], v166, s[56:57]
	s_waitcnt vmcnt(19)
	v_pk_mul_f32 v[128:129], v[104:105], s[70:71]
	v_pk_mul_f32 v[130:131], v[106:107], s[70:71]
	v_lshlrev_b32_e32 v140, 16, v150
	v_exp_f32_e32 v128, v128
	v_exp_f32_e32 v129, v129
	v_exp_f32_e32 v130, v130
	v_exp_f32_e32 v131, v131
	v_and_b32_e32 v141, 0xffff0000, v150
	v_pk_add_f32 v[128:129], v[128:129], 1.0 op_sel_hi:[1,0]
	v_pk_add_f32 v[130:131], v[130:131], 1.0 op_sel_hi:[1,0]
	v_rcp_f32_e32 v132, v128
	v_rcp_f32_e32 v133, v129
	v_rcp_f32_e32 v134, v130
	v_rcp_f32_e32 v135, v131
	v_lshlrev_b32_e32 v142, 16, v151
	v_and_b32_e32 v143, 0xffff0000, v151
	v_pk_fma_f32 v[128:129], v[128:129], v[132:133], 1.0 op_sel_hi:[1,1,0] neg_lo:[1,0,0] neg_hi:[1,0,0]
	v_pk_fma_f32 v[130:131], v[130:131], v[134:135], 1.0 op_sel_hi:[1,1,0] neg_lo:[1,0,0] neg_hi:[1,0,0]
	v_pk_fma_f32 v[132:133], v[128:129], v[132:133], v[132:133]
	v_pk_fma_f32 v[134:135], v[130:131], v[134:135], v[134:135]
	v_pk_fma_f32 v[220:221], v[132:133], v[140:141], v[220:221]
	v_pk_fma_f32 v[222:223], v[134:135], v[142:143], v[222:223]
	global_store_dwordx4 v166, v[220:223], s[68:69] offset:64
	global_load_dwordx2 v[150:151], v167, s[58:59] offset:32
	global_load_dwordx4 v[220:223], v166, s[56:57] offset:64
	s_waitcnt vmcnt(20)
; DEV float bflo(unsigned w) { return __uint_as_float(w << 16); }
; DEV float bfhi(unsigned w) { return __uint_as_float(w & 0xffff0000u); }
; DEV float sigmoidf_(float x) { return 1.0f / (1.0f + __expf(-x)); }
;   DEV void operator()(const f32x4 (&acc)[2][2][4][2], const Unit& u, int wr, int wc, int fr, int fq) const {
;     const int row0 = u.pm * BM + wr * 64 + fr, col0 = u.pn * BM + wc * 32 + 4 * fq;
; #pragma unroll
;     for (int ai = 0; ai < 2; ++ai)
; #pragma unroll
;       for (int mp = 0; mp < 2; ++mp) {
;         f32x4 xv[2][2][2]; u32x2 pw[2][2][2];
; #pragma unroll
;         for (int mm = 0; mm < 2; ++mm)
; #pragma unroll
;           for (int bj = 0; bj < 2; ++bj)
; #pragma unroll
;             for (int n = 0; n < 2; ++n) {
;               const size_t o = (size_t)(row0 + ai * HALF + (mp * 2 + mm) * 16) * D + col0 + bj * HALF + n * 16;
;               pw[mm][bj][n] = *(const u32x2*)(PROJ + o);
;               xv[mm][bj][n] = *(const f32x4*)(X + o);
;             }
; #pragma unroll
;         for (int mm = 0; mm < 2; ++mm)
; #pragma unroll
;           for (int bj = 0; bj < 2; ++bj)
; #pragma unroll
;             for (int n = 0; n < 2; ++n) {
;               const size_t o = (size_t)(row0 + ai * HALF + (mp * 2 + mm) * 16) * D + col0 + bj * HALF + n * 16;
;               const f32x4 v = acc[ai][bj][mp * 2 + mm][n];
;               f32x4 x = xv[mm][bj][n]; const u32x2 w = pw[mm][bj][n];
;               x[0] += sigmoidf_(v[0]) * bflo(w.x); x[1] += sigmoidf_(v[1]) * bfhi(w.x); x[2] += sigmoidf_(v[2]) * bflo(w.y); x[3] += sigmoidf_(v[3]) * bfhi(w.y);
;               *(f32x4*)(X + o) = x;
;             }
;         asm volatile("" ::: "memory");
;       }
;   }
	v_pk_mul_f32 v[128:129], v[100:101], s[70:71]
	v_pk_mul_f32 v[130:131], v[102:103], s[70:71]
	v_lshlrev_b32_e32 v140, 16, v152
	v_exp_f32_e32 v128, v128
	v_exp_f32_e32 v129, v129
	v_exp_f32_e32 v130, v130
	v_exp_f32_e32 v131, v131
	v_and_b32_e32 v141, 0xffff0000, v152
	v_pk_add_f32 v[128:129], v[128:129], 1.0 op_sel_hi:[1,0]
	v_pk_add_f32 v[130:131], v[130:131], 1.0 op_sel_hi:[1,0]
	v_rcp_f32_e32 v132, v128
	v_rcp_f32_e32 v133, v129
	v_rcp_f32_e32 v134, v130
	v_rcp_f32_e32 v135, v131
	v_lshlrev_b32_e32 v142, 16, v153
	v_and_b32_e32 v143, 0xffff0000, v153
	v_pk_fma_f32 v[128:129], v[128:129], v[132:133], 1.0 op_sel_hi:[1,1,0] neg_lo:[1,0,0] neg_hi:[1,0,0]
	v_pk_fma_f32 v[130:131], v[130:131], v[134:135], 1.0 op_sel_hi:[1,1,0] neg_lo:[1,0,0] neg_hi:[1,0,0]
	v_pk_fma_f32 v[132:133], v[128:129], v[132:133], v[132:133]
	v_pk_fma_f32 v[134:135], v[130:131], v[134:135], v[134:135]
	v_pk_fma_f32 v[224:225], v[132:133], v[140:141], v[224:225]
	v_pk_fma_f32 v[226:227], v[134:135], v[142:143], v[226:227]
	global_store_dwordx4 v166, v[224:227], s[68:69] offset:512
	global_load_dwordx2 v[152:153], v167, s[58:59] offset:256
	global_load_dwordx4 v[224:227], v166, s[56:57] offset:512
	s_waitcnt vmcnt(21)
	v_pk_mul_f32 v[128:129], v[96:97], s[70:71]
	v_pk_mul_f32 v[130:131], v[98:99], s[70:71]
	v_lshlrev_b32_e32 v140, 16, v154
	v_exp_f32_e32 v128, v128
	v_exp_f32_e32 v129, v129
	v_exp_f32_e32 v130, v130
	v_exp_f32_e32 v131, v131
	v_and_b32_e32 v141, 0xffff0000, v154
	v_pk_add_f32 v[128:129], v[128:129], 1.0 op_sel_hi:[1,0]
	v_pk_add_f32 v[130:131], v[130:131], 1.0 op_sel_hi:[1,0]
	v_rcp_f32_e32 v132, v128
	v_rcp_f32_e32 v133, v129
	v_rcp_f32_e32 v134, v130
	v_rcp_f32_e32 v135, v131
	v_lshlrev_b32_e32 v142, 16, v155
	v_and_b32_e32 v143, 0xffff0000, v155
	v_pk_fma_f32 v[128:129], v[128:129], v[132:133], 1.0 op_sel_hi:[1,1,0] neg_lo:[1,0,0] neg_hi:[1,0,0]
	v_pk_fma_f32 v[130:131], v[130:131], v[134:135], 1.0 op_sel_hi:[1,1,0] neg_lo:[1,0,0] neg_hi:[1,0,0]
	v_pk_fma_f32 v[132:133], v[128:129], v[132:133], v[132:133]
	v_pk_fma_f32 v[134:135], v[130:131], v[134:135], v[134:135]
	v_pk_fma_f32 v[228:229], v[132:133], v[140:141], v[228:229]
	v_pk_fma_f32 v[230:231], v[134:135], v[142:143], v[230:231]
	global_store_dwordx4 v166, v[228:231], s[68:69] offset:576
	s_add_u32 s68, s68, 0x10000
	s_addc_u32 s69, s69, 0
	global_load_dwordx2 v[154:155], v167, s[58:59] offset:288
	global_load_dwordx4 v[228:231], v166, s[56:57] offset:576
	s_add_u32 s56, s56, 0x50000
	s_addc_u32 s57, s57, 0
	s_add_u32 s58, s58, 0x28000
	s_addc_u32 s59, s59, 0
	s_waitcnt vmcnt(21)
	v_pk_mul_f32 v[128:129], v[92:93], s[70:71]
	v_pk_mul_f32 v[130:131], v[94:95], s[70:71]
	v_lshlrev_b32_e32 v140, 16, v232
	v_exp_f32_e32 v128, v128
	v_exp_f32_e32 v129, v129
	v_exp_f32_e32 v130, v130
	v_exp_f32_e32 v131, v131
	v_and_b32_e32 v141, 0xffff0000, v232
	v_pk_add_f32 v[128:129], v[128:129], 1.0 op_sel_hi:[1,0]
	v_pk_add_f32 v[130:131], v[130:131], 1.0 op_sel_hi:[1,0]
	v_rcp_f32_e32 v132, v128
	v_rcp_f32_e32 v133, v129
	v_rcp_f32_e32 v134, v130
	v_rcp_f32_e32 v135, v131
	v_lshlrev_b32_e32 v142, 16, v233
	v_and_b32_e32 v143, 0xffff0000, v233
	v_pk_fma_f32 v[128:129], v[128:129], v[132:133], 1.0 op_sel_hi:[1,1,0] neg_lo:[1,0,0] neg_hi:[1,0,0]
	v_pk_fma_f32 v[130:131], v[130:131], v[134:135], 1.0 op_sel_hi:[1,1,0] neg_lo:[1,0,0] neg_hi:[1,0,0]
	v_pk_fma_f32 v[132:133], v[128:129], v[132:133], v[132:133]
	v_pk_fma_f32 v[134:135], v[130:131], v[134:135], v[134:135]
	v_pk_fma_f32 v[180:181], v[132:133], v[140:141], v[180:181]
	v_pk_fma_f32 v[182:183], v[134:135], v[142:143], v[182:183]
	global_store_dwordx4 v166, v[180:183], s[68:69]
	global_load_dwordx2 v[232:233], v167, s[58:59]
	global_load_dwordx4 v[180:183], v166, s[56:57]
	s_waitcnt vmcnt(21)
	v_pk_mul_f32 v[128:129], v[88:89], s[70:71]
	v_pk_mul_f32 v[130:131], v[90:91], s[70:71]
	v_lshlrev_b32_e32 v140, 16, v234
	v_exp_f32_e32 v128, v128
	v_exp_f32_e32 v129, v129
	v_exp_f32_e32 v130, v130
	v_exp_f32_e32 v131, v131
	v_and_b32_e32 v141, 0xffff0000, v234
	v_pk_add_f32 v[128:129], v[128:129], 1.0 op_sel_hi:[1,0]
	v_pk_add_f32 v[130:131], v[130:131], 1.0 op_sel_hi:[1,0]
	v_rcp_f32_e32 v132, v128
	v_rcp_f32_e32 v133, v129
	v_rcp_f32_e32 v134, v130
	v_rcp_f32_e32 v135, v131
	v_lshlrev_b32_e32 v142, 16, v235
	v_and_b32_e32 v143, 0xffff0000, v235
	v_pk_fma_f32 v[128:129], v[128:129], v[132:133], 1.0 op_sel_hi:[1,1,0] neg_lo:[1,0,0] neg_hi:[1,0,0]
	v_pk_fma_f32 v[130:131], v[130:131], v[134:135], 1.0 op_sel_hi:[1,1,0] neg_lo:[1,0,0] neg_hi:[1,0,0]
	v_pk_fma_f32 v[132:133], v[128:129], v[132:133], v[132:133]
	v_pk_fma_f32 v[134:135], v[130:131], v[134:135], v[134:135]
	v_pk_fma_f32 v[184:185], v[132:133], v[140:141], v[184:185]
	v_pk_fma_f32 v[186:187], v[134:135], v[142:143], v[186:187]
	global_store_dwordx4 v166, v[184:187], s[68:69] offset:64
	global_load_dwordx2 v[234:235], v167, s[58:59] offset:32
	global_load_dwordx4 v[184:187], v166, s[56:57] offset:64
	s_waitcnt vmcnt(21)
	v_pk_mul_f32 v[128:129], v[84:85], s[70:71]
	v_pk_mul_f32 v[130:131], v[86:87], s[70:71]
	v_lshlrev_b32_e32 v140, 16, v236
	v_exp_f32_e32 v128, v128
	v_exp_f32_e32 v129, v129
	v_exp_f32_e32 v130, v130
	v_exp_f32_e32 v131, v131
	v_and_b32_e32 v141, 0xffff0000, v236
	v_pk_add_f32 v[128:129], v[128:129], 1.0 op_sel_hi:[1,0]
	v_pk_add_f32 v[130:131], v[130:131], 1.0 op_sel_hi:[1,0]
	v_rcp_f32_e32 v132, v128
	v_rcp_f32_e32 v133, v129
	v_rcp_f32_e32 v134, v130
	v_rcp_f32_e32 v135, v131
	v_lshlrev_b32_e32 v142, 16, v237
	v_and_b32_e32 v143, 0xffff0000, v237
	v_pk_fma_f32 v[128:129], v[128:129], v[132:133], 1.0 op_sel_hi:[1,1,0] neg_lo:[1,0,0] neg_hi:[1,0,0]
	v_pk_fma_f32 v[130:131], v[130:131], v[134:135], 1.0 op_sel_hi:[1,1,0] neg_lo:[1,0,0] neg_hi:[1,0,0]
	v_pk_fma_f32 v[132:133], v[128:129], v[132:133], v[132:133]
	v_pk_fma_f32 v[134:135], v[130:131], v[134:135], v[134:135]
	v_pk_fma_f32 v[188:189], v[132:133], v[140:141], v[188:189]
	v_pk_fma_f32 v[190:191], v[134:135], v[142:143], v[190:191]
	global_store_dwordx4 v166, v[188:191], s[68:69] offset:512
	global_load_dwordx2 v[236:237], v167, s[58:59] offset:256
	global_load_dwordx4 v[188:191], v166, s[56:57] offset:512
	s_waitcnt vmcnt(21)
; DEV float bflo(unsigned w) { return __uint_as_float(w << 16); }
; DEV float bfhi(unsigned w) { return __uint_as_float(w & 0xffff0000u); }
; DEV float sigmoidf_(float x) { return 1.0f / (1.0f + __expf(-x)); }
;   DEV void operator()(const f32x4 (&acc)[2][2][4][2], const Unit& u, int wr, int wc, int fr, int fq) const {
;     const int row0 = u.pm * BM + wr * 64 + fr, col0 = u.pn * BM + wc * 32 + 4 * fq;
; #pragma unroll
;     for (int ai = 0; ai < 2; ++ai)
; #pragma unroll
;       for (int mp = 0; mp < 2; ++mp) {
;         f32x4 xv[2][2][2]; u32x2 pw[2][2][2];
; #pragma unroll
;         for (int mm = 0; mm < 2; ++mm)
; #pragma unroll
;           for (int bj = 0; bj < 2; ++bj)
; #pragma unroll
;             for (int n = 0; n < 2; ++n) {
;               const size_t o = (size_t)(row0 + ai * HALF + (mp * 2 + mm) * 16) * D + col0 + bj * HALF + n * 16;
;               pw[mm][bj][n] = *(const u32x2*)(PROJ + o);
;               xv[mm][bj][n] = *(const f32x4*)(X + o);
;             }
; #pragma unroll
;         for (int mm = 0; mm < 2; ++mm)
; #pragma unroll
;           for (int bj = 0; bj < 2; ++bj)
; #pragma unroll
;             for (int n = 0; n < 2; ++n) {
;               const size_t o = (size_t)(row0 + ai * HALF + (mp * 2 + mm) * 16) * D + col0 + bj * HALF + n * 16;
;               const f32x4 v = acc[ai][bj][mp * 2 + mm][n];
;               f32x4 x = xv[mm][bj][n]; const u32x2 w = pw[mm][bj][n];
;               x[0] += sigmoidf_(v[0]) * bflo(w.x); x[1] += sigmoidf_(v[1]) * bfhi(w.x); x[2] += sigmoidf_(v[2]) * bflo(w.y); x[3] += sigmoidf_(v[3]) * bfhi(w.y);
;               *(f32x4*)(X + o) = x;
;             }
;         asm volatile("" ::: "memory");
;       }
;   }
	v_pk_mul_f32 v[128:129], v[80:81], s[70:71]
	v_pk_mul_f32 v[130:131], v[82:83], s[70:71]
	v_lshlrev_b32_e32 v140, 16, v238
	v_exp_f32_e32 v128, v128
	v_exp_f32_e32 v129, v129
	v_exp_f32_e32 v130, v130
	v_exp_f32_e32 v131, v131
	v_and_b32_e32 v141, 0xffff0000, v238
	v_pk_add_f32 v[128:129], v[128:129], 1.0 op_sel_hi:[1,0]
	v_pk_add_f32 v[130:131], v[130:131], 1.0 op_sel_hi:[1,0]
	v_rcp_f32_e32 v132, v128
	v_rcp_f32_e32 v133, v129
	v_rcp_f32_e32 v134, v130
	v_rcp_f32_e32 v135, v131
	v_lshlrev_b32_e32 v142, 16, v239
	v_and_b32_e32 v143, 0xffff0000, v239
	v_pk_fma_f32 v[128:129], v[128:129], v[132:133], 1.0 op_sel_hi:[1,1,0] neg_lo:[1,0,0] neg_hi:[1,0,0]
	v_pk_fma_f32 v[130:131], v[130:131], v[134:135], 1.0 op_sel_hi:[1,1,0] neg_lo:[1,0,0] neg_hi:[1,0,0]
	v_pk_fma_f32 v[132:133], v[128:129], v[132:133], v[132:133]
	v_pk_fma_f32 v[134:135], v[130:131], v[134:135], v[134:135]
	v_pk_fma_f32 v[192:193], v[132:133], v[140:141], v[192:193]
	v_pk_fma_f32 v[194:195], v[134:135], v[142:143], v[194:195]
	global_store_dwordx4 v166, v[192:195], s[68:69] offset:576
	s_add_u32 s68, s68, 0x10000
	s_addc_u32 s69, s69, 0
	global_load_dwordx2 v[238:239], v167, s[58:59] offset:288
	global_load_dwordx4 v[192:195], v166, s[56:57] offset:576
	s_add_u32 s56, s56, 0x10000
	s_addc_u32 s57, s57, 0
	s_add_u32 s58, s58, 0x8000
	s_addc_u32 s59, s59, 0
	s_waitcnt vmcnt(21)
	v_pk_mul_f32 v[128:129], v[76:77], s[70:71]
	v_pk_mul_f32 v[130:131], v[78:79], s[70:71]
	v_lshlrev_b32_e32 v140, 16, v148
	v_exp_f32_e32 v128, v128
	v_exp_f32_e32 v129, v129
	v_exp_f32_e32 v130, v130
	v_exp_f32_e32 v131, v131
	v_and_b32_e32 v141, 0xffff0000, v148
	v_pk_add_f32 v[128:129], v[128:129], 1.0 op_sel_hi:[1,0]
	v_pk_add_f32 v[130:131], v[130:131], 1.0 op_sel_hi:[1,0]
	v_rcp_f32_e32 v132, v128
	v_rcp_f32_e32 v133, v129
	v_rcp_f32_e32 v134, v130
	v_rcp_f32_e32 v135, v131
	v_lshlrev_b32_e32 v142, 16, v149
	v_and_b32_e32 v143, 0xffff0000, v149
	v_pk_fma_f32 v[128:129], v[128:129], v[132:133], 1.0 op_sel_hi:[1,1,0] neg_lo:[1,0,0] neg_hi:[1,0,0]
	v_pk_fma_f32 v[130:131], v[130:131], v[134:135], 1.0 op_sel_hi:[1,1,0] neg_lo:[1,0,0] neg_hi:[1,0,0]
	v_pk_fma_f32 v[132:133], v[128:129], v[132:133], v[132:133]
	v_pk_fma_f32 v[134:135], v[130:131], v[134:135], v[134:135]
	v_pk_fma_f32 v[196:197], v[132:133], v[140:141], v[196:197]
	v_pk_fma_f32 v[198:199], v[134:135], v[142:143], v[198:199]
	global_store_dwordx4 v166, v[196:199], s[68:69]
	global_load_dwordx2 v[148:149], v167, s[58:59]
	global_load_dwordx4 v[196:199], v166, s[56:57]
	s_waitcnt vmcnt(21)
	v_pk_mul_f32 v[128:129], v[72:73], s[70:71]
	v_pk_mul_f32 v[130:131], v[74:75], s[70:71]
	v_lshlrev_b32_e32 v140, 16, v150
	v_exp_f32_e32 v128, v128
	v_exp_f32_e32 v129, v129
	v_exp_f32_e32 v130, v130
	v_exp_f32_e32 v131, v131
	v_and_b32_e32 v141, 0xffff0000, v150
	v_pk_add_f32 v[128:129], v[128:129], 1.0 op_sel_hi:[1,0]
	v_pk_add_f32 v[130:131], v[130:131], 1.0 op_sel_hi:[1,0]
	v_rcp_f32_e32 v132, v128
	v_rcp_f32_e32 v133, v129
	v_rcp_f32_e32 v134, v130
	v_rcp_f32_e32 v135, v131
	v_lshlrev_b32_e32 v142, 16, v151
	v_and_b32_e32 v143, 0xffff0000, v151
	v_pk_fma_f32 v[128:129], v[128:129], v[132:133], 1.0 op_sel_hi:[1,1,0] neg_lo:[1,0,0] neg_hi:[1,0,0]
	v_pk_fma_f32 v[130:131], v[130:131], v[134:135], 1.0 op_sel_hi:[1,1,0] neg_lo:[1,0,0] neg_hi:[1,0,0]
	v_pk_fma_f32 v[132:133], v[128:129], v[132:133], v[132:133]
	v_pk_fma_f32 v[134:135], v[130:131], v[134:135], v[134:135]
	v_pk_fma_f32 v[220:221], v[132:133], v[140:141], v[220:221]
	v_pk_fma_f32 v[222:223], v[134:135], v[142:143], v[222:223]
	global_store_dwordx4 v166, v[220:223], s[68:69] offset:64
	global_load_dwordx2 v[150:151], v167, s[58:59] offset:32
	global_load_dwordx4 v[220:223], v166, s[56:57] offset:64
	s_waitcnt vmcnt(21)
	v_pk_mul_f32 v[128:129], v[68:69], s[70:71]
	v_pk_mul_f32 v[130:131], v[70:71], s[70:71]
	v_lshlrev_b32_e32 v140, 16, v152
	v_exp_f32_e32 v128, v128
	v_exp_f32_e32 v129, v129
	v_exp_f32_e32 v130, v130
	v_exp_f32_e32 v131, v131
	v_and_b32_e32 v141, 0xffff0000, v152
	v_pk_add_f32 v[128:129], v[128:129], 1.0 op_sel_hi:[1,0]
	v_pk_add_f32 v[130:131], v[130:131], 1.0 op_sel_hi:[1,0]
	v_rcp_f32_e32 v132, v128
	v_rcp_f32_e32 v133, v129
	v_rcp_f32_e32 v134, v130
	v_rcp_f32_e32 v135, v131
	v_lshlrev_b32_e32 v142, 16, v153
	v_and_b32_e32 v143, 0xffff0000, v153
	v_pk_fma_f32 v[128:129], v[128:129], v[132:133], 1.0 op_sel_hi:[1,1,0] neg_lo:[1,0,0] neg_hi:[1,0,0]
	v_pk_fma_f32 v[130:131], v[130:131], v[134:135], 1.0 op_sel_hi:[1,1,0] neg_lo:[1,0,0] neg_hi:[1,0,0]
	v_pk_fma_f32 v[132:133], v[128:129], v[132:133], v[132:133]
	v_pk_fma_f32 v[134:135], v[130:131], v[134:135], v[134:135]
	v_pk_fma_f32 v[224:225], v[132:133], v[140:141], v[224:225]
	v_pk_fma_f32 v[226:227], v[134:135], v[142:143], v[226:227]
	global_store_dwordx4 v166, v[224:227], s[68:69] offset:512
	global_load_dwordx2 v[152:153], v167, s[58:59] offset:256
	global_load_dwordx4 v[224:227], v166, s[56:57] offset:512
	s_waitcnt vmcnt(21)
	v_pk_mul_f32 v[128:129], v[64:65], s[70:71]
	v_pk_mul_f32 v[130:131], v[66:67], s[70:71]
	v_lshlrev_b32_e32 v140, 16, v154
	v_exp_f32_e32 v128, v128
	v_exp_f32_e32 v129, v129
	v_exp_f32_e32 v130, v130
	v_exp_f32_e32 v131, v131
	v_and_b32_e32 v141, 0xffff0000, v154
	v_pk_add_f32 v[128:129], v[128:129], 1.0 op_sel_hi:[1,0]
	v_pk_add_f32 v[130:131], v[130:131], 1.0 op_sel_hi:[1,0]
	v_rcp_f32_e32 v132, v128
	v_rcp_f32_e32 v133, v129
	v_rcp_f32_e32 v134, v130
	v_rcp_f32_e32 v135, v131
	v_lshlrev_b32_e32 v142, 16, v155
	v_and_b32_e32 v143, 0xffff0000, v155
	v_pk_fma_f32 v[128:129], v[128:129], v[132:133], 1.0 op_sel_hi:[1,1,0] neg_lo:[1,0,0] neg_hi:[1,0,0]
	v_pk_fma_f32 v[130:131], v[130:131], v[134:135], 1.0 op_sel_hi:[1,1,0] neg_lo:[1,0,0] neg_hi:[1,0,0]
	v_pk_fma_f32 v[132:133], v[128:129], v[132:133], v[132:133]
	v_pk_fma_f32 v[134:135], v[130:131], v[134:135], v[134:135]
	v_pk_fma_f32 v[228:229], v[132:133], v[140:141], v[228:229]
	v_pk_fma_f32 v[230:231], v[134:135], v[142:143], v[230:231]
	global_store_dwordx4 v166, v[228:231], s[68:69] offset:576
	s_add_u32 s68, s68, 0x50000
	s_addc_u32 s69, s69, 0
	global_load_dwordx2 v[154:155], v167, s[58:59] offset:288
	global_load_dwordx4 v[228:231], v166, s[56:57] offset:576
	s_add_u32 s56, s56, 0x10000
	s_addc_u32 s57, s57, 0
	s_add_u32 s58, s58, 0x8000
	s_addc_u32 s59, s59, 0
	s_waitcnt vmcnt(21)
; DEV float bflo(unsigned w) { return __uint_as_float(w << 16); }
; DEV float bfhi(unsigned w) { return __uint_as_float(w & 0xffff0000u); }
; DEV float sigmoidf_(float x) { return 1.0f / (1.0f + __expf(-x)); }
;   DEV void operator()(const f32x4 (&acc)[2][2][4][2], const Unit& u, int wr, int wc, int fr, int fq) const {
;     const int row0 = u.pm * BM + wr * 64 + fr, col0 = u.pn * BM + wc * 32 + 4 * fq;
; #pragma unroll
;     for (int ai = 0; ai < 2; ++ai)
; #pragma unroll
;       for (int mp = 0; mp < 2; ++mp) {
;         f32x4 xv[2][2][2]; u32x2 pw[2][2][2];
; #pragma unroll
;         for (int mm = 0; mm < 2; ++mm)
; #pragma unroll
;           for (int bj = 0; bj < 2; ++bj)
; #pragma unroll
;             for (int n = 0; n < 2; ++n) {
;               const size_t o = (size_t)(row0 + ai * HALF + (mp * 2 + mm) * 16) * D + col0 + bj * HALF + n * 16;
;               pw[mm][bj][n] = *(const u32x2*)(PROJ + o);
;               xv[mm][bj][n] = *(const f32x4*)(X + o);
;             }
; #pragma unroll
;         for (int mm = 0; mm < 2; ++mm)
; #pragma unroll
;           for (int bj = 0; bj < 2; ++bj)
; #pragma unroll
;             for (int n = 0; n < 2; ++n) {
;               const size_t o = (size_t)(row0 + ai * HALF + (mp * 2 + mm) * 16) * D + col0 + bj * HALF + n * 16;
;               const f32x4 v = acc[ai][bj][mp * 2 + mm][n];
;               f32x4 x = xv[mm][bj][n]; const u32x2 w = pw[mm][bj][n];
;               x[0] += sigmoidf_(v[0]) * bflo(w.x); x[1] += sigmoidf_(v[1]) * bfhi(w.x); x[2] += sigmoidf_(v[2]) * bflo(w.y); x[3] += sigmoidf_(v[3]) * bfhi(w.y);
;               *(f32x4*)(X + o) = x;
;             }
;         asm volatile("" ::: "memory");
;       }
;   }
	v_pk_mul_f32 v[128:129], v[60:61], s[70:71]
	v_pk_mul_f32 v[130:131], v[62:63], s[70:71]
	v_lshlrev_b32_e32 v140, 16, v232
	v_exp_f32_e32 v128, v128
	v_exp_f32_e32 v129, v129
	v_exp_f32_e32 v130, v130
	v_exp_f32_e32 v131, v131
	v_and_b32_e32 v141, 0xffff0000, v232
	v_pk_add_f32 v[128:129], v[128:129], 1.0 op_sel_hi:[1,0]
	v_pk_add_f32 v[130:131], v[130:131], 1.0 op_sel_hi:[1,0]
	v_rcp_f32_e32 v132, v128
	v_rcp_f32_e32 v133, v129
	v_rcp_f32_e32 v134, v130
	v_rcp_f32_e32 v135, v131
	v_lshlrev_b32_e32 v142, 16, v233
	v_and_b32_e32 v143, 0xffff0000, v233
	v_pk_fma_f32 v[128:129], v[128:129], v[132:133], 1.0 op_sel_hi:[1,1,0] neg_lo:[1,0,0] neg_hi:[1,0,0]
	v_pk_fma_f32 v[130:131], v[130:131], v[134:135], 1.0 op_sel_hi:[1,1,0] neg_lo:[1,0,0] neg_hi:[1,0,0]
	v_pk_fma_f32 v[132:133], v[128:129], v[132:133], v[132:133]
	v_pk_fma_f32 v[134:135], v[130:131], v[134:135], v[134:135]
	v_pk_fma_f32 v[180:181], v[132:133], v[140:141], v[180:181]
	v_pk_fma_f32 v[182:183], v[134:135], v[142:143], v[182:183]
	global_store_dwordx4 v166, v[180:183], s[68:69]
	global_load_dwordx2 v[232:233], v167, s[58:59]
	global_load_dwordx4 v[180:183], v166, s[56:57]
	s_waitcnt vmcnt(21)
	v_pk_mul_f32 v[128:129], v[56:57], s[70:71]
	v_pk_mul_f32 v[130:131], v[58:59], s[70:71]
	v_lshlrev_b32_e32 v140, 16, v234
	v_exp_f32_e32 v128, v128
	v_exp_f32_e32 v129, v129
	v_exp_f32_e32 v130, v130
	v_exp_f32_e32 v131, v131
	v_and_b32_e32 v141, 0xffff0000, v234
	v_pk_add_f32 v[128:129], v[128:129], 1.0 op_sel_hi:[1,0]
	v_pk_add_f32 v[130:131], v[130:131], 1.0 op_sel_hi:[1,0]
	v_rcp_f32_e32 v132, v128
	v_rcp_f32_e32 v133, v129
	v_rcp_f32_e32 v134, v130
	v_rcp_f32_e32 v135, v131
	v_lshlrev_b32_e32 v142, 16, v235
	v_and_b32_e32 v143, 0xffff0000, v235
	v_pk_fma_f32 v[128:129], v[128:129], v[132:133], 1.0 op_sel_hi:[1,1,0] neg_lo:[1,0,0] neg_hi:[1,0,0]
	v_pk_fma_f32 v[130:131], v[130:131], v[134:135], 1.0 op_sel_hi:[1,1,0] neg_lo:[1,0,0] neg_hi:[1,0,0]
	v_pk_fma_f32 v[132:133], v[128:129], v[132:133], v[132:133]
	v_pk_fma_f32 v[134:135], v[130:131], v[134:135], v[134:135]
	v_pk_fma_f32 v[184:185], v[132:133], v[140:141], v[184:185]
	v_pk_fma_f32 v[186:187], v[134:135], v[142:143], v[186:187]
	global_store_dwordx4 v166, v[184:187], s[68:69] offset:64
	global_load_dwordx2 v[234:235], v167, s[58:59] offset:32
	global_load_dwordx4 v[184:187], v166, s[56:57] offset:64
	s_waitcnt vmcnt(21)
	v_pk_mul_f32 v[128:129], v[52:53], s[70:71]
	v_pk_mul_f32 v[130:131], v[54:55], s[70:71]
	v_lshlrev_b32_e32 v140, 16, v236
	v_exp_f32_e32 v128, v128
	v_exp_f32_e32 v129, v129
	v_exp_f32_e32 v130, v130
	v_exp_f32_e32 v131, v131
	v_and_b32_e32 v141, 0xffff0000, v236
	v_pk_add_f32 v[128:129], v[128:129], 1.0 op_sel_hi:[1,0]
	v_pk_add_f32 v[130:131], v[130:131], 1.0 op_sel_hi:[1,0]
	v_rcp_f32_e32 v132, v128
	v_rcp_f32_e32 v133, v129
	v_rcp_f32_e32 v134, v130
	v_rcp_f32_e32 v135, v131
	v_lshlrev_b32_e32 v142, 16, v237
	v_and_b32_e32 v143, 0xffff0000, v237
	v_pk_fma_f32 v[128:129], v[128:129], v[132:133], 1.0 op_sel_hi:[1,1,0] neg_lo:[1,0,0] neg_hi:[1,0,0]
	v_pk_fma_f32 v[130:131], v[130:131], v[134:135], 1.0 op_sel_hi:[1,1,0] neg_lo:[1,0,0] neg_hi:[1,0,0]
	v_pk_fma_f32 v[132:133], v[128:129], v[132:133], v[132:133]
	v_pk_fma_f32 v[134:135], v[130:131], v[134:135], v[134:135]
	v_pk_fma_f32 v[188:189], v[132:133], v[140:141], v[188:189]
	v_pk_fma_f32 v[190:191], v[134:135], v[142:143], v[190:191]
	global_store_dwordx4 v166, v[188:191], s[68:69] offset:512
	global_load_dwordx2 v[236:237], v167, s[58:59] offset:256
	global_load_dwordx4 v[188:191], v166, s[56:57] offset:512
	s_waitcnt vmcnt(21)
	v_pk_mul_f32 v[128:129], v[48:49], s[70:71]
	v_pk_mul_f32 v[130:131], v[50:51], s[70:71]
	v_lshlrev_b32_e32 v140, 16, v238
	v_exp_f32_e32 v128, v128
	v_exp_f32_e32 v129, v129
	v_exp_f32_e32 v130, v130
	v_exp_f32_e32 v131, v131
	v_and_b32_e32 v141, 0xffff0000, v238
	v_pk_add_f32 v[128:129], v[128:129], 1.0 op_sel_hi:[1,0]
	v_pk_add_f32 v[130:131], v[130:131], 1.0 op_sel_hi:[1,0]
	v_rcp_f32_e32 v132, v128
	v_rcp_f32_e32 v133, v129
	v_rcp_f32_e32 v134, v130
	v_rcp_f32_e32 v135, v131
	v_lshlrev_b32_e32 v142, 16, v239
	v_and_b32_e32 v143, 0xffff0000, v239
	v_pk_fma_f32 v[128:129], v[128:129], v[132:133], 1.0 op_sel_hi:[1,1,0] neg_lo:[1,0,0] neg_hi:[1,0,0]
	v_pk_fma_f32 v[130:131], v[130:131], v[134:135], 1.0 op_sel_hi:[1,1,0] neg_lo:[1,0,0] neg_hi:[1,0,0]
	v_pk_fma_f32 v[132:133], v[128:129], v[132:133], v[132:133]
	v_pk_fma_f32 v[134:135], v[130:131], v[134:135], v[134:135]
	v_pk_fma_f32 v[192:193], v[132:133], v[140:141], v[192:193]
	v_pk_fma_f32 v[194:195], v[134:135], v[142:143], v[194:195]
	global_store_dwordx4 v166, v[192:195], s[68:69] offset:576
	s_add_u32 s68, s68, 0x10000
	s_addc_u32 s69, s69, 0
	global_load_dwordx2 v[238:239], v167, s[58:59] offset:288
	global_load_dwordx4 v[192:195], v166, s[56:57] offset:576
	s_add_u32 s56, s56, 0x10000
	s_addc_u32 s57, s57, 0
	s_add_u32 s58, s58, 0x8000
	s_addc_u32 s59, s59, 0
	s_waitcnt vmcnt(21)
	v_pk_mul_f32 v[128:129], v[44:45], s[70:71]
	v_pk_mul_f32 v[130:131], v[46:47], s[70:71]
	v_lshlrev_b32_e32 v140, 16, v148
	v_exp_f32_e32 v128, v128
	v_exp_f32_e32 v129, v129
	v_exp_f32_e32 v130, v130
	v_exp_f32_e32 v131, v131
	v_and_b32_e32 v141, 0xffff0000, v148
	v_pk_add_f32 v[128:129], v[128:129], 1.0 op_sel_hi:[1,0]
	v_pk_add_f32 v[130:131], v[130:131], 1.0 op_sel_hi:[1,0]
	v_rcp_f32_e32 v132, v128
	v_rcp_f32_e32 v133, v129
	v_rcp_f32_e32 v134, v130
	v_rcp_f32_e32 v135, v131
	v_lshlrev_b32_e32 v142, 16, v149
	v_and_b32_e32 v143, 0xffff0000, v149
	v_pk_fma_f32 v[128:129], v[128:129], v[132:133], 1.0 op_sel_hi:[1,1,0] neg_lo:[1,0,0] neg_hi:[1,0,0]
	v_pk_fma_f32 v[130:131], v[130:131], v[134:135], 1.0 op_sel_hi:[1,1,0] neg_lo:[1,0,0] neg_hi:[1,0,0]
	v_pk_fma_f32 v[132:133], v[128:129], v[132:133], v[132:133]
	v_pk_fma_f32 v[134:135], v[130:131], v[134:135], v[134:135]
	v_pk_fma_f32 v[196:197], v[132:133], v[140:141], v[196:197]
	v_pk_fma_f32 v[198:199], v[134:135], v[142:143], v[198:199]
	global_store_dwordx4 v166, v[196:199], s[68:69]
	global_load_dwordx2 v[148:149], v167, s[58:59]
	global_load_dwordx4 v[196:199], v166, s[56:57]
	s_waitcnt vmcnt(21)
; DEV float bflo(unsigned w) { return __uint_as_float(w << 16); }
; DEV float bfhi(unsigned w) { return __uint_as_float(w & 0xffff0000u); }
; DEV float sigmoidf_(float x) { return 1.0f / (1.0f + __expf(-x)); }
;   DEV void operator()(const f32x4 (&acc)[2][2][4][2], const Unit& u, int wr, int wc, int fr, int fq) const {
;     const int row0 = u.pm * BM + wr * 64 + fr, col0 = u.pn * BM + wc * 32 + 4 * fq;
; #pragma unroll
;     for (int ai = 0; ai < 2; ++ai)
; #pragma unroll
;       for (int mp = 0; mp < 2; ++mp) {
;         f32x4 xv[2][2][2]; u32x2 pw[2][2][2];
; #pragma unroll
;         for (int mm = 0; mm < 2; ++mm)
; #pragma unroll
;           for (int bj = 0; bj < 2; ++bj)
; #pragma unroll
;             for (int n = 0; n < 2; ++n) {
;               const size_t o = (size_t)(row0 + ai * HALF + (mp * 2 + mm) * 16) * D + col0 + bj * HALF + n * 16;
;               pw[mm][bj][n] = *(const u32x2*)(PROJ + o);
;               xv[mm][bj][n] = *(const f32x4*)(X + o);
;             }
; #pragma unroll
;         for (int mm = 0; mm < 2; ++mm)
; #pragma unroll
;           for (int bj = 0; bj < 2; ++bj)
; #pragma unroll
;             for (int n = 0; n < 2; ++n) {
;               const size_t o = (size_t)(row0 + ai * HALF + (mp * 2 + mm) * 16) * D + col0 + bj * HALF + n * 16;
;               const f32x4 v = acc[ai][bj][mp * 2 + mm][n];
;               f32x4 x = xv[mm][bj][n]; const u32x2 w = pw[mm][bj][n];
;               x[0] += sigmoidf_(v[0]) * bflo(w.x); x[1] += sigmoidf_(v[1]) * bfhi(w.x); x[2] += sigmoidf_(v[2]) * bflo(w.y); x[3] += sigmoidf_(v[3]) * bfhi(w.y);
;               *(f32x4*)(X + o) = x;
;             }
;         asm volatile("" ::: "memory");
;       }
;   }
	v_pk_mul_f32 v[128:129], v[40:41], s[70:71]
	v_pk_mul_f32 v[130:131], v[42:43], s[70:71]
	v_lshlrev_b32_e32 v140, 16, v150
	v_exp_f32_e32 v128, v128
	v_exp_f32_e32 v129, v129
	v_exp_f32_e32 v130, v130
	v_exp_f32_e32 v131, v131
	v_and_b32_e32 v141, 0xffff0000, v150
	v_pk_add_f32 v[128:129], v[128:129], 1.0 op_sel_hi:[1,0]
	v_pk_add_f32 v[130:131], v[130:131], 1.0 op_sel_hi:[1,0]
	v_rcp_f32_e32 v132, v128
	v_rcp_f32_e32 v133, v129
	v_rcp_f32_e32 v134, v130
	v_rcp_f32_e32 v135, v131
	v_lshlrev_b32_e32 v142, 16, v151
	v_and_b32_e32 v143, 0xffff0000, v151
	v_pk_fma_f32 v[128:129], v[128:129], v[132:133], 1.0 op_sel_hi:[1,1,0] neg_lo:[1,0,0] neg_hi:[1,0,0]
	v_pk_fma_f32 v[130:131], v[130:131], v[134:135], 1.0 op_sel_hi:[1,1,0] neg_lo:[1,0,0] neg_hi:[1,0,0]
	v_pk_fma_f32 v[132:133], v[128:129], v[132:133], v[132:133]
	v_pk_fma_f32 v[134:135], v[130:131], v[134:135], v[134:135]
	v_pk_fma_f32 v[220:221], v[132:133], v[140:141], v[220:221]
	v_pk_fma_f32 v[222:223], v[134:135], v[142:143], v[222:223]
	global_store_dwordx4 v166, v[220:223], s[68:69] offset:64
	global_load_dwordx2 v[150:151], v167, s[58:59] offset:32
	global_load_dwordx4 v[220:223], v166, s[56:57] offset:64
	s_waitcnt vmcnt(21)
	v_pk_mul_f32 v[128:129], v[36:37], s[70:71]
	v_pk_mul_f32 v[130:131], v[38:39], s[70:71]
	v_lshlrev_b32_e32 v140, 16, v152
	v_exp_f32_e32 v128, v128
	v_exp_f32_e32 v129, v129
	v_exp_f32_e32 v130, v130
	v_exp_f32_e32 v131, v131
	v_and_b32_e32 v141, 0xffff0000, v152
	v_pk_add_f32 v[128:129], v[128:129], 1.0 op_sel_hi:[1,0]
	v_pk_add_f32 v[130:131], v[130:131], 1.0 op_sel_hi:[1,0]
	v_rcp_f32_e32 v132, v128
	v_rcp_f32_e32 v133, v129
	v_rcp_f32_e32 v134, v130
	v_rcp_f32_e32 v135, v131
	v_lshlrev_b32_e32 v142, 16, v153
	v_and_b32_e32 v143, 0xffff0000, v153
	v_pk_fma_f32 v[128:129], v[128:129], v[132:133], 1.0 op_sel_hi:[1,1,0] neg_lo:[1,0,0] neg_hi:[1,0,0]
	v_pk_fma_f32 v[130:131], v[130:131], v[134:135], 1.0 op_sel_hi:[1,1,0] neg_lo:[1,0,0] neg_hi:[1,0,0]
	v_pk_fma_f32 v[132:133], v[128:129], v[132:133], v[132:133]
	v_pk_fma_f32 v[134:135], v[130:131], v[134:135], v[134:135]
	v_pk_fma_f32 v[224:225], v[132:133], v[140:141], v[224:225]
	v_pk_fma_f32 v[226:227], v[134:135], v[142:143], v[226:227]
	global_store_dwordx4 v166, v[224:227], s[68:69] offset:512
	global_load_dwordx2 v[152:153], v167, s[58:59] offset:256
	global_load_dwordx4 v[224:227], v166, s[56:57] offset:512
	s_waitcnt vmcnt(21)
	v_pk_mul_f32 v[128:129], v[32:33], s[70:71]
	v_pk_mul_f32 v[130:131], v[34:35], s[70:71]
	v_lshlrev_b32_e32 v140, 16, v154
	v_exp_f32_e32 v128, v128
	v_exp_f32_e32 v129, v129
	v_exp_f32_e32 v130, v130
	v_exp_f32_e32 v131, v131
	v_and_b32_e32 v141, 0xffff0000, v154
	v_pk_add_f32 v[128:129], v[128:129], 1.0 op_sel_hi:[1,0]
	v_pk_add_f32 v[130:131], v[130:131], 1.0 op_sel_hi:[1,0]
	v_rcp_f32_e32 v132, v128
	v_rcp_f32_e32 v133, v129
	v_rcp_f32_e32 v134, v130
	v_rcp_f32_e32 v135, v131
	v_lshlrev_b32_e32 v142, 16, v155
	v_and_b32_e32 v143, 0xffff0000, v155
	v_pk_fma_f32 v[128:129], v[128:129], v[132:133], 1.0 op_sel_hi:[1,1,0] neg_lo:[1,0,0] neg_hi:[1,0,0]
	v_pk_fma_f32 v[130:131], v[130:131], v[134:135], 1.0 op_sel_hi:[1,1,0] neg_lo:[1,0,0] neg_hi:[1,0,0]
	v_pk_fma_f32 v[132:133], v[128:129], v[132:133], v[132:133]
	v_pk_fma_f32 v[134:135], v[130:131], v[134:135], v[134:135]
	v_pk_fma_f32 v[228:229], v[132:133], v[140:141], v[228:229]
	v_pk_fma_f32 v[230:231], v[134:135], v[142:143], v[230:231]
	global_store_dwordx4 v166, v[228:231], s[68:69] offset:576
	s_add_u32 s68, s68, 0x10000
	s_addc_u32 s69, s69, 0
	global_load_dwordx2 v[154:155], v167, s[58:59] offset:288
	global_load_dwordx4 v[228:231], v166, s[56:57] offset:576
	s_waitcnt vmcnt(21)
	v_pk_mul_f32 v[128:129], v[28:29], s[70:71]
	v_pk_mul_f32 v[130:131], v[30:31], s[70:71]
	v_lshlrev_b32_e32 v140, 16, v232
	v_exp_f32_e32 v128, v128
	v_exp_f32_e32 v129, v129
	v_exp_f32_e32 v130, v130
	v_exp_f32_e32 v131, v131
	v_and_b32_e32 v141, 0xffff0000, v232
	v_pk_add_f32 v[128:129], v[128:129], 1.0 op_sel_hi:[1,0]
	v_pk_add_f32 v[130:131], v[130:131], 1.0 op_sel_hi:[1,0]
	v_rcp_f32_e32 v132, v128
	v_rcp_f32_e32 v133, v129
	v_rcp_f32_e32 v134, v130
	v_rcp_f32_e32 v135, v131
	v_lshlrev_b32_e32 v142, 16, v233
	v_and_b32_e32 v143, 0xffff0000, v233
	v_pk_fma_f32 v[128:129], v[128:129], v[132:133], 1.0 op_sel_hi:[1,1,0] neg_lo:[1,0,0] neg_hi:[1,0,0]
	v_pk_fma_f32 v[130:131], v[130:131], v[134:135], 1.0 op_sel_hi:[1,1,0] neg_lo:[1,0,0] neg_hi:[1,0,0]
	v_pk_fma_f32 v[132:133], v[128:129], v[132:133], v[132:133]
	v_pk_fma_f32 v[134:135], v[130:131], v[134:135], v[134:135]
	v_pk_fma_f32 v[180:181], v[132:133], v[140:141], v[180:181]
	v_pk_fma_f32 v[182:183], v[134:135], v[142:143], v[182:183]
	global_store_dwordx4 v166, v[180:183], s[68:69]
	s_waitcnt vmcnt(19)
	v_pk_mul_f32 v[128:129], v[24:25], s[70:71]
	v_pk_mul_f32 v[130:131], v[26:27], s[70:71]
	v_lshlrev_b32_e32 v140, 16, v234
	v_exp_f32_e32 v128, v128
	v_exp_f32_e32 v129, v129
	v_exp_f32_e32 v130, v130
	v_exp_f32_e32 v131, v131
	v_and_b32_e32 v141, 0xffff0000, v234
	v_pk_add_f32 v[128:129], v[128:129], 1.0 op_sel_hi:[1,0]
	v_pk_add_f32 v[130:131], v[130:131], 1.0 op_sel_hi:[1,0]
	v_rcp_f32_e32 v132, v128
	v_rcp_f32_e32 v133, v129
	v_rcp_f32_e32 v134, v130
	v_rcp_f32_e32 v135, v131
	v_lshlrev_b32_e32 v142, 16, v235
	v_and_b32_e32 v143, 0xffff0000, v235
	v_pk_fma_f32 v[128:129], v[128:129], v[132:133], 1.0 op_sel_hi:[1,1,0] neg_lo:[1,0,0] neg_hi:[1,0,0]
	v_pk_fma_f32 v[130:131], v[130:131], v[134:135], 1.0 op_sel_hi:[1,1,0] neg_lo:[1,0,0] neg_hi:[1,0,0]
	v_pk_fma_f32 v[132:133], v[128:129], v[132:133], v[132:133]
	v_pk_fma_f32 v[134:135], v[130:131], v[134:135], v[134:135]
	v_pk_fma_f32 v[184:185], v[132:133], v[140:141], v[184:185]
	v_pk_fma_f32 v[186:187], v[134:135], v[142:143], v[186:187]
	global_store_dwordx4 v166, v[184:187], s[68:69] offset:64
	s_waitcnt vmcnt(17)
; DEV float bflo(unsigned w) { return __uint_as_float(w << 16); }
; DEV float bfhi(unsigned w) { return __uint_as_float(w & 0xffff0000u); }
; DEV float sigmoidf_(float x) { return 1.0f / (1.0f + __expf(-x)); }
; #define PG8_BAR __builtin_amdgcn_s_barrier()
; template <class Epi, bool SEQ>
; DEV void gemm_phase(PG8_LAS unsigned char* lds, const Gemm g, const Epi& E) {
;     ...
;     if (!has_next) break;
;     if (!keep) {
; #pragma unroll
;       for (int a = 0; a < 2; ++a)
; #pragma unroll
;         for (int b = 0; b < 2; ++b)
; #pragma unroll
;           for (int m = 0; m < 4; ++m)
; #pragma unroll
;             for (int n = 0; n < 2; ++n) acc[a][b][m][n] = (f32x4){0.f, 0.f, 0.f, 0.f};
;     }
;     cur = nxt; cA = nA; cB = nB; ++ui;
;     if (wr == 1) PG8_BAR;
;   DEV void operator()(const f32x4 (&acc)[2][2][4][2], const Unit& u, int wr, int wc, int fr, int fq) const {
;     ...
;         for (int mm = 0; mm < 2; ++mm)
; #pragma unroll
;           for (int bj = 0; bj < 2; ++bj)
; #pragma unroll
;             for (int n = 0; n < 2; ++n) {
;               const size_t o = (size_t)(row0 + ai * HALF + (mp * 2 + mm) * 16) * D + col0 + bj * HALF + n * 16;
;               const f32x4 v = acc[ai][bj][mp * 2 + mm][n];
;               f32x4 x = xv[mm][bj][n]; const u32x2 w = pw[mm][bj][n];
;               x[0] += sigmoidf_(v[0]) * bflo(w.x); x[1] += sigmoidf_(v[1]) * bfhi(w.x); x[2] += sigmoidf_(v[2]) * bflo(w.y); x[3] += sigmoidf_(v[3]) * bfhi(w.y);
;               *(f32x4*)(X + o) = x;
;             }
	v_pk_mul_f32 v[128:129], v[20:21], s[70:71]
	v_pk_mul_f32 v[130:131], v[22:23], s[70:71]
	v_lshlrev_b32_e32 v140, 16, v236
	v_exp_f32_e32 v128, v128
	v_exp_f32_e32 v129, v129
	v_exp_f32_e32 v130, v130
	v_exp_f32_e32 v131, v131
	v_and_b32_e32 v141, 0xffff0000, v236
	v_pk_add_f32 v[128:129], v[128:129], 1.0 op_sel_hi:[1,0]
	v_pk_add_f32 v[130:131], v[130:131], 1.0 op_sel_hi:[1,0]
	v_rcp_f32_e32 v132, v128
	v_rcp_f32_e32 v133, v129
	v_rcp_f32_e32 v134, v130
	v_rcp_f32_e32 v135, v131
	v_lshlrev_b32_e32 v142, 16, v237
	v_and_b32_e32 v143, 0xffff0000, v237
	v_pk_fma_f32 v[128:129], v[128:129], v[132:133], 1.0 op_sel_hi:[1,1,0] neg_lo:[1,0,0] neg_hi:[1,0,0]
	v_pk_fma_f32 v[130:131], v[130:131], v[134:135], 1.0 op_sel_hi:[1,1,0] neg_lo:[1,0,0] neg_hi:[1,0,0]
	v_pk_fma_f32 v[132:133], v[128:129], v[132:133], v[132:133]
	v_pk_fma_f32 v[134:135], v[130:131], v[134:135], v[134:135]
	v_pk_fma_f32 v[188:189], v[132:133], v[140:141], v[188:189]
	v_pk_fma_f32 v[190:191], v[134:135], v[142:143], v[190:191]
	global_store_dwordx4 v166, v[188:191], s[68:69] offset:512
	s_waitcnt vmcnt(15)
	v_pk_mul_f32 v[128:129], v[16:17], s[70:71]
	v_pk_mul_f32 v[130:131], v[18:19], s[70:71]
	v_lshlrev_b32_e32 v140, 16, v238
	v_exp_f32_e32 v128, v128
	v_exp_f32_e32 v129, v129
	v_exp_f32_e32 v130, v130
	v_exp_f32_e32 v131, v131
	v_and_b32_e32 v141, 0xffff0000, v238
	v_pk_add_f32 v[128:129], v[128:129], 1.0 op_sel_hi:[1,0]
	v_pk_add_f32 v[130:131], v[130:131], 1.0 op_sel_hi:[1,0]
	v_rcp_f32_e32 v132, v128
	v_rcp_f32_e32 v133, v129
	v_rcp_f32_e32 v134, v130
	v_rcp_f32_e32 v135, v131
	v_lshlrev_b32_e32 v142, 16, v239
	v_and_b32_e32 v143, 0xffff0000, v239
	v_pk_fma_f32 v[128:129], v[128:129], v[132:133], 1.0 op_sel_hi:[1,1,0] neg_lo:[1,0,0] neg_hi:[1,0,0]
	v_pk_fma_f32 v[130:131], v[130:131], v[134:135], 1.0 op_sel_hi:[1,1,0] neg_lo:[1,0,0] neg_hi:[1,0,0]
	v_pk_fma_f32 v[132:133], v[128:129], v[132:133], v[132:133]
	v_pk_fma_f32 v[134:135], v[130:131], v[134:135], v[134:135]
	v_pk_fma_f32 v[192:193], v[132:133], v[140:141], v[192:193]
	v_pk_fma_f32 v[194:195], v[134:135], v[142:143], v[194:195]
	global_store_dwordx4 v166, v[192:195], s[68:69] offset:576
	s_add_u32 s68, s68, 0x10000
	s_addc_u32 s69, s69, 0
	s_waitcnt vmcnt(13)
	v_pk_mul_f32 v[128:129], v[12:13], s[70:71]
	v_pk_mul_f32 v[130:131], v[14:15], s[70:71]
	v_lshlrev_b32_e32 v140, 16, v148
	v_exp_f32_e32 v128, v128
	v_exp_f32_e32 v129, v129
	v_exp_f32_e32 v130, v130
	v_exp_f32_e32 v131, v131
	v_and_b32_e32 v141, 0xffff0000, v148
	v_pk_add_f32 v[128:129], v[128:129], 1.0 op_sel_hi:[1,0]
	v_pk_add_f32 v[130:131], v[130:131], 1.0 op_sel_hi:[1,0]
	v_rcp_f32_e32 v132, v128
	v_rcp_f32_e32 v133, v129
	v_rcp_f32_e32 v134, v130
	v_rcp_f32_e32 v135, v131
	v_lshlrev_b32_e32 v142, 16, v149
	v_and_b32_e32 v143, 0xffff0000, v149
	v_pk_fma_f32 v[128:129], v[128:129], v[132:133], 1.0 op_sel_hi:[1,1,0] neg_lo:[1,0,0] neg_hi:[1,0,0]
	v_pk_fma_f32 v[130:131], v[130:131], v[134:135], 1.0 op_sel_hi:[1,1,0] neg_lo:[1,0,0] neg_hi:[1,0,0]
	v_pk_fma_f32 v[132:133], v[128:129], v[132:133], v[132:133]
	v_pk_fma_f32 v[134:135], v[130:131], v[134:135], v[134:135]
	v_pk_fma_f32 v[196:197], v[132:133], v[140:141], v[196:197]
	v_pk_fma_f32 v[198:199], v[134:135], v[142:143], v[198:199]
	global_store_dwordx4 v166, v[196:199], s[68:69]
	s_waitcnt vmcnt(11)
	v_pk_mul_f32 v[128:129], v[8:9], s[70:71]
	v_pk_mul_f32 v[130:131], v[10:11], s[70:71]
	v_lshlrev_b32_e32 v140, 16, v150
	v_exp_f32_e32 v128, v128
	v_exp_f32_e32 v129, v129
	v_exp_f32_e32 v130, v130
	v_exp_f32_e32 v131, v131
	v_and_b32_e32 v141, 0xffff0000, v150
	v_pk_add_f32 v[128:129], v[128:129], 1.0 op_sel_hi:[1,0]
	v_pk_add_f32 v[130:131], v[130:131], 1.0 op_sel_hi:[1,0]
	v_rcp_f32_e32 v132, v128
	v_rcp_f32_e32 v133, v129
	v_rcp_f32_e32 v134, v130
	v_rcp_f32_e32 v135, v131
	v_lshlrev_b32_e32 v142, 16, v151
	v_and_b32_e32 v143, 0xffff0000, v151
	v_pk_fma_f32 v[128:129], v[128:129], v[132:133], 1.0 op_sel_hi:[1,1,0] neg_lo:[1,0,0] neg_hi:[1,0,0]
	v_pk_fma_f32 v[130:131], v[130:131], v[134:135], 1.0 op_sel_hi:[1,1,0] neg_lo:[1,0,0] neg_hi:[1,0,0]
	v_pk_fma_f32 v[132:133], v[128:129], v[132:133], v[132:133]
	v_pk_fma_f32 v[134:135], v[130:131], v[134:135], v[134:135]
	v_pk_fma_f32 v[220:221], v[132:133], v[140:141], v[220:221]
	v_pk_fma_f32 v[222:223], v[134:135], v[142:143], v[222:223]
	global_store_dwordx4 v166, v[220:223], s[68:69] offset:64
	s_waitcnt vmcnt(9)
	v_pk_mul_f32 v[128:129], v[4:5], s[70:71]
	v_pk_mul_f32 v[130:131], v[6:7], s[70:71]
	v_lshlrev_b32_e32 v140, 16, v152
	v_exp_f32_e32 v128, v128
	v_exp_f32_e32 v129, v129
	v_exp_f32_e32 v130, v130
	v_exp_f32_e32 v131, v131
	v_and_b32_e32 v141, 0xffff0000, v152
	v_pk_add_f32 v[128:129], v[128:129], 1.0 op_sel_hi:[1,0]
	v_pk_add_f32 v[130:131], v[130:131], 1.0 op_sel_hi:[1,0]
	v_rcp_f32_e32 v132, v128
	v_rcp_f32_e32 v133, v129
	v_rcp_f32_e32 v134, v130
	v_rcp_f32_e32 v135, v131
	v_lshlrev_b32_e32 v142, 16, v153
	v_and_b32_e32 v143, 0xffff0000, v153
	v_pk_fma_f32 v[128:129], v[128:129], v[132:133], 1.0 op_sel_hi:[1,1,0] neg_lo:[1,0,0] neg_hi:[1,0,0]
	v_pk_fma_f32 v[130:131], v[130:131], v[134:135], 1.0 op_sel_hi:[1,1,0] neg_lo:[1,0,0] neg_hi:[1,0,0]
	v_pk_fma_f32 v[132:133], v[128:129], v[132:133], v[132:133]
	v_pk_fma_f32 v[134:135], v[130:131], v[134:135], v[134:135]
	v_pk_fma_f32 v[224:225], v[132:133], v[140:141], v[224:225]
	v_pk_fma_f32 v[226:227], v[134:135], v[142:143], v[226:227]
	global_store_dwordx4 v166, v[224:227], s[68:69] offset:512
	s_waitcnt vmcnt(7)
	v_pk_mul_f32 v[128:129], v[0:1], s[70:71]
	v_pk_mul_f32 v[130:131], v[2:3], s[70:71]
	v_lshlrev_b32_e32 v140, 16, v154
	v_exp_f32_e32 v128, v128
	v_exp_f32_e32 v129, v129
	v_exp_f32_e32 v130, v130
	v_exp_f32_e32 v131, v131
	v_and_b32_e32 v141, 0xffff0000, v154
	v_pk_add_f32 v[128:129], v[128:129], 1.0 op_sel_hi:[1,0]
	v_pk_add_f32 v[130:131], v[130:131], 1.0 op_sel_hi:[1,0]
	v_rcp_f32_e32 v132, v128
	v_rcp_f32_e32 v133, v129
	v_rcp_f32_e32 v134, v130
	v_rcp_f32_e32 v135, v131
	v_lshlrev_b32_e32 v142, 16, v155
	v_and_b32_e32 v143, 0xffff0000, v155
	v_pk_fma_f32 v[128:129], v[128:129], v[132:133], 1.0 op_sel_hi:[1,1,0] neg_lo:[1,0,0] neg_hi:[1,0,0]
	v_pk_fma_f32 v[130:131], v[130:131], v[134:135], 1.0 op_sel_hi:[1,1,0] neg_lo:[1,0,0] neg_hi:[1,0,0]
	v_pk_fma_f32 v[132:133], v[128:129], v[132:133], v[132:133]
	v_pk_fma_f32 v[134:135], v[130:131], v[134:135], v[134:135]
	v_pk_fma_f32 v[228:229], v[132:133], v[140:141], v[228:229]
	v_pk_fma_f32 v[230:231], v[134:135], v[142:143], v[230:231]
	global_store_dwordx4 v166, v[228:231], s[68:69] offset:576
	s_mov_b64 s[2:3], -1
	s_andn2_b64 vcc, exec, s[62:63]
	s_cbranch_vccnz .LBB0_122
	s_andn2_b64 vcc, exec, s[54:55]
	s_cbranch_vccnz .LBB0_121
	s_barrier
	s_branch .LBB0_121

; #define PG8_STAGE(bufoff, gbase, voff) do { _Pragma("unroll") for (int _i = 0; _i < 2; ++_i) \
;     __builtin_amdgcn_global_load_lds((const unsigned*)((const char*)(gbase) + (voff)[_i]), (PG8_LAS unsigned*)(lds + (bufoff) + ldsw + _i * 8192), 16, 0, 0); } while (0)
; #define PG8_LDA(dst, b, h) do { _Pragma("unroll") for (int m = 0; m < 4; ++m) _Pragma("unroll") for (int k = 0; k < 2; ++k) dst[m][k] = *(const PG8_LAS bf16x8*)(lds + PG8_SA(b, h) + aoff + m * 2048 + k * 1024); } while (0)
; #define PG8_LDB(dst, b, h) do { _Pragma("unroll") for (int n = 0; n < 2; ++n) _Pragma("unroll") for (int k = 0; k < 2; ++k) dst[n][k] = *(const PG8_LAS bf16x8*)(lds + PG8_SB(b, h) + boff + n * 2048 + k * 1024); } while (0)
; #define PG8_MMA(ai, bj, At, Bt) do { __builtin_amdgcn_s_setprio(1); _Pragma("unroll") for (int m = 0; m < 4; ++m) _Pragma("unroll") for (int n = 0; n < 2; ++n) _Pragma("unroll") for (int k = 0; k < 2; ++k) \
;     acc[ai][bj][m][n] = __builtin_amdgcn_mfma_f32_16x16x32_bf16(Bt[n][k], At[m][k], acc[ai][bj][m][n], 0, 0, 0); __builtin_amdgcn_s_setprio(0); } while (0)
; #define PG8_WAIT_V(n) asm volatile("s_waitcnt vmcnt(" #n ")" ::: "memory")
; template <class Epi, bool SEQ>
; DEV void gemm_phase(PG8_LAS unsigned char* lds, const Gemm g, const Epi& E) {
;     ...
;   for (;;) {
;     const bool has_next = next_unit<SEQ>(g, ui + 1, G, cblk, nxt);
;     const char* nA = has_next ? PG8_ABASE(nxt) : cA; const char* nB = has_next ? PG8_BBASE(nxt) : cB;
;     for (int t = 0; t < nt; t += 2) {
;       const bool last = (t == nt - 2);
;       const char* a1 = cA + (size_t)(t + 1) * kstep;
;       const char* a2 = last ? nA : cA + (size_t)(t + 2) * kstep; const char* b2 = last ? nB : cB + (size_t)(t + 2) * kstep;
;       const char* a3 = a2 + kstep; const char* b3 = b2 + kstep;
;       PG8_LDB(B0, 0, 0); PG8_LDB(B1, 0, 1); PG8_SCHED; PG8_LDA(At, 0, 0); PG8_STAGE(PG8_SA(1, 1), a1 + hstepA, voffA);
;       PG8_WAIT_V(8); PG8_WAIT_L(0); PG8_BAR; PG8_MMA(0, 0, At, B0); PG8_MMA(0, 1, At, B1); PG8_BAR; PG8_SCHED;
;     ...
;     if (!keep) {
; #pragma unroll
;       for (int a = 0; a < 2; ++a)
; #pragma unroll
;         for (int b = 0; b < 2; ++b)
; #pragma unroll
;           for (int m = 0; m < 4; ++m)
; #pragma unroll
;             for (int n = 0; n < 2; ++n) acc[a][b][m][n] = (f32x4){0.f, 0.f, 0.f, 0.f};
;     }
;     cur = nxt; cA = nA; cB = nB; ++ui;
.LBB0_170:
	s_add_u32 s26, s26, 0x80
	s_addc_u32 s27, s27, 0
	s_add_u32 s5, s36, 0x100
	v_mov_b64_e32 v[0:1], 0
	v_mov_b64_e32 v[2:3], 0
	v_mov_b64_e32 v[4:5], 0
	v_mov_b64_e32 v[6:7], 0
	v_mov_b64_e32 v[8:9], 0
	v_mov_b64_e32 v[10:11], 0
	v_mov_b64_e32 v[12:13], 0
	v_mov_b64_e32 v[14:15], 0
	v_mov_b64_e32 v[16:17], 0
	v_mov_b64_e32 v[18:19], 0
	v_mov_b64_e32 v[20:21], 0
	v_mov_b64_e32 v[22:23], 0
	v_mov_b64_e32 v[24:25], 0
	v_mov_b64_e32 v[26:27], 0
	v_mov_b64_e32 v[28:29], 0
	v_mov_b64_e32 v[30:31], 0
	v_mov_b64_e32 v[32:33], 0
	v_mov_b64_e32 v[34:35], 0
	v_mov_b64_e32 v[36:37], 0
	v_mov_b64_e32 v[38:39], 0
	v_mov_b64_e32 v[40:41], 0
	v_mov_b64_e32 v[42:43], 0
	v_mov_b64_e32 v[44:45], 0
	v_mov_b64_e32 v[46:47], 0
	v_mov_b64_e32 v[48:49], 0
	v_mov_b64_e32 v[50:51], 0
	v_mov_b64_e32 v[52:53], 0
	v_mov_b64_e32 v[54:55], 0
	v_mov_b64_e32 v[56:57], 0
	v_mov_b64_e32 v[58:59], 0
	v_mov_b64_e32 v[60:61], 0
	v_mov_b64_e32 v[62:63], 0
	v_mov_b64_e32 v[64:65], 0
	v_mov_b64_e32 v[66:67], 0
	v_mov_b64_e32 v[68:69], 0
	v_mov_b64_e32 v[70:71], 0
	v_mov_b64_e32 v[72:73], 0
	v_mov_b64_e32 v[74:75], 0
	v_mov_b64_e32 v[76:77], 0
	v_mov_b64_e32 v[78:79], 0
	v_mov_b64_e32 v[80:81], 0
	v_mov_b64_e32 v[82:83], 0
	v_mov_b64_e32 v[84:85], 0
	v_mov_b64_e32 v[86:87], 0
	v_mov_b64_e32 v[88:89], 0
	v_mov_b64_e32 v[90:91], 0
	v_mov_b64_e32 v[92:93], 0
	v_mov_b64_e32 v[94:95], 0
	v_mov_b64_e32 v[96:97], 0
	v_mov_b64_e32 v[98:99], 0
	v_mov_b64_e32 v[100:101], 0
	v_mov_b64_e32 v[102:103], 0
	v_mov_b64_e32 v[104:105], 0
	v_mov_b64_e32 v[106:107], 0
	v_mov_b64_e32 v[108:109], 0
	v_mov_b64_e32 v[110:111], 0
	v_mov_b64_e32 v[112:113], 0
	v_mov_b64_e32 v[114:115], 0
	v_mov_b64_e32 v[116:117], 0
	v_mov_b64_e32 v[118:119], 0
	v_mov_b64_e32 v[120:121], 0
	v_mov_b64_e32 v[122:123], 0
	v_mov_b64_e32 v[124:125], 0
	v_mov_b64_e32 v[126:127], 0
	s_addc_u32 s15, s37, 0
	s_mov_b32 s17, 0
	v_readfirstlane_b32 s98, v171
	s_nop 3
	s_lshr_b32 s98, s98, 6
	s_cmp_lt_u32 s98, 4
	s_cbranch_scc0 .Lprio_171
	s_setprio 1
.Lprio_171:
.LBB0_171:
	s_add_i32 s70, s17, 2
	s_add_u32 s36, s26, 0x80
	s_addc_u32 s37, s27, 0
	s_add_i32 s71, 0, 0x10000
	s_cmp_eq_u32 s67, s17
	s_cselect_b32 s37, s19, s37
	s_cselect_b32 s36, s18, s36
	s_cselect_b32 s73, s21, s15
	s_cselect_b32 s72, s20, s5
	s_add_i32 s17, 0, 0x14000
	v_add_u32_e32 v150, s71, v135
	v_add_u32_e32 v166, s17, v135
	ds_read_b128 v[138:141], v150
	ds_read_b128 v[142:145], v150 offset:1024
	ds_read_b128 v[146:149], v150 offset:2048
	ds_read_b128 v[150:153], v150 offset:3072
	ds_read_b128 v[154:157], v166
	ds_read_b128 v[158:161], v166 offset:1024
	ds_read_b128 v[162:165], v166 offset:2048
	ds_read_b128 v[180:183], v166 offset:3072
	v_lshl_add_u64 v[166:167], s[26:27], 0, v[130:131]
	s_add_i32 m0, s9, 0xc000
	ds_read_b128 v[184:187], v137
	ds_read_b128 v[188:191], v137 offset:1024
	ds_read_b128 v[192:195], v137 offset:2048
	ds_read_b128 v[196:199], v137 offset:3072
	ds_read_b128 v[218:221], v137 offset:4096
	ds_read_b128 v[222:225], v137 offset:5120
	ds_read_b128 v[226:229], v137 offset:6144
	ds_read_b128 v[230:233], v137 offset:7168
	global_load_lds_dwordx4 v[166:167], off
	v_lshl_add_u64 v[166:167], s[26:27], 0, v[132:133]
	s_add_i32 m0, s9, 0xe000
	s_nop 0
	global_load_lds_dwordx4 v[166:167], off
	s_waitcnt vmcnt(8)
	s_waitcnt lgkmcnt(0)
	s_barrier
	s_waitcnt lgkmcnt(0)
	v_mfma_f32_16x16x32_bf16 v[124:127], v[138:141], v[184:187], v[124:127]
	v_mfma_f32_16x16x32_bf16 v[120:123], v[146:149], v[184:187], v[120:123]
	v_mfma_f32_16x16x32_bf16 v[116:119], v[138:141], v[192:195], v[116:119]
	v_mfma_f32_16x16x32_bf16 v[108:111], v[146:149], v[192:195], v[108:111]
	v_mfma_f32_16x16x32_bf16 v[100:103], v[138:141], v[218:221], v[100:103]
	v_mfma_f32_16x16x32_bf16 v[92:95], v[146:149], v[218:221], v[92:95]
	v_mfma_f32_16x16x32_bf16 v[84:87], v[138:141], v[226:229], v[84:87]
	v_mfma_f32_16x16x32_bf16 v[76:79], v[146:149], v[226:229], v[76:79]
	v_mfma_f32_16x16x32_bf16 v[124:127], v[142:145], v[188:191], v[124:127]
	v_mfma_f32_16x16x32_bf16 v[120:123], v[150:153], v[188:191], v[120:123]
	v_mfma_f32_16x16x32_bf16 v[116:119], v[142:145], v[196:199], v[116:119]
	v_mfma_f32_16x16x32_bf16 v[108:111], v[150:153], v[196:199], v[108:111]
	v_mfma_f32_16x16x32_bf16 v[100:103], v[142:145], v[222:225], v[100:103]
	v_mfma_f32_16x16x32_bf16 v[92:95], v[150:153], v[222:225], v[92:95]
	v_mfma_f32_16x16x32_bf16 v[84:87], v[142:145], v[230:233], v[84:87]
	v_mfma_f32_16x16x32_bf16 v[76:79], v[150:153], v[230:233], v[76:79]
	v_mfma_f32_16x16x32_bf16 v[112:115], v[154:157], v[184:187], v[112:115]
	v_mfma_f32_16x16x32_bf16 v[104:107], v[162:165], v[184:187], v[104:107]
	v_mfma_f32_16x16x32_bf16 v[96:99], v[154:157], v[192:195], v[96:99]
	v_mfma_f32_16x16x32_bf16 v[88:91], v[162:165], v[192:195], v[88:91]
	v_mfma_f32_16x16x32_bf16 v[80:83], v[154:157], v[218:221], v[80:83]
	v_mfma_f32_16x16x32_bf16 v[72:75], v[162:165], v[218:221], v[72:75]
	v_mfma_f32_16x16x32_bf16 v[68:71], v[154:157], v[226:229], v[68:71]
	v_mfma_f32_16x16x32_bf16 v[64:67], v[162:165], v[226:229], v[64:67]
	v_mfma_f32_16x16x32_bf16 v[112:115], v[158:161], v[188:191], v[112:115]
	v_mfma_f32_16x16x32_bf16 v[104:107], v[180:183], v[188:191], v[104:107]
	v_mfma_f32_16x16x32_bf16 v[96:99], v[158:161], v[196:199], v[96:99]
	v_mfma_f32_16x16x32_bf16 v[88:91], v[180:183], v[196:199], v[88:91]
	v_mfma_f32_16x16x32_bf16 v[80:83], v[158:161], v[222:225], v[80:83]
	v_mfma_f32_16x16x32_bf16 v[72:75], v[180:183], v[222:225], v[72:75]
	v_mfma_f32_16x16x32_bf16 v[68:71], v[158:161], v[230:233], v[68:71]
	v_mfma_f32_16x16x32_bf16 v[64:67], v[180:183], v[230:233], v[64:67]
	s_barrier
; #define PG8_STAGE(bufoff, gbase, voff) do { _Pragma("unroll") for (int _i = 0; _i < 2; ++_i) \
;     __builtin_amdgcn_global_load_lds((const unsigned*)((const char*)(gbase) + (voff)[_i]), (PG8_LAS unsigned*)(lds + (bufoff) + ldsw + _i * 8192), 16, 0, 0); } while (0)
; #define PG8_LDA(dst, b, h) do { _Pragma("unroll") for (int m = 0; m < 4; ++m) _Pragma("unroll") for (int k = 0; k < 2; ++k) dst[m][k] = *(const PG8_LAS bf16x8*)(lds + PG8_SA(b, h) + aoff + m * 2048 + k * 1024); } while (0)
; #define PG8_LDB(dst, b, h) do { _Pragma("unroll") for (int n = 0; n < 2; ++n) _Pragma("unroll") for (int k = 0; k < 2; ++k) dst[n][k] = *(const PG8_LAS bf16x8*)(lds + PG8_SB(b, h) + boff + n * 2048 + k * 1024); } while (0)
; #define PG8_MMA(ai, bj, At, Bt) do { __builtin_amdgcn_s_setprio(1); _Pragma("unroll") for (int m = 0; m < 4; ++m) _Pragma("unroll") for (int n = 0; n < 2; ++n) _Pragma("unroll") for (int k = 0; k < 2; ++k) \
;     acc[ai][bj][m][n] = __builtin_amdgcn_mfma_f32_16x16x32_bf16(Bt[n][k], At[m][k], acc[ai][bj][m][n], 0, 0, 0); __builtin_amdgcn_s_setprio(0); } while (0)
; #define PG8_WAIT_V(n) asm volatile("s_waitcnt vmcnt(" #n ")" ::: "memory")
; #define PG8_WAIT_L(n) asm volatile("s_waitcnt lgkmcnt(" #n ")" ::: "memory")
; #define PG8_BAR __builtin_amdgcn_s_barrier()
; #define PG8_SCHED __builtin_amdgcn_sched_barrier(0)
; template <class Epi, bool SEQ>
; DEV void gemm_phase(PG8_LAS unsigned char* lds, const Gemm g, const Epi& E) {
;     ...
;       PG8_LDA(At, 0, 1); PG8_STAGE(PG8_SB(0, 0), b2, voffB); PG8_STAGE(PG8_SB(0, 1), b2 + hstepB, voffB); PG8_STAGE(PG8_SA(0, 0), a2, voffA);
;       PG8_WAIT_V(8); PG8_WAIT_L(0); PG8_BAR; PG8_MMA(1, 0, At, B0); PG8_MMA(1, 1, At, B1); PG8_BAR; PG8_SCHED;
;       PG8_LDB(B0, 1, 0); PG8_LDB(B1, 1, 1); PG8_SCHED; PG8_LDA(At, 1, 0); PG8_STAGE(PG8_SA(0, 1), a2 + hstepA, voffA);
	s_add_i32 s71, s71, s47
	v_lshl_add_u64 v[166:167], s[72:73], 0, v[168:169]
	s_mov_b32 m0, s71
	ds_read_b128 v[184:187], v137 offset:16384
	ds_read_b128 v[188:191], v137 offset:17408
	ds_read_b128 v[192:195], v137 offset:18432
	ds_read_b128 v[196:199], v137 offset:19456
	ds_read_b128 v[218:221], v137 offset:20480
	ds_read_b128 v[222:225], v137 offset:21504
	ds_read_b128 v[226:229], v137 offset:22528
	ds_read_b128 v[230:233], v137 offset:23552
	global_load_lds_dwordx4 v[166:167], off
	s_add_i32 m0, s71, 0x2000
	v_lshl_add_u64 v[234:235], s[72:73], 0, v[128:129]
	s_add_u32 s72, s72, s6
	s_addc_u32 s73, s73, 0
	s_add_i32 s17, s17, s47
	global_load_lds_dwordx4 v[234:235], off
	v_lshl_add_u64 v[236:237], s[72:73], 0, v[168:169]
	s_mov_b32 m0, s17
	v_lshl_add_u64 v[238:239], s[72:73], 0, v[128:129]
	global_load_lds_dwordx4 v[236:237], off
	s_add_i32 m0, s17, 0x2000
	v_lshl_add_u64 v[240:241], s[36:37], 0, v[168:169]
	global_load_lds_dwordx4 v[238:239], off
	s_mov_b32 m0, s9
	v_lshl_add_u64 v[242:243], s[36:37], 0, v[128:129]
	global_load_lds_dwordx4 v[240:241], off
	s_mov_b32 m0, s55
	s_nop 0
	global_load_lds_dwordx4 v[242:243], off
	s_waitcnt vmcnt(8)
	s_waitcnt lgkmcnt(0)
	s_barrier
	s_waitcnt lgkmcnt(0)
	v_mfma_f32_16x16x32_bf16 v[60:63], v[138:141], v[184:187], v[60:63]
	v_mfma_f32_16x16x32_bf16 v[56:59], v[146:149], v[184:187], v[56:59]
	v_mfma_f32_16x16x32_bf16 v[52:55], v[138:141], v[192:195], v[52:55]
	v_mfma_f32_16x16x32_bf16 v[44:47], v[146:149], v[192:195], v[44:47]
	v_mfma_f32_16x16x32_bf16 v[36:39], v[138:141], v[218:221], v[36:39]
	v_mfma_f32_16x16x32_bf16 v[28:31], v[146:149], v[218:221], v[28:31]
	v_mfma_f32_16x16x32_bf16 v[20:23], v[138:141], v[226:229], v[20:23]
	v_mfma_f32_16x16x32_bf16 v[12:15], v[146:149], v[226:229], v[12:15]
	v_mfma_f32_16x16x32_bf16 v[60:63], v[142:145], v[188:191], v[60:63]
	v_mfma_f32_16x16x32_bf16 v[56:59], v[150:153], v[188:191], v[56:59]
	v_mfma_f32_16x16x32_bf16 v[52:55], v[142:145], v[196:199], v[52:55]
	v_mfma_f32_16x16x32_bf16 v[44:47], v[150:153], v[196:199], v[44:47]
	v_mfma_f32_16x16x32_bf16 v[36:39], v[142:145], v[222:225], v[36:39]
	v_mfma_f32_16x16x32_bf16 v[28:31], v[150:153], v[222:225], v[28:31]
	v_mfma_f32_16x16x32_bf16 v[20:23], v[142:145], v[230:233], v[20:23]
	v_mfma_f32_16x16x32_bf16 v[12:15], v[150:153], v[230:233], v[12:15]
	v_mfma_f32_16x16x32_bf16 v[48:51], v[154:157], v[184:187], v[48:51]
	v_mfma_f32_16x16x32_bf16 v[40:43], v[162:165], v[184:187], v[40:43]
	v_mfma_f32_16x16x32_bf16 v[32:35], v[154:157], v[192:195], v[32:35]
	v_mfma_f32_16x16x32_bf16 v[24:27], v[162:165], v[192:195], v[24:27]
	v_mfma_f32_16x16x32_bf16 v[16:19], v[154:157], v[218:221], v[16:19]
	v_mfma_f32_16x16x32_bf16 v[8:11], v[162:165], v[218:221], v[8:11]
	v_mfma_f32_16x16x32_bf16 v[4:7], v[154:157], v[226:229], v[4:7]
	v_mfma_f32_16x16x32_bf16 v[0:3], v[162:165], v[226:229], v[0:3]
	v_mfma_f32_16x16x32_bf16 v[48:51], v[158:161], v[188:191], v[48:51]
	v_mfma_f32_16x16x32_bf16 v[40:43], v[180:183], v[188:191], v[40:43]
	v_mfma_f32_16x16x32_bf16 v[32:35], v[158:161], v[196:199], v[32:35]
	v_mfma_f32_16x16x32_bf16 v[24:27], v[180:183], v[196:199], v[24:27]
	v_mfma_f32_16x16x32_bf16 v[16:19], v[158:161], v[222:225], v[16:19]
	v_mfma_f32_16x16x32_bf16 v[8:11], v[180:183], v[222:225], v[8:11]
	v_mfma_f32_16x16x32_bf16 v[4:7], v[158:161], v[230:233], v[4:7]
	v_mfma_f32_16x16x32_bf16 v[0:3], v[180:183], v[230:233], v[0:3]
	s_barrier
	s_add_i32 s17, 0, 0x18000
	s_add_i32 s71, 0, 0x1c000
	v_add_u32_e32 v150, s17, v135
	v_add_u32_e32 v177, s71, v135
	ds_read_b128 v[138:141], v150
	ds_read_b128 v[142:145], v150 offset:1024
	ds_read_b128 v[146:149], v150 offset:2048
	ds_read_b128 v[150:153], v150 offset:3072
	ds_read_b128 v[154:157], v177
	ds_read_b128 v[158:161], v177 offset:1024
	ds_read_b128 v[162:165], v177 offset:2048
	ds_read_b128 v[180:183], v177 offset:3072
	s_add_u32 s36, s36, s6
	s_addc_u32 s37, s37, 0
	s_mov_b32 m0, s56
	v_lshl_add_u64 v[244:245], s[36:37], 0, v[168:169]
	ds_read_b128 v[184:187], v137 offset:32768
	ds_read_b128 v[188:191], v137 offset:33792
	ds_read_b128 v[192:195], v137 offset:34816
	ds_read_b128 v[196:199], v137 offset:35840
	ds_read_b128 v[218:221], v137 offset:36864
	ds_read_b128 v[222:225], v137 offset:37888
	ds_read_b128 v[226:229], v137 offset:38912
	ds_read_b128 v[230:233], v137 offset:39936
	global_load_lds_dwordx4 v[244:245], off
	v_lshl_add_u64 v[244:245], s[36:37], 0, v[128:129]
	s_mov_b32 m0, s57
	s_nop 0
	global_load_lds_dwordx4 v[244:245], off
	s_waitcnt vmcnt(8)
	s_waitcnt lgkmcnt(0)
	s_barrier
; #define PG8_STAGE(bufoff, gbase, voff) do { _Pragma("unroll") for (int _i = 0; _i < 2; ++_i) \
;     __builtin_amdgcn_global_load_lds((const unsigned*)((const char*)(gbase) + (voff)[_i]), (PG8_LAS unsigned*)(lds + (bufoff) + ldsw + _i * 8192), 16, 0, 0); } while (0)
; #define PG8_LDA(dst, b, h) do { _Pragma("unroll") for (int m = 0; m < 4; ++m) _Pragma("unroll") for (int k = 0; k < 2; ++k) dst[m][k] = *(const PG8_LAS bf16x8*)(lds + PG8_SA(b, h) + aoff + m * 2048 + k * 1024); } while (0)
; #define PG8_MMA(ai, bj, At, Bt) do { __builtin_amdgcn_s_setprio(1); _Pragma("unroll") for (int m = 0; m < 4; ++m) _Pragma("unroll") for (int n = 0; n < 2; ++n) _Pragma("unroll") for (int k = 0; k < 2; ++k) \
;     acc[ai][bj][m][n] = __builtin_amdgcn_mfma_f32_16x16x32_bf16(Bt[n][k], At[m][k], acc[ai][bj][m][n], 0, 0, 0); __builtin_amdgcn_s_setprio(0); } while (0)
; #define PG8_WAIT_V(n) asm volatile("s_waitcnt vmcnt(" #n ")" ::: "memory")
; #define PG8_WAIT_L(n) asm volatile("s_waitcnt lgkmcnt(" #n ")" ::: "memory")
; #define PG8_BAR __builtin_amdgcn_s_barrier()
; #define PG8_SCHED __builtin_amdgcn_sched_barrier(0)
; template <class Epi, bool SEQ>
; DEV void gemm_phase(PG8_LAS unsigned char* lds, const Gemm g, const Epi& E) {
;     ...
;       PG8_WAIT_V(8); PG8_WAIT_L(0); PG8_BAR; PG8_MMA(0, 0, At, B0); PG8_MMA(0, 1, At, B1); PG8_BAR; PG8_SCHED;
;       PG8_LDA(At, 1, 1); PG8_STAGE(PG8_SB(1, 0), b3, voffB); PG8_STAGE(PG8_SB(1, 1), b3 + hstepB, voffB); PG8_STAGE(PG8_SA(1, 0), a3, voffA);
;       PG8_WAIT_V(8); PG8_WAIT_L(0); PG8_BAR; PG8_MMA(1, 0, At, B0); PG8_MMA(1, 1, At, B1); PG8_BAR; PG8_SCHED;
;     }
;     if (wr == 0) PG8_BAR;
	s_waitcnt lgkmcnt(0)
	v_mfma_f32_16x16x32_bf16 v[124:127], v[138:141], v[184:187], v[124:127]
	v_mfma_f32_16x16x32_bf16 v[120:123], v[146:149], v[184:187], v[120:123]
	v_mfma_f32_16x16x32_bf16 v[116:119], v[138:141], v[192:195], v[116:119]
	v_mfma_f32_16x16x32_bf16 v[108:111], v[146:149], v[192:195], v[108:111]
	v_mfma_f32_16x16x32_bf16 v[100:103], v[138:141], v[218:221], v[100:103]
	v_mfma_f32_16x16x32_bf16 v[92:95], v[146:149], v[218:221], v[92:95]
	v_mfma_f32_16x16x32_bf16 v[84:87], v[138:141], v[226:229], v[84:87]
	v_mfma_f32_16x16x32_bf16 v[76:79], v[146:149], v[226:229], v[76:79]
	v_mfma_f32_16x16x32_bf16 v[124:127], v[142:145], v[188:191], v[124:127]
	v_mfma_f32_16x16x32_bf16 v[120:123], v[150:153], v[188:191], v[120:123]
	v_mfma_f32_16x16x32_bf16 v[116:119], v[142:145], v[196:199], v[116:119]
	v_mfma_f32_16x16x32_bf16 v[108:111], v[150:153], v[196:199], v[108:111]
	v_mfma_f32_16x16x32_bf16 v[100:103], v[142:145], v[222:225], v[100:103]
	v_mfma_f32_16x16x32_bf16 v[92:95], v[150:153], v[222:225], v[92:95]
	v_mfma_f32_16x16x32_bf16 v[84:87], v[142:145], v[230:233], v[84:87]
	v_mfma_f32_16x16x32_bf16 v[76:79], v[150:153], v[230:233], v[76:79]
	v_mfma_f32_16x16x32_bf16 v[112:115], v[154:157], v[184:187], v[112:115]
	v_mfma_f32_16x16x32_bf16 v[104:107], v[162:165], v[184:187], v[104:107]
	v_mfma_f32_16x16x32_bf16 v[96:99], v[154:157], v[192:195], v[96:99]
	v_mfma_f32_16x16x32_bf16 v[88:91], v[162:165], v[192:195], v[88:91]
	v_mfma_f32_16x16x32_bf16 v[80:83], v[154:157], v[218:221], v[80:83]
	v_mfma_f32_16x16x32_bf16 v[72:75], v[162:165], v[218:221], v[72:75]
	v_mfma_f32_16x16x32_bf16 v[68:71], v[154:157], v[226:229], v[68:71]
	v_mfma_f32_16x16x32_bf16 v[64:67], v[162:165], v[226:229], v[64:67]
	v_mfma_f32_16x16x32_bf16 v[112:115], v[158:161], v[188:191], v[112:115]
	v_mfma_f32_16x16x32_bf16 v[104:107], v[180:183], v[188:191], v[104:107]
	v_mfma_f32_16x16x32_bf16 v[96:99], v[158:161], v[196:199], v[96:99]
	v_mfma_f32_16x16x32_bf16 v[88:91], v[180:183], v[196:199], v[88:91]
	v_mfma_f32_16x16x32_bf16 v[80:83], v[158:161], v[222:225], v[80:83]
	v_mfma_f32_16x16x32_bf16 v[72:75], v[180:183], v[222:225], v[72:75]
	v_mfma_f32_16x16x32_bf16 v[68:71], v[158:161], v[230:233], v[68:71]
	v_mfma_f32_16x16x32_bf16 v[64:67], v[180:183], v[230:233], v[64:67]
	s_barrier
	s_add_i32 s17, s17, s47
	v_lshl_add_u64 v[166:167], v[166:167], 0, s[10:11]
	s_mov_b32 m0, s17
	ds_read_b128 v[184:187], v137 offset:49152
	ds_read_b128 v[188:191], v137 offset:50176
	ds_read_b128 v[192:195], v137 offset:51200
	ds_read_b128 v[196:199], v137 offset:52224
	ds_read_b128 v[218:221], v137 offset:53248
	ds_read_b128 v[222:225], v137 offset:54272
	ds_read_b128 v[226:229], v137 offset:55296
	ds_read_b128 v[230:233], v137 offset:56320
	global_load_lds_dwordx4 v[166:167], off
	v_lshl_add_u64 v[166:167], v[234:235], 0, s[10:11]
	s_add_i32 m0, s17, 0x2000
	s_add_i32 s17, s71, s47
	global_load_lds_dwordx4 v[166:167], off
	v_lshl_add_u64 v[166:167], v[236:237], 0, s[10:11]
	s_mov_b32 m0, s17
	s_nop 0
	global_load_lds_dwordx4 v[166:167], off
	v_lshl_add_u64 v[166:167], v[238:239], 0, s[10:11]
	s_add_i32 m0, s17, 0x2000
	s_nop 0
	global_load_lds_dwordx4 v[166:167], off
	v_lshl_add_u64 v[166:167], v[240:241], 0, s[10:11]
	s_mov_b32 m0, s65
	s_nop 0
	global_load_lds_dwordx4 v[166:167], off
	v_lshl_add_u64 v[166:167], v[242:243], 0, s[10:11]
	s_mov_b32 m0, s66
	s_nop 0
	global_load_lds_dwordx4 v[166:167], off
	s_waitcnt vmcnt(8)
	s_waitcnt lgkmcnt(0)
	s_barrier
	s_waitcnt lgkmcnt(0)
	v_mfma_f32_16x16x32_bf16 v[60:63], v[138:141], v[184:187], v[60:63]
	v_mfma_f32_16x16x32_bf16 v[56:59], v[146:149], v[184:187], v[56:59]
	v_mfma_f32_16x16x32_bf16 v[52:55], v[138:141], v[192:195], v[52:55]
	v_mfma_f32_16x16x32_bf16 v[44:47], v[146:149], v[192:195], v[44:47]
	v_mfma_f32_16x16x32_bf16 v[36:39], v[138:141], v[218:221], v[36:39]
	v_mfma_f32_16x16x32_bf16 v[28:31], v[146:149], v[218:221], v[28:31]
	v_mfma_f32_16x16x32_bf16 v[20:23], v[138:141], v[226:229], v[20:23]
	v_mfma_f32_16x16x32_bf16 v[12:15], v[146:149], v[226:229], v[12:15]
	v_mfma_f32_16x16x32_bf16 v[60:63], v[142:145], v[188:191], v[60:63]
	v_mfma_f32_16x16x32_bf16 v[56:59], v[150:153], v[188:191], v[56:59]
	v_mfma_f32_16x16x32_bf16 v[52:55], v[142:145], v[196:199], v[52:55]
	v_mfma_f32_16x16x32_bf16 v[44:47], v[150:153], v[196:199], v[44:47]
	v_mfma_f32_16x16x32_bf16 v[36:39], v[142:145], v[222:225], v[36:39]
	v_mfma_f32_16x16x32_bf16 v[28:31], v[150:153], v[222:225], v[28:31]
	v_mfma_f32_16x16x32_bf16 v[20:23], v[142:145], v[230:233], v[20:23]
	v_mfma_f32_16x16x32_bf16 v[12:15], v[150:153], v[230:233], v[12:15]
	v_mfma_f32_16x16x32_bf16 v[48:51], v[154:157], v[184:187], v[48:51]
	v_mfma_f32_16x16x32_bf16 v[40:43], v[162:165], v[184:187], v[40:43]
	v_mfma_f32_16x16x32_bf16 v[32:35], v[154:157], v[192:195], v[32:35]
	v_mfma_f32_16x16x32_bf16 v[24:27], v[162:165], v[192:195], v[24:27]
	v_mfma_f32_16x16x32_bf16 v[16:19], v[154:157], v[218:221], v[16:19]
	v_mfma_f32_16x16x32_bf16 v[8:11], v[162:165], v[218:221], v[8:11]
	v_mfma_f32_16x16x32_bf16 v[4:7], v[154:157], v[226:229], v[4:7]
	v_mfma_f32_16x16x32_bf16 v[0:3], v[162:165], v[226:229], v[0:3]
	v_mfma_f32_16x16x32_bf16 v[48:51], v[158:161], v[188:191], v[48:51]
	v_mfma_f32_16x16x32_bf16 v[40:43], v[180:183], v[188:191], v[40:43]
	v_mfma_f32_16x16x32_bf16 v[32:35], v[158:161], v[196:199], v[32:35]
	v_mfma_f32_16x16x32_bf16 v[24:27], v[180:183], v[196:199], v[24:27]
	v_mfma_f32_16x16x32_bf16 v[16:19], v[158:161], v[222:225], v[16:19]
	v_mfma_f32_16x16x32_bf16 v[8:11], v[180:183], v[222:225], v[8:11]
	v_mfma_f32_16x16x32_bf16 v[4:7], v[158:161], v[230:233], v[4:7]
	v_mfma_f32_16x16x32_bf16 v[0:3], v[180:183], v[230:233], v[0:3]
	s_barrier
	s_add_u32 s26, s26, 0x100
	s_addc_u32 s27, s27, 0
	s_add_u32 s5, s5, 0x100
	s_addc_u32 s15, s15, 0
	s_cmp_ge_u32 s70, s58
	s_mov_b32 s17, s70
	s_cbranch_scc0 .LBB0_171
	s_and_b64 vcc, exec, s[12:13]
	s_cbranch_vccz .LBB0_174
	s_barrier
; DEV unsigned cvt_pk_bf16(float lo, float hi) { const f32x2_ v = {lo, hi}; return __builtin_bit_cast(unsigned, __builtin_convertvector(v, bf16x2n_)); }
;   DEV void operator()(const f32x4 (&acc)[2][2][4][2], const Unit& u, int wr, int wc, int fr, int fq) const {
;     const int row0 = u.pm * BM + wr * 64 + fr, col0 = u.pn * BM + wc * 32 + 4 * fq;
; #pragma unroll
;     for (int ai = 0; ai < 2; ++ai)
; #pragma unroll
;       for (int m = 0; m < 4; ++m) {
;         const size_t ro = (size_t)(row0 + ai * HALF + m * 16) * D + col0;
; #pragma unroll
;         for (int bj = 0; bj < 2; ++bj)
; #pragma unroll
;           for (int n = 0; n < 2; ++n) {
;             const f32x4 v = acc[ai][bj][m][n];
;             u32x2 w; w.x = cvt_pk_bf16(v[0], v[1]); w.y = cvt_pk_bf16(v[2], v[3]);
;             *(u32x2*)((u.seg == 0 ? C0 : C1) + ro + bj * HALF + n * 16) = w;
;           }
;       }
;   }
.LBB0_174:
	s_setprio 0
	v_lshl_add_u32 v140, s8, 8, v134
	v_lshl_or_b32 v138, s4, 8, v136
	v_ashrrev_i32_e32 v141, 31, v140
	s_cmp_eq_u32 s59, 0
	v_ashrrev_i32_e32 v139, 31, v138
	v_lshlrev_b64 v[142:143], 11, v[140:141]
	s_cselect_b32 s5, s63, s25
	s_cselect_b32 s4, s62, s24
	v_cvt_pk_bf16_f32 v124, v124, v125
	v_cvt_pk_bf16_f32 v125, v126, v127
	v_lshl_add_u64 v[126:127], s[4:5], 0, v[142:143]
	v_lshlrev_b64 v[138:139], 1, v[138:139]
	v_lshl_add_u64 v[126:127], v[126:127], 0, v[138:139]
	v_cvt_pk_bf16_f32 v104, v104, v105
	v_cvt_pk_bf16_f32 v105, v106, v107
	global_store_dwordx2 v[126:127], v[104:105], off offset:288
	v_or_b32_e32 v104, 16, v140
	v_ashrrev_i32_e32 v105, 31, v104
	v_lshlrev_b64 v[104:105], 11, v[104:105]
	v_lshl_add_u64 v[104:105], s[4:5], 0, v[104:105]
	v_lshl_add_u64 v[104:105], v[104:105], 0, v[138:139]
	v_cvt_pk_bf16_f32 v88, v88, v89
	v_cvt_pk_bf16_f32 v89, v90, v91
	global_store_dwordx2 v[104:105], v[88:89], off offset:288
	v_or_b32_e32 v88, 32, v140
	v_ashrrev_i32_e32 v89, 31, v88
	v_lshlrev_b64 v[88:89], 11, v[88:89]
	v_lshl_add_u64 v[88:89], s[4:5], 0, v[88:89]
	v_lshl_add_u64 v[88:89], v[88:89], 0, v[138:139]
	v_cvt_pk_bf16_f32 v72, v72, v73
	v_cvt_pk_bf16_f32 v73, v74, v75
	global_store_dwordx2 v[88:89], v[72:73], off offset:288
	v_or_b32_e32 v72, 48, v140
	v_ashrrev_i32_e32 v73, 31, v72
	v_lshlrev_b64 v[72:73], 11, v[72:73]
	v_lshl_add_u64 v[72:73], s[4:5], 0, v[72:73]
	v_lshl_add_u64 v[72:73], v[72:73], 0, v[138:139]
	v_cvt_pk_bf16_f32 v64, v64, v65
	v_cvt_pk_bf16_f32 v65, v66, v67
	global_store_dwordx2 v[72:73], v[64:65], off offset:288
	s_mov_b64 s[4:5], 0x40000
	v_add_co_u32_e32 v64, vcc, s92, v126
	v_cvt_pk_bf16_f32 v60, v60, v61
	v_cvt_pk_bf16_f32 v61, v62, v63
	v_lshl_add_u64 v[62:63], v[126:127], 0, s[4:5]
	v_addc_co_u32_e32 v65, vcc, 0, v127, vcc
	v_cvt_pk_bf16_f32 v48, v48, v49
	v_cvt_pk_bf16_f32 v49, v50, v51
	global_store_dwordx2 v[62:63], v[48:49], off offset:256
	s_mov_b64 s[4:5], 0x48000
	v_add_co_u32_e32 v48, vcc, s93, v126
	v_cvt_pk_bf16_f32 v40, v40, v41
	v_cvt_pk_bf16_f32 v41, v42, v43
	v_lshl_add_u64 v[42:43], v[126:127], 0, s[4:5]
	v_addc_co_u32_e32 v49, vcc, 0, v127, vcc
	v_cvt_pk_bf16_f32 v32, v32, v33
	v_cvt_pk_bf16_f32 v33, v34, v35
	global_store_dwordx2 v[42:43], v[32:33], off offset:256
	s_mov_b64 s[4:5], 0x50000
	v_add_co_u32_e32 v32, vcc, s96, v126
	v_cvt_pk_bf16_f32 v24, v24, v25
	v_cvt_pk_bf16_f32 v25, v26, v27
	v_lshl_add_u64 v[26:27], v[126:127], 0, s[4:5]
	v_addc_co_u32_e32 v33, vcc, 0, v127, vcc
	v_cvt_pk_bf16_f32 v16, v16, v17
	v_cvt_pk_bf16_f32 v17, v18, v19
	global_store_dwordx2 v[26:27], v[16:17], off offset:256
	v_cvt_pk_bf16_f32 v8, v8, v9
	v_cvt_pk_bf16_f32 v9, v10, v11
	v_add_co_u32_e32 v16, vcc, s97, v126
	v_cvt_pk_bf16_f32 v106, v116, v117
	v_cvt_pk_bf16_f32 v107, v118, v119
	v_cvt_pk_bf16_f32 v90, v100, v101
	v_cvt_pk_bf16_f32 v91, v102, v103
	v_cvt_pk_bf16_f32 v74, v84, v85
	v_cvt_pk_bf16_f32 v75, v86, v87
	global_store_dwordx2 v[62:63], v[40:41], off offset:288
	v_cvt_pk_bf16_f32 v40, v52, v53
	v_cvt_pk_bf16_f32 v41, v54, v55
	global_store_dwordx2 v[42:43], v[24:25], off offset:288
	v_cvt_pk_bf16_f32 v24, v36, v37
	v_cvt_pk_bf16_f32 v25, v38, v39
	global_store_dwordx2 v[26:27], v[8:9], off offset:288
	v_cvt_pk_bf16_f32 v8, v20, v21
	v_cvt_pk_bf16_f32 v9, v22, v23
	s_mov_b64 s[4:5], 0x58000
	v_addc_co_u32_e32 v17, vcc, 0, v127, vcc
	v_cvt_pk_bf16_f32 v120, v120, v121
	v_cvt_pk_bf16_f32 v121, v122, v123
	v_cvt_pk_bf16_f32 v112, v112, v113
	v_cvt_pk_bf16_f32 v113, v114, v115
	global_store_dwordx2 v[104:105], v[106:107], off
	v_cvt_pk_bf16_f32 v106, v108, v109
	v_cvt_pk_bf16_f32 v107, v110, v111
	v_cvt_pk_bf16_f32 v96, v96, v97
	v_cvt_pk_bf16_f32 v97, v98, v99
	global_store_dwordx2 v[88:89], v[90:91], off
	v_cvt_pk_bf16_f32 v90, v92, v93
	v_cvt_pk_bf16_f32 v91, v94, v95
	v_cvt_pk_bf16_f32 v80, v80, v81
	v_cvt_pk_bf16_f32 v81, v82, v83
	global_store_dwordx2 v[72:73], v[74:75], off
	v_cvt_pk_bf16_f32 v74, v76, v77
	v_cvt_pk_bf16_f32 v75, v78, v79
	v_cvt_pk_bf16_f32 v68, v68, v69
	v_cvt_pk_bf16_f32 v69, v70, v71
	v_cvt_pk_bf16_f32 v56, v56, v57
	v_cvt_pk_bf16_f32 v57, v58, v59
	global_store_dwordx2 v[48:49], v[40:41], off
	v_cvt_pk_bf16_f32 v40, v44, v45
	v_cvt_pk_bf16_f32 v41, v46, v47
	global_store_dwordx2 v[32:33], v[24:25], off
	v_cvt_pk_bf16_f32 v24, v28, v29
	v_cvt_pk_bf16_f32 v25, v30, v31
	v_lshl_add_u64 v[10:11], v[126:127], 0, s[4:5]
	global_store_dwordx2 v[16:17], v[8:9], off
	v_cvt_pk_bf16_f32 v8, v12, v13
	v_cvt_pk_bf16_f32 v9, v14, v15
	v_cvt_pk_bf16_f32 v4, v4, v5
	v_cvt_pk_bf16_f32 v5, v6, v7
	v_cvt_pk_bf16_f32 v0, v0, v1
	v_cvt_pk_bf16_f32 v1, v2, v3
	s_and_b64 vcc, exec, s[38:39]
	s_mov_b64 s[4:5], -1
	global_store_dwordx2 v[126:127], v[124:125], off
	global_store_dwordx2 v[126:127], v[120:121], off offset:32
	global_store_dwordx2 v[126:127], v[112:113], off offset:256
	global_store_dwordx2 v[104:105], v[106:107], off offset:32
	global_store_dwordx2 v[104:105], v[96:97], off offset:256
	global_store_dwordx2 v[88:89], v[90:91], off offset:32
	global_store_dwordx2 v[88:89], v[80:81], off offset:256
	global_store_dwordx2 v[72:73], v[74:75], off offset:32
	global_store_dwordx2 v[72:73], v[68:69], off offset:256
	global_store_dwordx2 v[64:65], v[60:61], off
	global_store_dwordx2 v[62:63], v[56:57], off offset:32
	global_store_dwordx2 v[42:43], v[40:41], off offset:32
	global_store_dwordx2 v[26:27], v[24:25], off offset:32
	global_store_dwordx2 v[10:11], v[8:9], off offset:32
	global_store_dwordx2 v[10:11], v[4:5], off offset:256
	global_store_dwordx2 v[10:11], v[0:1], off offset:288
	s_cmp_lg_u32 s58, 64
	s_cbranch_scc1 .Lp8_zf_skip
; DEV unsigned cvt_pk_bf16(float lo, float hi) { const f32x2_ v = {lo, hi}; return __builtin_bit_cast(unsigned, __builtin_convertvector(v, bf16x2n_)); }
;   DEV void operator()(const f32x4 (&acc)[2][2][4][2], const Unit& u, int wr, int wc, int fr, int fq) const {
;     ...
;         const size_t ro = (size_t)(row0 + ai * HALF + m * 16) * D + col0;
; #pragma unroll
;         for (int bj = 0; bj < 2; ++bj)
; #pragma unroll
;           for (int n = 0; n < 2; ++n) {
;             const f32x4 v = acc[ai][bj][m][n];
;             u32x2 w; w.x = cvt_pk_bf16(v[0], v[1]); w.y = cvt_pk_bf16(v[2], v[3]);
;             *(u32x2*)((u.seg == 0 ? C0 : C1) + ro + bj * HALF + n * 16) = w;
;           }
	s_cmp_eq_u32 s59, 0
	s_cselect_b32 s22, s24, s62
	s_cselect_b32 s23, s25, s63
	s_cselect_b32 s34, s62, s24
	s_cselect_b32 s35, s63, s25
	s_sub_u32 s22, s22, s34
	s_subb_u32 s23, s23, s35
	v_mov_b32_e32 v2, 0
	v_mov_b32_e32 v3, 0
	v_lshl_add_u64 v[126:127], v[126:127], 0, s[22:23]
	v_lshl_add_u64 v[104:105], v[104:105], 0, s[22:23]
	v_lshl_add_u64 v[88:89], v[88:89], 0, s[22:23]
	v_lshl_add_u64 v[72:73], v[72:73], 0, s[22:23]
	v_lshl_add_u64 v[62:63], v[62:63], 0, s[22:23]
	v_lshl_add_u64 v[42:43], v[42:43], 0, s[22:23]
	v_lshl_add_u64 v[26:27], v[26:27], 0, s[22:23]
	v_lshl_add_u64 v[48:49], v[48:49], 0, s[22:23]
	v_lshl_add_u64 v[32:33], v[32:33], 0, s[22:23]
	v_lshl_add_u64 v[16:17], v[16:17], 0, s[22:23]
	v_lshl_add_u64 v[64:65], v[64:65], 0, s[22:23]
	v_lshl_add_u64 v[10:11], v[10:11], 0, s[22:23]
	global_store_dwordx2 v[126:127], v[2:3], off offset:288
	global_store_dwordx2 v[104:105], v[2:3], off offset:288
	global_store_dwordx2 v[88:89], v[2:3], off offset:288
	global_store_dwordx2 v[72:73], v[2:3], off offset:288
	global_store_dwordx2 v[62:63], v[2:3], off offset:256
	global_store_dwordx2 v[42:43], v[2:3], off offset:256
	global_store_dwordx2 v[26:27], v[2:3], off offset:256
	global_store_dwordx2 v[62:63], v[2:3], off offset:288
	global_store_dwordx2 v[42:43], v[2:3], off offset:288
	global_store_dwordx2 v[26:27], v[2:3], off offset:288
	global_store_dwordx2 v[104:105], v[2:3], off
	global_store_dwordx2 v[88:89], v[2:3], off
	global_store_dwordx2 v[72:73], v[2:3], off
	global_store_dwordx2 v[48:49], v[2:3], off
	global_store_dwordx2 v[32:33], v[2:3], off
	global_store_dwordx2 v[16:17], v[2:3], off
	global_store_dwordx2 v[126:127], v[2:3], off
	global_store_dwordx2 v[126:127], v[2:3], off offset:32
	global_store_dwordx2 v[126:127], v[2:3], off offset:256
	global_store_dwordx2 v[104:105], v[2:3], off offset:32
	global_store_dwordx2 v[104:105], v[2:3], off offset:256
	global_store_dwordx2 v[88:89], v[2:3], off offset:32
	global_store_dwordx2 v[88:89], v[2:3], off offset:256
	global_store_dwordx2 v[72:73], v[2:3], off offset:32
	global_store_dwordx2 v[72:73], v[2:3], off offset:256
	global_store_dwordx2 v[64:65], v[2:3], off
	global_store_dwordx2 v[62:63], v[2:3], off offset:32
	global_store_dwordx2 v[42:43], v[2:3], off offset:32
	global_store_dwordx2 v[26:27], v[2:3], off offset:32
	global_store_dwordx2 v[10:11], v[2:3], off offset:32
	global_store_dwordx2 v[10:11], v[2:3], off offset:256
	global_store_dwordx2 v[10:11], v[2:3], off offset:288

; #define PG8_STAGE(bufoff, gbase, voff) do { _Pragma("unroll") for (int _i = 0; _i < 2; ++_i) \
;     __builtin_amdgcn_global_load_lds((const unsigned*)((const char*)(gbase) + (voff)[_i]), (PG8_LAS unsigned*)(lds + (bufoff) + ldsw + _i * 8192), 16, 0, 0); } while (0)
; #define PG8_LDA(dst, b, h) do { _Pragma("unroll") for (int m = 0; m < 4; ++m) _Pragma("unroll") for (int k = 0; k < 2; ++k) dst[m][k] = *(const PG8_LAS bf16x8*)(lds + PG8_SA(b, h) + aoff + m * 2048 + k * 1024); } while (0)
; #define PG8_LDB(dst, b, h) do { _Pragma("unroll") for (int n = 0; n < 2; ++n) _Pragma("unroll") for (int k = 0; k < 2; ++k) dst[n][k] = *(const PG8_LAS bf16x8*)(lds + PG8_SB(b, h) + boff + n * 2048 + k * 1024); } while (0)
; #define PG8_MMA(ai, bj, At, Bt) do { __builtin_amdgcn_s_setprio(1); _Pragma("unroll") for (int m = 0; m < 4; ++m) _Pragma("unroll") for (int n = 0; n < 2; ++n) _Pragma("unroll") for (int k = 0; k < 2; ++k) \
;     acc[ai][bj][m][n] = __builtin_amdgcn_mfma_f32_16x16x32_bf16(Bt[n][k], At[m][k], acc[ai][bj][m][n], 0, 0, 0); __builtin_amdgcn_s_setprio(0); } while (0)
; #define PG8_WAIT_V(n) asm volatile("s_waitcnt vmcnt(" #n ")" ::: "memory")
; template <class Epi, bool SEQ>
; DEV void gemm_phase(PG8_LAS unsigned char* lds, const Gemm g, const Epi& E) {
;     ...
;   for (;;) {
;     const bool has_next = next_unit<SEQ>(g, ui + 1, G, cblk, nxt);
;     const char* nA = has_next ? PG8_ABASE(nxt) : cA; const char* nB = has_next ? PG8_BBASE(nxt) : cB;
;     for (int t = 0; t < nt; t += 2) {
;       const bool last = (t == nt - 2);
;       const char* a1 = cA + (size_t)(t + 1) * kstep;
;       const char* a2 = last ? nA : cA + (size_t)(t + 2) * kstep; const char* b2 = last ? nB : cB + (size_t)(t + 2) * kstep;
;       const char* a3 = a2 + kstep; const char* b3 = b2 + kstep;
;       PG8_LDB(B0, 0, 0); PG8_LDB(B1, 0, 1); PG8_SCHED; PG8_LDA(At, 0, 0); PG8_STAGE(PG8_SA(1, 1), a1 + hstepA, voffA);
;       PG8_WAIT_V(8); PG8_WAIT_L(0); PG8_BAR; PG8_MMA(0, 0, At, B0); PG8_MMA(0, 1, At, B1); PG8_BAR; PG8_SCHED;
;     ...
;     if (!keep) {
; #pragma unroll
;       for (int a = 0; a < 2; ++a)
; #pragma unroll
;         for (int b = 0; b < 2; ++b)
; #pragma unroll
;           for (int m = 0; m < 4; ++m)
; #pragma unroll
;             for (int n = 0; n < 2; ++n) acc[a][b][m][n] = (f32x4){0.f, 0.f, 0.f, 0.f};
;     }
;     cur = nxt; cA = nA; cB = nB; ++ui;
.LBB0_204:
	s_ashr_i32 s5, s4, 31
	s_lshl_b64 s[14:15], s[4:5], 19
	s_add_u32 s14, s24, s14
	s_addc_u32 s15, s25, s15
	s_and_b64 s[16:17], s[12:13], exec
	s_cselect_b32 s5, s15, s19
	s_cselect_b32 s48, s14, s18
	s_ashr_i32 s9, s8, 31
	s_lshl_b64 s[16:17], s[8:9], 19
	s_add_u32 s16, s37, s16
	s_addc_u32 s17, s38, s17
	s_and_b64 s[26:27], s[12:13], exec
	s_cselect_b32 s9, s17, s21
	s_cselect_b32 s49, s16, s20
	s_add_u32 s18, s18, 0x40080
	s_addc_u32 s19, s19, 0
	s_add_u32 s50, s20, 0x100
	v_mov_b64_e32 v[0:1], 0
	v_mov_b64_e32 v[2:3], 0
	v_mov_b64_e32 v[4:5], 0
	v_mov_b64_e32 v[6:7], 0
	v_mov_b64_e32 v[8:9], 0
	v_mov_b64_e32 v[10:11], 0
	v_mov_b64_e32 v[12:13], 0
	v_mov_b64_e32 v[14:15], 0
	v_mov_b64_e32 v[16:17], 0
	v_mov_b64_e32 v[18:19], 0
	v_mov_b64_e32 v[20:21], 0
	v_mov_b64_e32 v[22:23], 0
	v_mov_b64_e32 v[24:25], 0
	v_mov_b64_e32 v[26:27], 0
	v_mov_b64_e32 v[28:29], 0
	v_mov_b64_e32 v[30:31], 0
	v_mov_b64_e32 v[32:33], 0
	v_mov_b64_e32 v[34:35], 0
	v_mov_b64_e32 v[36:37], 0
	v_mov_b64_e32 v[38:39], 0
	v_mov_b64_e32 v[40:41], 0
	v_mov_b64_e32 v[42:43], 0
	v_mov_b64_e32 v[44:45], 0
	v_mov_b64_e32 v[46:47], 0
	v_mov_b64_e32 v[48:49], 0
	v_mov_b64_e32 v[50:51], 0
	v_mov_b64_e32 v[52:53], 0
	v_mov_b64_e32 v[54:55], 0
	v_mov_b64_e32 v[56:57], 0
	v_mov_b64_e32 v[58:59], 0
	v_mov_b64_e32 v[60:61], 0
	v_mov_b64_e32 v[62:63], 0
	v_mov_b64_e32 v[64:65], 0
	v_mov_b64_e32 v[66:67], 0
	v_mov_b64_e32 v[68:69], 0
	v_mov_b64_e32 v[70:71], 0
	v_mov_b64_e32 v[72:73], 0
	v_mov_b64_e32 v[74:75], 0
	v_mov_b64_e32 v[76:77], 0
	v_mov_b64_e32 v[78:79], 0
	v_mov_b64_e32 v[80:81], 0
	v_mov_b64_e32 v[82:83], 0
	v_mov_b64_e32 v[84:85], 0
	v_mov_b64_e32 v[86:87], 0
	v_mov_b64_e32 v[88:89], 0
	v_mov_b64_e32 v[90:91], 0
	v_mov_b64_e32 v[92:93], 0
	v_mov_b64_e32 v[94:95], 0
	v_mov_b64_e32 v[96:97], 0
	v_mov_b64_e32 v[98:99], 0
	v_mov_b64_e32 v[100:101], 0
	v_mov_b64_e32 v[102:103], 0
	v_mov_b64_e32 v[104:105], 0
	v_mov_b64_e32 v[106:107], 0
	v_mov_b64_e32 v[108:109], 0
	v_mov_b64_e32 v[110:111], 0
	v_mov_b64_e32 v[112:113], 0
	v_mov_b64_e32 v[114:115], 0
	v_mov_b64_e32 v[116:117], 0
	v_mov_b64_e32 v[118:119], 0
	v_mov_b64_e32 v[120:121], 0
	v_mov_b64_e32 v[122:123], 0
	v_mov_b64_e32 v[124:125], 0
	v_mov_b64_e32 v[126:127], 0
	s_addc_u32 s51, s21, 0
	s_mov_b32 s52, -2
	s_waitcnt lgkmcnt(0)
	v_readfirstlane_b32 s98, v171
	s_nop 3
	s_lshr_b32 s98, s98, 6
	s_cmp_lt_u32 s98, 4
	s_cbranch_scc0 .Lprio_205
	s_setprio 1
.Lprio_205:
.LBB0_205:
	s_add_u32 s20, s18, 0xfffc0080
	s_addc_u32 s21, s19, -1
	s_add_i32 s53, 0, 0x10000
	s_cmp_eq_u32 s52, 12
	s_cselect_b32 s27, s5, s21
	s_cselect_b32 s26, s48, s20
	v_add_u32_e32 v138, s53, v141
	s_cselect_b32 s21, s9, s51
	s_cselect_b32 s20, s49, s50
	s_add_i32 s56, 0, 0x14000
	ds_read_b128 v[144:147], v138
	ds_read_b128 v[148:151], v138 offset:1024
	ds_read_b128 v[152:155], v138 offset:2048
	ds_read_b128 v[156:159], v138 offset:3072
	v_add_u32_e32 v138, s56, v141
	ds_read_b128 v[160:163], v138
	ds_read_b128 v[164:167], v138 offset:1024
	ds_read_b128 v[180:183], v138 offset:2048
	ds_read_b128 v[184:187], v138 offset:3072
	v_lshl_add_u64 v[138:139], s[18:19], 0, v[134:135]
	s_add_i32 m0, s39, 0xc000
	ds_read_b128 v[188:191], v143
	ds_read_b128 v[192:195], v143 offset:1024
	ds_read_b128 v[196:199], v143 offset:2048
	ds_read_b128 v[218:221], v143 offset:3072
	ds_read_b128 v[222:225], v143 offset:4096
	ds_read_b128 v[226:229], v143 offset:5120
	ds_read_b128 v[230:233], v143 offset:6144
	ds_read_b128 v[234:237], v143 offset:7168
	global_load_lds_dwordx4 v[138:139], off
	v_lshl_add_u64 v[138:139], s[18:19], 0, v[136:137]
	s_add_i32 m0, s39, 0xe000
	s_nop 0
	global_load_lds_dwordx4 v[138:139], off
	s_waitcnt vmcnt(8)
	s_waitcnt lgkmcnt(0)
	s_barrier
	s_waitcnt lgkmcnt(0)
	v_mfma_f32_16x16x32_bf16 v[124:127], v[144:147], v[188:191], v[124:127]
	v_mfma_f32_16x16x32_bf16 v[120:123], v[152:155], v[188:191], v[120:123]
	v_mfma_f32_16x16x32_bf16 v[108:111], v[144:147], v[196:199], v[108:111]
	v_mfma_f32_16x16x32_bf16 v[104:107], v[152:155], v[196:199], v[104:107]
	v_mfma_f32_16x16x32_bf16 v[92:95], v[144:147], v[222:225], v[92:95]
	v_mfma_f32_16x16x32_bf16 v[88:91], v[152:155], v[222:225], v[88:91]
	v_mfma_f32_16x16x32_bf16 v[76:79], v[144:147], v[230:233], v[76:79]
	v_mfma_f32_16x16x32_bf16 v[72:75], v[152:155], v[230:233], v[72:75]
	v_mfma_f32_16x16x32_bf16 v[124:127], v[148:151], v[192:195], v[124:127]
	v_mfma_f32_16x16x32_bf16 v[120:123], v[156:159], v[192:195], v[120:123]
	v_mfma_f32_16x16x32_bf16 v[108:111], v[148:151], v[218:221], v[108:111]
	v_mfma_f32_16x16x32_bf16 v[104:107], v[156:159], v[218:221], v[104:107]
	v_mfma_f32_16x16x32_bf16 v[92:95], v[148:151], v[226:229], v[92:95]
	v_mfma_f32_16x16x32_bf16 v[88:91], v[156:159], v[226:229], v[88:91]
	v_mfma_f32_16x16x32_bf16 v[76:79], v[148:151], v[234:237], v[76:79]
	v_mfma_f32_16x16x32_bf16 v[72:75], v[156:159], v[234:237], v[72:75]
	v_mfma_f32_16x16x32_bf16 v[116:119], v[160:163], v[188:191], v[116:119]
	v_mfma_f32_16x16x32_bf16 v[112:115], v[180:183], v[188:191], v[112:115]
	v_mfma_f32_16x16x32_bf16 v[100:103], v[160:163], v[196:199], v[100:103]
	v_mfma_f32_16x16x32_bf16 v[96:99], v[180:183], v[196:199], v[96:99]
	v_mfma_f32_16x16x32_bf16 v[84:87], v[160:163], v[222:225], v[84:87]
	v_mfma_f32_16x16x32_bf16 v[80:83], v[180:183], v[222:225], v[80:83]
	v_mfma_f32_16x16x32_bf16 v[68:71], v[160:163], v[230:233], v[68:71]
	v_mfma_f32_16x16x32_bf16 v[64:67], v[180:183], v[230:233], v[64:67]
	v_mfma_f32_16x16x32_bf16 v[116:119], v[164:167], v[192:195], v[116:119]
	v_mfma_f32_16x16x32_bf16 v[112:115], v[184:187], v[192:195], v[112:115]
	v_mfma_f32_16x16x32_bf16 v[100:103], v[164:167], v[218:221], v[100:103]
	v_mfma_f32_16x16x32_bf16 v[96:99], v[184:187], v[218:221], v[96:99]
	v_mfma_f32_16x16x32_bf16 v[84:87], v[164:167], v[226:229], v[84:87]
	v_mfma_f32_16x16x32_bf16 v[80:83], v[184:187], v[226:229], v[80:83]
	v_mfma_f32_16x16x32_bf16 v[68:71], v[164:167], v[234:237], v[68:71]
	v_mfma_f32_16x16x32_bf16 v[64:67], v[184:187], v[234:237], v[64:67]
	s_barrier
; #define PG8_STAGE(bufoff, gbase, voff) do { _Pragma("unroll") for (int _i = 0; _i < 2; ++_i) \
;     __builtin_amdgcn_global_load_lds((const unsigned*)((const char*)(gbase) + (voff)[_i]), (PG8_LAS unsigned*)(lds + (bufoff) + ldsw + _i * 8192), 16, 0, 0); } while (0)
; #define PG8_LDA(dst, b, h) do { _Pragma("unroll") for (int m = 0; m < 4; ++m) _Pragma("unroll") for (int k = 0; k < 2; ++k) dst[m][k] = *(const PG8_LAS bf16x8*)(lds + PG8_SA(b, h) + aoff + m * 2048 + k * 1024); } while (0)
; #define PG8_LDB(dst, b, h) do { _Pragma("unroll") for (int n = 0; n < 2; ++n) _Pragma("unroll") for (int k = 0; k < 2; ++k) dst[n][k] = *(const PG8_LAS bf16x8*)(lds + PG8_SB(b, h) + boff + n * 2048 + k * 1024); } while (0)
; #define PG8_MMA(ai, bj, At, Bt) do { __builtin_amdgcn_s_setprio(1); _Pragma("unroll") for (int m = 0; m < 4; ++m) _Pragma("unroll") for (int n = 0; n < 2; ++n) _Pragma("unroll") for (int k = 0; k < 2; ++k) \
;     acc[ai][bj][m][n] = __builtin_amdgcn_mfma_f32_16x16x32_bf16(Bt[n][k], At[m][k], acc[ai][bj][m][n], 0, 0, 0); __builtin_amdgcn_s_setprio(0); } while (0)
; #define PG8_WAIT_V(n) asm volatile("s_waitcnt vmcnt(" #n ")" ::: "memory")
; #define PG8_WAIT_L(n) asm volatile("s_waitcnt lgkmcnt(" #n ")" ::: "memory")
; #define PG8_BAR __builtin_amdgcn_s_barrier()
; #define PG8_SCHED __builtin_amdgcn_sched_barrier(0)
; template <class Epi, bool SEQ>
; DEV void gemm_phase(PG8_LAS unsigned char* lds, const Gemm g, const Epi& E) {
;     ...
;       PG8_LDA(At, 0, 1); PG8_STAGE(PG8_SB(0, 0), b2, voffB); PG8_STAGE(PG8_SB(0, 1), b2 + hstepB, voffB); PG8_STAGE(PG8_SA(0, 0), a2, voffA);
;       PG8_WAIT_V(8); PG8_WAIT_L(0); PG8_BAR; PG8_MMA(1, 0, At, B0); PG8_MMA(1, 1, At, B1); PG8_BAR; PG8_SCHED;
;       PG8_LDB(B0, 1, 0); PG8_LDB(B1, 1, 1); PG8_SCHED; PG8_LDA(At, 1, 0); PG8_STAGE(PG8_SA(0, 1), a2 + hstepA, voffA);
	s_add_i32 s53, s53, s36
	v_lshl_add_u64 v[138:139], s[20:21], 0, v[168:169]
	s_mov_b32 m0, s53
	ds_read_b128 v[188:191], v143 offset:16384
	ds_read_b128 v[192:195], v143 offset:17408
	ds_read_b128 v[196:199], v143 offset:18432
	ds_read_b128 v[218:221], v143 offset:19456
	ds_read_b128 v[222:225], v143 offset:20480
	ds_read_b128 v[226:229], v143 offset:21504
	ds_read_b128 v[230:233], v143 offset:22528
	ds_read_b128 v[234:237], v143 offset:23552
	global_load_lds_dwordx4 v[138:139], off
	s_add_i32 m0, s53, 0x2000
	s_add_u32 s54, s20, 0x40000
	v_lshl_add_u64 v[238:239], s[20:21], 0, v[128:129]
	s_addc_u32 s55, s21, 0
	s_add_i32 s53, s56, s36
	global_load_lds_dwordx4 v[238:239], off
	v_lshl_add_u64 v[240:241], s[54:55], 0, v[168:169]
	s_mov_b32 m0, s53
	v_lshl_add_u64 v[242:243], s[26:27], 0, v[130:131]
	global_load_lds_dwordx4 v[240:241], off
	v_lshl_add_u64 v[240:241], s[54:55], 0, v[128:129]
	s_add_i32 m0, s53, 0x2000
	s_nop 0
	global_load_lds_dwordx4 v[240:241], off
	v_lshl_add_u64 v[240:241], s[26:27], 0, v[132:133]
	s_mov_b32 m0, s39
	s_nop 0
	global_load_lds_dwordx4 v[240:241], off
	s_mov_b32 m0, s40
	s_nop 0
	global_load_lds_dwordx4 v[242:243], off
	s_waitcnt vmcnt(8)
	s_waitcnt lgkmcnt(0)
	s_barrier
	s_waitcnt lgkmcnt(0)
	v_mfma_f32_16x16x32_bf16 v[60:63], v[144:147], v[188:191], v[60:63]
	v_mfma_f32_16x16x32_bf16 v[56:59], v[152:155], v[188:191], v[56:59]
	v_mfma_f32_16x16x32_bf16 v[44:47], v[144:147], v[196:199], v[44:47]
	v_mfma_f32_16x16x32_bf16 v[40:43], v[152:155], v[196:199], v[40:43]
	v_mfma_f32_16x16x32_bf16 v[28:31], v[144:147], v[222:225], v[28:31]
	v_mfma_f32_16x16x32_bf16 v[24:27], v[152:155], v[222:225], v[24:27]
	v_mfma_f32_16x16x32_bf16 v[12:15], v[144:147], v[230:233], v[12:15]
	v_mfma_f32_16x16x32_bf16 v[8:11], v[152:155], v[230:233], v[8:11]
	v_mfma_f32_16x16x32_bf16 v[60:63], v[148:151], v[192:195], v[60:63]
	v_mfma_f32_16x16x32_bf16 v[56:59], v[156:159], v[192:195], v[56:59]
	v_mfma_f32_16x16x32_bf16 v[44:47], v[148:151], v[218:221], v[44:47]
	v_mfma_f32_16x16x32_bf16 v[40:43], v[156:159], v[218:221], v[40:43]
	v_mfma_f32_16x16x32_bf16 v[28:31], v[148:151], v[226:229], v[28:31]
	v_mfma_f32_16x16x32_bf16 v[24:27], v[156:159], v[226:229], v[24:27]
	v_mfma_f32_16x16x32_bf16 v[12:15], v[148:151], v[234:237], v[12:15]
	v_mfma_f32_16x16x32_bf16 v[8:11], v[156:159], v[234:237], v[8:11]
	v_mfma_f32_16x16x32_bf16 v[52:55], v[160:163], v[188:191], v[52:55]
	v_mfma_f32_16x16x32_bf16 v[48:51], v[180:183], v[188:191], v[48:51]
	v_mfma_f32_16x16x32_bf16 v[36:39], v[160:163], v[196:199], v[36:39]
	v_mfma_f32_16x16x32_bf16 v[32:35], v[180:183], v[196:199], v[32:35]
	v_mfma_f32_16x16x32_bf16 v[20:23], v[160:163], v[222:225], v[20:23]
	v_mfma_f32_16x16x32_bf16 v[16:19], v[180:183], v[222:225], v[16:19]
	v_mfma_f32_16x16x32_bf16 v[4:7], v[160:163], v[230:233], v[4:7]
	v_mfma_f32_16x16x32_bf16 v[0:3], v[180:183], v[230:233], v[0:3]
	v_mfma_f32_16x16x32_bf16 v[52:55], v[164:167], v[192:195], v[52:55]
	v_mfma_f32_16x16x32_bf16 v[48:51], v[184:187], v[192:195], v[48:51]
	v_mfma_f32_16x16x32_bf16 v[36:39], v[164:167], v[218:221], v[36:39]
	v_mfma_f32_16x16x32_bf16 v[32:35], v[184:187], v[218:221], v[32:35]
	v_mfma_f32_16x16x32_bf16 v[20:23], v[164:167], v[226:229], v[20:23]
	v_mfma_f32_16x16x32_bf16 v[16:19], v[184:187], v[226:229], v[16:19]
	v_mfma_f32_16x16x32_bf16 v[4:7], v[164:167], v[234:237], v[4:7]
	v_mfma_f32_16x16x32_bf16 v[0:3], v[184:187], v[234:237], v[0:3]
	s_barrier
	s_add_i32 s53, 0, 0x18000
	s_add_i32 s54, 0, 0x1c000
	v_add_u32_e32 v156, s53, v141
	v_add_u32_e32 v177, s54, v141
	ds_read_b128 v[144:147], v156
	ds_read_b128 v[148:151], v156 offset:1024
	ds_read_b128 v[152:155], v156 offset:2048
	ds_read_b128 v[156:159], v156 offset:3072
	ds_read_b128 v[160:163], v177
	ds_read_b128 v[164:167], v177 offset:1024
	ds_read_b128 v[180:183], v177 offset:2048
	ds_read_b128 v[184:187], v177 offset:3072
	s_add_u32 s26, s26, 0x40000
	s_addc_u32 s27, s27, 0
	s_mov_b32 m0, s41
	v_lshl_add_u64 v[244:245], s[26:27], 0, v[132:133]
	ds_read_b128 v[188:191], v143 offset:32768
	ds_read_b128 v[192:195], v143 offset:33792
	ds_read_b128 v[196:199], v143 offset:34816
	ds_read_b128 v[218:221], v143 offset:35840
	ds_read_b128 v[222:225], v143 offset:36864
	ds_read_b128 v[226:229], v143 offset:37888
	ds_read_b128 v[230:233], v143 offset:38912
	ds_read_b128 v[234:237], v143 offset:39936
	global_load_lds_dwordx4 v[244:245], off
	v_lshl_add_u64 v[244:245], s[26:27], 0, v[130:131]
	s_mov_b32 m0, s42
	s_nop 0
	global_load_lds_dwordx4 v[244:245], off
	s_waitcnt vmcnt(8)
	s_waitcnt lgkmcnt(0)
	s_barrier
; #define PG8_STAGE(bufoff, gbase, voff) do { _Pragma("unroll") for (int _i = 0; _i < 2; ++_i) \
;     __builtin_amdgcn_global_load_lds((const unsigned*)((const char*)(gbase) + (voff)[_i]), (PG8_LAS unsigned*)(lds + (bufoff) + ldsw + _i * 8192), 16, 0, 0); } while (0)
; #define PG8_LDA(dst, b, h) do { _Pragma("unroll") for (int m = 0; m < 4; ++m) _Pragma("unroll") for (int k = 0; k < 2; ++k) dst[m][k] = *(const PG8_LAS bf16x8*)(lds + PG8_SA(b, h) + aoff + m * 2048 + k * 1024); } while (0)
; #define PG8_MMA(ai, bj, At, Bt) do { __builtin_amdgcn_s_setprio(1); _Pragma("unroll") for (int m = 0; m < 4; ++m) _Pragma("unroll") for (int n = 0; n < 2; ++n) _Pragma("unroll") for (int k = 0; k < 2; ++k) \
;     acc[ai][bj][m][n] = __builtin_amdgcn_mfma_f32_16x16x32_bf16(Bt[n][k], At[m][k], acc[ai][bj][m][n], 0, 0, 0); __builtin_amdgcn_s_setprio(0); } while (0)
; #define PG8_WAIT_V(n) asm volatile("s_waitcnt vmcnt(" #n ")" ::: "memory")
; #define PG8_WAIT_L(n) asm volatile("s_waitcnt lgkmcnt(" #n ")" ::: "memory")
; #define PG8_BAR __builtin_amdgcn_s_barrier()
; #define PG8_SCHED __builtin_amdgcn_sched_barrier(0)
; template <class Epi, bool SEQ>
; DEV void gemm_phase(PG8_LAS unsigned char* lds, const Gemm g, const Epi& E) {
;     ...
;       PG8_WAIT_V(8); PG8_WAIT_L(0); PG8_BAR; PG8_MMA(0, 0, At, B0); PG8_MMA(0, 1, At, B1); PG8_BAR; PG8_SCHED;
;       PG8_LDA(At, 1, 1); PG8_STAGE(PG8_SB(1, 0), b3, voffB); PG8_STAGE(PG8_SB(1, 1), b3 + hstepB, voffB); PG8_STAGE(PG8_SA(1, 0), a3, voffA);
;       PG8_WAIT_V(8); PG8_WAIT_L(0); PG8_BAR; PG8_MMA(1, 0, At, B0); PG8_MMA(1, 1, At, B1); PG8_BAR; PG8_SCHED;
;     }
;     if (wr == 0) PG8_BAR;
	s_waitcnt lgkmcnt(0)
	v_mfma_f32_16x16x32_bf16 v[124:127], v[144:147], v[188:191], v[124:127]
	v_mfma_f32_16x16x32_bf16 v[120:123], v[152:155], v[188:191], v[120:123]
	v_mfma_f32_16x16x32_bf16 v[108:111], v[144:147], v[196:199], v[108:111]
	v_mfma_f32_16x16x32_bf16 v[104:107], v[152:155], v[196:199], v[104:107]
	v_mfma_f32_16x16x32_bf16 v[92:95], v[144:147], v[222:225], v[92:95]
	v_mfma_f32_16x16x32_bf16 v[88:91], v[152:155], v[222:225], v[88:91]
	v_mfma_f32_16x16x32_bf16 v[76:79], v[144:147], v[230:233], v[76:79]
	v_mfma_f32_16x16x32_bf16 v[72:75], v[152:155], v[230:233], v[72:75]
	v_mfma_f32_16x16x32_bf16 v[124:127], v[148:151], v[192:195], v[124:127]
	v_mfma_f32_16x16x32_bf16 v[120:123], v[156:159], v[192:195], v[120:123]
	v_mfma_f32_16x16x32_bf16 v[108:111], v[148:151], v[218:221], v[108:111]
	v_mfma_f32_16x16x32_bf16 v[104:107], v[156:159], v[218:221], v[104:107]
	v_mfma_f32_16x16x32_bf16 v[92:95], v[148:151], v[226:229], v[92:95]
	v_mfma_f32_16x16x32_bf16 v[88:91], v[156:159], v[226:229], v[88:91]
	v_mfma_f32_16x16x32_bf16 v[76:79], v[148:151], v[234:237], v[76:79]
	v_mfma_f32_16x16x32_bf16 v[72:75], v[156:159], v[234:237], v[72:75]
	v_mfma_f32_16x16x32_bf16 v[116:119], v[160:163], v[188:191], v[116:119]
	v_mfma_f32_16x16x32_bf16 v[112:115], v[180:183], v[188:191], v[112:115]
	v_mfma_f32_16x16x32_bf16 v[100:103], v[160:163], v[196:199], v[100:103]
	v_mfma_f32_16x16x32_bf16 v[96:99], v[180:183], v[196:199], v[96:99]
	v_mfma_f32_16x16x32_bf16 v[84:87], v[160:163], v[222:225], v[84:87]
	v_mfma_f32_16x16x32_bf16 v[80:83], v[180:183], v[222:225], v[80:83]
	v_mfma_f32_16x16x32_bf16 v[68:71], v[160:163], v[230:233], v[68:71]
	v_mfma_f32_16x16x32_bf16 v[64:67], v[180:183], v[230:233], v[64:67]
	v_mfma_f32_16x16x32_bf16 v[116:119], v[164:167], v[192:195], v[116:119]
	v_mfma_f32_16x16x32_bf16 v[112:115], v[184:187], v[192:195], v[112:115]
	v_mfma_f32_16x16x32_bf16 v[100:103], v[164:167], v[218:221], v[100:103]
	v_mfma_f32_16x16x32_bf16 v[96:99], v[184:187], v[218:221], v[96:99]
	v_mfma_f32_16x16x32_bf16 v[84:87], v[164:167], v[226:229], v[84:87]
	v_mfma_f32_16x16x32_bf16 v[80:83], v[184:187], v[226:229], v[80:83]
	v_mfma_f32_16x16x32_bf16 v[68:71], v[164:167], v[234:237], v[68:71]
	v_mfma_f32_16x16x32_bf16 v[64:67], v[184:187], v[234:237], v[64:67]
	s_barrier
	s_add_i32 s26, s53, s36
	v_lshl_add_u64 v[138:139], v[138:139], 0, s[10:11]
	s_mov_b32 m0, s26
	ds_read_b128 v[188:191], v143 offset:49152
	ds_read_b128 v[192:195], v143 offset:50176
	ds_read_b128 v[196:199], v143 offset:51200
	ds_read_b128 v[218:221], v143 offset:52224
	ds_read_b128 v[222:225], v143 offset:53248
	ds_read_b128 v[226:229], v143 offset:54272
	ds_read_b128 v[230:233], v143 offset:55296
	ds_read_b128 v[234:237], v143 offset:56320
	global_load_lds_dwordx4 v[138:139], off
	s_add_i32 m0, s26, 0x2000
	s_add_u32 s20, s20, 0x40080
	v_lshl_add_u64 v[138:139], v[238:239], 0, s[10:11]
	s_addc_u32 s21, s21, 0
	s_add_i32 s26, s54, s36
	global_load_lds_dwordx4 v[138:139], off
	v_lshl_add_u64 v[138:139], s[20:21], 0, v[168:169]
	s_mov_b32 m0, s26
	s_nop 0
	global_load_lds_dwordx4 v[138:139], off
	v_lshl_add_u64 v[138:139], s[20:21], 0, v[128:129]
	s_add_i32 m0, s26, 0x2000
	s_nop 0
	global_load_lds_dwordx4 v[138:139], off
	v_lshl_add_u64 v[138:139], v[240:241], 0, s[10:11]
	s_mov_b32 m0, s43
	s_nop 0
	global_load_lds_dwordx4 v[138:139], off
	v_lshl_add_u64 v[138:139], v[242:243], 0, s[10:11]
	s_mov_b32 m0, s44
	s_nop 0
	global_load_lds_dwordx4 v[138:139], off
	s_waitcnt vmcnt(8)
	s_waitcnt lgkmcnt(0)
	s_barrier
	s_waitcnt lgkmcnt(0)
	v_mfma_f32_16x16x32_bf16 v[60:63], v[144:147], v[188:191], v[60:63]
	v_mfma_f32_16x16x32_bf16 v[56:59], v[152:155], v[188:191], v[56:59]
	v_mfma_f32_16x16x32_bf16 v[44:47], v[144:147], v[196:199], v[44:47]
	v_mfma_f32_16x16x32_bf16 v[40:43], v[152:155], v[196:199], v[40:43]
	v_mfma_f32_16x16x32_bf16 v[28:31], v[144:147], v[222:225], v[28:31]
	v_mfma_f32_16x16x32_bf16 v[24:27], v[152:155], v[222:225], v[24:27]
	v_mfma_f32_16x16x32_bf16 v[12:15], v[144:147], v[230:233], v[12:15]
	v_mfma_f32_16x16x32_bf16 v[8:11], v[152:155], v[230:233], v[8:11]
	v_mfma_f32_16x16x32_bf16 v[60:63], v[148:151], v[192:195], v[60:63]
	v_mfma_f32_16x16x32_bf16 v[56:59], v[156:159], v[192:195], v[56:59]
	v_mfma_f32_16x16x32_bf16 v[44:47], v[148:151], v[218:221], v[44:47]
	v_mfma_f32_16x16x32_bf16 v[40:43], v[156:159], v[218:221], v[40:43]
	v_mfma_f32_16x16x32_bf16 v[28:31], v[148:151], v[226:229], v[28:31]
	v_mfma_f32_16x16x32_bf16 v[24:27], v[156:159], v[226:229], v[24:27]
	v_mfma_f32_16x16x32_bf16 v[12:15], v[148:151], v[234:237], v[12:15]
	v_mfma_f32_16x16x32_bf16 v[8:11], v[156:159], v[234:237], v[8:11]
	v_mfma_f32_16x16x32_bf16 v[52:55], v[160:163], v[188:191], v[52:55]
	v_mfma_f32_16x16x32_bf16 v[48:51], v[180:183], v[188:191], v[48:51]
	v_mfma_f32_16x16x32_bf16 v[36:39], v[160:163], v[196:199], v[36:39]
	v_mfma_f32_16x16x32_bf16 v[32:35], v[180:183], v[196:199], v[32:35]
	v_mfma_f32_16x16x32_bf16 v[20:23], v[160:163], v[222:225], v[20:23]
	v_mfma_f32_16x16x32_bf16 v[16:19], v[180:183], v[222:225], v[16:19]
	v_mfma_f32_16x16x32_bf16 v[4:7], v[160:163], v[230:233], v[4:7]
	v_mfma_f32_16x16x32_bf16 v[0:3], v[180:183], v[230:233], v[0:3]
	v_mfma_f32_16x16x32_bf16 v[52:55], v[164:167], v[192:195], v[52:55]
	v_mfma_f32_16x16x32_bf16 v[48:51], v[184:187], v[192:195], v[48:51]
	v_mfma_f32_16x16x32_bf16 v[36:39], v[164:167], v[218:221], v[36:39]
	v_mfma_f32_16x16x32_bf16 v[32:35], v[184:187], v[218:221], v[32:35]
	v_mfma_f32_16x16x32_bf16 v[20:23], v[164:167], v[226:229], v[20:23]
	v_mfma_f32_16x16x32_bf16 v[16:19], v[184:187], v[226:229], v[16:19]
	v_mfma_f32_16x16x32_bf16 v[4:7], v[164:167], v[234:237], v[4:7]
	v_mfma_f32_16x16x32_bf16 v[0:3], v[184:187], v[234:237], v[0:3]
	s_barrier
	s_add_i32 s52, s52, 2
	s_add_u32 s18, s18, 0x100
	s_addc_u32 s19, s19, 0
	s_add_u32 s50, s50, 0x100
	s_addc_u32 s51, s51, 0
	s_cmp_gt_u32 s52, 13
	s_cbranch_scc0 .LBB0_205
	s_and_b64 vcc, exec, s[2:3]
	s_cbranch_vccz .LBB0_208
	s_barrier
; DEV unsigned cvt_pk_bf16(float lo, float hi) { const f32x2_ v = {lo, hi}; return __builtin_bit_cast(unsigned, __builtin_convertvector(v, bf16x2n_)); }
;   DEV void operator()(const f32x4 (&acc)[2][2][4][2], const Unit& u, int wr, int wc, int fr, int fq) const {
;     const int row0 = u.pm * BM + wr * 64 + fr, col0 = u.pn * BM + wc * 32 + 8 * fq;
; #pragma unroll
;     for (int ai = 0; ai < 2; ++ai)
; #pragma unroll
;       for (int m = 0; m < 4; ++m) {
;         bf16_t* rowp = O + (size_t)(row0 + ai * HALF + m * 16) * ldc + col0;
; #pragma unroll
;         for (int bj = 0; bj < 2; ++bj) {
;           f32x4 v0 = acc[ai][bj][m][0], v1 = acc[ai][bj][m][1];
;           if (ACT == 1) {
; #pragma unroll
;             for (int c = 0; c < 4; ++c) { const float a = fmaxf(v0[c], 0.f), b = fmaxf(v1[c], 0.f); v0[c] = a * a; v1[c] = b * b; }
;           }
;           u32x4 w; w.x = cvt_pk_bf16(v0[0], v0[1]); w.y = cvt_pk_bf16(v0[2], v0[3]); w.z = cvt_pk_bf16(v1[0], v1[1]); w.w = cvt_pk_bf16(v1[2], v1[3]);
;           *(u32x4*)(rowp + bj * HALF) = w;
;         }
;       }
;   }
.LBB0_208:
	s_setprio 0
	v_lshl_add_u32 v144, s47, 8, v140
	v_lshl_or_b32 v138, s46, 8, v142
	v_ashrrev_i32_e32 v145, 31, v144
	v_ashrrev_i32_e32 v139, 31, v138
	v_lshlrev_b64 v[146:147], 13, v[144:145]
	v_lshl_add_u64 v[146:147], s[30:31], 0, v[146:147]
	v_lshlrev_b64 v[148:149], 1, v[138:139]
	v_max_f32_e32 v120, 0, v120
	v_max_f32_e32 v121, 0, v121
	v_lshl_add_u64 v[138:139], v[146:147], 0, v[148:149]
	v_pk_mul_f32 v[146:147], v[120:121], v[120:121]
	v_max_f32_e32 v121, v122, v122
	v_max_f32_e32 v120, v126, v126
	v_max_f32_e32 v122, 0, v121
	v_max_f32_e32 v121, v127, v127
	v_max_f32_e32 v124, 0, v124
	v_max_f32_e32 v125, 0, v125
	v_max_f32_e32 v120, 0, v120
	v_max_f32_e32 v121, 0, v121
	v_max_f32_e32 v123, 0, v123
	v_pk_mul_f32 v[124:125], v[124:125], v[124:125]
	v_pk_mul_f32 v[126:127], v[120:121], v[120:121]
	v_pk_mul_f32 v[150:151], v[122:123], v[122:123]
	v_cvt_pk_bf16_f32 v120, v124, v125
	v_cvt_pk_bf16_f32 v121, v126, v127
	v_cvt_pk_bf16_f32 v122, v146, v147
	v_cvt_pk_bf16_f32 v123, v150, v151
	v_max_f32_e32 v112, 0, v112
	v_max_f32_e32 v113, 0, v113
	global_store_dwordx4 v[138:139], v[120:123], off
	s_nop 1
	v_pk_mul_f32 v[120:121], v[112:113], v[112:113]
	v_max_f32_e32 v113, v114, v114
	v_max_f32_e32 v112, v118, v118
	v_max_f32_e32 v114, 0, v113
	v_max_f32_e32 v113, v119, v119
	v_max_f32_e32 v116, 0, v116
	v_max_f32_e32 v117, 0, v117
	v_max_f32_e32 v112, 0, v112
	v_max_f32_e32 v113, 0, v113
	v_max_f32_e32 v115, 0, v115
	v_pk_mul_f32 v[116:117], v[116:117], v[116:117]
	v_pk_mul_f32 v[118:119], v[112:113], v[112:113]
	v_pk_mul_f32 v[122:123], v[114:115], v[114:115]
	v_cvt_pk_bf16_f32 v112, v116, v117
	v_cvt_pk_bf16_f32 v113, v118, v119
	v_cvt_pk_bf16_f32 v114, v120, v121
	v_cvt_pk_bf16_f32 v115, v122, v123
	v_max_f32_e32 v104, 0, v104
	v_max_f32_e32 v105, 0, v105
	global_store_dwordx4 v[138:139], v[112:115], off offset:256
	s_nop 1
	v_or_b32_e32 v112, 16, v144
	s_nop 0
	v_pk_mul_f32 v[114:115], v[104:105], v[104:105]
	v_max_f32_e32 v105, v106, v106
	v_ashrrev_i32_e32 v113, 31, v112
	v_max_f32_e32 v104, v110, v110
	v_max_f32_e32 v106, 0, v105
	v_max_f32_e32 v105, v111, v111
	v_lshlrev_b64 v[112:113], 13, v[112:113]
	v_max_f32_e32 v108, 0, v108
	v_max_f32_e32 v109, 0, v109
	v_max_f32_e32 v104, 0, v104
	v_max_f32_e32 v105, 0, v105
	v_max_f32_e32 v107, 0, v107
	v_lshl_add_u64 v[112:113], s[30:31], 0, v[112:113]
	v_pk_mul_f32 v[108:109], v[108:109], v[108:109]
	v_pk_mul_f32 v[110:111], v[104:105], v[104:105]
	v_pk_mul_f32 v[116:117], v[106:107], v[106:107]
	v_lshl_add_u64 v[112:113], v[112:113], 0, v[148:149]
	v_cvt_pk_bf16_f32 v104, v108, v109
	v_cvt_pk_bf16_f32 v105, v110, v111
	v_cvt_pk_bf16_f32 v106, v114, v115
	v_cvt_pk_bf16_f32 v107, v116, v117
	v_max_f32_e32 v96, 0, v96
	v_max_f32_e32 v97, 0, v97
	global_store_dwordx4 v[112:113], v[104:107], off
	s_nop 1
	v_pk_mul_f32 v[104:105], v[96:97], v[96:97]
	v_max_f32_e32 v97, v98, v98
	v_max_f32_e32 v96, v102, v102
	v_max_f32_e32 v98, 0, v97
	v_max_f32_e32 v97, v103, v103
	v_max_f32_e32 v100, 0, v100
	v_max_f32_e32 v101, 0, v101
	v_max_f32_e32 v96, 0, v96
	v_max_f32_e32 v97, 0, v97
	v_max_f32_e32 v99, 0, v99
	v_pk_mul_f32 v[100:101], v[100:101], v[100:101]
	v_pk_mul_f32 v[102:103], v[96:97], v[96:97]
	v_pk_mul_f32 v[106:107], v[98:99], v[98:99]
	v_cvt_pk_bf16_f32 v96, v100, v101
	v_cvt_pk_bf16_f32 v97, v102, v103
	v_cvt_pk_bf16_f32 v98, v104, v105
	v_cvt_pk_bf16_f32 v99, v106, v107
	v_max_f32_e32 v88, 0, v88
	v_max_f32_e32 v89, 0, v89
	global_store_dwordx4 v[112:113], v[96:99], off offset:256
	s_nop 1
	v_or_b32_e32 v96, 32, v144
	s_nop 0
	v_pk_mul_f32 v[98:99], v[88:89], v[88:89]
	v_max_f32_e32 v89, v90, v90
	v_ashrrev_i32_e32 v97, 31, v96
	v_max_f32_e32 v88, v94, v94
	v_max_f32_e32 v90, 0, v89
	v_max_f32_e32 v89, v95, v95
	v_lshlrev_b64 v[96:97], 13, v[96:97]
	v_max_f32_e32 v92, 0, v92
	v_max_f32_e32 v93, 0, v93
	v_max_f32_e32 v88, 0, v88
	v_max_f32_e32 v89, 0, v89
	v_max_f32_e32 v91, 0, v91
	v_lshl_add_u64 v[96:97], s[30:31], 0, v[96:97]
	v_pk_mul_f32 v[92:93], v[92:93], v[92:93]
	v_pk_mul_f32 v[94:95], v[88:89], v[88:89]
	v_pk_mul_f32 v[100:101], v[90:91], v[90:91]
	v_lshl_add_u64 v[96:97], v[96:97], 0, v[148:149]
	v_cvt_pk_bf16_f32 v88, v92, v93
	v_cvt_pk_bf16_f32 v89, v94, v95
	v_cvt_pk_bf16_f32 v90, v98, v99
	v_cvt_pk_bf16_f32 v91, v100, v101
	v_max_f32_e32 v80, 0, v80
	v_max_f32_e32 v81, 0, v81
	global_store_dwordx4 v[96:97], v[88:91], off
	s_nop 1
	v_pk_mul_f32 v[88:89], v[80:81], v[80:81]
	v_max_f32_e32 v81, v82, v82
	v_max_f32_e32 v80, v86, v86
	v_max_f32_e32 v82, 0, v81
	v_max_f32_e32 v81, v87, v87
	v_max_f32_e32 v84, 0, v84
	v_max_f32_e32 v85, 0, v85
	v_max_f32_e32 v80, 0, v80
	v_max_f32_e32 v81, 0, v81
	v_max_f32_e32 v83, 0, v83
	v_pk_mul_f32 v[84:85], v[84:85], v[84:85]
	v_pk_mul_f32 v[86:87], v[80:81], v[80:81]
	v_pk_mul_f32 v[90:91], v[82:83], v[82:83]
	v_cvt_pk_bf16_f32 v80, v84, v85
	v_cvt_pk_bf16_f32 v81, v86, v87
	v_cvt_pk_bf16_f32 v82, v88, v89
	v_cvt_pk_bf16_f32 v83, v90, v91
	v_max_f32_e32 v72, 0, v72
	v_max_f32_e32 v73, 0, v73
	global_store_dwordx4 v[96:97], v[80:83], off offset:256
	s_nop 1
	v_or_b32_e32 v80, 48, v144
	s_nop 0
	v_pk_mul_f32 v[82:83], v[72:73], v[72:73]
	v_max_f32_e32 v73, v74, v74
	v_ashrrev_i32_e32 v81, 31, v80
	v_max_f32_e32 v72, v78, v78
	v_max_f32_e32 v74, 0, v73
	v_max_f32_e32 v73, v79, v79
	v_lshlrev_b64 v[80:81], 13, v[80:81]
	v_max_f32_e32 v76, 0, v76
	v_max_f32_e32 v77, 0, v77
	v_max_f32_e32 v72, 0, v72
	v_max_f32_e32 v73, 0, v73
	v_max_f32_e32 v75, 0, v75
	v_lshl_add_u64 v[80:81], s[30:31], 0, v[80:81]
	v_pk_mul_f32 v[76:77], v[76:77], v[76:77]
	v_pk_mul_f32 v[78:79], v[72:73], v[72:73]
	v_pk_mul_f32 v[84:85], v[74:75], v[74:75]
; DEV unsigned cvt_pk_bf16(float lo, float hi) { const f32x2_ v = {lo, hi}; return __builtin_bit_cast(unsigned, __builtin_convertvector(v, bf16x2n_)); }
;   DEV void operator()(const f32x4 (&acc)[2][2][4][2], const Unit& u, int wr, int wc, int fr, int fq) const {
;     const int row0 = u.pm * BM + wr * 64 + fr, col0 = u.pn * BM + wc * 32 + 8 * fq;
; #pragma unroll
;     for (int ai = 0; ai < 2; ++ai)
; #pragma unroll
;       for (int m = 0; m < 4; ++m) {
;         bf16_t* rowp = O + (size_t)(row0 + ai * HALF + m * 16) * ldc + col0;
; #pragma unroll
;         for (int bj = 0; bj < 2; ++bj) {
;           f32x4 v0 = acc[ai][bj][m][0], v1 = acc[ai][bj][m][1];
;           if (ACT == 1) {
; #pragma unroll
;             for (int c = 0; c < 4; ++c) { const float a = fmaxf(v0[c], 0.f), b = fmaxf(v1[c], 0.f); v0[c] = a * a; v1[c] = b * b; }
;           }
;           u32x4 w; w.x = cvt_pk_bf16(v0[0], v0[1]); w.y = cvt_pk_bf16(v0[2], v0[3]); w.z = cvt_pk_bf16(v1[0], v1[1]); w.w = cvt_pk_bf16(v1[2], v1[3]);
;           *(u32x4*)(rowp + bj * HALF) = w;
;         }
;       }
;   }
	v_lshl_add_u64 v[80:81], v[80:81], 0, v[148:149]
	v_cvt_pk_bf16_f32 v72, v76, v77
	v_cvt_pk_bf16_f32 v73, v78, v79
	v_cvt_pk_bf16_f32 v74, v82, v83
	v_cvt_pk_bf16_f32 v75, v84, v85
	v_max_f32_e32 v64, 0, v64
	v_max_f32_e32 v65, 0, v65
	global_store_dwordx4 v[80:81], v[72:75], off
	s_nop 1
	v_pk_mul_f32 v[72:73], v[64:65], v[64:65]
	v_max_f32_e32 v65, v66, v66
	v_max_f32_e32 v64, v70, v70
	v_max_f32_e32 v66, 0, v65
	v_max_f32_e32 v65, v71, v71
	v_max_f32_e32 v68, 0, v68
	v_max_f32_e32 v69, 0, v69
	v_max_f32_e32 v64, 0, v64
	v_max_f32_e32 v65, 0, v65
	v_max_f32_e32 v67, 0, v67
	v_pk_mul_f32 v[68:69], v[68:69], v[68:69]
	v_pk_mul_f32 v[70:71], v[64:65], v[64:65]
	v_pk_mul_f32 v[74:75], v[66:67], v[66:67]
	v_cvt_pk_bf16_f32 v64, v68, v69
	v_cvt_pk_bf16_f32 v65, v70, v71
	v_cvt_pk_bf16_f32 v66, v72, v73
	v_cvt_pk_bf16_f32 v67, v74, v75
	v_max_f32_e32 v56, 0, v56
	v_max_f32_e32 v57, 0, v57
	global_store_dwordx4 v[80:81], v[64:67], off offset:256
	s_nop 1
	v_pk_mul_f32 v[66:67], v[56:57], v[56:57]
	v_max_f32_e32 v57, v58, v58
	v_max_f32_e32 v60, 0, v60
	v_max_f32_e32 v61, 0, v61
	v_max_f32_e32 v56, v62, v62
	v_max_f32_e32 v58, 0, v57
	v_max_f32_e32 v57, v63, v63
	v_pk_mul_f32 v[60:61], v[60:61], v[60:61]
	v_max_f32_e32 v56, 0, v56
	v_max_f32_e32 v57, 0, v57
	v_max_f32_e32 v59, 0, v59
	s_mov_b32 s5, 0x100000
	v_pk_mul_f32 v[62:63], v[56:57], v[56:57]
	v_pk_mul_f32 v[68:69], v[58:59], v[58:59]
	v_cvt_pk_bf16_f32 v56, v60, v61
	v_add_co_u32_e32 v60, vcc, s5, v138
	v_cvt_pk_bf16_f32 v57, v62, v63
	v_cvt_pk_bf16_f32 v58, v66, v67
	v_cvt_pk_bf16_f32 v59, v68, v69
	v_addc_co_u32_e32 v61, vcc, 0, v139, vcc
	v_max_f32_e32 v48, 0, v48
	v_max_f32_e32 v49, 0, v49
	global_store_dwordx4 v[60:61], v[56:59], off
	s_nop 1
	v_pk_mul_f32 v[56:57], v[48:49], v[48:49]
	v_max_f32_e32 v49, v50, v50
	v_max_f32_e32 v48, v54, v54
	v_max_f32_e32 v50, 0, v49
	v_max_f32_e32 v49, v55, v55
	v_max_f32_e32 v52, 0, v52
	v_max_f32_e32 v53, 0, v53
	v_max_f32_e32 v48, 0, v48
	v_max_f32_e32 v49, 0, v49
	v_max_f32_e32 v51, 0, v51
	s_mov_b64 s[18:19], 0x100000
	v_pk_mul_f32 v[52:53], v[52:53], v[52:53]
	v_pk_mul_f32 v[54:55], v[48:49], v[48:49]
	v_pk_mul_f32 v[58:59], v[50:51], v[50:51]
	v_lshl_add_u64 v[64:65], v[138:139], 0, s[18:19]
	v_cvt_pk_bf16_f32 v48, v52, v53
	v_cvt_pk_bf16_f32 v49, v54, v55
	v_cvt_pk_bf16_f32 v50, v56, v57
	v_cvt_pk_bf16_f32 v51, v58, v59
	v_max_f32_e32 v40, 0, v40
	v_max_f32_e32 v41, 0, v41
	global_store_dwordx4 v[64:65], v[48:51], off offset:256
	s_nop 1
	v_pk_mul_f32 v[50:51], v[40:41], v[40:41]
	v_max_f32_e32 v41, v42, v42
	v_max_f32_e32 v44, 0, v44
	v_max_f32_e32 v45, 0, v45
	v_max_f32_e32 v40, v46, v46
	v_max_f32_e32 v42, 0, v41
	v_max_f32_e32 v41, v47, v47
	v_pk_mul_f32 v[44:45], v[44:45], v[44:45]
	v_max_f32_e32 v40, 0, v40
	v_max_f32_e32 v41, 0, v41
	v_max_f32_e32 v43, 0, v43
	s_mov_b32 s5, 0x120000
	v_pk_mul_f32 v[46:47], v[40:41], v[40:41]
	v_pk_mul_f32 v[52:53], v[42:43], v[42:43]
	v_cvt_pk_bf16_f32 v40, v44, v45
	v_add_co_u32_e32 v44, vcc, s5, v138
	v_cvt_pk_bf16_f32 v41, v46, v47
	v_cvt_pk_bf16_f32 v42, v50, v51
	v_cvt_pk_bf16_f32 v43, v52, v53
	v_addc_co_u32_e32 v45, vcc, 0, v139, vcc
	v_max_f32_e32 v32, 0, v32
	v_max_f32_e32 v33, 0, v33
	global_store_dwordx4 v[44:45], v[40:43], off
	s_nop 1
	v_pk_mul_f32 v[40:41], v[32:33], v[32:33]
	v_max_f32_e32 v33, v34, v34
	v_max_f32_e32 v32, v38, v38
	v_max_f32_e32 v34, 0, v33
	v_max_f32_e32 v33, v39, v39
	v_max_f32_e32 v36, 0, v36
	v_max_f32_e32 v37, 0, v37
	v_max_f32_e32 v32, 0, v32
	v_max_f32_e32 v33, 0, v33
	v_max_f32_e32 v35, 0, v35
	s_mov_b64 s[18:19], 0x120000
	v_pk_mul_f32 v[36:37], v[36:37], v[36:37]
	v_pk_mul_f32 v[38:39], v[32:33], v[32:33]
	v_pk_mul_f32 v[42:43], v[34:35], v[34:35]
	v_lshl_add_u64 v[48:49], v[138:139], 0, s[18:19]
	v_cvt_pk_bf16_f32 v32, v36, v37
	v_cvt_pk_bf16_f32 v33, v38, v39
	v_cvt_pk_bf16_f32 v34, v40, v41
	v_cvt_pk_bf16_f32 v35, v42, v43
	v_max_f32_e32 v24, 0, v24
	v_max_f32_e32 v25, 0, v25
	global_store_dwordx4 v[48:49], v[32:35], off offset:256
	s_nop 1
	v_pk_mul_f32 v[34:35], v[24:25], v[24:25]
	v_max_f32_e32 v25, v26, v26
	v_max_f32_e32 v28, 0, v28
	v_max_f32_e32 v29, 0, v29
	v_max_f32_e32 v24, v30, v30
	v_max_f32_e32 v26, 0, v25
	v_max_f32_e32 v25, v31, v31
	v_pk_mul_f32 v[28:29], v[28:29], v[28:29]
	v_max_f32_e32 v24, 0, v24
	v_max_f32_e32 v25, 0, v25
	v_max_f32_e32 v27, 0, v27
	s_mov_b32 s5, 0x140000
	v_pk_mul_f32 v[30:31], v[24:25], v[24:25]
	v_pk_mul_f32 v[36:37], v[26:27], v[26:27]
	v_cvt_pk_bf16_f32 v24, v28, v29
	v_add_co_u32_e32 v28, vcc, s5, v138
	v_cvt_pk_bf16_f32 v25, v30, v31
	v_cvt_pk_bf16_f32 v26, v34, v35
	v_cvt_pk_bf16_f32 v27, v36, v37
	v_addc_co_u32_e32 v29, vcc, 0, v139, vcc
	v_max_f32_e32 v16, 0, v16
	v_max_f32_e32 v17, 0, v17
	global_store_dwordx4 v[28:29], v[24:27], off
	s_nop 1
	v_pk_mul_f32 v[24:25], v[16:17], v[16:17]
	v_max_f32_e32 v17, v18, v18
	v_max_f32_e32 v16, v22, v22
	v_max_f32_e32 v18, 0, v17
	v_max_f32_e32 v17, v23, v23
	v_max_f32_e32 v20, 0, v20
	v_max_f32_e32 v21, 0, v21
	v_max_f32_e32 v16, 0, v16
	v_max_f32_e32 v17, 0, v17
	v_max_f32_e32 v19, 0, v19
	s_mov_b64 s[18:19], 0x140000
	v_pk_mul_f32 v[20:21], v[20:21], v[20:21]
	v_pk_mul_f32 v[22:23], v[16:17], v[16:17]
	v_pk_mul_f32 v[26:27], v[18:19], v[18:19]
	v_lshl_add_u64 v[32:33], v[138:139], 0, s[18:19]
	v_cvt_pk_bf16_f32 v16, v20, v21
	v_cvt_pk_bf16_f32 v17, v22, v23
	v_cvt_pk_bf16_f32 v18, v24, v25
	v_cvt_pk_bf16_f32 v19, v26, v27
	v_max_f32_e32 v8, 0, v8
	v_max_f32_e32 v9, 0, v9
	global_store_dwordx4 v[32:33], v[16:19], off offset:256
	s_nop 1
	v_pk_mul_f32 v[18:19], v[8:9], v[8:9]
	v_max_f32_e32 v9, v10, v10
	v_max_f32_e32 v12, 0, v12
	v_max_f32_e32 v13, 0, v13
	v_max_f32_e32 v8, v14, v14
	v_max_f32_e32 v10, 0, v9
	v_max_f32_e32 v9, v15, v15
	v_pk_mul_f32 v[12:13], v[12:13], v[12:13]
	v_max_f32_e32 v8, 0, v8
	v_max_f32_e32 v9, 0, v9
	v_max_f32_e32 v11, 0, v11
	s_mov_b32 s5, 0x160000
	v_pk_mul_f32 v[14:15], v[8:9], v[8:9]
	v_pk_mul_f32 v[20:21], v[10:11], v[10:11]
	v_cvt_pk_bf16_f32 v8, v12, v13
	v_add_co_u32_e32 v12, vcc, s5, v138
	v_cvt_pk_bf16_f32 v9, v14, v15
	v_cvt_pk_bf16_f32 v10, v18, v19
	v_cvt_pk_bf16_f32 v11, v20, v21
	v_addc_co_u32_e32 v13, vcc, 0, v139, vcc
	v_max_f32_e32 v0, 0, v0
	v_max_f32_e32 v1, 0, v1
	global_store_dwordx4 v[12:13], v[8:11], off
	s_nop 1
	v_pk_mul_f32 v[8:9], v[0:1], v[0:1]
	v_max_f32_e32 v1, v2, v2
	v_max_f32_e32 v0, v6, v6
	v_max_f32_e32 v2, 0, v1
	v_max_f32_e32 v1, v7, v7
	v_max_f32_e32 v4, 0, v4
	v_max_f32_e32 v5, 0, v5
	v_max_f32_e32 v0, 0, v0
	v_max_f32_e32 v1, 0, v1
	v_max_f32_e32 v3, 0, v3
	s_mov_b64 s[18:19], 0x160000
	v_pk_mul_f32 v[4:5], v[4:5], v[4:5]
	v_pk_mul_f32 v[6:7], v[0:1], v[0:1]
	v_pk_mul_f32 v[10:11], v[2:3], v[2:3]
	v_lshl_add_u64 v[16:17], v[138:139], 0, s[18:19]
	v_cvt_pk_bf16_f32 v0, v4, v5
	v_cvt_pk_bf16_f32 v1, v6, v7
	v_cvt_pk_bf16_f32 v2, v8, v9
	v_cvt_pk_bf16_f32 v3, v10, v11
	s_andn2_b64 vcc, exec, s[12:13]
	s_mov_b64 s[12:13], -1
	global_store_dwordx4 v[16:17], v[0:3], off offset:256
	s_cbranch_vccnz .LBB0_201
; #define PG8_BAR __builtin_amdgcn_s_barrier()
; template <class Epi, bool SEQ>
; DEV void gemm_phase(PG8_LAS unsigned char* lds, const Gemm g, const Epi& E) {
;     ...
;     if (!has_next) break;
;     if (!keep) {
; #pragma unroll
;       for (int a = 0; a < 2; ++a)
; #pragma unroll
;         for (int b = 0; b < 2; ++b)
; #pragma unroll
;           for (int m = 0; m < 4; ++m)
; #pragma unroll
;             for (int n = 0; n < 2; ++n) acc[a][b][m][n] = (f32x4){0.f, 0.f, 0.f, 0.f};
;     }
;     cur = nxt; cA = nA; cB = nB; ++ui;
;     if (wr == 1) PG8_BAR;
	s_andn2_b64 vcc, exec, s[0:1]
	s_cbranch_vccnz .LBB0_200
	s_barrier
	s_branch .LBB0_200

; #define PG8_STAGE(bufoff, gbase, voff) do { _Pragma("unroll") for (int _i = 0; _i < 2; ++_i) \
;     __builtin_amdgcn_global_load_lds((const unsigned*)((const char*)(gbase) + (voff)[_i]), (PG8_LAS unsigned*)(lds + (bufoff) + ldsw + _i * 8192), 16, 0, 0); } while (0)
; #define PG8_LDA(dst, b, h) do { _Pragma("unroll") for (int m = 0; m < 4; ++m) _Pragma("unroll") for (int k = 0; k < 2; ++k) dst[m][k] = *(const PG8_LAS bf16x8*)(lds + PG8_SA(b, h) + aoff + m * 2048 + k * 1024); } while (0)
; #define PG8_LDB(dst, b, h) do { _Pragma("unroll") for (int n = 0; n < 2; ++n) _Pragma("unroll") for (int k = 0; k < 2; ++k) dst[n][k] = *(const PG8_LAS bf16x8*)(lds + PG8_SB(b, h) + boff + n * 2048 + k * 1024); } while (0)
; #define PG8_MMA(ai, bj, At, Bt) do { __builtin_amdgcn_s_setprio(1); _Pragma("unroll") for (int m = 0; m < 4; ++m) _Pragma("unroll") for (int n = 0; n < 2; ++n) _Pragma("unroll") for (int k = 0; k < 2; ++k) \
;     acc[ai][bj][m][n] = __builtin_amdgcn_mfma_f32_16x16x32_bf16(Bt[n][k], At[m][k], acc[ai][bj][m][n], 0, 0, 0); __builtin_amdgcn_s_setprio(0); } while (0)
; #define PG8_WAIT_V(n) asm volatile("s_waitcnt vmcnt(" #n ")" ::: "memory")
; template <class Epi, bool SEQ>
; DEV void gemm_phase(PG8_LAS unsigned char* lds, const Gemm g, const Epi& E) {
;     ...
;   for (;;) {
;     const bool has_next = next_unit<SEQ>(g, ui + 1, G, cblk, nxt);
;     const char* nA = has_next ? PG8_ABASE(nxt) : cA; const char* nB = has_next ? PG8_BBASE(nxt) : cB;
;     for (int t = 0; t < nt; t += 2) {
;       const bool last = (t == nt - 2);
;       const char* a1 = cA + (size_t)(t + 1) * kstep;
;       const char* a2 = last ? nA : cA + (size_t)(t + 2) * kstep; const char* b2 = last ? nB : cB + (size_t)(t + 2) * kstep;
;       const char* a3 = a2 + kstep; const char* b3 = b2 + kstep;
;       PG8_LDB(B0, 0, 0); PG8_LDB(B1, 0, 1); PG8_SCHED; PG8_LDA(At, 0, 0); PG8_STAGE(PG8_SA(1, 1), a1 + hstepA, voffA);
;       PG8_WAIT_V(8); PG8_WAIT_L(0); PG8_BAR; PG8_MMA(0, 0, At, B0); PG8_MMA(0, 1, At, B1); PG8_BAR; PG8_SCHED;
;     ...
;     if (!keep) {
; #pragma unroll
;       for (int a = 0; a < 2; ++a)
; #pragma unroll
;         for (int b = 0; b < 2; ++b)
; #pragma unroll
;           for (int m = 0; m < 4; ++m)
; #pragma unroll
;             for (int n = 0; n < 2; ++n) acc[a][b][m][n] = (f32x4){0.f, 0.f, 0.f, 0.f};
;     }
;     cur = nxt; cA = nA; cB = nB; ++ui;
.LBB0_286:
	s_ashr_i32 s13, s12, 31
	s_lshl_b64 s[16:17], s[12:13], 19
	s_add_u32 s16, s24, s16
	s_addc_u32 s17, s25, s17
	s_and_b64 s[18:19], s[8:9], exec
	s_cselect_b32 s13, s17, s21
	s_cselect_b32 s49, s16, s20
	s_ashr_i32 s15, s14, 31
	s_lshl_b64 s[18:19], s[14:15], 19
	s_add_u32 s18, s0, s18
	s_addc_u32 s19, s1, s19
	s_and_b64 s[36:37], s[8:9], exec
	s_cselect_b32 s15, s19, s27
	s_cselect_b32 s50, s18, s26
	s_add_u32 s20, s20, 0x40080
	s_addc_u32 s21, s21, 0
	s_add_u32 s51, s26, 0x100
	v_mov_b64_e32 v[0:1], 0
	v_mov_b64_e32 v[2:3], 0
	v_mov_b64_e32 v[4:5], 0
	v_mov_b64_e32 v[6:7], 0
	v_mov_b64_e32 v[8:9], 0
	v_mov_b64_e32 v[10:11], 0
	v_mov_b64_e32 v[12:13], 0
	v_mov_b64_e32 v[14:15], 0
	v_mov_b64_e32 v[16:17], 0
	v_mov_b64_e32 v[18:19], 0
	v_mov_b64_e32 v[20:21], 0
	v_mov_b64_e32 v[22:23], 0
	v_mov_b64_e32 v[24:25], 0
	v_mov_b64_e32 v[26:27], 0
	v_mov_b64_e32 v[28:29], 0
	v_mov_b64_e32 v[30:31], 0
	v_mov_b64_e32 v[32:33], 0
	v_mov_b64_e32 v[34:35], 0
	v_mov_b64_e32 v[36:37], 0
	v_mov_b64_e32 v[38:39], 0
	v_mov_b64_e32 v[40:41], 0
	v_mov_b64_e32 v[42:43], 0
	v_mov_b64_e32 v[44:45], 0
	v_mov_b64_e32 v[46:47], 0
	v_mov_b64_e32 v[48:49], 0
	v_mov_b64_e32 v[50:51], 0
	v_mov_b64_e32 v[52:53], 0
	v_mov_b64_e32 v[54:55], 0
	v_mov_b64_e32 v[56:57], 0
	v_mov_b64_e32 v[58:59], 0
	v_mov_b64_e32 v[60:61], 0
	v_mov_b64_e32 v[62:63], 0
	v_mov_b64_e32 v[64:65], 0
	v_mov_b64_e32 v[66:67], 0
	v_mov_b64_e32 v[68:69], 0
	v_mov_b64_e32 v[70:71], 0
	v_mov_b64_e32 v[72:73], 0
	v_mov_b64_e32 v[74:75], 0
	v_mov_b64_e32 v[76:77], 0
	v_mov_b64_e32 v[78:79], 0
	v_mov_b64_e32 v[80:81], 0
	v_mov_b64_e32 v[82:83], 0
	v_mov_b64_e32 v[84:85], 0
	v_mov_b64_e32 v[86:87], 0
	v_mov_b64_e32 v[88:89], 0
	v_mov_b64_e32 v[90:91], 0
	v_mov_b64_e32 v[92:93], 0
	v_mov_b64_e32 v[94:95], 0
	v_mov_b64_e32 v[96:97], 0
	v_mov_b64_e32 v[98:99], 0
	v_mov_b64_e32 v[100:101], 0
	v_mov_b64_e32 v[102:103], 0
	v_mov_b64_e32 v[104:105], 0
	v_mov_b64_e32 v[106:107], 0
	v_mov_b64_e32 v[108:109], 0
	v_mov_b64_e32 v[110:111], 0
	v_mov_b64_e32 v[112:113], 0
	v_mov_b64_e32 v[114:115], 0
	v_mov_b64_e32 v[116:117], 0
	v_mov_b64_e32 v[118:119], 0
	v_mov_b64_e32 v[120:121], 0
	v_mov_b64_e32 v[122:123], 0
	v_mov_b64_e32 v[124:125], 0
	v_mov_b64_e32 v[126:127], 0
	s_addc_u32 s52, s27, 0
	s_mov_b32 s53, -2
	v_readfirstlane_b32 s98, v171
	s_nop 3
	s_lshr_b32 s98, s98, 6
	s_cmp_lt_u32 s98, 4
	s_cbranch_scc0 .Lprio_287
	s_setprio 1
.Lprio_287:
.LBB0_287:
	s_add_u32 s26, s20, 0xfffc0080
	s_addc_u32 s27, s21, -1
	s_add_i32 s54, 0, 0x10000
	s_cmp_eq_u32 s53, 12
	s_cselect_b32 s37, s13, s27
	s_cselect_b32 s36, s49, s26
	s_cselect_b32 s27, s15, s52
	s_cselect_b32 s26, s50, s51
	s_add_i32 s56, 0, 0x14000
	v_add_u32_e32 v154, s54, v139
	v_add_u32_e32 v166, s56, v139
	ds_read_b128 v[142:145], v154
	ds_read_b128 v[146:149], v154 offset:1024
	ds_read_b128 v[150:153], v154 offset:2048
	ds_read_b128 v[154:157], v154 offset:3072
	ds_read_b128 v[158:161], v166
	ds_read_b128 v[162:165], v166 offset:1024
	ds_read_b128 v[180:183], v166 offset:2048
	ds_read_b128 v[184:187], v166 offset:3072
	v_lshl_add_u64 v[166:167], s[20:21], 0, v[134:135]
	s_add_i32 m0, s39, 0xc000
	ds_read_b128 v[188:191], v141
	ds_read_b128 v[192:195], v141 offset:1024
	ds_read_b128 v[196:199], v141 offset:2048
	ds_read_b128 v[218:221], v141 offset:3072
	ds_read_b128 v[222:225], v141 offset:4096
	ds_read_b128 v[226:229], v141 offset:5120
	ds_read_b128 v[230:233], v141 offset:6144
	ds_read_b128 v[234:237], v141 offset:7168
	global_load_lds_dwordx4 v[166:167], off
	v_lshl_add_u64 v[166:167], s[20:21], 0, v[136:137]
	s_add_i32 m0, s39, 0xe000
	s_nop 0
	global_load_lds_dwordx4 v[166:167], off
	s_waitcnt vmcnt(8)
	s_waitcnt lgkmcnt(0)
	s_barrier
	s_waitcnt lgkmcnt(0)
	v_mfma_f32_16x16x32_bf16 v[124:127], v[142:145], v[188:191], v[124:127]
	v_mfma_f32_16x16x32_bf16 v[120:123], v[150:153], v[188:191], v[120:123]
	v_mfma_f32_16x16x32_bf16 v[116:119], v[142:145], v[196:199], v[116:119]
	v_mfma_f32_16x16x32_bf16 v[112:115], v[150:153], v[196:199], v[112:115]
	v_mfma_f32_16x16x32_bf16 v[100:103], v[142:145], v[222:225], v[100:103]
	v_mfma_f32_16x16x32_bf16 v[96:99], v[150:153], v[222:225], v[96:99]
	v_mfma_f32_16x16x32_bf16 v[84:87], v[142:145], v[230:233], v[84:87]
	v_mfma_f32_16x16x32_bf16 v[80:83], v[150:153], v[230:233], v[80:83]
	v_mfma_f32_16x16x32_bf16 v[124:127], v[146:149], v[192:195], v[124:127]
	v_mfma_f32_16x16x32_bf16 v[120:123], v[154:157], v[192:195], v[120:123]
	v_mfma_f32_16x16x32_bf16 v[116:119], v[146:149], v[218:221], v[116:119]
	v_mfma_f32_16x16x32_bf16 v[112:115], v[154:157], v[218:221], v[112:115]
	v_mfma_f32_16x16x32_bf16 v[100:103], v[146:149], v[226:229], v[100:103]
	v_mfma_f32_16x16x32_bf16 v[96:99], v[154:157], v[226:229], v[96:99]
	v_mfma_f32_16x16x32_bf16 v[84:87], v[146:149], v[234:237], v[84:87]
	v_mfma_f32_16x16x32_bf16 v[80:83], v[154:157], v[234:237], v[80:83]
	v_mfma_f32_16x16x32_bf16 v[108:111], v[158:161], v[188:191], v[108:111]
	v_mfma_f32_16x16x32_bf16 v[104:107], v[180:183], v[188:191], v[104:107]
	v_mfma_f32_16x16x32_bf16 v[92:95], v[158:161], v[196:199], v[92:95]
	v_mfma_f32_16x16x32_bf16 v[88:91], v[180:183], v[196:199], v[88:91]
	v_mfma_f32_16x16x32_bf16 v[76:79], v[158:161], v[222:225], v[76:79]
	v_mfma_f32_16x16x32_bf16 v[72:75], v[180:183], v[222:225], v[72:75]
	v_mfma_f32_16x16x32_bf16 v[68:71], v[158:161], v[230:233], v[68:71]
	v_mfma_f32_16x16x32_bf16 v[64:67], v[180:183], v[230:233], v[64:67]
	v_mfma_f32_16x16x32_bf16 v[108:111], v[162:165], v[192:195], v[108:111]
	v_mfma_f32_16x16x32_bf16 v[104:107], v[184:187], v[192:195], v[104:107]
	v_mfma_f32_16x16x32_bf16 v[92:95], v[162:165], v[218:221], v[92:95]
	v_mfma_f32_16x16x32_bf16 v[88:91], v[184:187], v[218:221], v[88:91]
	v_mfma_f32_16x16x32_bf16 v[76:79], v[162:165], v[226:229], v[76:79]
	v_mfma_f32_16x16x32_bf16 v[72:75], v[184:187], v[226:229], v[72:75]
	v_mfma_f32_16x16x32_bf16 v[68:71], v[162:165], v[234:237], v[68:71]
	v_mfma_f32_16x16x32_bf16 v[64:67], v[184:187], v[234:237], v[64:67]
	s_barrier
; #define PG8_STAGE(bufoff, gbase, voff) do { _Pragma("unroll") for (int _i = 0; _i < 2; ++_i) \
;     __builtin_amdgcn_global_load_lds((const unsigned*)((const char*)(gbase) + (voff)[_i]), (PG8_LAS unsigned*)(lds + (bufoff) + ldsw + _i * 8192), 16, 0, 0); } while (0)
; #define PG8_LDA(dst, b, h) do { _Pragma("unroll") for (int m = 0; m < 4; ++m) _Pragma("unroll") for (int k = 0; k < 2; ++k) dst[m][k] = *(const PG8_LAS bf16x8*)(lds + PG8_SA(b, h) + aoff + m * 2048 + k * 1024); } while (0)
; #define PG8_LDB(dst, b, h) do { _Pragma("unroll") for (int n = 0; n < 2; ++n) _Pragma("unroll") for (int k = 0; k < 2; ++k) dst[n][k] = *(const PG8_LAS bf16x8*)(lds + PG8_SB(b, h) + boff + n * 2048 + k * 1024); } while (0)
; #define PG8_MMA(ai, bj, At, Bt) do { __builtin_amdgcn_s_setprio(1); _Pragma("unroll") for (int m = 0; m < 4; ++m) _Pragma("unroll") for (int n = 0; n < 2; ++n) _Pragma("unroll") for (int k = 0; k < 2; ++k) \
;     acc[ai][bj][m][n] = __builtin_amdgcn_mfma_f32_16x16x32_bf16(Bt[n][k], At[m][k], acc[ai][bj][m][n], 0, 0, 0); __builtin_amdgcn_s_setprio(0); } while (0)
; #define PG8_WAIT_V(n) asm volatile("s_waitcnt vmcnt(" #n ")" ::: "memory")
; #define PG8_WAIT_L(n) asm volatile("s_waitcnt lgkmcnt(" #n ")" ::: "memory")
; #define PG8_BAR __builtin_amdgcn_s_barrier()
; #define PG8_SCHED __builtin_amdgcn_sched_barrier(0)
; template <class Epi, bool SEQ>
; DEV void gemm_phase(PG8_LAS unsigned char* lds, const Gemm g, const Epi& E) {
;     ...
;       PG8_LDA(At, 0, 1); PG8_STAGE(PG8_SB(0, 0), b2, voffB); PG8_STAGE(PG8_SB(0, 1), b2 + hstepB, voffB); PG8_STAGE(PG8_SA(0, 0), a2, voffA);
;       PG8_WAIT_V(8); PG8_WAIT_L(0); PG8_BAR; PG8_MMA(1, 0, At, B0); PG8_MMA(1, 1, At, B1); PG8_BAR; PG8_SCHED;
;       PG8_LDB(B0, 1, 0); PG8_LDB(B1, 1, 1); PG8_SCHED; PG8_LDA(At, 1, 0); PG8_STAGE(PG8_SA(0, 1), a2 + hstepA, voffA);
	s_add_i32 s54, s54, s38
	v_lshl_add_u64 v[166:167], s[26:27], 0, v[168:169]
	s_mov_b32 m0, s54
	ds_read_b128 v[188:191], v141 offset:16384
	ds_read_b128 v[192:195], v141 offset:17408
	ds_read_b128 v[196:199], v141 offset:18432
	ds_read_b128 v[218:221], v141 offset:19456
	ds_read_b128 v[222:225], v141 offset:20480
	ds_read_b128 v[226:229], v141 offset:21504
	ds_read_b128 v[230:233], v141 offset:22528
	ds_read_b128 v[234:237], v141 offset:23552
	global_load_lds_dwordx4 v[166:167], off
	s_add_i32 m0, s54, 0x2000
	s_add_u32 s54, s26, 0x40000
	v_lshl_add_u64 v[238:239], s[26:27], 0, v[128:129]
	s_addc_u32 s55, s27, 0
	s_add_i32 s56, s56, s38
	global_load_lds_dwordx4 v[238:239], off
	v_lshl_add_u64 v[240:241], s[54:55], 0, v[168:169]
	s_mov_b32 m0, s56
	v_lshl_add_u64 v[242:243], s[36:37], 0, v[130:131]
	global_load_lds_dwordx4 v[240:241], off
	v_lshl_add_u64 v[240:241], s[54:55], 0, v[128:129]
	s_add_i32 m0, s56, 0x2000
	s_nop 0
	global_load_lds_dwordx4 v[240:241], off
	v_lshl_add_u64 v[240:241], s[36:37], 0, v[132:133]
	s_mov_b32 m0, s39
	s_nop 0
	global_load_lds_dwordx4 v[240:241], off
	s_mov_b32 m0, s40
	s_nop 0
	global_load_lds_dwordx4 v[242:243], off
	s_waitcnt vmcnt(8)
	s_waitcnt lgkmcnt(0)
	s_barrier
	s_waitcnt lgkmcnt(0)
	v_mfma_f32_16x16x32_bf16 v[60:63], v[142:145], v[188:191], v[60:63]
	v_mfma_f32_16x16x32_bf16 v[56:59], v[150:153], v[188:191], v[56:59]
	v_mfma_f32_16x16x32_bf16 v[52:55], v[142:145], v[196:199], v[52:55]
	v_mfma_f32_16x16x32_bf16 v[48:51], v[150:153], v[196:199], v[48:51]
	v_mfma_f32_16x16x32_bf16 v[36:39], v[142:145], v[222:225], v[36:39]
	v_mfma_f32_16x16x32_bf16 v[32:35], v[150:153], v[222:225], v[32:35]
	v_mfma_f32_16x16x32_bf16 v[20:23], v[142:145], v[230:233], v[20:23]
	v_mfma_f32_16x16x32_bf16 v[16:19], v[150:153], v[230:233], v[16:19]
	v_mfma_f32_16x16x32_bf16 v[60:63], v[146:149], v[192:195], v[60:63]
	v_mfma_f32_16x16x32_bf16 v[56:59], v[154:157], v[192:195], v[56:59]
	v_mfma_f32_16x16x32_bf16 v[52:55], v[146:149], v[218:221], v[52:55]
	v_mfma_f32_16x16x32_bf16 v[48:51], v[154:157], v[218:221], v[48:51]
	v_mfma_f32_16x16x32_bf16 v[36:39], v[146:149], v[226:229], v[36:39]
	v_mfma_f32_16x16x32_bf16 v[32:35], v[154:157], v[226:229], v[32:35]
	v_mfma_f32_16x16x32_bf16 v[20:23], v[146:149], v[234:237], v[20:23]
	v_mfma_f32_16x16x32_bf16 v[16:19], v[154:157], v[234:237], v[16:19]
	v_mfma_f32_16x16x32_bf16 v[44:47], v[158:161], v[188:191], v[44:47]
	v_mfma_f32_16x16x32_bf16 v[40:43], v[180:183], v[188:191], v[40:43]
	v_mfma_f32_16x16x32_bf16 v[28:31], v[158:161], v[196:199], v[28:31]
	v_mfma_f32_16x16x32_bf16 v[24:27], v[180:183], v[196:199], v[24:27]
	v_mfma_f32_16x16x32_bf16 v[12:15], v[158:161], v[222:225], v[12:15]
	v_mfma_f32_16x16x32_bf16 v[8:11], v[180:183], v[222:225], v[8:11]
	v_mfma_f32_16x16x32_bf16 v[4:7], v[158:161], v[230:233], v[4:7]
	v_mfma_f32_16x16x32_bf16 v[0:3], v[180:183], v[230:233], v[0:3]
	v_mfma_f32_16x16x32_bf16 v[44:47], v[162:165], v[192:195], v[44:47]
	v_mfma_f32_16x16x32_bf16 v[40:43], v[184:187], v[192:195], v[40:43]
	v_mfma_f32_16x16x32_bf16 v[28:31], v[162:165], v[218:221], v[28:31]
	v_mfma_f32_16x16x32_bf16 v[24:27], v[184:187], v[218:221], v[24:27]
	v_mfma_f32_16x16x32_bf16 v[12:15], v[162:165], v[226:229], v[12:15]
	v_mfma_f32_16x16x32_bf16 v[8:11], v[184:187], v[226:229], v[8:11]
	v_mfma_f32_16x16x32_bf16 v[4:7], v[162:165], v[234:237], v[4:7]
	v_mfma_f32_16x16x32_bf16 v[0:3], v[184:187], v[234:237], v[0:3]
	s_barrier
	s_add_i32 s54, 0, 0x18000
	s_add_i32 s55, 0, 0x1c000
	v_add_u32_e32 v154, s54, v139
	v_add_u32_e32 v177, s55, v139
	ds_read_b128 v[142:145], v154
	ds_read_b128 v[146:149], v154 offset:1024
	ds_read_b128 v[150:153], v154 offset:2048
	ds_read_b128 v[154:157], v154 offset:3072
	ds_read_b128 v[158:161], v177
	ds_read_b128 v[162:165], v177 offset:1024
	ds_read_b128 v[180:183], v177 offset:2048
	ds_read_b128 v[184:187], v177 offset:3072
	s_add_u32 s36, s36, 0x40000
	s_addc_u32 s37, s37, 0
	s_mov_b32 m0, s41
	v_lshl_add_u64 v[244:245], s[36:37], 0, v[132:133]
	ds_read_b128 v[188:191], v141 offset:32768
	ds_read_b128 v[192:195], v141 offset:33792
	ds_read_b128 v[196:199], v141 offset:34816
	ds_read_b128 v[218:221], v141 offset:35840
	ds_read_b128 v[222:225], v141 offset:36864
	ds_read_b128 v[226:229], v141 offset:37888
	ds_read_b128 v[230:233], v141 offset:38912
	ds_read_b128 v[234:237], v141 offset:39936
	global_load_lds_dwordx4 v[244:245], off
	v_lshl_add_u64 v[244:245], s[36:37], 0, v[130:131]
	s_mov_b32 m0, s42
	s_nop 0
	global_load_lds_dwordx4 v[244:245], off
	s_waitcnt vmcnt(8)
	s_waitcnt lgkmcnt(0)
	s_barrier
; #define PG8_STAGE(bufoff, gbase, voff) do { _Pragma("unroll") for (int _i = 0; _i < 2; ++_i) \
;     __builtin_amdgcn_global_load_lds((const unsigned*)((const char*)(gbase) + (voff)[_i]), (PG8_LAS unsigned*)(lds + (bufoff) + ldsw + _i * 8192), 16, 0, 0); } while (0)
; #define PG8_LDA(dst, b, h) do { _Pragma("unroll") for (int m = 0; m < 4; ++m) _Pragma("unroll") for (int k = 0; k < 2; ++k) dst[m][k] = *(const PG8_LAS bf16x8*)(lds + PG8_SA(b, h) + aoff + m * 2048 + k * 1024); } while (0)
; #define PG8_MMA(ai, bj, At, Bt) do { __builtin_amdgcn_s_setprio(1); _Pragma("unroll") for (int m = 0; m < 4; ++m) _Pragma("unroll") for (int n = 0; n < 2; ++n) _Pragma("unroll") for (int k = 0; k < 2; ++k) \
;     acc[ai][bj][m][n] = __builtin_amdgcn_mfma_f32_16x16x32_bf16(Bt[n][k], At[m][k], acc[ai][bj][m][n], 0, 0, 0); __builtin_amdgcn_s_setprio(0); } while (0)
; #define PG8_WAIT_V(n) asm volatile("s_waitcnt vmcnt(" #n ")" ::: "memory")
; #define PG8_WAIT_L(n) asm volatile("s_waitcnt lgkmcnt(" #n ")" ::: "memory")
; #define PG8_BAR __builtin_amdgcn_s_barrier()
; #define PG8_SCHED __builtin_amdgcn_sched_barrier(0)
; template <class Epi, bool SEQ>
; DEV void gemm_phase(PG8_LAS unsigned char* lds, const Gemm g, const Epi& E) {
;     ...
;       PG8_WAIT_V(8); PG8_WAIT_L(0); PG8_BAR; PG8_MMA(0, 0, At, B0); PG8_MMA(0, 1, At, B1); PG8_BAR; PG8_SCHED;
;       PG8_LDA(At, 1, 1); PG8_STAGE(PG8_SB(1, 0), b3, voffB); PG8_STAGE(PG8_SB(1, 1), b3 + hstepB, voffB); PG8_STAGE(PG8_SA(1, 0), a3, voffA);
;       PG8_WAIT_V(8); PG8_WAIT_L(0); PG8_BAR; PG8_MMA(1, 0, At, B0); PG8_MMA(1, 1, At, B1); PG8_BAR; PG8_SCHED;
;     }
;     if (wr == 0) PG8_BAR;
	s_waitcnt lgkmcnt(0)
	v_mfma_f32_16x16x32_bf16 v[124:127], v[142:145], v[188:191], v[124:127]
	v_mfma_f32_16x16x32_bf16 v[120:123], v[150:153], v[188:191], v[120:123]
	v_mfma_f32_16x16x32_bf16 v[116:119], v[142:145], v[196:199], v[116:119]
	v_mfma_f32_16x16x32_bf16 v[112:115], v[150:153], v[196:199], v[112:115]
	v_mfma_f32_16x16x32_bf16 v[100:103], v[142:145], v[222:225], v[100:103]
	v_mfma_f32_16x16x32_bf16 v[96:99], v[150:153], v[222:225], v[96:99]
	v_mfma_f32_16x16x32_bf16 v[84:87], v[142:145], v[230:233], v[84:87]
	v_mfma_f32_16x16x32_bf16 v[80:83], v[150:153], v[230:233], v[80:83]
	v_mfma_f32_16x16x32_bf16 v[124:127], v[146:149], v[192:195], v[124:127]
	v_mfma_f32_16x16x32_bf16 v[120:123], v[154:157], v[192:195], v[120:123]
	v_mfma_f32_16x16x32_bf16 v[116:119], v[146:149], v[218:221], v[116:119]
	v_mfma_f32_16x16x32_bf16 v[112:115], v[154:157], v[218:221], v[112:115]
	v_mfma_f32_16x16x32_bf16 v[100:103], v[146:149], v[226:229], v[100:103]
	v_mfma_f32_16x16x32_bf16 v[96:99], v[154:157], v[226:229], v[96:99]
	v_mfma_f32_16x16x32_bf16 v[84:87], v[146:149], v[234:237], v[84:87]
	v_mfma_f32_16x16x32_bf16 v[80:83], v[154:157], v[234:237], v[80:83]
	v_mfma_f32_16x16x32_bf16 v[108:111], v[158:161], v[188:191], v[108:111]
	v_mfma_f32_16x16x32_bf16 v[104:107], v[180:183], v[188:191], v[104:107]
	v_mfma_f32_16x16x32_bf16 v[92:95], v[158:161], v[196:199], v[92:95]
	v_mfma_f32_16x16x32_bf16 v[88:91], v[180:183], v[196:199], v[88:91]
	v_mfma_f32_16x16x32_bf16 v[76:79], v[158:161], v[222:225], v[76:79]
	v_mfma_f32_16x16x32_bf16 v[72:75], v[180:183], v[222:225], v[72:75]
	v_mfma_f32_16x16x32_bf16 v[68:71], v[158:161], v[230:233], v[68:71]
	v_mfma_f32_16x16x32_bf16 v[64:67], v[180:183], v[230:233], v[64:67]
	v_mfma_f32_16x16x32_bf16 v[108:111], v[162:165], v[192:195], v[108:111]
	v_mfma_f32_16x16x32_bf16 v[104:107], v[184:187], v[192:195], v[104:107]
	v_mfma_f32_16x16x32_bf16 v[92:95], v[162:165], v[218:221], v[92:95]
	v_mfma_f32_16x16x32_bf16 v[88:91], v[184:187], v[218:221], v[88:91]
	v_mfma_f32_16x16x32_bf16 v[76:79], v[162:165], v[226:229], v[76:79]
	v_mfma_f32_16x16x32_bf16 v[72:75], v[184:187], v[226:229], v[72:75]
	v_mfma_f32_16x16x32_bf16 v[68:71], v[162:165], v[234:237], v[68:71]
	v_mfma_f32_16x16x32_bf16 v[64:67], v[184:187], v[234:237], v[64:67]
	s_barrier
	s_add_i32 s36, s54, s38
	v_lshl_add_u64 v[166:167], v[166:167], 0, s[10:11]
	s_mov_b32 m0, s36
	ds_read_b128 v[188:191], v141 offset:49152
	ds_read_b128 v[192:195], v141 offset:50176
	ds_read_b128 v[196:199], v141 offset:51200
	ds_read_b128 v[218:221], v141 offset:52224
	ds_read_b128 v[222:225], v141 offset:53248
	ds_read_b128 v[226:229], v141 offset:54272
	ds_read_b128 v[230:233], v141 offset:55296
	ds_read_b128 v[234:237], v141 offset:56320
	global_load_lds_dwordx4 v[166:167], off
	s_add_i32 m0, s36, 0x2000
	s_add_u32 s26, s26, 0x40080
	v_lshl_add_u64 v[166:167], v[238:239], 0, s[10:11]
	s_addc_u32 s27, s27, 0
	s_add_i32 s36, s55, s38
	global_load_lds_dwordx4 v[166:167], off
	v_lshl_add_u64 v[166:167], s[26:27], 0, v[168:169]
	s_mov_b32 m0, s36
	s_nop 0
	global_load_lds_dwordx4 v[166:167], off
	v_lshl_add_u64 v[166:167], s[26:27], 0, v[128:129]
	s_add_i32 m0, s36, 0x2000
	s_nop 0
	global_load_lds_dwordx4 v[166:167], off
	v_lshl_add_u64 v[166:167], v[240:241], 0, s[10:11]
	s_mov_b32 m0, s45
	s_nop 0
	global_load_lds_dwordx4 v[166:167], off
	v_lshl_add_u64 v[166:167], v[242:243], 0, s[10:11]
	s_mov_b32 m0, s46
	s_nop 0
	global_load_lds_dwordx4 v[166:167], off
	s_waitcnt vmcnt(8)
	s_waitcnt lgkmcnt(0)
	s_barrier
	s_waitcnt lgkmcnt(0)
	v_mfma_f32_16x16x32_bf16 v[60:63], v[142:145], v[188:191], v[60:63]
	v_mfma_f32_16x16x32_bf16 v[56:59], v[150:153], v[188:191], v[56:59]
	v_mfma_f32_16x16x32_bf16 v[52:55], v[142:145], v[196:199], v[52:55]
	v_mfma_f32_16x16x32_bf16 v[48:51], v[150:153], v[196:199], v[48:51]
	v_mfma_f32_16x16x32_bf16 v[36:39], v[142:145], v[222:225], v[36:39]
	v_mfma_f32_16x16x32_bf16 v[32:35], v[150:153], v[222:225], v[32:35]
	v_mfma_f32_16x16x32_bf16 v[20:23], v[142:145], v[230:233], v[20:23]
	v_mfma_f32_16x16x32_bf16 v[16:19], v[150:153], v[230:233], v[16:19]
	v_mfma_f32_16x16x32_bf16 v[60:63], v[146:149], v[192:195], v[60:63]
	v_mfma_f32_16x16x32_bf16 v[56:59], v[154:157], v[192:195], v[56:59]
	v_mfma_f32_16x16x32_bf16 v[52:55], v[146:149], v[218:221], v[52:55]
	v_mfma_f32_16x16x32_bf16 v[48:51], v[154:157], v[218:221], v[48:51]
	v_mfma_f32_16x16x32_bf16 v[36:39], v[146:149], v[226:229], v[36:39]
	v_mfma_f32_16x16x32_bf16 v[32:35], v[154:157], v[226:229], v[32:35]
	v_mfma_f32_16x16x32_bf16 v[20:23], v[146:149], v[234:237], v[20:23]
	v_mfma_f32_16x16x32_bf16 v[16:19], v[154:157], v[234:237], v[16:19]
	v_mfma_f32_16x16x32_bf16 v[44:47], v[158:161], v[188:191], v[44:47]
	v_mfma_f32_16x16x32_bf16 v[40:43], v[180:183], v[188:191], v[40:43]
	v_mfma_f32_16x16x32_bf16 v[28:31], v[158:161], v[196:199], v[28:31]
	v_mfma_f32_16x16x32_bf16 v[24:27], v[180:183], v[196:199], v[24:27]
	v_mfma_f32_16x16x32_bf16 v[12:15], v[158:161], v[222:225], v[12:15]
	v_mfma_f32_16x16x32_bf16 v[8:11], v[180:183], v[222:225], v[8:11]
	v_mfma_f32_16x16x32_bf16 v[4:7], v[158:161], v[230:233], v[4:7]
	v_mfma_f32_16x16x32_bf16 v[0:3], v[180:183], v[230:233], v[0:3]
	v_mfma_f32_16x16x32_bf16 v[44:47], v[162:165], v[192:195], v[44:47]
	v_mfma_f32_16x16x32_bf16 v[40:43], v[184:187], v[192:195], v[40:43]
	v_mfma_f32_16x16x32_bf16 v[28:31], v[162:165], v[218:221], v[28:31]
	v_mfma_f32_16x16x32_bf16 v[24:27], v[184:187], v[218:221], v[24:27]
	v_mfma_f32_16x16x32_bf16 v[12:15], v[162:165], v[226:229], v[12:15]
	v_mfma_f32_16x16x32_bf16 v[8:11], v[184:187], v[226:229], v[8:11]
	v_mfma_f32_16x16x32_bf16 v[4:7], v[162:165], v[234:237], v[4:7]
	v_mfma_f32_16x16x32_bf16 v[0:3], v[184:187], v[234:237], v[0:3]
	s_barrier
	s_add_i32 s53, s53, 2
	s_add_u32 s20, s20, 0x100
	s_addc_u32 s21, s21, 0
	s_add_u32 s51, s51, 0x100
	s_addc_u32 s52, s52, 0
	s_cmp_gt_u32 s53, 13
	s_cbranch_scc0 .LBB0_287
	s_and_b64 vcc, exec, s[4:5]
	s_cbranch_vccz .LBB0_290
	s_barrier
; DEV unsigned cvt_pk_bf16(float lo, float hi) { const f32x2_ v = {lo, hi}; return __builtin_bit_cast(unsigned, __builtin_convertvector(v, bf16x2n_)); }
;   DEV void operator()(const f32x4 (&acc)[2][2][4][2], const Unit& u, int wr, int wc, int fr, int fq) const {
;     const int row0 = u.pm * BM + wr * 64 + fr, col0 = u.pn * BM + wc * 32 + 8 * fq;
; #pragma unroll
;     for (int ai = 0; ai < 2; ++ai)
; #pragma unroll
;       for (int m = 0; m < 4; ++m) {
;         bf16_t* rowp = O + (size_t)(row0 + ai * HALF + m * 16) * ldc + col0;
; #pragma unroll
;         for (int bj = 0; bj < 2; ++bj) {
;           f32x4 v0 = acc[ai][bj][m][0], v1 = acc[ai][bj][m][1];
;           if (ACT == 1) {
; #pragma unroll
;             for (int c = 0; c < 4; ++c) { const float a = fmaxf(v0[c], 0.f), b = fmaxf(v1[c], 0.f); v0[c] = a * a; v1[c] = b * b; }
;           }
;           u32x4 w; w.x = cvt_pk_bf16(v0[0], v0[1]); w.y = cvt_pk_bf16(v0[2], v0[3]); w.z = cvt_pk_bf16(v1[0], v1[1]); w.w = cvt_pk_bf16(v1[2], v1[3]);
;           *(u32x4*)(rowp + bj * HALF) = w;
;         }
;       }
;   }
.LBB0_290:
	s_setprio 0
	v_lshl_add_u32 v142, s47, 8, v138
	v_lshl_or_b32 v144, s48, 8, v140
	v_ashrrev_i32_e32 v143, 31, v142
	v_ashrrev_i32_e32 v145, 31, v144
	v_lshlrev_b64 v[146:147], 11, v[142:143]
	v_lshl_add_u64 v[146:147], s[30:31], 0, v[146:147]
	v_lshlrev_b64 v[144:145], 1, v[144:145]
	v_lshl_add_u64 v[146:147], v[146:147], 0, v[144:145]
	s_mov_b64 s[20:21], 0x40000
	v_cvt_pk_bf16_f32 v60, v60, v61
	v_cvt_pk_bf16_f32 v61, v62, v63
	v_cvt_pk_bf16_f32 v62, v56, v57
	v_add_co_u32_e32 v56, vcc, s92, v146
	v_cvt_pk_bf16_f32 v68, v68, v69
	v_cvt_pk_bf16_f32 v69, v70, v71
	v_cvt_pk_bf16_f32 v70, v64, v65
	v_lshl_add_u64 v[64:65], v[146:147], 0, s[20:21]
	v_addc_co_u32_e32 v57, vcc, 0, v147, vcc
	v_cvt_pk_bf16_f32 v44, v44, v45
	v_cvt_pk_bf16_f32 v45, v46, v47
	v_cvt_pk_bf16_f32 v46, v40, v41
	v_cvt_pk_bf16_f32 v47, v42, v43
	v_cvt_pk_bf16_f32 v108, v108, v109
	v_cvt_pk_bf16_f32 v109, v110, v111
	v_cvt_pk_bf16_f32 v110, v104, v105
	v_or_b32_e32 v104, 16, v142
	global_store_dwordx4 v[64:65], v[44:47], off offset:256
	s_mov_b64 s[20:21], 0x48000
	v_ashrrev_i32_e32 v105, 31, v104
	v_add_co_u32_e32 v46, vcc, s93, v146
	v_cvt_pk_bf16_f32 v92, v92, v93
	v_cvt_pk_bf16_f32 v93, v94, v95
	v_cvt_pk_bf16_f32 v94, v88, v89
	v_or_b32_e32 v88, 32, v142
	v_lshl_add_u64 v[44:45], v[146:147], 0, s[20:21]
	v_addc_co_u32_e32 v47, vcc, 0, v147, vcc
	v_cvt_pk_bf16_f32 v28, v28, v29
	v_cvt_pk_bf16_f32 v29, v30, v31
	v_cvt_pk_bf16_f32 v30, v24, v25
	v_cvt_pk_bf16_f32 v31, v26, v27
	v_lshlrev_b64 v[104:105], 11, v[104:105]
	v_ashrrev_i32_e32 v89, 31, v88
	v_cvt_pk_bf16_f32 v76, v76, v77
	v_cvt_pk_bf16_f32 v77, v78, v79
	v_cvt_pk_bf16_f32 v78, v72, v73
	v_or_b32_e32 v72, 48, v142
	global_store_dwordx4 v[44:45], v[28:31], off offset:256
	s_mov_b64 s[20:21], 0x50000
	v_cvt_pk_bf16_f32 v111, v106, v107
	v_add_co_u32_e32 v30, vcc, s96, v146
	v_lshl_add_u64 v[104:105], s[30:31], 0, v[104:105]
	v_lshlrev_b64 v[88:89], 11, v[88:89]
	v_ashrrev_i32_e32 v73, 31, v72
	v_lshl_add_u64 v[28:29], v[146:147], 0, s[20:21]
	v_addc_co_u32_e32 v31, vcc, 0, v147, vcc
	v_cvt_pk_bf16_f32 v12, v12, v13
	v_cvt_pk_bf16_f32 v13, v14, v15
	v_cvt_pk_bf16_f32 v14, v8, v9
	v_cvt_pk_bf16_f32 v15, v10, v11
	global_store_dwordx4 v[146:147], v[108:111], off offset:256
	v_cvt_pk_bf16_f32 v95, v90, v91
	v_lshl_add_u64 v[88:89], s[30:31], 0, v[88:89]
	v_lshl_add_u64 v[108:109], v[104:105], 0, v[144:145]
	v_lshlrev_b64 v[72:73], 11, v[72:73]
	global_store_dwordx4 v[28:29], v[12:15], off offset:256
	global_store_dwordx4 v[108:109], v[92:95], off offset:256
	v_cvt_pk_bf16_f32 v79, v74, v75
	v_add_co_u32_e32 v14, vcc, s97, v146
	v_lshl_add_u64 v[92:93], v[88:89], 0, v[144:145]
	v_lshl_add_u64 v[72:73], s[30:31], 0, v[72:73]
	s_mov_b64 s[20:21], 0x58000
	v_addc_co_u32_e32 v15, vcc, 0, v147, vcc
	v_cvt_pk_bf16_f32 v124, v124, v125
	v_cvt_pk_bf16_f32 v125, v126, v127
	v_cvt_pk_bf16_f32 v126, v120, v121
	v_cvt_pk_bf16_f32 v127, v122, v123
	v_cvt_pk_bf16_f32 v104, v116, v117
	v_cvt_pk_bf16_f32 v105, v118, v119
	v_cvt_pk_bf16_f32 v106, v112, v113
	v_cvt_pk_bf16_f32 v107, v114, v115
	v_cvt_pk_bf16_f32 v88, v100, v101
	v_cvt_pk_bf16_f32 v89, v102, v103
	v_cvt_pk_bf16_f32 v90, v96, v97
	v_cvt_pk_bf16_f32 v91, v98, v99
	global_store_dwordx4 v[92:93], v[76:79], off offset:256
	v_cvt_pk_bf16_f32 v74, v80, v81
	v_cvt_pk_bf16_f32 v75, v82, v83
	v_lshl_add_u64 v[76:77], v[72:73], 0, v[144:145]
	v_cvt_pk_bf16_f32 v72, v84, v85
	v_cvt_pk_bf16_f32 v73, v86, v87
	v_cvt_pk_bf16_f32 v71, v66, v67
	v_cvt_pk_bf16_f32 v63, v58, v59
	v_cvt_pk_bf16_f32 v40, v52, v53
	v_cvt_pk_bf16_f32 v41, v54, v55
	v_cvt_pk_bf16_f32 v42, v48, v49
	v_cvt_pk_bf16_f32 v43, v50, v51
	v_cvt_pk_bf16_f32 v24, v36, v37
	v_cvt_pk_bf16_f32 v25, v38, v39
	v_cvt_pk_bf16_f32 v26, v32, v33
	v_cvt_pk_bf16_f32 v27, v34, v35
	v_lshl_add_u64 v[12:13], v[146:147], 0, s[20:21]
	v_cvt_pk_bf16_f32 v8, v20, v21
	v_cvt_pk_bf16_f32 v9, v22, v23
	v_cvt_pk_bf16_f32 v10, v16, v17
	v_cvt_pk_bf16_f32 v11, v18, v19
	v_cvt_pk_bf16_f32 v4, v4, v5
	v_cvt_pk_bf16_f32 v5, v6, v7
	v_cvt_pk_bf16_f32 v6, v0, v1
	v_cvt_pk_bf16_f32 v7, v2, v3
	s_andn2_b64 vcc, exec, s[8:9]
	s_mov_b64 s[8:9], -1
	global_store_dwordx4 v[146:147], v[124:127], off
	global_store_dwordx4 v[108:109], v[104:107], off
	global_store_dwordx4 v[92:93], v[88:91], off
	global_store_dwordx4 v[76:77], v[72:75], off
	global_store_dwordx4 v[76:77], v[68:71], off offset:256
	global_store_dwordx4 v[56:57], v[60:63], off
	global_store_dwordx4 v[46:47], v[40:43], off
	global_store_dwordx4 v[30:31], v[24:27], off
	global_store_dwordx4 v[14:15], v[8:11], off
	global_store_dwordx4 v[12:13], v[4:7], off offset:256
	s_cbranch_vccnz .LBB0_279
	s_andn2_b64 vcc, exec, s[2:3]
	s_cbranch_vccnz .LBB0_278
	s_barrier
	s_branch .LBB0_278

; #define PG8_STAGE(bufoff, gbase, voff) do { _Pragma("unroll") for (int _i = 0; _i < 2; ++_i) \
;     __builtin_amdgcn_global_load_lds((const unsigned*)((const char*)(gbase) + (voff)[_i]), (PG8_LAS unsigned*)(lds + (bufoff) + ldsw + _i * 8192), 16, 0, 0); } while (0)
; #define PG8_LDA(dst, b, h) do { _Pragma("unroll") for (int m = 0; m < 4; ++m) _Pragma("unroll") for (int k = 0; k < 2; ++k) dst[m][k] = *(const PG8_LAS bf16x8*)(lds + PG8_SA(b, h) + aoff + m * 2048 + k * 1024); } while (0)
; #define PG8_LDB(dst, b, h) do { _Pragma("unroll") for (int n = 0; n < 2; ++n) _Pragma("unroll") for (int k = 0; k < 2; ++k) dst[n][k] = *(const PG8_LAS bf16x8*)(lds + PG8_SB(b, h) + boff + n * 2048 + k * 1024); } while (0)
; #define PG8_MMA(ai, bj, At, Bt) do { __builtin_amdgcn_s_setprio(1); _Pragma("unroll") for (int m = 0; m < 4; ++m) _Pragma("unroll") for (int n = 0; n < 2; ++n) _Pragma("unroll") for (int k = 0; k < 2; ++k) \
;     acc[ai][bj][m][n] = __builtin_amdgcn_mfma_f32_16x16x32_bf16(Bt[n][k], At[m][k], acc[ai][bj][m][n], 0, 0, 0); __builtin_amdgcn_s_setprio(0); } while (0)
; #define PG8_WAIT_V(n) asm volatile("s_waitcnt vmcnt(" #n ")" ::: "memory")
; #define PG8_WAIT_L(n) asm volatile("s_waitcnt lgkmcnt(" #n ")" ::: "memory")
; #define PG8_BAR __builtin_amdgcn_s_barrier()
; #define PG8_SCHED __builtin_amdgcn_sched_barrier(0)
; template <class Epi, bool SEQ>
; DEV void gemm_phase(PG8_LAS unsigned char* lds, const Gemm g, const Epi& E) {
;     ...
;     const bool has_next = next_unit<SEQ>(g, ui + 1, G, cblk, nxt);
;     const char* nA = has_next ? PG8_ABASE(nxt) : cA; const char* nB = has_next ? PG8_BBASE(nxt) : cB;
;     for (int t = 0; t < nt; t += 2) {
;       const bool last = (t == nt - 2);
;       const char* a1 = cA + (size_t)(t + 1) * kstep;
;       const char* a2 = last ? nA : cA + (size_t)(t + 2) * kstep; const char* b2 = last ? nB : cB + (size_t)(t + 2) * kstep;
;       const char* a3 = a2 + kstep; const char* b3 = b2 + kstep;
;       PG8_LDB(B0, 0, 0); PG8_LDB(B1, 0, 1); PG8_SCHED; PG8_LDA(At, 0, 0); PG8_STAGE(PG8_SA(1, 1), a1 + hstepA, voffA);
;       PG8_WAIT_V(8); PG8_WAIT_L(0); PG8_BAR; PG8_MMA(0, 0, At, B0); PG8_MMA(0, 1, At, B1); PG8_BAR; PG8_SCHED;
;       PG8_LDA(At, 0, 1); PG8_STAGE(PG8_SB(0, 0), b2, voffB); PG8_STAGE(PG8_SB(0, 1), b2 + hstepB, voffB); PG8_STAGE(PG8_SA(0, 0), a2, voffA);
.LBB0_316:
	s_ashr_i32 s13, s12, 31
	s_lshl_b64 s[16:17], s[12:13], 20
	s_add_u32 s13, s35, s16
	s_addc_u32 s26, s36, s17
	s_ashr_i32 s9, s8, 31
	s_lshl_b64 s[16:17], s[8:9], 18
	s_add_u32 s16, s13, s16
	s_addc_u32 s17, s26, s17
	s_and_b64 s[0:1], s[0:1], exec
	s_cselect_b32 s9, s17, s21
	s_cselect_b32 s13, s16, s20
	s_add_u32 s51, s20, 0x100
	s_addc_u32 s52, s21, 0
	s_mov_b32 s53, -2
	v_readfirstlane_b32 s98, v171
	s_nop 3
	s_lshr_b32 s98, s98, 6
	s_cmp_lt_u32 s98, 4
	s_cbranch_scc0 .Lprio_317
	s_setprio 1
.Lprio_317:
.LBB0_317:
	s_add_u32 s0, s18, 0x100
	s_addc_u32 s1, s19, 0
	s_add_i32 s54, 0, 0x10000
	s_cmp_eq_u32 s53, 4
	s_cselect_b32 s27, s15, s1
	s_cselect_b32 s26, s14, s0
	v_add_u32_e32 v146, s54, v162
	s_cselect_b32 s21, s9, s52
	s_cselect_b32 s20, s13, s51
	s_add_i32 s55, 0, 0x14000
	ds_read_b128 v[128:131], v146
	ds_read_b128 v[142:145], v146 offset:1024
	ds_read_b128 v[148:151], v146 offset:2048
	ds_read_b128 v[152:155], v146 offset:3072
	v_add_u32_e32 v146, s55, v162
	ds_read_b128 v[156:159], v146
	ds_read_b128 v[180:183], v146 offset:1024
	ds_read_b128 v[184:187], v146 offset:2048
	ds_read_b128 v[188:191], v146 offset:3072
	v_lshl_add_u64 v[160:161], s[18:19], 0, v[138:139]
	s_add_i32 m0, s37, 0xc000
	ds_read_b128 v[192:195], v164
	ds_read_b128 v[196:199], v164 offset:1024
	ds_read_b128 v[218:221], v164 offset:2048
	ds_read_b128 v[222:225], v164 offset:3072
	ds_read_b128 v[226:229], v164 offset:4096
	ds_read_b128 v[230:233], v164 offset:5120
	ds_read_b128 v[234:237], v164 offset:6144
	ds_read_b128 v[238:241], v164 offset:7168
	global_load_lds_dwordx4 v[160:161], off
	v_lshl_add_u64 v[160:161], s[18:19], 0, v[140:141]
	s_add_i32 m0, s37, 0xe000
	s_nop 0
	global_load_lds_dwordx4 v[160:161], off
	s_waitcnt vmcnt(8)
	s_waitcnt lgkmcnt(0)
	s_barrier
	s_waitcnt lgkmcnt(0)
	v_mfma_f32_16x16x32_bf16 v[124:127], v[128:131], v[192:195], v[124:127]
	v_mfma_f32_16x16x32_bf16 v[120:123], v[148:151], v[192:195], v[120:123]
	v_mfma_f32_16x16x32_bf16 v[116:119], v[128:131], v[218:221], v[116:119]
	v_mfma_f32_16x16x32_bf16 v[112:115], v[148:151], v[218:221], v[112:115]
	v_mfma_f32_16x16x32_bf16 v[108:111], v[128:131], v[226:229], v[108:111]
	v_mfma_f32_16x16x32_bf16 v[104:107], v[148:151], v[226:229], v[104:107]
	v_mfma_f32_16x16x32_bf16 v[100:103], v[128:131], v[234:237], v[100:103]
	v_mfma_f32_16x16x32_bf16 v[96:99], v[148:151], v[234:237], v[96:99]
	v_mfma_f32_16x16x32_bf16 v[124:127], v[142:145], v[196:199], v[124:127]
	v_mfma_f32_16x16x32_bf16 v[120:123], v[152:155], v[196:199], v[120:123]
	v_mfma_f32_16x16x32_bf16 v[116:119], v[142:145], v[222:225], v[116:119]
	v_mfma_f32_16x16x32_bf16 v[112:115], v[152:155], v[222:225], v[112:115]
	v_mfma_f32_16x16x32_bf16 v[108:111], v[142:145], v[230:233], v[108:111]
	v_mfma_f32_16x16x32_bf16 v[104:107], v[152:155], v[230:233], v[104:107]
	v_mfma_f32_16x16x32_bf16 v[100:103], v[142:145], v[238:241], v[100:103]
	v_mfma_f32_16x16x32_bf16 v[96:99], v[152:155], v[238:241], v[96:99]
	v_mfma_f32_16x16x32_bf16 v[92:95], v[156:159], v[192:195], v[92:95]
	v_mfma_f32_16x16x32_bf16 v[88:91], v[184:187], v[192:195], v[88:91]
	v_mfma_f32_16x16x32_bf16 v[84:87], v[156:159], v[218:221], v[84:87]
	v_mfma_f32_16x16x32_bf16 v[80:83], v[184:187], v[218:221], v[80:83]
	v_mfma_f32_16x16x32_bf16 v[76:79], v[156:159], v[226:229], v[76:79]
	v_mfma_f32_16x16x32_bf16 v[72:75], v[184:187], v[226:229], v[72:75]
	v_mfma_f32_16x16x32_bf16 v[68:71], v[156:159], v[234:237], v[68:71]
	v_mfma_f32_16x16x32_bf16 v[64:67], v[184:187], v[234:237], v[64:67]
	v_mfma_f32_16x16x32_bf16 v[92:95], v[180:183], v[196:199], v[92:95]
	v_mfma_f32_16x16x32_bf16 v[88:91], v[188:191], v[196:199], v[88:91]
	v_mfma_f32_16x16x32_bf16 v[84:87], v[180:183], v[222:225], v[84:87]
	v_mfma_f32_16x16x32_bf16 v[80:83], v[188:191], v[222:225], v[80:83]
	v_mfma_f32_16x16x32_bf16 v[76:79], v[180:183], v[230:233], v[76:79]
	v_mfma_f32_16x16x32_bf16 v[72:75], v[188:191], v[230:233], v[72:75]
	v_mfma_f32_16x16x32_bf16 v[68:71], v[180:183], v[238:241], v[68:71]
	v_mfma_f32_16x16x32_bf16 v[64:67], v[188:191], v[238:241], v[64:67]
	s_barrier
	s_add_i32 s18, s54, s34
	v_lshl_add_u64 v[160:161], s[20:21], 0, v[168:169]
	s_mov_b32 m0, s18
	ds_read_b128 v[192:195], v164 offset:16384
	ds_read_b128 v[196:199], v164 offset:17408
	ds_read_b128 v[218:221], v164 offset:18432
	ds_read_b128 v[222:225], v164 offset:19456
	ds_read_b128 v[226:229], v164 offset:20480
	ds_read_b128 v[230:233], v164 offset:21504
	ds_read_b128 v[234:237], v164 offset:22528
	ds_read_b128 v[238:241], v164 offset:23552
	global_load_lds_dwordx4 v[160:161], off
	s_add_i32 m0, s18, 0x2000
	s_add_u32 s18, s20, 0x20000
	v_lshl_add_u64 v[166:167], s[20:21], 0, v[132:133]
	s_addc_u32 s19, s21, 0
	s_add_i32 s54, s55, s34
	global_load_lds_dwordx4 v[166:167], off
	v_lshl_add_u64 v[242:243], s[18:19], 0, v[168:169]
	s_mov_b32 m0, s54
	v_lshl_add_u64 v[244:245], s[26:27], 0, v[134:135]
	global_load_lds_dwordx4 v[242:243], off
	v_lshl_add_u64 v[242:243], s[18:19], 0, v[132:133]
	s_add_i32 m0, s54, 0x2000
	s_nop 0
	global_load_lds_dwordx4 v[242:243], off
	v_lshl_add_u64 v[242:243], s[26:27], 0, v[136:137]
	s_mov_b32 m0, s37
	s_nop 0
	global_load_lds_dwordx4 v[242:243], off
	s_mov_b32 m0, s40
	s_nop 0
	global_load_lds_dwordx4 v[244:245], off
	s_waitcnt vmcnt(8)
	s_waitcnt lgkmcnt(0)
	s_barrier
; #define PG8_STAGE(bufoff, gbase, voff) do { _Pragma("unroll") for (int _i = 0; _i < 2; ++_i) \
;     __builtin_amdgcn_global_load_lds((const unsigned*)((const char*)(gbase) + (voff)[_i]), (PG8_LAS unsigned*)(lds + (bufoff) + ldsw + _i * 8192), 16, 0, 0); } while (0)
; #define PG8_LDA(dst, b, h) do { _Pragma("unroll") for (int m = 0; m < 4; ++m) _Pragma("unroll") for (int k = 0; k < 2; ++k) dst[m][k] = *(const PG8_LAS bf16x8*)(lds + PG8_SA(b, h) + aoff + m * 2048 + k * 1024); } while (0)
; #define PG8_LDB(dst, b, h) do { _Pragma("unroll") for (int n = 0; n < 2; ++n) _Pragma("unroll") for (int k = 0; k < 2; ++k) dst[n][k] = *(const PG8_LAS bf16x8*)(lds + PG8_SB(b, h) + boff + n * 2048 + k * 1024); } while (0)
; #define PG8_MMA(ai, bj, At, Bt) do { __builtin_amdgcn_s_setprio(1); _Pragma("unroll") for (int m = 0; m < 4; ++m) _Pragma("unroll") for (int n = 0; n < 2; ++n) _Pragma("unroll") for (int k = 0; k < 2; ++k) \
;     acc[ai][bj][m][n] = __builtin_amdgcn_mfma_f32_16x16x32_bf16(Bt[n][k], At[m][k], acc[ai][bj][m][n], 0, 0, 0); __builtin_amdgcn_s_setprio(0); } while (0)
; #define PG8_WAIT_V(n) asm volatile("s_waitcnt vmcnt(" #n ")" ::: "memory")
; #define PG8_WAIT_L(n) asm volatile("s_waitcnt lgkmcnt(" #n ")" ::: "memory")
; #define PG8_BAR __builtin_amdgcn_s_barrier()
; #define PG8_SCHED __builtin_amdgcn_sched_barrier(0)
; template <class Epi, bool SEQ>
; DEV void gemm_phase(PG8_LAS unsigned char* lds, const Gemm g, const Epi& E) {
;     ...
;       PG8_WAIT_V(8); PG8_WAIT_L(0); PG8_BAR; PG8_MMA(1, 0, At, B0); PG8_MMA(1, 1, At, B1); PG8_BAR; PG8_SCHED;
;       PG8_LDB(B0, 1, 0); PG8_LDB(B1, 1, 1); PG8_SCHED; PG8_LDA(At, 1, 0); PG8_STAGE(PG8_SA(0, 1), a2 + hstepA, voffA);
;       PG8_WAIT_V(8); PG8_WAIT_L(0); PG8_BAR; PG8_MMA(0, 0, At, B0); PG8_MMA(0, 1, At, B1); PG8_BAR; PG8_SCHED;
	s_waitcnt lgkmcnt(0)
	v_mfma_f32_16x16x32_bf16 v[60:63], v[128:131], v[192:195], v[60:63]
	v_mfma_f32_16x16x32_bf16 v[56:59], v[148:151], v[192:195], v[56:59]
	v_mfma_f32_16x16x32_bf16 v[52:55], v[128:131], v[218:221], v[52:55]
	v_mfma_f32_16x16x32_bf16 v[48:51], v[148:151], v[218:221], v[48:51]
	v_mfma_f32_16x16x32_bf16 v[44:47], v[128:131], v[226:229], v[44:47]
	v_mfma_f32_16x16x32_bf16 v[40:43], v[148:151], v[226:229], v[40:43]
	v_mfma_f32_16x16x32_bf16 v[36:39], v[128:131], v[234:237], v[36:39]
	v_mfma_f32_16x16x32_bf16 v[32:35], v[148:151], v[234:237], v[32:35]
	v_mfma_f32_16x16x32_bf16 v[60:63], v[142:145], v[196:199], v[60:63]
	v_mfma_f32_16x16x32_bf16 v[56:59], v[152:155], v[196:199], v[56:59]
	v_mfma_f32_16x16x32_bf16 v[52:55], v[142:145], v[222:225], v[52:55]
	v_mfma_f32_16x16x32_bf16 v[48:51], v[152:155], v[222:225], v[48:51]
	v_mfma_f32_16x16x32_bf16 v[44:47], v[142:145], v[230:233], v[44:47]
	v_mfma_f32_16x16x32_bf16 v[40:43], v[152:155], v[230:233], v[40:43]
	v_mfma_f32_16x16x32_bf16 v[36:39], v[142:145], v[238:241], v[36:39]
	v_mfma_f32_16x16x32_bf16 v[32:35], v[152:155], v[238:241], v[32:35]
	v_mfma_f32_16x16x32_bf16 v[28:31], v[156:159], v[192:195], v[28:31]
	v_mfma_f32_16x16x32_bf16 v[24:27], v[184:187], v[192:195], v[24:27]
	v_mfma_f32_16x16x32_bf16 v[20:23], v[156:159], v[218:221], v[20:23]
	v_mfma_f32_16x16x32_bf16 v[16:19], v[184:187], v[218:221], v[16:19]
	v_mfma_f32_16x16x32_bf16 v[12:15], v[156:159], v[226:229], v[12:15]
	v_mfma_f32_16x16x32_bf16 v[8:11], v[184:187], v[226:229], v[8:11]
	v_mfma_f32_16x16x32_bf16 v[4:7], v[156:159], v[234:237], v[4:7]
	v_mfma_f32_16x16x32_bf16 v[0:3], v[184:187], v[234:237], v[0:3]
	v_mfma_f32_16x16x32_bf16 v[28:31], v[180:183], v[196:199], v[28:31]
	v_mfma_f32_16x16x32_bf16 v[24:27], v[188:191], v[196:199], v[24:27]
	v_mfma_f32_16x16x32_bf16 v[20:23], v[180:183], v[222:225], v[20:23]
	v_mfma_f32_16x16x32_bf16 v[16:19], v[188:191], v[222:225], v[16:19]
	v_mfma_f32_16x16x32_bf16 v[12:15], v[180:183], v[230:233], v[12:15]
	v_mfma_f32_16x16x32_bf16 v[8:11], v[188:191], v[230:233], v[8:11]
	v_mfma_f32_16x16x32_bf16 v[4:7], v[180:183], v[238:241], v[4:7]
	v_mfma_f32_16x16x32_bf16 v[0:3], v[188:191], v[238:241], v[0:3]
	s_barrier
	s_add_i32 s54, 0, 0x18000
	v_add_u32_e32 v146, s54, v162
	s_add_i32 s55, 0, 0x1c000
	ds_read_b128 v[128:131], v146
	ds_read_b128 v[142:145], v146 offset:1024
	ds_read_b128 v[148:151], v146 offset:2048
	ds_read_b128 v[152:155], v146 offset:3072
	v_add_u32_e32 v146, s55, v162
	ds_read_b128 v[156:159], v146
	ds_read_b128 v[180:183], v146 offset:1024
	ds_read_b128 v[184:187], v146 offset:2048
	ds_read_b128 v[188:191], v146 offset:3072
	s_add_u32 s18, s26, 0x1b0000
	s_addc_u32 s19, s27, 0
	s_mov_b32 m0, s41
	v_lshl_add_u64 v[246:247], s[18:19], 0, v[136:137]
	ds_read_b128 v[192:195], v164 offset:32768
	ds_read_b128 v[196:199], v164 offset:33792
	ds_read_b128 v[218:221], v164 offset:34816
	ds_read_b128 v[222:225], v164 offset:35840
	ds_read_b128 v[226:229], v164 offset:36864
	ds_read_b128 v[230:233], v164 offset:37888
	ds_read_b128 v[234:237], v164 offset:38912
	ds_read_b128 v[238:241], v164 offset:39936
	global_load_lds_dwordx4 v[246:247], off
	v_lshl_add_u64 v[246:247], s[18:19], 0, v[134:135]
	s_mov_b32 m0, s42
	s_nop 0
	global_load_lds_dwordx4 v[246:247], off
	s_waitcnt vmcnt(8)
	s_waitcnt lgkmcnt(0)
	s_barrier
	s_waitcnt lgkmcnt(0)
	v_mfma_f32_16x16x32_bf16 v[124:127], v[128:131], v[192:195], v[124:127]
	v_mfma_f32_16x16x32_bf16 v[120:123], v[148:151], v[192:195], v[120:123]
	v_mfma_f32_16x16x32_bf16 v[116:119], v[128:131], v[218:221], v[116:119]
	v_mfma_f32_16x16x32_bf16 v[112:115], v[148:151], v[218:221], v[112:115]
	v_mfma_f32_16x16x32_bf16 v[108:111], v[128:131], v[226:229], v[108:111]
	v_mfma_f32_16x16x32_bf16 v[104:107], v[148:151], v[226:229], v[104:107]
	v_mfma_f32_16x16x32_bf16 v[100:103], v[128:131], v[234:237], v[100:103]
	v_mfma_f32_16x16x32_bf16 v[96:99], v[148:151], v[234:237], v[96:99]
	v_mfma_f32_16x16x32_bf16 v[124:127], v[142:145], v[196:199], v[124:127]
	v_mfma_f32_16x16x32_bf16 v[120:123], v[152:155], v[196:199], v[120:123]
	v_mfma_f32_16x16x32_bf16 v[116:119], v[142:145], v[222:225], v[116:119]
	v_mfma_f32_16x16x32_bf16 v[112:115], v[152:155], v[222:225], v[112:115]
	v_mfma_f32_16x16x32_bf16 v[108:111], v[142:145], v[230:233], v[108:111]
	v_mfma_f32_16x16x32_bf16 v[104:107], v[152:155], v[230:233], v[104:107]
	v_mfma_f32_16x16x32_bf16 v[100:103], v[142:145], v[238:241], v[100:103]
	v_mfma_f32_16x16x32_bf16 v[96:99], v[152:155], v[238:241], v[96:99]
	v_mfma_f32_16x16x32_bf16 v[92:95], v[156:159], v[192:195], v[92:95]
	v_mfma_f32_16x16x32_bf16 v[88:91], v[184:187], v[192:195], v[88:91]
	v_mfma_f32_16x16x32_bf16 v[84:87], v[156:159], v[218:221], v[84:87]
	v_mfma_f32_16x16x32_bf16 v[80:83], v[184:187], v[218:221], v[80:83]
	v_mfma_f32_16x16x32_bf16 v[76:79], v[156:159], v[226:229], v[76:79]
	v_mfma_f32_16x16x32_bf16 v[72:75], v[184:187], v[226:229], v[72:75]
	v_mfma_f32_16x16x32_bf16 v[68:71], v[156:159], v[234:237], v[68:71]
	v_mfma_f32_16x16x32_bf16 v[64:67], v[184:187], v[234:237], v[64:67]
	v_mfma_f32_16x16x32_bf16 v[92:95], v[180:183], v[196:199], v[92:95]
	v_mfma_f32_16x16x32_bf16 v[88:91], v[188:191], v[196:199], v[88:91]
	v_mfma_f32_16x16x32_bf16 v[84:87], v[180:183], v[222:225], v[84:87]
	v_mfma_f32_16x16x32_bf16 v[80:83], v[188:191], v[222:225], v[80:83]
	v_mfma_f32_16x16x32_bf16 v[76:79], v[180:183], v[230:233], v[76:79]
	v_mfma_f32_16x16x32_bf16 v[72:75], v[188:191], v[230:233], v[72:75]
	v_mfma_f32_16x16x32_bf16 v[68:71], v[180:183], v[238:241], v[68:71]
	v_mfma_f32_16x16x32_bf16 v[64:67], v[188:191], v[238:241], v[64:67]
	s_barrier
; #define PG8_STAGE(bufoff, gbase, voff) do { _Pragma("unroll") for (int _i = 0; _i < 2; ++_i) \
;     __builtin_amdgcn_global_load_lds((const unsigned*)((const char*)(gbase) + (voff)[_i]), (PG8_LAS unsigned*)(lds + (bufoff) + ldsw + _i * 8192), 16, 0, 0); } while (0)
; #define PG8_LDA(dst, b, h) do { _Pragma("unroll") for (int m = 0; m < 4; ++m) _Pragma("unroll") for (int k = 0; k < 2; ++k) dst[m][k] = *(const PG8_LAS bf16x8*)(lds + PG8_SA(b, h) + aoff + m * 2048 + k * 1024); } while (0)
; #define PG8_MMA(ai, bj, At, Bt) do { __builtin_amdgcn_s_setprio(1); _Pragma("unroll") for (int m = 0; m < 4; ++m) _Pragma("unroll") for (int n = 0; n < 2; ++n) _Pragma("unroll") for (int k = 0; k < 2; ++k) \
;     acc[ai][bj][m][n] = __builtin_amdgcn_mfma_f32_16x16x32_bf16(Bt[n][k], At[m][k], acc[ai][bj][m][n], 0, 0, 0); __builtin_amdgcn_s_setprio(0); } while (0)
; #define PG8_WAIT_V(n) asm volatile("s_waitcnt vmcnt(" #n ")" ::: "memory")
; #define PG8_WAIT_L(n) asm volatile("s_waitcnt lgkmcnt(" #n ")" ::: "memory")
; #define PG8_BAR __builtin_amdgcn_s_barrier()
; #define PG8_SCHED __builtin_amdgcn_sched_barrier(0)
; template <class Epi, bool SEQ>
; DEV void gemm_phase(PG8_LAS unsigned char* lds, const Gemm g, const Epi& E) {
;     ...
;       PG8_LDA(At, 1, 1); PG8_STAGE(PG8_SB(1, 0), b3, voffB); PG8_STAGE(PG8_SB(1, 1), b3 + hstepB, voffB); PG8_STAGE(PG8_SA(1, 0), a3, voffA);
;       PG8_WAIT_V(8); PG8_WAIT_L(0); PG8_BAR; PG8_MMA(1, 0, At, B0); PG8_MMA(1, 1, At, B1); PG8_BAR; PG8_SCHED;
;     }
;     if (wr == 0) PG8_BAR;
;   DEV bool rescale(f32x4 (&acc)[2][2][4][2], const Unit& u, int wr, int wc, int fr, int fq) const {
;     const int row0 = u.pm * BM + wr * 64 + fr, col0 = u.pn * BM + wc * 32 + 8 * fq;
;     const bool lastseg = u.seg == 2;
;     const int sb = lastseg ? 2 : u.seg + 1;
;     const float one = lastseg ? 0.f : 1.f;
; #pragma unroll
;     for (int ai = 0; ai < 2; ++ai)
; #pragma unroll
;       for (int m = 0; m < 4; ++m) {
;         const size_t r = (size_t)(row0 + ai * HALF + m * 16);
	s_add_i32 s18, s54, s34
	v_lshl_add_u64 v[160:161], v[160:161], 0, s[10:11]
	s_mov_b32 m0, s18
	ds_read_b128 v[192:195], v164 offset:49152
	ds_read_b128 v[196:199], v164 offset:50176
	ds_read_b128 v[218:221], v164 offset:51200
	ds_read_b128 v[222:225], v164 offset:52224
	ds_read_b128 v[226:229], v164 offset:53248
	ds_read_b128 v[230:233], v164 offset:54272
	ds_read_b128 v[234:237], v164 offset:55296
	ds_read_b128 v[238:241], v164 offset:56320
	global_load_lds_dwordx4 v[160:161], off
	s_add_i32 m0, s18, 0x2000
	s_add_u32 s18, s20, 0x20080
	v_lshl_add_u64 v[160:161], v[166:167], 0, s[10:11]
	s_addc_u32 s19, s21, 0
	s_add_i32 s20, s55, s34
	global_load_lds_dwordx4 v[160:161], off
	v_lshl_add_u64 v[160:161], s[18:19], 0, v[168:169]
	s_mov_b32 m0, s20
	s_nop 0
	global_load_lds_dwordx4 v[160:161], off
	v_lshl_add_u64 v[160:161], s[18:19], 0, v[132:133]
	s_add_i32 m0, s20, 0x2000
	s_nop 0
	global_load_lds_dwordx4 v[160:161], off
	v_lshl_add_u64 v[160:161], v[242:243], 0, s[10:11]
	s_mov_b32 m0, s44
	s_nop 0
	global_load_lds_dwordx4 v[160:161], off
	v_lshl_add_u64 v[160:161], v[244:245], 0, s[10:11]
	s_mov_b32 m0, s45
	s_nop 0
	global_load_lds_dwordx4 v[160:161], off
	s_waitcnt vmcnt(8)
	s_waitcnt lgkmcnt(0)
	s_barrier
	s_waitcnt lgkmcnt(0)
	v_mfma_f32_16x16x32_bf16 v[60:63], v[128:131], v[192:195], v[60:63]
	v_mfma_f32_16x16x32_bf16 v[56:59], v[148:151], v[192:195], v[56:59]
	v_mfma_f32_16x16x32_bf16 v[52:55], v[128:131], v[218:221], v[52:55]
	v_mfma_f32_16x16x32_bf16 v[48:51], v[148:151], v[218:221], v[48:51]
	v_mfma_f32_16x16x32_bf16 v[44:47], v[128:131], v[226:229], v[44:47]
	v_mfma_f32_16x16x32_bf16 v[40:43], v[148:151], v[226:229], v[40:43]
	v_mfma_f32_16x16x32_bf16 v[36:39], v[128:131], v[234:237], v[36:39]
	v_mfma_f32_16x16x32_bf16 v[32:35], v[148:151], v[234:237], v[32:35]
	v_mfma_f32_16x16x32_bf16 v[60:63], v[142:145], v[196:199], v[60:63]
	v_mfma_f32_16x16x32_bf16 v[56:59], v[152:155], v[196:199], v[56:59]
	v_mfma_f32_16x16x32_bf16 v[52:55], v[142:145], v[222:225], v[52:55]
	v_mfma_f32_16x16x32_bf16 v[48:51], v[152:155], v[222:225], v[48:51]
	v_mfma_f32_16x16x32_bf16 v[44:47], v[142:145], v[230:233], v[44:47]
	v_mfma_f32_16x16x32_bf16 v[40:43], v[152:155], v[230:233], v[40:43]
	v_mfma_f32_16x16x32_bf16 v[36:39], v[142:145], v[238:241], v[36:39]
	v_mfma_f32_16x16x32_bf16 v[32:35], v[152:155], v[238:241], v[32:35]
	v_mfma_f32_16x16x32_bf16 v[28:31], v[156:159], v[192:195], v[28:31]
	v_mfma_f32_16x16x32_bf16 v[24:27], v[184:187], v[192:195], v[24:27]
	v_mfma_f32_16x16x32_bf16 v[20:23], v[156:159], v[218:221], v[20:23]
	v_mfma_f32_16x16x32_bf16 v[16:19], v[184:187], v[218:221], v[16:19]
	v_mfma_f32_16x16x32_bf16 v[12:15], v[156:159], v[226:229], v[12:15]
	v_mfma_f32_16x16x32_bf16 v[8:11], v[184:187], v[226:229], v[8:11]
	v_mfma_f32_16x16x32_bf16 v[4:7], v[156:159], v[234:237], v[4:7]
	v_mfma_f32_16x16x32_bf16 v[0:3], v[184:187], v[234:237], v[0:3]
	v_mfma_f32_16x16x32_bf16 v[28:31], v[180:183], v[196:199], v[28:31]
	v_mfma_f32_16x16x32_bf16 v[24:27], v[188:191], v[196:199], v[24:27]
	v_mfma_f32_16x16x32_bf16 v[20:23], v[180:183], v[222:225], v[20:23]
	v_mfma_f32_16x16x32_bf16 v[16:19], v[188:191], v[222:225], v[16:19]
	v_mfma_f32_16x16x32_bf16 v[12:15], v[180:183], v[230:233], v[12:15]
	v_mfma_f32_16x16x32_bf16 v[8:11], v[188:191], v[230:233], v[8:11]
	v_mfma_f32_16x16x32_bf16 v[4:7], v[180:183], v[238:241], v[4:7]
	v_mfma_f32_16x16x32_bf16 v[0:3], v[188:191], v[238:241], v[0:3]
	s_barrier
	s_add_i32 s53, s53, 2
	s_add_u32 s51, s51, 0x100
	s_addc_u32 s52, s52, 0
	s_cmp_gt_u32 s53, 5
	s_mov_b64 s[18:19], s[0:1]
	s_cbranch_scc0 .LBB0_317
	s_and_b64 vcc, exec, s[4:5]
	s_cbranch_vccz .LBB0_320
	s_barrier
.LBB0_320:
	s_setprio 0
	v_lshl_add_u32 v144, s49, 8, v147
	v_lshl_or_b32 v145, s50, 8, v163
	v_mov_b64_e32 v[218:219], s[30:31]
	s_lshl_b32 s18, s48, 11
	s_add_i32 s18, s18, 0x1e00
	s_mov_b32 s19, 0
	v_lshlrev_b32_e32 v145, 1, v145
	v_mad_i64_i32 v[142:143], s[26:27], v144, s95, v[218:219]
	s_mov_b32 s20, 0x36000
	s_mov_b32 s21, 0
	v_lshl_add_u64 v[142:143], v[142:143], 0, s[18:19]
	s_mov_b32 s26, 0x10e000
	s_mov_b32 s27, 0
	v_add_co_u32_e32 v218, vcc, v142, v145
	s_nop 1
	v_addc_co_u32_e32 v219, vcc, 0, v143, vcc
	s_cmp_eq_u32 s48, 2
	s_cselect_b64 s[0:1], -1, 0
	s_cbranch_scc1 .Lp4epi_last
; DEV float bflo(unsigned w) { return __uint_as_float(w << 16); }
; DEV float bfhi(unsigned w) { return __uint_as_float(w & 0xffff0000u); }
; #define RS_(xa, xb) ((1.0f + one * __expf(-(xb))) * __builtin_amdgcn_rcpf(1.0f + __expf(-(xa))))
;   DEV bool rescale(f32x4 (&acc)[2][2][4][2], const Unit& u, int wr, int wc, int fr, int fq) const {
;     ...
;         const size_t r = (size_t)(row0 + ai * HALF + m * 16);
; #pragma unroll
;         for (int bj = 0; bj < 2; ++bj) {
;           const int c = col0 + bj * HALF;
;           const u32x4 ga = *(const u32x4*)(Z + r * NIN + GT + u.seg * D + c);
;           const u32x4 gb = *(const u32x4*)(Z + r * NIN + GT + sb * D + c);
;     ...
;           acc[ai][bj][m][0][0] *= RS_(bflo(ga.x), bflo(gb.x)); acc[ai][bj][m][0][1] *= RS_(bfhi(ga.x), bfhi(gb.x));
;           acc[ai][bj][m][0][2] *= RS_(bflo(ga.y), bflo(gb.y)); acc[ai][bj][m][0][3] *= RS_(bfhi(ga.y), bfhi(gb.y));
;           acc[ai][bj][m][1][0] *= RS_(bflo(ga.z), bflo(gb.z)); acc[ai][bj][m][1][1] *= RS_(bfhi(ga.z), bfhi(gb.z));
;           acc[ai][bj][m][1][2] *= RS_(bflo(ga.w), bflo(gb.w)); acc[ai][bj][m][1][3] *= RS_(bfhi(ga.w), bfhi(gb.w));
	s_mov_b32 s18, 0xbfb8aa3b
	s_mov_b32 s19, 0xbfb8aa3b
	global_load_dwordx4 v[180:183], v[218:219], off
	global_load_dwordx4 v[188:191], v[218:219], off offset:2048
	global_load_dwordx4 v[184:187], v[218:219], off offset:256
	global_load_dwordx4 v[192:195], v[218:219], off offset:2304
	v_lshl_add_u64 v[218:219], v[218:219], 0, s[20:21]
	global_load_dwordx4 v[196:199], v[218:219], off
	global_load_dwordx4 v[224:227], v[218:219], off offset:2048
	global_load_dwordx4 v[220:223], v[218:219], off offset:256
	global_load_dwordx4 v[228:231], v[218:219], off offset:2304
	v_lshl_add_u64 v[218:219], v[218:219], 0, s[20:21]
	global_load_dwordx4 v[232:235], v[218:219], off
	global_load_dwordx4 v[240:243], v[218:219], off offset:2048
	global_load_dwordx4 v[236:239], v[218:219], off offset:256
	global_load_dwordx4 v[148:151], v[218:219], off offset:2304
	v_lshl_add_u64 v[218:219], v[218:219], 0, s[20:21]
	s_waitcnt vmcnt(8)
	v_lshlrev_b32_e32 v128, 16, v180
	v_and_b32_e32 v129, 0xffff0000, v180
	v_lshlrev_b32_e32 v156, 16, v188
	v_and_b32_e32 v157, 0xffff0000, v188
	v_lshlrev_b32_e32 v130, 16, v181
	v_and_b32_e32 v131, 0xffff0000, v181
	v_lshlrev_b32_e32 v158, 16, v189
	v_and_b32_e32 v159, 0xffff0000, v189
	v_lshlrev_b32_e32 v152, 16, v182
	v_and_b32_e32 v153, 0xffff0000, v182
	v_lshlrev_b32_e32 v160, 16, v190
	v_and_b32_e32 v161, 0xffff0000, v190
	v_lshlrev_b32_e32 v154, 16, v183
	v_and_b32_e32 v155, 0xffff0000, v183
	v_lshlrev_b32_e32 v166, 16, v191
	v_and_b32_e32 v167, 0xffff0000, v191
	v_pk_mul_f32 v[128:129], v[128:129], s[18:19]
	v_pk_mul_f32 v[156:157], v[156:157], s[18:19]
	v_pk_mul_f32 v[130:131], v[130:131], s[18:19]
	v_pk_mul_f32 v[158:159], v[158:159], s[18:19]
	v_pk_mul_f32 v[152:153], v[152:153], s[18:19]
	v_pk_mul_f32 v[160:161], v[160:161], s[18:19]
	v_pk_mul_f32 v[154:155], v[154:155], s[18:19]
	v_pk_mul_f32 v[166:167], v[166:167], s[18:19]
	v_exp_f32_e32 v128, v128
	v_exp_f32_e32 v129, v129
	v_exp_f32_e32 v156, v156
	v_exp_f32_e32 v157, v157
	v_exp_f32_e32 v130, v130
	v_exp_f32_e32 v131, v131
	v_exp_f32_e32 v158, v158
	v_exp_f32_e32 v159, v159
	v_exp_f32_e32 v152, v152
	v_exp_f32_e32 v153, v153
	v_exp_f32_e32 v160, v160
	v_exp_f32_e32 v161, v161
	v_exp_f32_e32 v154, v154
	v_exp_f32_e32 v155, v155
	v_exp_f32_e32 v166, v166
	v_exp_f32_e32 v167, v167
	v_pk_add_f32 v[128:129], v[128:129], 1.0 op_sel_hi:[1,0]
	v_pk_add_f32 v[156:157], v[156:157], 1.0 op_sel_hi:[1,0]
	v_pk_add_f32 v[130:131], v[130:131], 1.0 op_sel_hi:[1,0]
	v_pk_add_f32 v[158:159], v[158:159], 1.0 op_sel_hi:[1,0]
	v_pk_add_f32 v[152:153], v[152:153], 1.0 op_sel_hi:[1,0]
	v_pk_add_f32 v[160:161], v[160:161], 1.0 op_sel_hi:[1,0]
	v_pk_add_f32 v[154:155], v[154:155], 1.0 op_sel_hi:[1,0]
	v_pk_add_f32 v[166:167], v[166:167], 1.0 op_sel_hi:[1,0]
	v_rcp_f32_e32 v128, v128
	v_rcp_f32_e32 v129, v129
	v_rcp_f32_e32 v130, v130
	v_rcp_f32_e32 v131, v131
	v_rcp_f32_e32 v152, v152
	v_rcp_f32_e32 v153, v153
	v_rcp_f32_e32 v154, v154
	v_rcp_f32_e32 v155, v155
	v_pk_mul_f32 v[128:129], v[128:129], v[156:157]
	v_pk_mul_f32 v[130:131], v[130:131], v[158:159]
	v_pk_mul_f32 v[152:153], v[152:153], v[160:161]
	v_pk_mul_f32 v[154:155], v[154:155], v[166:167]
	v_pk_mul_f32 v[124:125], v[124:125], v[128:129]
	v_pk_mul_f32 v[126:127], v[126:127], v[130:131]
	v_pk_mul_f32 v[120:121], v[120:121], v[152:153]
	v_pk_mul_f32 v[122:123], v[122:123], v[154:155]
	v_lshlrev_b32_e32 v128, 16, v184
	v_and_b32_e32 v129, 0xffff0000, v184
	v_lshlrev_b32_e32 v156, 16, v192
	v_and_b32_e32 v157, 0xffff0000, v192
	v_lshlrev_b32_e32 v130, 16, v185
	v_and_b32_e32 v131, 0xffff0000, v185
	v_lshlrev_b32_e32 v158, 16, v193
	v_and_b32_e32 v159, 0xffff0000, v193
	v_lshlrev_b32_e32 v152, 16, v186
	v_and_b32_e32 v153, 0xffff0000, v186
	v_lshlrev_b32_e32 v160, 16, v194
	v_and_b32_e32 v161, 0xffff0000, v194
	v_lshlrev_b32_e32 v154, 16, v187
	v_and_b32_e32 v155, 0xffff0000, v187
	v_lshlrev_b32_e32 v166, 16, v195
	v_and_b32_e32 v167, 0xffff0000, v195
	v_pk_mul_f32 v[128:129], v[128:129], s[18:19]
	v_pk_mul_f32 v[156:157], v[156:157], s[18:19]
	v_pk_mul_f32 v[130:131], v[130:131], s[18:19]
	v_pk_mul_f32 v[158:159], v[158:159], s[18:19]
	v_pk_mul_f32 v[152:153], v[152:153], s[18:19]
	v_pk_mul_f32 v[160:161], v[160:161], s[18:19]
	v_pk_mul_f32 v[154:155], v[154:155], s[18:19]
	v_pk_mul_f32 v[166:167], v[166:167], s[18:19]
	v_exp_f32_e32 v128, v128
	v_exp_f32_e32 v129, v129
	v_exp_f32_e32 v156, v156
	v_exp_f32_e32 v157, v157
	v_exp_f32_e32 v130, v130
	v_exp_f32_e32 v131, v131
	v_exp_f32_e32 v158, v158
	v_exp_f32_e32 v159, v159
	v_exp_f32_e32 v152, v152
	v_exp_f32_e32 v153, v153
	v_exp_f32_e32 v160, v160
	v_exp_f32_e32 v161, v161
	v_exp_f32_e32 v154, v154
	v_exp_f32_e32 v155, v155
	v_exp_f32_e32 v166, v166
	v_exp_f32_e32 v167, v167
	v_pk_add_f32 v[128:129], v[128:129], 1.0 op_sel_hi:[1,0]
	v_pk_add_f32 v[156:157], v[156:157], 1.0 op_sel_hi:[1,0]
	v_pk_add_f32 v[130:131], v[130:131], 1.0 op_sel_hi:[1,0]
	v_pk_add_f32 v[158:159], v[158:159], 1.0 op_sel_hi:[1,0]
	v_pk_add_f32 v[152:153], v[152:153], 1.0 op_sel_hi:[1,0]
	v_pk_add_f32 v[160:161], v[160:161], 1.0 op_sel_hi:[1,0]
	v_pk_add_f32 v[154:155], v[154:155], 1.0 op_sel_hi:[1,0]
	v_pk_add_f32 v[166:167], v[166:167], 1.0 op_sel_hi:[1,0]
	v_rcp_f32_e32 v128, v128
	v_rcp_f32_e32 v129, v129
	v_rcp_f32_e32 v130, v130
	v_rcp_f32_e32 v131, v131
	v_rcp_f32_e32 v152, v152
	v_rcp_f32_e32 v153, v153
	v_rcp_f32_e32 v154, v154
	v_rcp_f32_e32 v155, v155
	v_pk_mul_f32 v[128:129], v[128:129], v[156:157]
	v_pk_mul_f32 v[130:131], v[130:131], v[158:159]
	v_pk_mul_f32 v[152:153], v[152:153], v[160:161]
	v_pk_mul_f32 v[154:155], v[154:155], v[166:167]
	v_pk_mul_f32 v[92:93], v[92:93], v[128:129]
	v_pk_mul_f32 v[94:95], v[94:95], v[130:131]
	v_pk_mul_f32 v[88:89], v[88:89], v[152:153]
	v_pk_mul_f32 v[90:91], v[90:91], v[154:155]
	global_load_dwordx4 v[180:183], v[218:219], off
	global_load_dwordx4 v[188:191], v[218:219], off offset:2048
	global_load_dwordx4 v[184:187], v[218:219], off offset:256
	global_load_dwordx4 v[192:195], v[218:219], off offset:2304
	v_lshl_add_u64 v[218:219], v[218:219], 0, s[26:27]
	s_waitcnt vmcnt(8)
; DEV float bflo(unsigned w) { return __uint_as_float(w << 16); }
; DEV float bfhi(unsigned w) { return __uint_as_float(w & 0xffff0000u); }
; #define RS_(xa, xb) ((1.0f + one * __expf(-(xb))) * __builtin_amdgcn_rcpf(1.0f + __expf(-(xa))))
;   DEV bool rescale(f32x4 (&acc)[2][2][4][2], const Unit& u, int wr, int wc, int fr, int fq) const {
;     ...
;         const size_t r = (size_t)(row0 + ai * HALF + m * 16);
; #pragma unroll
;         for (int bj = 0; bj < 2; ++bj) {
;           const int c = col0 + bj * HALF;
;           const u32x4 ga = *(const u32x4*)(Z + r * NIN + GT + u.seg * D + c);
;           const u32x4 gb = *(const u32x4*)(Z + r * NIN + GT + sb * D + c);
;     ...
;           acc[ai][bj][m][0][0] *= RS_(bflo(ga.x), bflo(gb.x)); acc[ai][bj][m][0][1] *= RS_(bfhi(ga.x), bfhi(gb.x));
;           acc[ai][bj][m][0][2] *= RS_(bflo(ga.y), bflo(gb.y)); acc[ai][bj][m][0][3] *= RS_(bfhi(ga.y), bfhi(gb.y));
;           acc[ai][bj][m][1][0] *= RS_(bflo(ga.z), bflo(gb.z)); acc[ai][bj][m][1][1] *= RS_(bfhi(ga.z), bfhi(gb.z));
;           acc[ai][bj][m][1][2] *= RS_(bflo(ga.w), bflo(gb.w)); acc[ai][bj][m][1][3] *= RS_(bfhi(ga.w), bfhi(gb.w));
	v_lshlrev_b32_e32 v128, 16, v196
	v_and_b32_e32 v129, 0xffff0000, v196
	v_lshlrev_b32_e32 v156, 16, v224
	v_and_b32_e32 v157, 0xffff0000, v224
	v_lshlrev_b32_e32 v130, 16, v197
	v_and_b32_e32 v131, 0xffff0000, v197
	v_lshlrev_b32_e32 v158, 16, v225
	v_and_b32_e32 v159, 0xffff0000, v225
	v_lshlrev_b32_e32 v152, 16, v198
	v_and_b32_e32 v153, 0xffff0000, v198
	v_lshlrev_b32_e32 v160, 16, v226
	v_and_b32_e32 v161, 0xffff0000, v226
	v_lshlrev_b32_e32 v154, 16, v199
	v_and_b32_e32 v155, 0xffff0000, v199
	v_lshlrev_b32_e32 v166, 16, v227
	v_and_b32_e32 v167, 0xffff0000, v227
	v_pk_mul_f32 v[128:129], v[128:129], s[18:19]
	v_pk_mul_f32 v[156:157], v[156:157], s[18:19]
	v_pk_mul_f32 v[130:131], v[130:131], s[18:19]
	v_pk_mul_f32 v[158:159], v[158:159], s[18:19]
	v_pk_mul_f32 v[152:153], v[152:153], s[18:19]
	v_pk_mul_f32 v[160:161], v[160:161], s[18:19]
	v_pk_mul_f32 v[154:155], v[154:155], s[18:19]
	v_pk_mul_f32 v[166:167], v[166:167], s[18:19]
	v_exp_f32_e32 v128, v128
	v_exp_f32_e32 v129, v129
	v_exp_f32_e32 v156, v156
	v_exp_f32_e32 v157, v157
	v_exp_f32_e32 v130, v130
	v_exp_f32_e32 v131, v131
	v_exp_f32_e32 v158, v158
	v_exp_f32_e32 v159, v159
	v_exp_f32_e32 v152, v152
	v_exp_f32_e32 v153, v153
	v_exp_f32_e32 v160, v160
	v_exp_f32_e32 v161, v161
	v_exp_f32_e32 v154, v154
	v_exp_f32_e32 v155, v155
	v_exp_f32_e32 v166, v166
	v_exp_f32_e32 v167, v167
	v_pk_add_f32 v[128:129], v[128:129], 1.0 op_sel_hi:[1,0]
	v_pk_add_f32 v[156:157], v[156:157], 1.0 op_sel_hi:[1,0]
	v_pk_add_f32 v[130:131], v[130:131], 1.0 op_sel_hi:[1,0]
	v_pk_add_f32 v[158:159], v[158:159], 1.0 op_sel_hi:[1,0]
	v_pk_add_f32 v[152:153], v[152:153], 1.0 op_sel_hi:[1,0]
	v_pk_add_f32 v[160:161], v[160:161], 1.0 op_sel_hi:[1,0]
	v_pk_add_f32 v[154:155], v[154:155], 1.0 op_sel_hi:[1,0]
	v_pk_add_f32 v[166:167], v[166:167], 1.0 op_sel_hi:[1,0]
	v_rcp_f32_e32 v128, v128
	v_rcp_f32_e32 v129, v129
	v_rcp_f32_e32 v130, v130
	v_rcp_f32_e32 v131, v131
	v_rcp_f32_e32 v152, v152
	v_rcp_f32_e32 v153, v153
	v_rcp_f32_e32 v154, v154
	v_rcp_f32_e32 v155, v155
	v_pk_mul_f32 v[128:129], v[128:129], v[156:157]
	v_pk_mul_f32 v[130:131], v[130:131], v[158:159]
	v_pk_mul_f32 v[152:153], v[152:153], v[160:161]
	v_pk_mul_f32 v[154:155], v[154:155], v[166:167]
	v_pk_mul_f32 v[116:117], v[116:117], v[128:129]
	v_pk_mul_f32 v[118:119], v[118:119], v[130:131]
	v_pk_mul_f32 v[112:113], v[112:113], v[152:153]
	v_pk_mul_f32 v[114:115], v[114:115], v[154:155]
	v_lshlrev_b32_e32 v128, 16, v220
	v_and_b32_e32 v129, 0xffff0000, v220
	v_lshlrev_b32_e32 v156, 16, v228
	v_and_b32_e32 v157, 0xffff0000, v228
	v_lshlrev_b32_e32 v130, 16, v221
	v_and_b32_e32 v131, 0xffff0000, v221
	v_lshlrev_b32_e32 v158, 16, v229
	v_and_b32_e32 v159, 0xffff0000, v229
	v_lshlrev_b32_e32 v152, 16, v222
	v_and_b32_e32 v153, 0xffff0000, v222
	v_lshlrev_b32_e32 v160, 16, v230
	v_and_b32_e32 v161, 0xffff0000, v230
	v_lshlrev_b32_e32 v154, 16, v223
	v_and_b32_e32 v155, 0xffff0000, v223
	v_lshlrev_b32_e32 v166, 16, v231
	v_and_b32_e32 v167, 0xffff0000, v231
	v_pk_mul_f32 v[128:129], v[128:129], s[18:19]
	v_pk_mul_f32 v[156:157], v[156:157], s[18:19]
	v_pk_mul_f32 v[130:131], v[130:131], s[18:19]
	v_pk_mul_f32 v[158:159], v[158:159], s[18:19]
	v_pk_mul_f32 v[152:153], v[152:153], s[18:19]
	v_pk_mul_f32 v[160:161], v[160:161], s[18:19]
	v_pk_mul_f32 v[154:155], v[154:155], s[18:19]
	v_pk_mul_f32 v[166:167], v[166:167], s[18:19]
	v_exp_f32_e32 v128, v128
	v_exp_f32_e32 v129, v129
	v_exp_f32_e32 v156, v156
	v_exp_f32_e32 v157, v157
	v_exp_f32_e32 v130, v130
	v_exp_f32_e32 v131, v131
	v_exp_f32_e32 v158, v158
	v_exp_f32_e32 v159, v159
	v_exp_f32_e32 v152, v152
	v_exp_f32_e32 v153, v153
	v_exp_f32_e32 v160, v160
	v_exp_f32_e32 v161, v161
	v_exp_f32_e32 v154, v154
	v_exp_f32_e32 v155, v155
	v_exp_f32_e32 v166, v166
	v_exp_f32_e32 v167, v167
	v_pk_add_f32 v[128:129], v[128:129], 1.0 op_sel_hi:[1,0]
	v_pk_add_f32 v[156:157], v[156:157], 1.0 op_sel_hi:[1,0]
	v_pk_add_f32 v[130:131], v[130:131], 1.0 op_sel_hi:[1,0]
	v_pk_add_f32 v[158:159], v[158:159], 1.0 op_sel_hi:[1,0]
	v_pk_add_f32 v[152:153], v[152:153], 1.0 op_sel_hi:[1,0]
	v_pk_add_f32 v[160:161], v[160:161], 1.0 op_sel_hi:[1,0]
	v_pk_add_f32 v[154:155], v[154:155], 1.0 op_sel_hi:[1,0]
	v_pk_add_f32 v[166:167], v[166:167], 1.0 op_sel_hi:[1,0]
	v_rcp_f32_e32 v128, v128
	v_rcp_f32_e32 v129, v129
	v_rcp_f32_e32 v130, v130
	v_rcp_f32_e32 v131, v131
	v_rcp_f32_e32 v152, v152
	v_rcp_f32_e32 v153, v153
	v_rcp_f32_e32 v154, v154
	v_rcp_f32_e32 v155, v155
	v_pk_mul_f32 v[128:129], v[128:129], v[156:157]
	v_pk_mul_f32 v[130:131], v[130:131], v[158:159]
	v_pk_mul_f32 v[152:153], v[152:153], v[160:161]
	v_pk_mul_f32 v[154:155], v[154:155], v[166:167]
	v_pk_mul_f32 v[84:85], v[84:85], v[128:129]
	v_pk_mul_f32 v[86:87], v[86:87], v[130:131]
	v_pk_mul_f32 v[80:81], v[80:81], v[152:153]
	v_pk_mul_f32 v[82:83], v[82:83], v[154:155]
	global_load_dwordx4 v[196:199], v[218:219], off
	global_load_dwordx4 v[224:227], v[218:219], off offset:2048
	global_load_dwordx4 v[220:223], v[218:219], off offset:256
	global_load_dwordx4 v[228:231], v[218:219], off offset:2304
	v_lshl_add_u64 v[218:219], v[218:219], 0, s[20:21]
	s_waitcnt vmcnt(8)
; DEV float bflo(unsigned w) { return __uint_as_float(w << 16); }
; DEV float bfhi(unsigned w) { return __uint_as_float(w & 0xffff0000u); }
; #define RS_(xa, xb) ((1.0f + one * __expf(-(xb))) * __builtin_amdgcn_rcpf(1.0f + __expf(-(xa))))
;   DEV bool rescale(f32x4 (&acc)[2][2][4][2], const Unit& u, int wr, int wc, int fr, int fq) const {
;     ...
;         const size_t r = (size_t)(row0 + ai * HALF + m * 16);
; #pragma unroll
;         for (int bj = 0; bj < 2; ++bj) {
;           const int c = col0 + bj * HALF;
;           const u32x4 ga = *(const u32x4*)(Z + r * NIN + GT + u.seg * D + c);
;           const u32x4 gb = *(const u32x4*)(Z + r * NIN + GT + sb * D + c);
;     ...
;           acc[ai][bj][m][0][0] *= RS_(bflo(ga.x), bflo(gb.x)); acc[ai][bj][m][0][1] *= RS_(bfhi(ga.x), bfhi(gb.x));
;           acc[ai][bj][m][0][2] *= RS_(bflo(ga.y), bflo(gb.y)); acc[ai][bj][m][0][3] *= RS_(bfhi(ga.y), bfhi(gb.y));
;           acc[ai][bj][m][1][0] *= RS_(bflo(ga.z), bflo(gb.z)); acc[ai][bj][m][1][1] *= RS_(bfhi(ga.z), bfhi(gb.z));
;           acc[ai][bj][m][1][2] *= RS_(bflo(ga.w), bflo(gb.w)); acc[ai][bj][m][1][3] *= RS_(bfhi(ga.w), bfhi(gb.w));
	v_lshlrev_b32_e32 v128, 16, v232
	v_and_b32_e32 v129, 0xffff0000, v232
	v_lshlrev_b32_e32 v156, 16, v240
	v_and_b32_e32 v157, 0xffff0000, v240
	v_lshlrev_b32_e32 v130, 16, v233
	v_and_b32_e32 v131, 0xffff0000, v233
	v_lshlrev_b32_e32 v158, 16, v241
	v_and_b32_e32 v159, 0xffff0000, v241
	v_lshlrev_b32_e32 v152, 16, v234
	v_and_b32_e32 v153, 0xffff0000, v234
	v_lshlrev_b32_e32 v160, 16, v242
	v_and_b32_e32 v161, 0xffff0000, v242
	v_lshlrev_b32_e32 v154, 16, v235
	v_and_b32_e32 v155, 0xffff0000, v235
	v_lshlrev_b32_e32 v166, 16, v243
	v_and_b32_e32 v167, 0xffff0000, v243
	v_pk_mul_f32 v[128:129], v[128:129], s[18:19]
	v_pk_mul_f32 v[156:157], v[156:157], s[18:19]
	v_pk_mul_f32 v[130:131], v[130:131], s[18:19]
	v_pk_mul_f32 v[158:159], v[158:159], s[18:19]
	v_pk_mul_f32 v[152:153], v[152:153], s[18:19]
	v_pk_mul_f32 v[160:161], v[160:161], s[18:19]
	v_pk_mul_f32 v[154:155], v[154:155], s[18:19]
	v_pk_mul_f32 v[166:167], v[166:167], s[18:19]
	v_exp_f32_e32 v128, v128
	v_exp_f32_e32 v129, v129
	v_exp_f32_e32 v156, v156
	v_exp_f32_e32 v157, v157
	v_exp_f32_e32 v130, v130
	v_exp_f32_e32 v131, v131
	v_exp_f32_e32 v158, v158
	v_exp_f32_e32 v159, v159
	v_exp_f32_e32 v152, v152
	v_exp_f32_e32 v153, v153
	v_exp_f32_e32 v160, v160
	v_exp_f32_e32 v161, v161
	v_exp_f32_e32 v154, v154
	v_exp_f32_e32 v155, v155
	v_exp_f32_e32 v166, v166
	v_exp_f32_e32 v167, v167
	v_pk_add_f32 v[128:129], v[128:129], 1.0 op_sel_hi:[1,0]
	v_pk_add_f32 v[156:157], v[156:157], 1.0 op_sel_hi:[1,0]
	v_pk_add_f32 v[130:131], v[130:131], 1.0 op_sel_hi:[1,0]
	v_pk_add_f32 v[158:159], v[158:159], 1.0 op_sel_hi:[1,0]
	v_pk_add_f32 v[152:153], v[152:153], 1.0 op_sel_hi:[1,0]
	v_pk_add_f32 v[160:161], v[160:161], 1.0 op_sel_hi:[1,0]
	v_pk_add_f32 v[154:155], v[154:155], 1.0 op_sel_hi:[1,0]
	v_pk_add_f32 v[166:167], v[166:167], 1.0 op_sel_hi:[1,0]
	v_rcp_f32_e32 v128, v128
	v_rcp_f32_e32 v129, v129
	v_rcp_f32_e32 v130, v130
	v_rcp_f32_e32 v131, v131
	v_rcp_f32_e32 v152, v152
	v_rcp_f32_e32 v153, v153
	v_rcp_f32_e32 v154, v154
	v_rcp_f32_e32 v155, v155
	v_pk_mul_f32 v[128:129], v[128:129], v[156:157]
	v_pk_mul_f32 v[130:131], v[130:131], v[158:159]
	v_pk_mul_f32 v[152:153], v[152:153], v[160:161]
	v_pk_mul_f32 v[154:155], v[154:155], v[166:167]
	v_pk_mul_f32 v[108:109], v[108:109], v[128:129]
	v_pk_mul_f32 v[110:111], v[110:111], v[130:131]
	v_pk_mul_f32 v[104:105], v[104:105], v[152:153]
	v_pk_mul_f32 v[106:107], v[106:107], v[154:155]
	v_lshlrev_b32_e32 v128, 16, v236
	v_and_b32_e32 v129, 0xffff0000, v236
	v_lshlrev_b32_e32 v156, 16, v148
	v_and_b32_e32 v157, 0xffff0000, v148
	v_lshlrev_b32_e32 v130, 16, v237
	v_and_b32_e32 v131, 0xffff0000, v237
	v_lshlrev_b32_e32 v158, 16, v149
	v_and_b32_e32 v159, 0xffff0000, v149
	v_lshlrev_b32_e32 v152, 16, v238
	v_and_b32_e32 v153, 0xffff0000, v238
	v_lshlrev_b32_e32 v160, 16, v150
	v_and_b32_e32 v161, 0xffff0000, v150
	v_lshlrev_b32_e32 v154, 16, v239
	v_and_b32_e32 v155, 0xffff0000, v239
	v_lshlrev_b32_e32 v166, 16, v151
	v_and_b32_e32 v167, 0xffff0000, v151
	v_pk_mul_f32 v[128:129], v[128:129], s[18:19]
	v_pk_mul_f32 v[156:157], v[156:157], s[18:19]
	v_pk_mul_f32 v[130:131], v[130:131], s[18:19]
	v_pk_mul_f32 v[158:159], v[158:159], s[18:19]
	v_pk_mul_f32 v[152:153], v[152:153], s[18:19]
	v_pk_mul_f32 v[160:161], v[160:161], s[18:19]
	v_pk_mul_f32 v[154:155], v[154:155], s[18:19]
	v_pk_mul_f32 v[166:167], v[166:167], s[18:19]
	v_exp_f32_e32 v128, v128
	v_exp_f32_e32 v129, v129
	v_exp_f32_e32 v156, v156
	v_exp_f32_e32 v157, v157
	v_exp_f32_e32 v130, v130
	v_exp_f32_e32 v131, v131
	v_exp_f32_e32 v158, v158
	v_exp_f32_e32 v159, v159
	v_exp_f32_e32 v152, v152
	v_exp_f32_e32 v153, v153
	v_exp_f32_e32 v160, v160
	v_exp_f32_e32 v161, v161
	v_exp_f32_e32 v154, v154
	v_exp_f32_e32 v155, v155
	v_exp_f32_e32 v166, v166
	v_exp_f32_e32 v167, v167
	v_pk_add_f32 v[128:129], v[128:129], 1.0 op_sel_hi:[1,0]
	v_pk_add_f32 v[156:157], v[156:157], 1.0 op_sel_hi:[1,0]
	v_pk_add_f32 v[130:131], v[130:131], 1.0 op_sel_hi:[1,0]
	v_pk_add_f32 v[158:159], v[158:159], 1.0 op_sel_hi:[1,0]
	v_pk_add_f32 v[152:153], v[152:153], 1.0 op_sel_hi:[1,0]
	v_pk_add_f32 v[160:161], v[160:161], 1.0 op_sel_hi:[1,0]
	v_pk_add_f32 v[154:155], v[154:155], 1.0 op_sel_hi:[1,0]
	v_pk_add_f32 v[166:167], v[166:167], 1.0 op_sel_hi:[1,0]
	v_rcp_f32_e32 v128, v128
	v_rcp_f32_e32 v129, v129
	v_rcp_f32_e32 v130, v130
	v_rcp_f32_e32 v131, v131
	v_rcp_f32_e32 v152, v152
	v_rcp_f32_e32 v153, v153
	v_rcp_f32_e32 v154, v154
	v_rcp_f32_e32 v155, v155
	v_pk_mul_f32 v[128:129], v[128:129], v[156:157]
	v_pk_mul_f32 v[130:131], v[130:131], v[158:159]
	v_pk_mul_f32 v[152:153], v[152:153], v[160:161]
	v_pk_mul_f32 v[154:155], v[154:155], v[166:167]
	v_pk_mul_f32 v[76:77], v[76:77], v[128:129]
	v_pk_mul_f32 v[78:79], v[78:79], v[130:131]
	v_pk_mul_f32 v[72:73], v[72:73], v[152:153]
	v_pk_mul_f32 v[74:75], v[74:75], v[154:155]
	global_load_dwordx4 v[232:235], v[218:219], off
	global_load_dwordx4 v[240:243], v[218:219], off offset:2048
	global_load_dwordx4 v[236:239], v[218:219], off offset:256
	global_load_dwordx4 v[148:151], v[218:219], off offset:2304
	v_lshl_add_u64 v[218:219], v[218:219], 0, s[20:21]
	s_waitcnt vmcnt(8)
; DEV float bflo(unsigned w) { return __uint_as_float(w << 16); }
; DEV float bfhi(unsigned w) { return __uint_as_float(w & 0xffff0000u); }
; #define RS_(xa, xb) ((1.0f + one * __expf(-(xb))) * __builtin_amdgcn_rcpf(1.0f + __expf(-(xa))))
;   DEV bool rescale(f32x4 (&acc)[2][2][4][2], const Unit& u, int wr, int wc, int fr, int fq) const {
;     ...
;         const size_t r = (size_t)(row0 + ai * HALF + m * 16);
; #pragma unroll
;         for (int bj = 0; bj < 2; ++bj) {
;           const int c = col0 + bj * HALF;
;           const u32x4 ga = *(const u32x4*)(Z + r * NIN + GT + u.seg * D + c);
;           const u32x4 gb = *(const u32x4*)(Z + r * NIN + GT + sb * D + c);
;     ...
;           acc[ai][bj][m][0][0] *= RS_(bflo(ga.x), bflo(gb.x)); acc[ai][bj][m][0][1] *= RS_(bfhi(ga.x), bfhi(gb.x));
;           acc[ai][bj][m][0][2] *= RS_(bflo(ga.y), bflo(gb.y)); acc[ai][bj][m][0][3] *= RS_(bfhi(ga.y), bfhi(gb.y));
;           acc[ai][bj][m][1][0] *= RS_(bflo(ga.z), bflo(gb.z)); acc[ai][bj][m][1][1] *= RS_(bfhi(ga.z), bfhi(gb.z));
;           acc[ai][bj][m][1][2] *= RS_(bflo(ga.w), bflo(gb.w)); acc[ai][bj][m][1][3] *= RS_(bfhi(ga.w), bfhi(gb.w));
	v_lshlrev_b32_e32 v128, 16, v180
	v_and_b32_e32 v129, 0xffff0000, v180
	v_lshlrev_b32_e32 v156, 16, v188
	v_and_b32_e32 v157, 0xffff0000, v188
	v_lshlrev_b32_e32 v130, 16, v181
	v_and_b32_e32 v131, 0xffff0000, v181
	v_lshlrev_b32_e32 v158, 16, v189
	v_and_b32_e32 v159, 0xffff0000, v189
	v_lshlrev_b32_e32 v152, 16, v182
	v_and_b32_e32 v153, 0xffff0000, v182
	v_lshlrev_b32_e32 v160, 16, v190
	v_and_b32_e32 v161, 0xffff0000, v190
	v_lshlrev_b32_e32 v154, 16, v183
	v_and_b32_e32 v155, 0xffff0000, v183
	v_lshlrev_b32_e32 v166, 16, v191
	v_and_b32_e32 v167, 0xffff0000, v191
	v_pk_mul_f32 v[128:129], v[128:129], s[18:19]
	v_pk_mul_f32 v[156:157], v[156:157], s[18:19]
	v_pk_mul_f32 v[130:131], v[130:131], s[18:19]
	v_pk_mul_f32 v[158:159], v[158:159], s[18:19]
	v_pk_mul_f32 v[152:153], v[152:153], s[18:19]
	v_pk_mul_f32 v[160:161], v[160:161], s[18:19]
	v_pk_mul_f32 v[154:155], v[154:155], s[18:19]
	v_pk_mul_f32 v[166:167], v[166:167], s[18:19]
	v_exp_f32_e32 v128, v128
	v_exp_f32_e32 v129, v129
	v_exp_f32_e32 v156, v156
	v_exp_f32_e32 v157, v157
	v_exp_f32_e32 v130, v130
	v_exp_f32_e32 v131, v131
	v_exp_f32_e32 v158, v158
	v_exp_f32_e32 v159, v159
	v_exp_f32_e32 v152, v152
	v_exp_f32_e32 v153, v153
	v_exp_f32_e32 v160, v160
	v_exp_f32_e32 v161, v161
	v_exp_f32_e32 v154, v154
	v_exp_f32_e32 v155, v155
	v_exp_f32_e32 v166, v166
	v_exp_f32_e32 v167, v167
	v_pk_add_f32 v[128:129], v[128:129], 1.0 op_sel_hi:[1,0]
	v_pk_add_f32 v[156:157], v[156:157], 1.0 op_sel_hi:[1,0]
	v_pk_add_f32 v[130:131], v[130:131], 1.0 op_sel_hi:[1,0]
	v_pk_add_f32 v[158:159], v[158:159], 1.0 op_sel_hi:[1,0]
	v_pk_add_f32 v[152:153], v[152:153], 1.0 op_sel_hi:[1,0]
	v_pk_add_f32 v[160:161], v[160:161], 1.0 op_sel_hi:[1,0]
	v_pk_add_f32 v[154:155], v[154:155], 1.0 op_sel_hi:[1,0]
	v_pk_add_f32 v[166:167], v[166:167], 1.0 op_sel_hi:[1,0]
	v_rcp_f32_e32 v128, v128
	v_rcp_f32_e32 v129, v129
	v_rcp_f32_e32 v130, v130
	v_rcp_f32_e32 v131, v131
	v_rcp_f32_e32 v152, v152
	v_rcp_f32_e32 v153, v153
	v_rcp_f32_e32 v154, v154
	v_rcp_f32_e32 v155, v155
	v_pk_mul_f32 v[128:129], v[128:129], v[156:157]
	v_pk_mul_f32 v[130:131], v[130:131], v[158:159]
	v_pk_mul_f32 v[152:153], v[152:153], v[160:161]
	v_pk_mul_f32 v[154:155], v[154:155], v[166:167]
	v_pk_mul_f32 v[100:101], v[100:101], v[128:129]
	v_pk_mul_f32 v[102:103], v[102:103], v[130:131]
	v_pk_mul_f32 v[96:97], v[96:97], v[152:153]
	v_pk_mul_f32 v[98:99], v[98:99], v[154:155]
	v_lshlrev_b32_e32 v128, 16, v184
	v_and_b32_e32 v129, 0xffff0000, v184
	v_lshlrev_b32_e32 v156, 16, v192
	v_and_b32_e32 v157, 0xffff0000, v192
	v_lshlrev_b32_e32 v130, 16, v185
	v_and_b32_e32 v131, 0xffff0000, v185
	v_lshlrev_b32_e32 v158, 16, v193
	v_and_b32_e32 v159, 0xffff0000, v193
	v_lshlrev_b32_e32 v152, 16, v186
	v_and_b32_e32 v153, 0xffff0000, v186
	v_lshlrev_b32_e32 v160, 16, v194
	v_and_b32_e32 v161, 0xffff0000, v194
	v_lshlrev_b32_e32 v154, 16, v187
	v_and_b32_e32 v155, 0xffff0000, v187
	v_lshlrev_b32_e32 v166, 16, v195
	v_and_b32_e32 v167, 0xffff0000, v195
	v_pk_mul_f32 v[128:129], v[128:129], s[18:19]
	v_pk_mul_f32 v[156:157], v[156:157], s[18:19]
	v_pk_mul_f32 v[130:131], v[130:131], s[18:19]
	v_pk_mul_f32 v[158:159], v[158:159], s[18:19]
	v_pk_mul_f32 v[152:153], v[152:153], s[18:19]
	v_pk_mul_f32 v[160:161], v[160:161], s[18:19]
	v_pk_mul_f32 v[154:155], v[154:155], s[18:19]
	v_pk_mul_f32 v[166:167], v[166:167], s[18:19]
	v_exp_f32_e32 v128, v128
	v_exp_f32_e32 v129, v129
	v_exp_f32_e32 v156, v156
	v_exp_f32_e32 v157, v157
	v_exp_f32_e32 v130, v130
	v_exp_f32_e32 v131, v131
	v_exp_f32_e32 v158, v158
	v_exp_f32_e32 v159, v159
	v_exp_f32_e32 v152, v152
	v_exp_f32_e32 v153, v153
	v_exp_f32_e32 v160, v160
	v_exp_f32_e32 v161, v161
	v_exp_f32_e32 v154, v154
	v_exp_f32_e32 v155, v155
	v_exp_f32_e32 v166, v166
	v_exp_f32_e32 v167, v167
	v_pk_add_f32 v[128:129], v[128:129], 1.0 op_sel_hi:[1,0]
	v_pk_add_f32 v[156:157], v[156:157], 1.0 op_sel_hi:[1,0]
	v_pk_add_f32 v[130:131], v[130:131], 1.0 op_sel_hi:[1,0]
	v_pk_add_f32 v[158:159], v[158:159], 1.0 op_sel_hi:[1,0]
	v_pk_add_f32 v[152:153], v[152:153], 1.0 op_sel_hi:[1,0]
	v_pk_add_f32 v[160:161], v[160:161], 1.0 op_sel_hi:[1,0]
	v_pk_add_f32 v[154:155], v[154:155], 1.0 op_sel_hi:[1,0]
	v_pk_add_f32 v[166:167], v[166:167], 1.0 op_sel_hi:[1,0]
	v_rcp_f32_e32 v128, v128
	v_rcp_f32_e32 v129, v129
	v_rcp_f32_e32 v130, v130
	v_rcp_f32_e32 v131, v131
	v_rcp_f32_e32 v152, v152
	v_rcp_f32_e32 v153, v153
	v_rcp_f32_e32 v154, v154
	v_rcp_f32_e32 v155, v155
	v_pk_mul_f32 v[128:129], v[128:129], v[156:157]
	v_pk_mul_f32 v[130:131], v[130:131], v[158:159]
	v_pk_mul_f32 v[152:153], v[152:153], v[160:161]
	v_pk_mul_f32 v[154:155], v[154:155], v[166:167]
	v_pk_mul_f32 v[68:69], v[68:69], v[128:129]
	v_pk_mul_f32 v[70:71], v[70:71], v[130:131]
	v_pk_mul_f32 v[64:65], v[64:65], v[152:153]
	v_pk_mul_f32 v[66:67], v[66:67], v[154:155]
	global_load_dwordx4 v[180:183], v[218:219], off
	global_load_dwordx4 v[188:191], v[218:219], off offset:2048
	global_load_dwordx4 v[184:187], v[218:219], off offset:256
	global_load_dwordx4 v[192:195], v[218:219], off offset:2304
	v_lshl_add_u64 v[218:219], v[218:219], 0, s[20:21]
	s_waitcnt vmcnt(8)
; DEV float bflo(unsigned w) { return __uint_as_float(w << 16); }
; DEV float bfhi(unsigned w) { return __uint_as_float(w & 0xffff0000u); }
; #define RS_(xa, xb) ((1.0f + one * __expf(-(xb))) * __builtin_amdgcn_rcpf(1.0f + __expf(-(xa))))
;   DEV bool rescale(f32x4 (&acc)[2][2][4][2], const Unit& u, int wr, int wc, int fr, int fq) const {
;     ...
;         const size_t r = (size_t)(row0 + ai * HALF + m * 16);
; #pragma unroll
;         for (int bj = 0; bj < 2; ++bj) {
;           const int c = col0 + bj * HALF;
;           const u32x4 ga = *(const u32x4*)(Z + r * NIN + GT + u.seg * D + c);
;           const u32x4 gb = *(const u32x4*)(Z + r * NIN + GT + sb * D + c);
;     ...
;           acc[ai][bj][m][0][0] *= RS_(bflo(ga.x), bflo(gb.x)); acc[ai][bj][m][0][1] *= RS_(bfhi(ga.x), bfhi(gb.x));
;           acc[ai][bj][m][0][2] *= RS_(bflo(ga.y), bflo(gb.y)); acc[ai][bj][m][0][3] *= RS_(bfhi(ga.y), bfhi(gb.y));
;           acc[ai][bj][m][1][0] *= RS_(bflo(ga.z), bflo(gb.z)); acc[ai][bj][m][1][1] *= RS_(bfhi(ga.z), bfhi(gb.z));
;           acc[ai][bj][m][1][2] *= RS_(bflo(ga.w), bflo(gb.w)); acc[ai][bj][m][1][3] *= RS_(bfhi(ga.w), bfhi(gb.w));
	v_lshlrev_b32_e32 v128, 16, v196
	v_and_b32_e32 v129, 0xffff0000, v196
	v_lshlrev_b32_e32 v156, 16, v224
	v_and_b32_e32 v157, 0xffff0000, v224
	v_lshlrev_b32_e32 v130, 16, v197
	v_and_b32_e32 v131, 0xffff0000, v197
	v_lshlrev_b32_e32 v158, 16, v225
	v_and_b32_e32 v159, 0xffff0000, v225
	v_lshlrev_b32_e32 v152, 16, v198
	v_and_b32_e32 v153, 0xffff0000, v198
	v_lshlrev_b32_e32 v160, 16, v226
	v_and_b32_e32 v161, 0xffff0000, v226
	v_lshlrev_b32_e32 v154, 16, v199
	v_and_b32_e32 v155, 0xffff0000, v199
	v_lshlrev_b32_e32 v166, 16, v227
	v_and_b32_e32 v167, 0xffff0000, v227
	v_pk_mul_f32 v[128:129], v[128:129], s[18:19]
	v_pk_mul_f32 v[156:157], v[156:157], s[18:19]
	v_pk_mul_f32 v[130:131], v[130:131], s[18:19]
	v_pk_mul_f32 v[158:159], v[158:159], s[18:19]
	v_pk_mul_f32 v[152:153], v[152:153], s[18:19]
	v_pk_mul_f32 v[160:161], v[160:161], s[18:19]
	v_pk_mul_f32 v[154:155], v[154:155], s[18:19]
	v_pk_mul_f32 v[166:167], v[166:167], s[18:19]
	v_exp_f32_e32 v128, v128
	v_exp_f32_e32 v129, v129
	v_exp_f32_e32 v156, v156
	v_exp_f32_e32 v157, v157
	v_exp_f32_e32 v130, v130
	v_exp_f32_e32 v131, v131
	v_exp_f32_e32 v158, v158
	v_exp_f32_e32 v159, v159
	v_exp_f32_e32 v152, v152
	v_exp_f32_e32 v153, v153
	v_exp_f32_e32 v160, v160
	v_exp_f32_e32 v161, v161
	v_exp_f32_e32 v154, v154
	v_exp_f32_e32 v155, v155
	v_exp_f32_e32 v166, v166
	v_exp_f32_e32 v167, v167
	v_pk_add_f32 v[128:129], v[128:129], 1.0 op_sel_hi:[1,0]
	v_pk_add_f32 v[156:157], v[156:157], 1.0 op_sel_hi:[1,0]
	v_pk_add_f32 v[130:131], v[130:131], 1.0 op_sel_hi:[1,0]
	v_pk_add_f32 v[158:159], v[158:159], 1.0 op_sel_hi:[1,0]
	v_pk_add_f32 v[152:153], v[152:153], 1.0 op_sel_hi:[1,0]
	v_pk_add_f32 v[160:161], v[160:161], 1.0 op_sel_hi:[1,0]
	v_pk_add_f32 v[154:155], v[154:155], 1.0 op_sel_hi:[1,0]
	v_pk_add_f32 v[166:167], v[166:167], 1.0 op_sel_hi:[1,0]
	v_rcp_f32_e32 v128, v128
	v_rcp_f32_e32 v129, v129
	v_rcp_f32_e32 v130, v130
	v_rcp_f32_e32 v131, v131
	v_rcp_f32_e32 v152, v152
	v_rcp_f32_e32 v153, v153
	v_rcp_f32_e32 v154, v154
	v_rcp_f32_e32 v155, v155
	v_pk_mul_f32 v[128:129], v[128:129], v[156:157]
	v_pk_mul_f32 v[130:131], v[130:131], v[158:159]
	v_pk_mul_f32 v[152:153], v[152:153], v[160:161]
	v_pk_mul_f32 v[154:155], v[154:155], v[166:167]
	v_pk_mul_f32 v[60:61], v[60:61], v[128:129]
	v_pk_mul_f32 v[62:63], v[62:63], v[130:131]
	v_pk_mul_f32 v[56:57], v[56:57], v[152:153]
	v_pk_mul_f32 v[58:59], v[58:59], v[154:155]
	v_lshlrev_b32_e32 v128, 16, v220
	v_and_b32_e32 v129, 0xffff0000, v220
	v_lshlrev_b32_e32 v156, 16, v228
	v_and_b32_e32 v157, 0xffff0000, v228
	v_lshlrev_b32_e32 v130, 16, v221
	v_and_b32_e32 v131, 0xffff0000, v221
	v_lshlrev_b32_e32 v158, 16, v229
	v_and_b32_e32 v159, 0xffff0000, v229
	v_lshlrev_b32_e32 v152, 16, v222
	v_and_b32_e32 v153, 0xffff0000, v222
	v_lshlrev_b32_e32 v160, 16, v230
	v_and_b32_e32 v161, 0xffff0000, v230
	v_lshlrev_b32_e32 v154, 16, v223
	v_and_b32_e32 v155, 0xffff0000, v223
	v_lshlrev_b32_e32 v166, 16, v231
	v_and_b32_e32 v167, 0xffff0000, v231
	v_pk_mul_f32 v[128:129], v[128:129], s[18:19]
	v_pk_mul_f32 v[156:157], v[156:157], s[18:19]
	v_pk_mul_f32 v[130:131], v[130:131], s[18:19]
	v_pk_mul_f32 v[158:159], v[158:159], s[18:19]
	v_pk_mul_f32 v[152:153], v[152:153], s[18:19]
	v_pk_mul_f32 v[160:161], v[160:161], s[18:19]
	v_pk_mul_f32 v[154:155], v[154:155], s[18:19]
	v_pk_mul_f32 v[166:167], v[166:167], s[18:19]
	v_exp_f32_e32 v128, v128
	v_exp_f32_e32 v129, v129
	v_exp_f32_e32 v156, v156
	v_exp_f32_e32 v157, v157
	v_exp_f32_e32 v130, v130
	v_exp_f32_e32 v131, v131
	v_exp_f32_e32 v158, v158
	v_exp_f32_e32 v159, v159
	v_exp_f32_e32 v152, v152
	v_exp_f32_e32 v153, v153
	v_exp_f32_e32 v160, v160
	v_exp_f32_e32 v161, v161
	v_exp_f32_e32 v154, v154
	v_exp_f32_e32 v155, v155
	v_exp_f32_e32 v166, v166
	v_exp_f32_e32 v167, v167
	v_pk_add_f32 v[128:129], v[128:129], 1.0 op_sel_hi:[1,0]
	v_pk_add_f32 v[156:157], v[156:157], 1.0 op_sel_hi:[1,0]
	v_pk_add_f32 v[130:131], v[130:131], 1.0 op_sel_hi:[1,0]
	v_pk_add_f32 v[158:159], v[158:159], 1.0 op_sel_hi:[1,0]
	v_pk_add_f32 v[152:153], v[152:153], 1.0 op_sel_hi:[1,0]
	v_pk_add_f32 v[160:161], v[160:161], 1.0 op_sel_hi:[1,0]
	v_pk_add_f32 v[154:155], v[154:155], 1.0 op_sel_hi:[1,0]
	v_pk_add_f32 v[166:167], v[166:167], 1.0 op_sel_hi:[1,0]
	v_rcp_f32_e32 v128, v128
	v_rcp_f32_e32 v129, v129
	v_rcp_f32_e32 v130, v130
	v_rcp_f32_e32 v131, v131
	v_rcp_f32_e32 v152, v152
	v_rcp_f32_e32 v153, v153
	v_rcp_f32_e32 v154, v154
	v_rcp_f32_e32 v155, v155
	v_pk_mul_f32 v[128:129], v[128:129], v[156:157]
	v_pk_mul_f32 v[130:131], v[130:131], v[158:159]
	v_pk_mul_f32 v[152:153], v[152:153], v[160:161]
	v_pk_mul_f32 v[154:155], v[154:155], v[166:167]
	v_pk_mul_f32 v[28:29], v[28:29], v[128:129]
	v_pk_mul_f32 v[30:31], v[30:31], v[130:131]
	v_pk_mul_f32 v[24:25], v[24:25], v[152:153]
	v_pk_mul_f32 v[26:27], v[26:27], v[154:155]
	global_load_dwordx4 v[196:199], v[218:219], off
	global_load_dwordx4 v[224:227], v[218:219], off offset:2048
	global_load_dwordx4 v[220:223], v[218:219], off offset:256
	global_load_dwordx4 v[228:231], v[218:219], off offset:2304
	s_waitcnt vmcnt(8)
; DEV float bflo(unsigned w) { return __uint_as_float(w << 16); }
; DEV float bfhi(unsigned w) { return __uint_as_float(w & 0xffff0000u); }
; #define RS_(xa, xb) ((1.0f + one * __expf(-(xb))) * __builtin_amdgcn_rcpf(1.0f + __expf(-(xa))))
;   DEV bool rescale(f32x4 (&acc)[2][2][4][2], const Unit& u, int wr, int wc, int fr, int fq) const {
;     ...
;         const size_t r = (size_t)(row0 + ai * HALF + m * 16);
; #pragma unroll
;         for (int bj = 0; bj < 2; ++bj) {
;           const int c = col0 + bj * HALF;
;           const u32x4 ga = *(const u32x4*)(Z + r * NIN + GT + u.seg * D + c);
;           const u32x4 gb = *(const u32x4*)(Z + r * NIN + GT + sb * D + c);
;     ...
;           acc[ai][bj][m][0][0] *= RS_(bflo(ga.x), bflo(gb.x)); acc[ai][bj][m][0][1] *= RS_(bfhi(ga.x), bfhi(gb.x));
;           acc[ai][bj][m][0][2] *= RS_(bflo(ga.y), bflo(gb.y)); acc[ai][bj][m][0][3] *= RS_(bfhi(ga.y), bfhi(gb.y));
;           acc[ai][bj][m][1][0] *= RS_(bflo(ga.z), bflo(gb.z)); acc[ai][bj][m][1][1] *= RS_(bfhi(ga.z), bfhi(gb.z));
;           acc[ai][bj][m][1][2] *= RS_(bflo(ga.w), bflo(gb.w)); acc[ai][bj][m][1][3] *= RS_(bfhi(ga.w), bfhi(gb.w));
	v_lshlrev_b32_e32 v128, 16, v232
	v_and_b32_e32 v129, 0xffff0000, v232
	v_lshlrev_b32_e32 v156, 16, v240
	v_and_b32_e32 v157, 0xffff0000, v240
	v_lshlrev_b32_e32 v130, 16, v233
	v_and_b32_e32 v131, 0xffff0000, v233
	v_lshlrev_b32_e32 v158, 16, v241
	v_and_b32_e32 v159, 0xffff0000, v241
	v_lshlrev_b32_e32 v152, 16, v234
	v_and_b32_e32 v153, 0xffff0000, v234
	v_lshlrev_b32_e32 v160, 16, v242
	v_and_b32_e32 v161, 0xffff0000, v242
	v_lshlrev_b32_e32 v154, 16, v235
	v_and_b32_e32 v155, 0xffff0000, v235
	v_lshlrev_b32_e32 v166, 16, v243
	v_and_b32_e32 v167, 0xffff0000, v243
	v_pk_mul_f32 v[128:129], v[128:129], s[18:19]
	v_pk_mul_f32 v[156:157], v[156:157], s[18:19]
	v_pk_mul_f32 v[130:131], v[130:131], s[18:19]
	v_pk_mul_f32 v[158:159], v[158:159], s[18:19]
	v_pk_mul_f32 v[152:153], v[152:153], s[18:19]
	v_pk_mul_f32 v[160:161], v[160:161], s[18:19]
	v_pk_mul_f32 v[154:155], v[154:155], s[18:19]
	v_pk_mul_f32 v[166:167], v[166:167], s[18:19]
	v_exp_f32_e32 v128, v128
	v_exp_f32_e32 v129, v129
	v_exp_f32_e32 v156, v156
	v_exp_f32_e32 v157, v157
	v_exp_f32_e32 v130, v130
	v_exp_f32_e32 v131, v131
	v_exp_f32_e32 v158, v158
	v_exp_f32_e32 v159, v159
	v_exp_f32_e32 v152, v152
	v_exp_f32_e32 v153, v153
	v_exp_f32_e32 v160, v160
	v_exp_f32_e32 v161, v161
	v_exp_f32_e32 v154, v154
	v_exp_f32_e32 v155, v155
	v_exp_f32_e32 v166, v166
	v_exp_f32_e32 v167, v167
	v_pk_add_f32 v[128:129], v[128:129], 1.0 op_sel_hi:[1,0]
	v_pk_add_f32 v[156:157], v[156:157], 1.0 op_sel_hi:[1,0]
	v_pk_add_f32 v[130:131], v[130:131], 1.0 op_sel_hi:[1,0]
	v_pk_add_f32 v[158:159], v[158:159], 1.0 op_sel_hi:[1,0]
	v_pk_add_f32 v[152:153], v[152:153], 1.0 op_sel_hi:[1,0]
	v_pk_add_f32 v[160:161], v[160:161], 1.0 op_sel_hi:[1,0]
	v_pk_add_f32 v[154:155], v[154:155], 1.0 op_sel_hi:[1,0]
	v_pk_add_f32 v[166:167], v[166:167], 1.0 op_sel_hi:[1,0]
	v_rcp_f32_e32 v128, v128
	v_rcp_f32_e32 v129, v129
	v_rcp_f32_e32 v130, v130
	v_rcp_f32_e32 v131, v131
	v_rcp_f32_e32 v152, v152
	v_rcp_f32_e32 v153, v153
	v_rcp_f32_e32 v154, v154
	v_rcp_f32_e32 v155, v155
	v_pk_mul_f32 v[128:129], v[128:129], v[156:157]
	v_pk_mul_f32 v[130:131], v[130:131], v[158:159]
	v_pk_mul_f32 v[152:153], v[152:153], v[160:161]
	v_pk_mul_f32 v[154:155], v[154:155], v[166:167]
	v_pk_mul_f32 v[52:53], v[52:53], v[128:129]
	v_pk_mul_f32 v[54:55], v[54:55], v[130:131]
	v_pk_mul_f32 v[48:49], v[48:49], v[152:153]
	v_pk_mul_f32 v[50:51], v[50:51], v[154:155]
	v_lshlrev_b32_e32 v128, 16, v236
	v_and_b32_e32 v129, 0xffff0000, v236
	v_lshlrev_b32_e32 v156, 16, v148
	v_and_b32_e32 v157, 0xffff0000, v148
	v_lshlrev_b32_e32 v130, 16, v237
	v_and_b32_e32 v131, 0xffff0000, v237
	v_lshlrev_b32_e32 v158, 16, v149
	v_and_b32_e32 v159, 0xffff0000, v149
	v_lshlrev_b32_e32 v152, 16, v238
	v_and_b32_e32 v153, 0xffff0000, v238
	v_lshlrev_b32_e32 v160, 16, v150
	v_and_b32_e32 v161, 0xffff0000, v150
	v_lshlrev_b32_e32 v154, 16, v239
	v_and_b32_e32 v155, 0xffff0000, v239
	v_lshlrev_b32_e32 v166, 16, v151
	v_and_b32_e32 v167, 0xffff0000, v151
	v_pk_mul_f32 v[128:129], v[128:129], s[18:19]
	v_pk_mul_f32 v[156:157], v[156:157], s[18:19]
	v_pk_mul_f32 v[130:131], v[130:131], s[18:19]
	v_pk_mul_f32 v[158:159], v[158:159], s[18:19]
	v_pk_mul_f32 v[152:153], v[152:153], s[18:19]
	v_pk_mul_f32 v[160:161], v[160:161], s[18:19]
	v_pk_mul_f32 v[154:155], v[154:155], s[18:19]
	v_pk_mul_f32 v[166:167], v[166:167], s[18:19]
	v_exp_f32_e32 v128, v128
	v_exp_f32_e32 v129, v129
	v_exp_f32_e32 v156, v156
	v_exp_f32_e32 v157, v157
	v_exp_f32_e32 v130, v130
	v_exp_f32_e32 v131, v131
	v_exp_f32_e32 v158, v158
	v_exp_f32_e32 v159, v159
	v_exp_f32_e32 v152, v152
	v_exp_f32_e32 v153, v153
	v_exp_f32_e32 v160, v160
	v_exp_f32_e32 v161, v161
	v_exp_f32_e32 v154, v154
	v_exp_f32_e32 v155, v155
	v_exp_f32_e32 v166, v166
	v_exp_f32_e32 v167, v167
	v_pk_add_f32 v[128:129], v[128:129], 1.0 op_sel_hi:[1,0]
	v_pk_add_f32 v[156:157], v[156:157], 1.0 op_sel_hi:[1,0]
	v_pk_add_f32 v[130:131], v[130:131], 1.0 op_sel_hi:[1,0]
	v_pk_add_f32 v[158:159], v[158:159], 1.0 op_sel_hi:[1,0]
	v_pk_add_f32 v[152:153], v[152:153], 1.0 op_sel_hi:[1,0]
	v_pk_add_f32 v[160:161], v[160:161], 1.0 op_sel_hi:[1,0]
	v_pk_add_f32 v[154:155], v[154:155], 1.0 op_sel_hi:[1,0]
	v_pk_add_f32 v[166:167], v[166:167], 1.0 op_sel_hi:[1,0]
	v_rcp_f32_e32 v128, v128
	v_rcp_f32_e32 v129, v129
	v_rcp_f32_e32 v130, v130
	v_rcp_f32_e32 v131, v131
	v_rcp_f32_e32 v152, v152
	v_rcp_f32_e32 v153, v153
	v_rcp_f32_e32 v154, v154
	v_rcp_f32_e32 v155, v155
	v_pk_mul_f32 v[128:129], v[128:129], v[156:157]
	v_pk_mul_f32 v[130:131], v[130:131], v[158:159]
	v_pk_mul_f32 v[152:153], v[152:153], v[160:161]
	v_pk_mul_f32 v[154:155], v[154:155], v[166:167]
	v_pk_mul_f32 v[20:21], v[20:21], v[128:129]
	v_pk_mul_f32 v[22:23], v[22:23], v[130:131]
	v_pk_mul_f32 v[16:17], v[16:17], v[152:153]
	v_pk_mul_f32 v[18:19], v[18:19], v[154:155]
	s_waitcnt vmcnt(4)
; DEV float bflo(unsigned w) { return __uint_as_float(w << 16); }
; DEV float bfhi(unsigned w) { return __uint_as_float(w & 0xffff0000u); }
; #define RS_(xa, xb) ((1.0f + one * __expf(-(xb))) * __builtin_amdgcn_rcpf(1.0f + __expf(-(xa))))
;   DEV bool rescale(f32x4 (&acc)[2][2][4][2], const Unit& u, int wr, int wc, int fr, int fq) const {
;     ...
;         const size_t r = (size_t)(row0 + ai * HALF + m * 16);
; #pragma unroll
;         for (int bj = 0; bj < 2; ++bj) {
;           const int c = col0 + bj * HALF;
;           const u32x4 ga = *(const u32x4*)(Z + r * NIN + GT + u.seg * D + c);
;           const u32x4 gb = *(const u32x4*)(Z + r * NIN + GT + sb * D + c);
;     ...
;           acc[ai][bj][m][0][0] *= RS_(bflo(ga.x), bflo(gb.x)); acc[ai][bj][m][0][1] *= RS_(bfhi(ga.x), bfhi(gb.x));
;           acc[ai][bj][m][0][2] *= RS_(bflo(ga.y), bflo(gb.y)); acc[ai][bj][m][0][3] *= RS_(bfhi(ga.y), bfhi(gb.y));
;           acc[ai][bj][m][1][0] *= RS_(bflo(ga.z), bflo(gb.z)); acc[ai][bj][m][1][1] *= RS_(bfhi(ga.z), bfhi(gb.z));
;           acc[ai][bj][m][1][2] *= RS_(bflo(ga.w), bflo(gb.w)); acc[ai][bj][m][1][3] *= RS_(bfhi(ga.w), bfhi(gb.w));
	v_lshlrev_b32_e32 v128, 16, v180
	v_and_b32_e32 v129, 0xffff0000, v180
	v_lshlrev_b32_e32 v156, 16, v188
	v_and_b32_e32 v157, 0xffff0000, v188
	v_lshlrev_b32_e32 v130, 16, v181
	v_and_b32_e32 v131, 0xffff0000, v181
	v_lshlrev_b32_e32 v158, 16, v189
	v_and_b32_e32 v159, 0xffff0000, v189
	v_lshlrev_b32_e32 v152, 16, v182
	v_and_b32_e32 v153, 0xffff0000, v182
	v_lshlrev_b32_e32 v160, 16, v190
	v_and_b32_e32 v161, 0xffff0000, v190
	v_lshlrev_b32_e32 v154, 16, v183
	v_and_b32_e32 v155, 0xffff0000, v183
	v_lshlrev_b32_e32 v166, 16, v191
	v_and_b32_e32 v167, 0xffff0000, v191
	v_pk_mul_f32 v[128:129], v[128:129], s[18:19]
	v_pk_mul_f32 v[156:157], v[156:157], s[18:19]
	v_pk_mul_f32 v[130:131], v[130:131], s[18:19]
	v_pk_mul_f32 v[158:159], v[158:159], s[18:19]
	v_pk_mul_f32 v[152:153], v[152:153], s[18:19]
	v_pk_mul_f32 v[160:161], v[160:161], s[18:19]
	v_pk_mul_f32 v[154:155], v[154:155], s[18:19]
	v_pk_mul_f32 v[166:167], v[166:167], s[18:19]
	v_exp_f32_e32 v128, v128
	v_exp_f32_e32 v129, v129
	v_exp_f32_e32 v156, v156
	v_exp_f32_e32 v157, v157
	v_exp_f32_e32 v130, v130
	v_exp_f32_e32 v131, v131
	v_exp_f32_e32 v158, v158
	v_exp_f32_e32 v159, v159
	v_exp_f32_e32 v152, v152
	v_exp_f32_e32 v153, v153
	v_exp_f32_e32 v160, v160
	v_exp_f32_e32 v161, v161
	v_exp_f32_e32 v154, v154
	v_exp_f32_e32 v155, v155
	v_exp_f32_e32 v166, v166
	v_exp_f32_e32 v167, v167
	v_pk_add_f32 v[128:129], v[128:129], 1.0 op_sel_hi:[1,0]
	v_pk_add_f32 v[156:157], v[156:157], 1.0 op_sel_hi:[1,0]
	v_pk_add_f32 v[130:131], v[130:131], 1.0 op_sel_hi:[1,0]
	v_pk_add_f32 v[158:159], v[158:159], 1.0 op_sel_hi:[1,0]
	v_pk_add_f32 v[152:153], v[152:153], 1.0 op_sel_hi:[1,0]
	v_pk_add_f32 v[160:161], v[160:161], 1.0 op_sel_hi:[1,0]
	v_pk_add_f32 v[154:155], v[154:155], 1.0 op_sel_hi:[1,0]
	v_pk_add_f32 v[166:167], v[166:167], 1.0 op_sel_hi:[1,0]
	v_rcp_f32_e32 v128, v128
	v_rcp_f32_e32 v129, v129
	v_rcp_f32_e32 v130, v130
	v_rcp_f32_e32 v131, v131
	v_rcp_f32_e32 v152, v152
	v_rcp_f32_e32 v153, v153
	v_rcp_f32_e32 v154, v154
	v_rcp_f32_e32 v155, v155
	v_pk_mul_f32 v[128:129], v[128:129], v[156:157]
	v_pk_mul_f32 v[130:131], v[130:131], v[158:159]
	v_pk_mul_f32 v[152:153], v[152:153], v[160:161]
	v_pk_mul_f32 v[154:155], v[154:155], v[166:167]
	v_pk_mul_f32 v[44:45], v[44:45], v[128:129]
	v_pk_mul_f32 v[46:47], v[46:47], v[130:131]
	v_pk_mul_f32 v[40:41], v[40:41], v[152:153]
	v_pk_mul_f32 v[42:43], v[42:43], v[154:155]
	v_lshlrev_b32_e32 v128, 16, v184
	v_and_b32_e32 v129, 0xffff0000, v184
	v_lshlrev_b32_e32 v156, 16, v192
	v_and_b32_e32 v157, 0xffff0000, v192
	v_lshlrev_b32_e32 v130, 16, v185
	v_and_b32_e32 v131, 0xffff0000, v185
	v_lshlrev_b32_e32 v158, 16, v193
	v_and_b32_e32 v159, 0xffff0000, v193
	v_lshlrev_b32_e32 v152, 16, v186
	v_and_b32_e32 v153, 0xffff0000, v186
	v_lshlrev_b32_e32 v160, 16, v194
	v_and_b32_e32 v161, 0xffff0000, v194
	v_lshlrev_b32_e32 v154, 16, v187
	v_and_b32_e32 v155, 0xffff0000, v187
	v_lshlrev_b32_e32 v166, 16, v195
	v_and_b32_e32 v167, 0xffff0000, v195
	v_pk_mul_f32 v[128:129], v[128:129], s[18:19]
	v_pk_mul_f32 v[156:157], v[156:157], s[18:19]
	v_pk_mul_f32 v[130:131], v[130:131], s[18:19]
	v_pk_mul_f32 v[158:159], v[158:159], s[18:19]
	v_pk_mul_f32 v[152:153], v[152:153], s[18:19]
	v_pk_mul_f32 v[160:161], v[160:161], s[18:19]
	v_pk_mul_f32 v[154:155], v[154:155], s[18:19]
	v_pk_mul_f32 v[166:167], v[166:167], s[18:19]
	v_exp_f32_e32 v128, v128
	v_exp_f32_e32 v129, v129
	v_exp_f32_e32 v156, v156
	v_exp_f32_e32 v157, v157
	v_exp_f32_e32 v130, v130
	v_exp_f32_e32 v131, v131
	v_exp_f32_e32 v158, v158
	v_exp_f32_e32 v159, v159
	v_exp_f32_e32 v152, v152
	v_exp_f32_e32 v153, v153
	v_exp_f32_e32 v160, v160
	v_exp_f32_e32 v161, v161
	v_exp_f32_e32 v154, v154
	v_exp_f32_e32 v155, v155
	v_exp_f32_e32 v166, v166
	v_exp_f32_e32 v167, v167
	v_pk_add_f32 v[128:129], v[128:129], 1.0 op_sel_hi:[1,0]
	v_pk_add_f32 v[156:157], v[156:157], 1.0 op_sel_hi:[1,0]
	v_pk_add_f32 v[130:131], v[130:131], 1.0 op_sel_hi:[1,0]
	v_pk_add_f32 v[158:159], v[158:159], 1.0 op_sel_hi:[1,0]
	v_pk_add_f32 v[152:153], v[152:153], 1.0 op_sel_hi:[1,0]
	v_pk_add_f32 v[160:161], v[160:161], 1.0 op_sel_hi:[1,0]
	v_pk_add_f32 v[154:155], v[154:155], 1.0 op_sel_hi:[1,0]
	v_pk_add_f32 v[166:167], v[166:167], 1.0 op_sel_hi:[1,0]
	v_rcp_f32_e32 v128, v128
	v_rcp_f32_e32 v129, v129
	v_rcp_f32_e32 v130, v130
	v_rcp_f32_e32 v131, v131
	v_rcp_f32_e32 v152, v152
	v_rcp_f32_e32 v153, v153
	v_rcp_f32_e32 v154, v154
	v_rcp_f32_e32 v155, v155
	v_pk_mul_f32 v[128:129], v[128:129], v[156:157]
	v_pk_mul_f32 v[130:131], v[130:131], v[158:159]
	v_pk_mul_f32 v[152:153], v[152:153], v[160:161]
	v_pk_mul_f32 v[154:155], v[154:155], v[166:167]
	v_pk_mul_f32 v[12:13], v[12:13], v[128:129]
	v_pk_mul_f32 v[14:15], v[14:15], v[130:131]
	v_pk_mul_f32 v[8:9], v[8:9], v[152:153]
	v_pk_mul_f32 v[10:11], v[10:11], v[154:155]
	s_waitcnt vmcnt(0)
; DEV float bflo(unsigned w) { return __uint_as_float(w << 16); }
; DEV float bfhi(unsigned w) { return __uint_as_float(w & 0xffff0000u); }
; #define RS_(xa, xb) ((1.0f + one * __expf(-(xb))) * __builtin_amdgcn_rcpf(1.0f + __expf(-(xa))))
;   DEV bool rescale(f32x4 (&acc)[2][2][4][2], const Unit& u, int wr, int wc, int fr, int fq) const {
;     ...
;         const size_t r = (size_t)(row0 + ai * HALF + m * 16);
; #pragma unroll
;         for (int bj = 0; bj < 2; ++bj) {
;           const int c = col0 + bj * HALF;
;           const u32x4 ga = *(const u32x4*)(Z + r * NIN + GT + u.seg * D + c);
;           const u32x4 gb = *(const u32x4*)(Z + r * NIN + GT + sb * D + c);
;     ...
;           acc[ai][bj][m][0][0] *= RS_(bflo(ga.x), bflo(gb.x)); acc[ai][bj][m][0][1] *= RS_(bfhi(ga.x), bfhi(gb.x));
;           acc[ai][bj][m][0][2] *= RS_(bflo(ga.y), bflo(gb.y)); acc[ai][bj][m][0][3] *= RS_(bfhi(ga.y), bfhi(gb.y));
;           acc[ai][bj][m][1][0] *= RS_(bflo(ga.z), bflo(gb.z)); acc[ai][bj][m][1][1] *= RS_(bfhi(ga.z), bfhi(gb.z));
;           acc[ai][bj][m][1][2] *= RS_(bflo(ga.w), bflo(gb.w)); acc[ai][bj][m][1][3] *= RS_(bfhi(ga.w), bfhi(gb.w));
	v_lshlrev_b32_e32 v128, 16, v196
	v_and_b32_e32 v129, 0xffff0000, v196
	v_lshlrev_b32_e32 v156, 16, v224
	v_and_b32_e32 v157, 0xffff0000, v224
	v_lshlrev_b32_e32 v130, 16, v197
	v_and_b32_e32 v131, 0xffff0000, v197
	v_lshlrev_b32_e32 v158, 16, v225
	v_and_b32_e32 v159, 0xffff0000, v225
	v_lshlrev_b32_e32 v152, 16, v198
	v_and_b32_e32 v153, 0xffff0000, v198
	v_lshlrev_b32_e32 v160, 16, v226
	v_and_b32_e32 v161, 0xffff0000, v226
	v_lshlrev_b32_e32 v154, 16, v199
	v_and_b32_e32 v155, 0xffff0000, v199
	v_lshlrev_b32_e32 v166, 16, v227
	v_and_b32_e32 v167, 0xffff0000, v227
	v_pk_mul_f32 v[128:129], v[128:129], s[18:19]
	v_pk_mul_f32 v[156:157], v[156:157], s[18:19]
	v_pk_mul_f32 v[130:131], v[130:131], s[18:19]
	v_pk_mul_f32 v[158:159], v[158:159], s[18:19]
	v_pk_mul_f32 v[152:153], v[152:153], s[18:19]
	v_pk_mul_f32 v[160:161], v[160:161], s[18:19]
	v_pk_mul_f32 v[154:155], v[154:155], s[18:19]
	v_pk_mul_f32 v[166:167], v[166:167], s[18:19]
	v_exp_f32_e32 v128, v128
	v_exp_f32_e32 v129, v129
	v_exp_f32_e32 v156, v156
	v_exp_f32_e32 v157, v157
	v_exp_f32_e32 v130, v130
	v_exp_f32_e32 v131, v131
	v_exp_f32_e32 v158, v158
	v_exp_f32_e32 v159, v159
	v_exp_f32_e32 v152, v152
	v_exp_f32_e32 v153, v153
	v_exp_f32_e32 v160, v160
	v_exp_f32_e32 v161, v161
	v_exp_f32_e32 v154, v154
	v_exp_f32_e32 v155, v155
	v_exp_f32_e32 v166, v166
	v_exp_f32_e32 v167, v167
	v_pk_add_f32 v[128:129], v[128:129], 1.0 op_sel_hi:[1,0]
	v_pk_add_f32 v[156:157], v[156:157], 1.0 op_sel_hi:[1,0]
	v_pk_add_f32 v[130:131], v[130:131], 1.0 op_sel_hi:[1,0]
	v_pk_add_f32 v[158:159], v[158:159], 1.0 op_sel_hi:[1,0]
	v_pk_add_f32 v[152:153], v[152:153], 1.0 op_sel_hi:[1,0]
	v_pk_add_f32 v[160:161], v[160:161], 1.0 op_sel_hi:[1,0]
	v_pk_add_f32 v[154:155], v[154:155], 1.0 op_sel_hi:[1,0]
	v_pk_add_f32 v[166:167], v[166:167], 1.0 op_sel_hi:[1,0]
	v_rcp_f32_e32 v128, v128
	v_rcp_f32_e32 v129, v129
	v_rcp_f32_e32 v130, v130
	v_rcp_f32_e32 v131, v131
	v_rcp_f32_e32 v152, v152
	v_rcp_f32_e32 v153, v153
	v_rcp_f32_e32 v154, v154
	v_rcp_f32_e32 v155, v155
	v_pk_mul_f32 v[128:129], v[128:129], v[156:157]
	v_pk_mul_f32 v[130:131], v[130:131], v[158:159]
	v_pk_mul_f32 v[152:153], v[152:153], v[160:161]
	v_pk_mul_f32 v[154:155], v[154:155], v[166:167]
	v_pk_mul_f32 v[36:37], v[36:37], v[128:129]
	v_pk_mul_f32 v[38:39], v[38:39], v[130:131]
	v_pk_mul_f32 v[32:33], v[32:33], v[152:153]
	v_pk_mul_f32 v[34:35], v[34:35], v[154:155]
	v_lshlrev_b32_e32 v128, 16, v220
	v_and_b32_e32 v129, 0xffff0000, v220
	v_lshlrev_b32_e32 v156, 16, v228
	v_and_b32_e32 v157, 0xffff0000, v228
	v_lshlrev_b32_e32 v130, 16, v221
	v_and_b32_e32 v131, 0xffff0000, v221
	v_lshlrev_b32_e32 v158, 16, v229
	v_and_b32_e32 v159, 0xffff0000, v229
	v_lshlrev_b32_e32 v152, 16, v222
	v_and_b32_e32 v153, 0xffff0000, v222
	v_lshlrev_b32_e32 v160, 16, v230
	v_and_b32_e32 v161, 0xffff0000, v230
	v_lshlrev_b32_e32 v154, 16, v223
	v_and_b32_e32 v155, 0xffff0000, v223
	v_lshlrev_b32_e32 v166, 16, v231
	v_and_b32_e32 v167, 0xffff0000, v231
	v_pk_mul_f32 v[128:129], v[128:129], s[18:19]
	v_pk_mul_f32 v[156:157], v[156:157], s[18:19]
	v_pk_mul_f32 v[130:131], v[130:131], s[18:19]
	v_pk_mul_f32 v[158:159], v[158:159], s[18:19]
	v_pk_mul_f32 v[152:153], v[152:153], s[18:19]
	v_pk_mul_f32 v[160:161], v[160:161], s[18:19]
	v_pk_mul_f32 v[154:155], v[154:155], s[18:19]
	v_pk_mul_f32 v[166:167], v[166:167], s[18:19]
	v_exp_f32_e32 v128, v128
	v_exp_f32_e32 v129, v129
	v_exp_f32_e32 v156, v156
	v_exp_f32_e32 v157, v157
	v_exp_f32_e32 v130, v130
	v_exp_f32_e32 v131, v131
	v_exp_f32_e32 v158, v158
	v_exp_f32_e32 v159, v159
	v_exp_f32_e32 v152, v152
	v_exp_f32_e32 v153, v153
	v_exp_f32_e32 v160, v160
	v_exp_f32_e32 v161, v161
	v_exp_f32_e32 v154, v154
	v_exp_f32_e32 v155, v155
	v_exp_f32_e32 v166, v166
	v_exp_f32_e32 v167, v167
	v_pk_add_f32 v[128:129], v[128:129], 1.0 op_sel_hi:[1,0]
	v_pk_add_f32 v[156:157], v[156:157], 1.0 op_sel_hi:[1,0]
	v_pk_add_f32 v[130:131], v[130:131], 1.0 op_sel_hi:[1,0]
	v_pk_add_f32 v[158:159], v[158:159], 1.0 op_sel_hi:[1,0]
	v_pk_add_f32 v[152:153], v[152:153], 1.0 op_sel_hi:[1,0]
	v_pk_add_f32 v[160:161], v[160:161], 1.0 op_sel_hi:[1,0]
	v_pk_add_f32 v[154:155], v[154:155], 1.0 op_sel_hi:[1,0]
	v_pk_add_f32 v[166:167], v[166:167], 1.0 op_sel_hi:[1,0]
	v_rcp_f32_e32 v128, v128
	v_rcp_f32_e32 v129, v129
	v_rcp_f32_e32 v130, v130
	v_rcp_f32_e32 v131, v131
	v_rcp_f32_e32 v152, v152
	v_rcp_f32_e32 v153, v153
	v_rcp_f32_e32 v154, v154
	v_rcp_f32_e32 v155, v155
	v_pk_mul_f32 v[128:129], v[128:129], v[156:157]
	v_pk_mul_f32 v[130:131], v[130:131], v[158:159]
	v_pk_mul_f32 v[152:153], v[152:153], v[160:161]
	v_pk_mul_f32 v[154:155], v[154:155], v[166:167]
	v_pk_mul_f32 v[4:5], v[4:5], v[128:129]
	v_pk_mul_f32 v[6:7], v[6:7], v[130:131]
	v_pk_mul_f32 v[0:1], v[0:1], v[152:153]
	v_pk_mul_f32 v[2:3], v[2:3], v[154:155]
	s_branch .LBB0_322

; #define PG8_STAGE(bufoff, gbase, voff) do { _Pragma("unroll") for (int _i = 0; _i < 2; ++_i) \
;     __builtin_amdgcn_global_load_lds((const unsigned*)((const char*)(gbase) + (voff)[_i]), (PG8_LAS unsigned*)(lds + (bufoff) + ldsw + _i * 8192), 16, 0, 0); } while (0)
; #define PG8_LDA(dst, b, h) do { _Pragma("unroll") for (int m = 0; m < 4; ++m) _Pragma("unroll") for (int k = 0; k < 2; ++k) dst[m][k] = *(const PG8_LAS bf16x8*)(lds + PG8_SA(b, h) + aoff + m * 2048 + k * 1024); } while (0)
; #define PG8_LDB(dst, b, h) do { _Pragma("unroll") for (int n = 0; n < 2; ++n) _Pragma("unroll") for (int k = 0; k < 2; ++k) dst[n][k] = *(const PG8_LAS bf16x8*)(lds + PG8_SB(b, h) + boff + n * 2048 + k * 1024); } while (0)
; #define PG8_MMA(ai, bj, At, Bt) do { __builtin_amdgcn_s_setprio(1); _Pragma("unroll") for (int m = 0; m < 4; ++m) _Pragma("unroll") for (int n = 0; n < 2; ++n) _Pragma("unroll") for (int k = 0; k < 2; ++k) \
;     acc[ai][bj][m][n] = __builtin_amdgcn_mfma_f32_16x16x32_bf16(Bt[n][k], At[m][k], acc[ai][bj][m][n], 0, 0, 0); __builtin_amdgcn_s_setprio(0); } while (0)
; #define PG8_WAIT_V(n) asm volatile("s_waitcnt vmcnt(" #n ")" ::: "memory")
; #define PG8_WAIT_L(n) asm volatile("s_waitcnt lgkmcnt(" #n ")" ::: "memory")
; #define PG8_BAR __builtin_amdgcn_s_barrier()
; #define PG8_SCHED __builtin_amdgcn_sched_barrier(0)
; template <class Epi, bool SEQ>
; DEV void gemm_phase(PG8_LAS unsigned char* lds, const Gemm g, const Epi& E) {
;     ...
;     const char* nA = has_next ? PG8_ABASE(nxt) : cA; const char* nB = has_next ? PG8_BBASE(nxt) : cB;
;     for (int t = 0; t < nt; t += 2) {
;       const bool last = (t == nt - 2);
;       const char* a1 = cA + (size_t)(t + 1) * kstep;
;       const char* a2 = last ? nA : cA + (size_t)(t + 2) * kstep; const char* b2 = last ? nB : cB + (size_t)(t + 2) * kstep;
;       const char* a3 = a2 + kstep; const char* b3 = b2 + kstep;
;       PG8_LDB(B0, 0, 0); PG8_LDB(B1, 0, 1); PG8_SCHED; PG8_LDA(At, 0, 0); PG8_STAGE(PG8_SA(1, 1), a1 + hstepA, voffA);
;       PG8_WAIT_V(8); PG8_WAIT_L(0); PG8_BAR; PG8_MMA(0, 0, At, B0); PG8_MMA(0, 1, At, B1); PG8_BAR; PG8_SCHED;
;     ...
; #pragma unroll
;       for (int a = 0; a < 2; ++a)
; #pragma unroll
;         for (int b = 0; b < 2; ++b)
; #pragma unroll
;           for (int m = 0; m < 4; ++m)
; #pragma unroll
;             for (int n = 0; n < 2; ++n) acc[a][b][m][n] = (f32x4){0.f, 0.f, 0.f, 0.f};
.LBB0_498:
	s_ashr_i32 s13, s12, 31
	s_lshl_b64 s[14:15], s[12:13], 19
	s_add_u32 s14, s24, s14
	s_addc_u32 s15, s25, s15
	s_and_b64 s[16:17], s[4:5], exec
	s_cselect_b32 s13, s15, s19
	s_cselect_b32 s44, s14, s18
	s_ashr_i32 s9, s8, 31
	s_lshl_b64 s[16:17], s[8:9], 19
	s_add_u32 s16, s28, s16
	s_addc_u32 s17, s29, s17
	s_and_b64 s[26:27], s[4:5], exec
	s_cselect_b32 s9, s17, s21
	s_cselect_b32 s45, s16, s20
	s_add_u32 s18, s18, 0x40080
	s_addc_u32 s19, s19, 0
	s_add_u32 s46, s20, 0x100
	v_mov_b64_e32 v[0:1], 0
	v_mov_b64_e32 v[2:3], 0
	v_mov_b64_e32 v[4:5], 0
	v_mov_b64_e32 v[6:7], 0
	v_mov_b64_e32 v[8:9], 0
	v_mov_b64_e32 v[10:11], 0
	v_mov_b64_e32 v[12:13], 0
	v_mov_b64_e32 v[14:15], 0
	v_mov_b64_e32 v[16:17], 0
	v_mov_b64_e32 v[18:19], 0
	v_mov_b64_e32 v[20:21], 0
	v_mov_b64_e32 v[22:23], 0
	v_mov_b64_e32 v[24:25], 0
	v_mov_b64_e32 v[26:27], 0
	v_mov_b64_e32 v[28:29], 0
	v_mov_b64_e32 v[30:31], 0
	v_mov_b64_e32 v[32:33], 0
	v_mov_b64_e32 v[34:35], 0
	v_mov_b64_e32 v[36:37], 0
	v_mov_b64_e32 v[38:39], 0
	v_mov_b64_e32 v[40:41], 0
	v_mov_b64_e32 v[42:43], 0
	v_mov_b64_e32 v[44:45], 0
	v_mov_b64_e32 v[46:47], 0
	v_mov_b64_e32 v[48:49], 0
	v_mov_b64_e32 v[50:51], 0
	v_mov_b64_e32 v[52:53], 0
	v_mov_b64_e32 v[54:55], 0
	v_mov_b64_e32 v[56:57], 0
	v_mov_b64_e32 v[58:59], 0
	v_mov_b64_e32 v[60:61], 0
	v_mov_b64_e32 v[62:63], 0
	v_mov_b64_e32 v[64:65], 0
	v_mov_b64_e32 v[66:67], 0
	v_mov_b64_e32 v[68:69], 0
	v_mov_b64_e32 v[70:71], 0
	v_mov_b64_e32 v[72:73], 0
	v_mov_b64_e32 v[74:75], 0
	v_mov_b64_e32 v[76:77], 0
	v_mov_b64_e32 v[78:79], 0
	v_mov_b64_e32 v[80:81], 0
	v_mov_b64_e32 v[82:83], 0
	v_mov_b64_e32 v[84:85], 0
	v_mov_b64_e32 v[86:87], 0
	v_mov_b64_e32 v[88:89], 0
	v_mov_b64_e32 v[90:91], 0
	v_mov_b64_e32 v[92:93], 0
	v_mov_b64_e32 v[94:95], 0
	v_mov_b64_e32 v[96:97], 0
	v_mov_b64_e32 v[98:99], 0
	v_mov_b64_e32 v[100:101], 0
	v_mov_b64_e32 v[102:103], 0
	v_mov_b64_e32 v[104:105], 0
	v_mov_b64_e32 v[106:107], 0
	v_mov_b64_e32 v[108:109], 0
	v_mov_b64_e32 v[110:111], 0
	v_mov_b64_e32 v[112:113], 0
	v_mov_b64_e32 v[114:115], 0
	v_mov_b64_e32 v[116:117], 0
	v_mov_b64_e32 v[118:119], 0
	v_mov_b64_e32 v[120:121], 0
	v_mov_b64_e32 v[122:123], 0
	v_mov_b64_e32 v[124:125], 0
	v_mov_b64_e32 v[126:127], 0
	s_addc_u32 s47, s21, 0
	s_mov_b32 s48, -2
	s_waitcnt lgkmcnt(0)
	v_readfirstlane_b32 s98, v171
	s_nop 3
	s_lshr_b32 s98, s98, 6
	s_cmp_lt_u32 s98, 4
	s_cbranch_scc0 .Lprio_499
	s_setprio 1
.Lprio_499:
.LBB0_499:
	s_add_u32 s20, s18, 0xfffc0080
	s_addc_u32 s21, s19, -1
	s_add_i32 s49, 0, 0x10000
	s_cmp_eq_u32 s48, 12
	s_cselect_b32 s27, s13, s21
	s_cselect_b32 s26, s44, s20
	s_cselect_b32 s21, s9, s47
	s_cselect_b32 s20, s45, s46
	s_add_i32 s52, 0, 0x14000
	v_add_u32_e32 v154, s49, v139
	v_add_u32_e32 v166, s52, v139
	ds_read_b128 v[142:145], v154
	ds_read_b128 v[146:149], v154 offset:1024
	ds_read_b128 v[150:153], v154 offset:2048
	ds_read_b128 v[154:157], v154 offset:3072
	ds_read_b128 v[158:161], v166
	ds_read_b128 v[162:165], v166 offset:1024
	ds_read_b128 v[180:183], v166 offset:2048
	ds_read_b128 v[184:187], v166 offset:3072
	v_lshl_add_u64 v[166:167], s[18:19], 0, v[134:135]
	s_add_i32 m0, s35, 0xc000
	ds_read_b128 v[188:191], v141
	ds_read_b128 v[192:195], v141 offset:1024
	ds_read_b128 v[196:199], v141 offset:2048
	ds_read_b128 v[218:221], v141 offset:3072
	ds_read_b128 v[222:225], v141 offset:4096
	ds_read_b128 v[226:229], v141 offset:5120
	ds_read_b128 v[230:233], v141 offset:6144
	ds_read_b128 v[234:237], v141 offset:7168
	global_load_lds_dwordx4 v[166:167], off
	v_lshl_add_u64 v[166:167], s[18:19], 0, v[136:137]
	s_add_i32 m0, s35, 0xe000
	s_nop 0
	global_load_lds_dwordx4 v[166:167], off
	s_waitcnt vmcnt(8)
	s_waitcnt lgkmcnt(0)
	s_barrier
	s_waitcnt lgkmcnt(0)
	v_mfma_f32_16x16x32_bf16 v[124:127], v[142:145], v[188:191], v[124:127]
	v_mfma_f32_16x16x32_bf16 v[120:123], v[150:153], v[188:191], v[120:123]
	v_mfma_f32_16x16x32_bf16 v[116:119], v[142:145], v[196:199], v[116:119]
	v_mfma_f32_16x16x32_bf16 v[112:115], v[150:153], v[196:199], v[112:115]
	v_mfma_f32_16x16x32_bf16 v[100:103], v[142:145], v[222:225], v[100:103]
	v_mfma_f32_16x16x32_bf16 v[96:99], v[150:153], v[222:225], v[96:99]
	v_mfma_f32_16x16x32_bf16 v[84:87], v[142:145], v[230:233], v[84:87]
	v_mfma_f32_16x16x32_bf16 v[80:83], v[150:153], v[230:233], v[80:83]
	v_mfma_f32_16x16x32_bf16 v[124:127], v[146:149], v[192:195], v[124:127]
	v_mfma_f32_16x16x32_bf16 v[120:123], v[154:157], v[192:195], v[120:123]
	v_mfma_f32_16x16x32_bf16 v[116:119], v[146:149], v[218:221], v[116:119]
	v_mfma_f32_16x16x32_bf16 v[112:115], v[154:157], v[218:221], v[112:115]
	v_mfma_f32_16x16x32_bf16 v[100:103], v[146:149], v[226:229], v[100:103]
	v_mfma_f32_16x16x32_bf16 v[96:99], v[154:157], v[226:229], v[96:99]
	v_mfma_f32_16x16x32_bf16 v[84:87], v[146:149], v[234:237], v[84:87]
	v_mfma_f32_16x16x32_bf16 v[80:83], v[154:157], v[234:237], v[80:83]
	v_mfma_f32_16x16x32_bf16 v[108:111], v[158:161], v[188:191], v[108:111]
	v_mfma_f32_16x16x32_bf16 v[104:107], v[180:183], v[188:191], v[104:107]
	v_mfma_f32_16x16x32_bf16 v[92:95], v[158:161], v[196:199], v[92:95]
	v_mfma_f32_16x16x32_bf16 v[88:91], v[180:183], v[196:199], v[88:91]
	v_mfma_f32_16x16x32_bf16 v[76:79], v[158:161], v[222:225], v[76:79]
	v_mfma_f32_16x16x32_bf16 v[72:75], v[180:183], v[222:225], v[72:75]
	v_mfma_f32_16x16x32_bf16 v[68:71], v[158:161], v[230:233], v[68:71]
	v_mfma_f32_16x16x32_bf16 v[64:67], v[180:183], v[230:233], v[64:67]
	v_mfma_f32_16x16x32_bf16 v[108:111], v[162:165], v[192:195], v[108:111]
	v_mfma_f32_16x16x32_bf16 v[104:107], v[184:187], v[192:195], v[104:107]
	v_mfma_f32_16x16x32_bf16 v[92:95], v[162:165], v[218:221], v[92:95]
	v_mfma_f32_16x16x32_bf16 v[88:91], v[184:187], v[218:221], v[88:91]
	v_mfma_f32_16x16x32_bf16 v[76:79], v[162:165], v[226:229], v[76:79]
	v_mfma_f32_16x16x32_bf16 v[72:75], v[184:187], v[226:229], v[72:75]
	v_mfma_f32_16x16x32_bf16 v[68:71], v[162:165], v[234:237], v[68:71]
	v_mfma_f32_16x16x32_bf16 v[64:67], v[184:187], v[234:237], v[64:67]
	s_barrier
; #define PG8_STAGE(bufoff, gbase, voff) do { _Pragma("unroll") for (int _i = 0; _i < 2; ++_i) \
;     __builtin_amdgcn_global_load_lds((const unsigned*)((const char*)(gbase) + (voff)[_i]), (PG8_LAS unsigned*)(lds + (bufoff) + ldsw + _i * 8192), 16, 0, 0); } while (0)
; #define PG8_LDA(dst, b, h) do { _Pragma("unroll") for (int m = 0; m < 4; ++m) _Pragma("unroll") for (int k = 0; k < 2; ++k) dst[m][k] = *(const PG8_LAS bf16x8*)(lds + PG8_SA(b, h) + aoff + m * 2048 + k * 1024); } while (0)
; #define PG8_LDB(dst, b, h) do { _Pragma("unroll") for (int n = 0; n < 2; ++n) _Pragma("unroll") for (int k = 0; k < 2; ++k) dst[n][k] = *(const PG8_LAS bf16x8*)(lds + PG8_SB(b, h) + boff + n * 2048 + k * 1024); } while (0)
; #define PG8_MMA(ai, bj, At, Bt) do { __builtin_amdgcn_s_setprio(1); _Pragma("unroll") for (int m = 0; m < 4; ++m) _Pragma("unroll") for (int n = 0; n < 2; ++n) _Pragma("unroll") for (int k = 0; k < 2; ++k) \
;     acc[ai][bj][m][n] = __builtin_amdgcn_mfma_f32_16x16x32_bf16(Bt[n][k], At[m][k], acc[ai][bj][m][n], 0, 0, 0); __builtin_amdgcn_s_setprio(0); } while (0)
; #define PG8_WAIT_V(n) asm volatile("s_waitcnt vmcnt(" #n ")" ::: "memory")
; #define PG8_WAIT_L(n) asm volatile("s_waitcnt lgkmcnt(" #n ")" ::: "memory")
; #define PG8_BAR __builtin_amdgcn_s_barrier()
; #define PG8_SCHED __builtin_amdgcn_sched_barrier(0)
; template <class Epi, bool SEQ>
; DEV void gemm_phase(PG8_LAS unsigned char* lds, const Gemm g, const Epi& E) {
;     ...
;       PG8_LDA(At, 0, 1); PG8_STAGE(PG8_SB(0, 0), b2, voffB); PG8_STAGE(PG8_SB(0, 1), b2 + hstepB, voffB); PG8_STAGE(PG8_SA(0, 0), a2, voffA);
;       PG8_WAIT_V(8); PG8_WAIT_L(0); PG8_BAR; PG8_MMA(1, 0, At, B0); PG8_MMA(1, 1, At, B1); PG8_BAR; PG8_SCHED;
;       PG8_LDB(B0, 1, 0); PG8_LDB(B1, 1, 1); PG8_SCHED; PG8_LDA(At, 1, 0); PG8_STAGE(PG8_SA(0, 1), a2 + hstepA, voffA);
;       PG8_WAIT_V(8); PG8_WAIT_L(0); PG8_BAR; PG8_MMA(0, 0, At, B0); PG8_MMA(0, 1, At, B1); PG8_BAR; PG8_SCHED;
	s_add_i32 s49, s49, s34
	v_lshl_add_u64 v[166:167], s[20:21], 0, v[168:169]
	s_mov_b32 m0, s49
	ds_read_b128 v[188:191], v141 offset:16384
	ds_read_b128 v[192:195], v141 offset:17408
	ds_read_b128 v[196:199], v141 offset:18432
	ds_read_b128 v[218:221], v141 offset:19456
	ds_read_b128 v[222:225], v141 offset:20480
	ds_read_b128 v[226:229], v141 offset:21504
	ds_read_b128 v[230:233], v141 offset:22528
	ds_read_b128 v[234:237], v141 offset:23552
	global_load_lds_dwordx4 v[166:167], off
	s_add_i32 m0, s49, 0x2000
	s_add_u32 s50, s20, 0x40000
	v_lshl_add_u64 v[238:239], s[20:21], 0, v[132:133]
	s_addc_u32 s51, s21, 0
	s_add_i32 s49, s52, s34
	global_load_lds_dwordx4 v[238:239], off
	v_lshl_add_u64 v[240:241], s[50:51], 0, v[168:169]
	s_mov_b32 m0, s49
	v_lshl_add_u64 v[242:243], s[26:27], 0, v[130:131]
	global_load_lds_dwordx4 v[240:241], off
	v_lshl_add_u64 v[240:241], s[50:51], 0, v[132:133]
	s_add_i32 m0, s49, 0x2000
	s_nop 0
	global_load_lds_dwordx4 v[240:241], off
	v_lshl_add_u64 v[240:241], s[26:27], 0, v[128:129]
	s_mov_b32 m0, s35
	s_nop 0
	global_load_lds_dwordx4 v[240:241], off
	s_mov_b32 m0, s36
	s_nop 0
	global_load_lds_dwordx4 v[242:243], off
	s_waitcnt vmcnt(8)
	s_waitcnt lgkmcnt(0)
	s_barrier
	s_waitcnt lgkmcnt(0)
	v_mfma_f32_16x16x32_bf16 v[60:63], v[142:145], v[188:191], v[60:63]
	v_mfma_f32_16x16x32_bf16 v[56:59], v[150:153], v[188:191], v[56:59]
	v_mfma_f32_16x16x32_bf16 v[52:55], v[142:145], v[196:199], v[52:55]
	v_mfma_f32_16x16x32_bf16 v[48:51], v[150:153], v[196:199], v[48:51]
	v_mfma_f32_16x16x32_bf16 v[36:39], v[142:145], v[222:225], v[36:39]
	v_mfma_f32_16x16x32_bf16 v[32:35], v[150:153], v[222:225], v[32:35]
	v_mfma_f32_16x16x32_bf16 v[20:23], v[142:145], v[230:233], v[20:23]
	v_mfma_f32_16x16x32_bf16 v[16:19], v[150:153], v[230:233], v[16:19]
	v_mfma_f32_16x16x32_bf16 v[60:63], v[146:149], v[192:195], v[60:63]
	v_mfma_f32_16x16x32_bf16 v[56:59], v[154:157], v[192:195], v[56:59]
	v_mfma_f32_16x16x32_bf16 v[52:55], v[146:149], v[218:221], v[52:55]
	v_mfma_f32_16x16x32_bf16 v[48:51], v[154:157], v[218:221], v[48:51]
	v_mfma_f32_16x16x32_bf16 v[36:39], v[146:149], v[226:229], v[36:39]
	v_mfma_f32_16x16x32_bf16 v[32:35], v[154:157], v[226:229], v[32:35]
	v_mfma_f32_16x16x32_bf16 v[20:23], v[146:149], v[234:237], v[20:23]
	v_mfma_f32_16x16x32_bf16 v[16:19], v[154:157], v[234:237], v[16:19]
	v_mfma_f32_16x16x32_bf16 v[44:47], v[158:161], v[188:191], v[44:47]
	v_mfma_f32_16x16x32_bf16 v[40:43], v[180:183], v[188:191], v[40:43]
	v_mfma_f32_16x16x32_bf16 v[28:31], v[158:161], v[196:199], v[28:31]
	v_mfma_f32_16x16x32_bf16 v[24:27], v[180:183], v[196:199], v[24:27]
	v_mfma_f32_16x16x32_bf16 v[12:15], v[158:161], v[222:225], v[12:15]
	v_mfma_f32_16x16x32_bf16 v[8:11], v[180:183], v[222:225], v[8:11]
	v_mfma_f32_16x16x32_bf16 v[4:7], v[158:161], v[230:233], v[4:7]
	v_mfma_f32_16x16x32_bf16 v[0:3], v[180:183], v[230:233], v[0:3]
	v_mfma_f32_16x16x32_bf16 v[44:47], v[162:165], v[192:195], v[44:47]
	v_mfma_f32_16x16x32_bf16 v[40:43], v[184:187], v[192:195], v[40:43]
	v_mfma_f32_16x16x32_bf16 v[28:31], v[162:165], v[218:221], v[28:31]
	v_mfma_f32_16x16x32_bf16 v[24:27], v[184:187], v[218:221], v[24:27]
	v_mfma_f32_16x16x32_bf16 v[12:15], v[162:165], v[226:229], v[12:15]
	v_mfma_f32_16x16x32_bf16 v[8:11], v[184:187], v[226:229], v[8:11]
	v_mfma_f32_16x16x32_bf16 v[4:7], v[162:165], v[234:237], v[4:7]
	v_mfma_f32_16x16x32_bf16 v[0:3], v[184:187], v[234:237], v[0:3]
	s_barrier
	s_add_i32 s49, 0, 0x18000
	s_add_i32 s50, 0, 0x1c000
	v_add_u32_e32 v154, s49, v139
	v_add_u32_e32 v177, s50, v139
	ds_read_b128 v[142:145], v154
	ds_read_b128 v[146:149], v154 offset:1024
	ds_read_b128 v[150:153], v154 offset:2048
	ds_read_b128 v[154:157], v154 offset:3072
	ds_read_b128 v[158:161], v177
	ds_read_b128 v[162:165], v177 offset:1024
	ds_read_b128 v[180:183], v177 offset:2048
	ds_read_b128 v[184:187], v177 offset:3072
	s_add_u32 s26, s26, 0x40000
	s_addc_u32 s27, s27, 0
	s_mov_b32 m0, s37
	v_lshl_add_u64 v[244:245], s[26:27], 0, v[128:129]
	ds_read_b128 v[188:191], v141 offset:32768
	ds_read_b128 v[192:195], v141 offset:33792
	ds_read_b128 v[196:199], v141 offset:34816
	ds_read_b128 v[218:221], v141 offset:35840
	ds_read_b128 v[222:225], v141 offset:36864
	ds_read_b128 v[226:229], v141 offset:37888
	ds_read_b128 v[230:233], v141 offset:38912
	ds_read_b128 v[234:237], v141 offset:39936
	global_load_lds_dwordx4 v[244:245], off
	v_lshl_add_u64 v[244:245], s[26:27], 0, v[130:131]
	s_mov_b32 m0, s38
	s_nop 0
	global_load_lds_dwordx4 v[244:245], off
	s_waitcnt vmcnt(8)
	s_waitcnt lgkmcnt(0)
	s_barrier
; #define PG8_STAGE(bufoff, gbase, voff) do { _Pragma("unroll") for (int _i = 0; _i < 2; ++_i) \
;     __builtin_amdgcn_global_load_lds((const unsigned*)((const char*)(gbase) + (voff)[_i]), (PG8_LAS unsigned*)(lds + (bufoff) + ldsw + _i * 8192), 16, 0, 0); } while (0)
; #define PG8_LDA(dst, b, h) do { _Pragma("unroll") for (int m = 0; m < 4; ++m) _Pragma("unroll") for (int k = 0; k < 2; ++k) dst[m][k] = *(const PG8_LAS bf16x8*)(lds + PG8_SA(b, h) + aoff + m * 2048 + k * 1024); } while (0)
; #define PG8_MMA(ai, bj, At, Bt) do { __builtin_amdgcn_s_setprio(1); _Pragma("unroll") for (int m = 0; m < 4; ++m) _Pragma("unroll") for (int n = 0; n < 2; ++n) _Pragma("unroll") for (int k = 0; k < 2; ++k) \
;     acc[ai][bj][m][n] = __builtin_amdgcn_mfma_f32_16x16x32_bf16(Bt[n][k], At[m][k], acc[ai][bj][m][n], 0, 0, 0); __builtin_amdgcn_s_setprio(0); } while (0)
; #define PG8_WAIT_V(n) asm volatile("s_waitcnt vmcnt(" #n ")" ::: "memory")
; #define PG8_WAIT_L(n) asm volatile("s_waitcnt lgkmcnt(" #n ")" ::: "memory")
; #define PG8_BAR __builtin_amdgcn_s_barrier()
; #define PG8_SCHED __builtin_amdgcn_sched_barrier(0)
; template <class Epi, bool SEQ>
; DEV void gemm_phase(PG8_LAS unsigned char* lds, const Gemm g, const Epi& E) {
;     ...
;       PG8_WAIT_V(8); PG8_WAIT_L(0); PG8_BAR; PG8_MMA(0, 0, At, B0); PG8_MMA(0, 1, At, B1); PG8_BAR; PG8_SCHED;
;       PG8_LDA(At, 1, 1); PG8_STAGE(PG8_SB(1, 0), b3, voffB); PG8_STAGE(PG8_SB(1, 1), b3 + hstepB, voffB); PG8_STAGE(PG8_SA(1, 0), a3, voffA);
;       PG8_WAIT_V(8); PG8_WAIT_L(0); PG8_BAR; PG8_MMA(1, 0, At, B0); PG8_MMA(1, 1, At, B1); PG8_BAR; PG8_SCHED;
;     }
;     if (wr == 0) PG8_BAR;
	s_waitcnt lgkmcnt(0)
	v_mfma_f32_16x16x32_bf16 v[124:127], v[142:145], v[188:191], v[124:127]
	v_mfma_f32_16x16x32_bf16 v[120:123], v[150:153], v[188:191], v[120:123]
	v_mfma_f32_16x16x32_bf16 v[116:119], v[142:145], v[196:199], v[116:119]
	v_mfma_f32_16x16x32_bf16 v[112:115], v[150:153], v[196:199], v[112:115]
	v_mfma_f32_16x16x32_bf16 v[100:103], v[142:145], v[222:225], v[100:103]
	v_mfma_f32_16x16x32_bf16 v[96:99], v[150:153], v[222:225], v[96:99]
	v_mfma_f32_16x16x32_bf16 v[84:87], v[142:145], v[230:233], v[84:87]
	v_mfma_f32_16x16x32_bf16 v[80:83], v[150:153], v[230:233], v[80:83]
	v_mfma_f32_16x16x32_bf16 v[124:127], v[146:149], v[192:195], v[124:127]
	v_mfma_f32_16x16x32_bf16 v[120:123], v[154:157], v[192:195], v[120:123]
	v_mfma_f32_16x16x32_bf16 v[116:119], v[146:149], v[218:221], v[116:119]
	v_mfma_f32_16x16x32_bf16 v[112:115], v[154:157], v[218:221], v[112:115]
	v_mfma_f32_16x16x32_bf16 v[100:103], v[146:149], v[226:229], v[100:103]
	v_mfma_f32_16x16x32_bf16 v[96:99], v[154:157], v[226:229], v[96:99]
	v_mfma_f32_16x16x32_bf16 v[84:87], v[146:149], v[234:237], v[84:87]
	v_mfma_f32_16x16x32_bf16 v[80:83], v[154:157], v[234:237], v[80:83]
	v_mfma_f32_16x16x32_bf16 v[108:111], v[158:161], v[188:191], v[108:111]
	v_mfma_f32_16x16x32_bf16 v[104:107], v[180:183], v[188:191], v[104:107]
	v_mfma_f32_16x16x32_bf16 v[92:95], v[158:161], v[196:199], v[92:95]
	v_mfma_f32_16x16x32_bf16 v[88:91], v[180:183], v[196:199], v[88:91]
	v_mfma_f32_16x16x32_bf16 v[76:79], v[158:161], v[222:225], v[76:79]
	v_mfma_f32_16x16x32_bf16 v[72:75], v[180:183], v[222:225], v[72:75]
	v_mfma_f32_16x16x32_bf16 v[68:71], v[158:161], v[230:233], v[68:71]
	v_mfma_f32_16x16x32_bf16 v[64:67], v[180:183], v[230:233], v[64:67]
	v_mfma_f32_16x16x32_bf16 v[108:111], v[162:165], v[192:195], v[108:111]
	v_mfma_f32_16x16x32_bf16 v[104:107], v[184:187], v[192:195], v[104:107]
	v_mfma_f32_16x16x32_bf16 v[92:95], v[162:165], v[218:221], v[92:95]
	v_mfma_f32_16x16x32_bf16 v[88:91], v[184:187], v[218:221], v[88:91]
	v_mfma_f32_16x16x32_bf16 v[76:79], v[162:165], v[226:229], v[76:79]
	v_mfma_f32_16x16x32_bf16 v[72:75], v[184:187], v[226:229], v[72:75]
	v_mfma_f32_16x16x32_bf16 v[68:71], v[162:165], v[234:237], v[68:71]
	v_mfma_f32_16x16x32_bf16 v[64:67], v[184:187], v[234:237], v[64:67]
	s_barrier
	s_add_i32 s26, s49, s34
	v_lshl_add_u64 v[166:167], v[166:167], 0, s[10:11]
	s_mov_b32 m0, s26
	ds_read_b128 v[188:191], v141 offset:49152
	ds_read_b128 v[192:195], v141 offset:50176
	ds_read_b128 v[196:199], v141 offset:51200
	ds_read_b128 v[218:221], v141 offset:52224
	ds_read_b128 v[222:225], v141 offset:53248
	ds_read_b128 v[226:229], v141 offset:54272
	ds_read_b128 v[230:233], v141 offset:55296
	ds_read_b128 v[234:237], v141 offset:56320
	global_load_lds_dwordx4 v[166:167], off
	s_add_i32 m0, s26, 0x2000
	s_add_u32 s20, s20, 0x40080
	v_lshl_add_u64 v[166:167], v[238:239], 0, s[10:11]
	s_addc_u32 s21, s21, 0
	s_add_i32 s26, s50, s34
	global_load_lds_dwordx4 v[166:167], off
	v_lshl_add_u64 v[166:167], s[20:21], 0, v[168:169]
	s_mov_b32 m0, s26
	s_nop 0
	global_load_lds_dwordx4 v[166:167], off
	v_lshl_add_u64 v[166:167], s[20:21], 0, v[132:133]
	s_add_i32 m0, s26, 0x2000
	s_nop 0
	global_load_lds_dwordx4 v[166:167], off
	v_lshl_add_u64 v[166:167], v[240:241], 0, s[10:11]
	s_mov_b32 m0, s39
	s_nop 0
	global_load_lds_dwordx4 v[166:167], off
	v_lshl_add_u64 v[166:167], v[242:243], 0, s[10:11]
	s_mov_b32 m0, s40
	s_nop 0
	global_load_lds_dwordx4 v[166:167], off
	s_waitcnt vmcnt(8)
	s_waitcnt lgkmcnt(0)
	s_barrier
	s_waitcnt lgkmcnt(0)
	v_mfma_f32_16x16x32_bf16 v[60:63], v[142:145], v[188:191], v[60:63]
	v_mfma_f32_16x16x32_bf16 v[56:59], v[150:153], v[188:191], v[56:59]
	v_mfma_f32_16x16x32_bf16 v[52:55], v[142:145], v[196:199], v[52:55]
	v_mfma_f32_16x16x32_bf16 v[48:51], v[150:153], v[196:199], v[48:51]
	v_mfma_f32_16x16x32_bf16 v[36:39], v[142:145], v[222:225], v[36:39]
	v_mfma_f32_16x16x32_bf16 v[32:35], v[150:153], v[222:225], v[32:35]
	v_mfma_f32_16x16x32_bf16 v[20:23], v[142:145], v[230:233], v[20:23]
	v_mfma_f32_16x16x32_bf16 v[16:19], v[150:153], v[230:233], v[16:19]
	v_mfma_f32_16x16x32_bf16 v[60:63], v[146:149], v[192:195], v[60:63]
	v_mfma_f32_16x16x32_bf16 v[56:59], v[154:157], v[192:195], v[56:59]
	v_mfma_f32_16x16x32_bf16 v[52:55], v[146:149], v[218:221], v[52:55]
	v_mfma_f32_16x16x32_bf16 v[48:51], v[154:157], v[218:221], v[48:51]
	v_mfma_f32_16x16x32_bf16 v[36:39], v[146:149], v[226:229], v[36:39]
	v_mfma_f32_16x16x32_bf16 v[32:35], v[154:157], v[226:229], v[32:35]
	v_mfma_f32_16x16x32_bf16 v[20:23], v[146:149], v[234:237], v[20:23]
	v_mfma_f32_16x16x32_bf16 v[16:19], v[154:157], v[234:237], v[16:19]
	v_mfma_f32_16x16x32_bf16 v[44:47], v[158:161], v[188:191], v[44:47]
	v_mfma_f32_16x16x32_bf16 v[40:43], v[180:183], v[188:191], v[40:43]
	v_mfma_f32_16x16x32_bf16 v[28:31], v[158:161], v[196:199], v[28:31]
	v_mfma_f32_16x16x32_bf16 v[24:27], v[180:183], v[196:199], v[24:27]
	v_mfma_f32_16x16x32_bf16 v[12:15], v[158:161], v[222:225], v[12:15]
	v_mfma_f32_16x16x32_bf16 v[8:11], v[180:183], v[222:225], v[8:11]
	v_mfma_f32_16x16x32_bf16 v[4:7], v[158:161], v[230:233], v[4:7]
	v_mfma_f32_16x16x32_bf16 v[0:3], v[180:183], v[230:233], v[0:3]
	v_mfma_f32_16x16x32_bf16 v[44:47], v[162:165], v[192:195], v[44:47]
	v_mfma_f32_16x16x32_bf16 v[40:43], v[184:187], v[192:195], v[40:43]
	v_mfma_f32_16x16x32_bf16 v[28:31], v[162:165], v[218:221], v[28:31]
	v_mfma_f32_16x16x32_bf16 v[24:27], v[184:187], v[218:221], v[24:27]
	v_mfma_f32_16x16x32_bf16 v[12:15], v[162:165], v[226:229], v[12:15]
	v_mfma_f32_16x16x32_bf16 v[8:11], v[184:187], v[226:229], v[8:11]
	v_mfma_f32_16x16x32_bf16 v[4:7], v[162:165], v[234:237], v[4:7]
	v_mfma_f32_16x16x32_bf16 v[0:3], v[184:187], v[234:237], v[0:3]
	s_barrier
	s_add_i32 s48, s48, 2
	s_add_u32 s18, s18, 0x100
	s_addc_u32 s19, s19, 0
	s_add_u32 s46, s46, 0x100
	s_addc_u32 s47, s47, 0
	s_cmp_gt_u32 s48, 13
	s_cbranch_scc0 .LBB0_499
	s_and_b64 vcc, exec, s[2:3]
	s_cbranch_vccz .LBB0_502
	s_barrier
; DEV unsigned cvt_pk_bf16(float lo, float hi) { const f32x2_ v = {lo, hi}; return __builtin_bit_cast(unsigned, __builtin_convertvector(v, bf16x2n_)); }
; #define PG8_BAR __builtin_amdgcn_s_barrier()
; template <class Epi, bool SEQ>
; DEV void gemm_phase(PG8_LAS unsigned char* lds, const Gemm g, const Epi& E) {
;     ...
;     if (!has_next) break;
;     if (!keep) {
; #pragma unroll
;       for (int a = 0; a < 2; ++a)
; #pragma unroll
;         for (int b = 0; b < 2; ++b)
; #pragma unroll
;           for (int m = 0; m < 4; ++m)
; #pragma unroll
;             for (int n = 0; n < 2; ++n) acc[a][b][m][n] = (f32x4){0.f, 0.f, 0.f, 0.f};
;     }
;     cur = nxt; cA = nA; cB = nB; ++ui;
;     if (wr == 1) PG8_BAR;
;   DEV void operator()(const f32x4 (&acc)[2][2][4][2], const Unit& u, int wr, int wc, int fr, int fq) const {
;     const int row0 = u.pm * BM + wr * 64 + fr, col0 = u.pn * BM + wc * 32 + 8 * fq;
; #pragma unroll
;     for (int ai = 0; ai < 2; ++ai)
; #pragma unroll
;       for (int m = 0; m < 4; ++m) {
;         bf16_t* rowp = O + (size_t)(row0 + ai * HALF + m * 16) * ldc + col0;
; #pragma unroll
;         for (int bj = 0; bj < 2; ++bj) {
;           f32x4 v0 = acc[ai][bj][m][0], v1 = acc[ai][bj][m][1];
;           if (ACT == 1) {
; #pragma unroll
;             for (int c = 0; c < 4; ++c) { const float a = fmaxf(v0[c], 0.f), b = fmaxf(v1[c], 0.f); v0[c] = a * a; v1[c] = b * b; }
;           }
;           u32x4 w; w.x = cvt_pk_bf16(v0[0], v0[1]); w.y = cvt_pk_bf16(v0[2], v0[3]); w.z = cvt_pk_bf16(v1[0], v1[1]); w.w = cvt_pk_bf16(v1[2], v1[3]);
;           *(u32x4*)(rowp + bj * HALF) = w;
;         }
;       }
.LBB0_502:
	s_setprio 0
	v_lshl_add_u32 v148, s43, 8, v138
	v_lshl_or_b32 v142, s42, 8, v140
	v_ashrrev_i32_e32 v143, 31, v142
	v_mov_b64_e32 v[144:145], s[30:31]
	v_cvt_pk_bf16_f32 v68, v68, v69
	v_cvt_pk_bf16_f32 v69, v70, v71
	v_cvt_pk_bf16_f32 v70, v64, v65
	v_add_u32_e32 v64, 0x80, v148
	v_mad_i64_i32 v[146:147], s[18:19], v148, s95, v[144:145]
	v_lshlrev_b64 v[142:143], 1, v[142:143]
	v_cvt_pk_bf16_f32 v108, v108, v109
	v_cvt_pk_bf16_f32 v109, v110, v111
	v_cvt_pk_bf16_f32 v110, v104, v105
	v_or_b32_e32 v104, 16, v148
	v_mad_i64_i32 v[64:65], s[18:19], v64, s95, v[144:145]
	v_cvt_pk_bf16_f32 v44, v44, v45
	v_cvt_pk_bf16_f32 v45, v46, v47
	v_cvt_pk_bf16_f32 v46, v40, v41
	v_add_u32_e32 v40, 0x90, v148
	v_lshl_add_u64 v[146:147], v[146:147], 0, v[142:143]
	v_cvt_pk_bf16_f32 v111, v106, v107
	v_mad_i64_i32 v[104:105], s[18:19], v104, s95, v[144:145]
	v_cvt_pk_bf16_f32 v92, v92, v93
	v_cvt_pk_bf16_f32 v93, v94, v95
	v_cvt_pk_bf16_f32 v94, v88, v89
	v_or_b32_e32 v88, 32, v148
	v_lshl_add_u64 v[64:65], v[64:65], 0, v[142:143]
	v_cvt_pk_bf16_f32 v47, v42, v43
	v_mad_i64_i32 v[40:41], s[18:19], v40, s95, v[144:145]
	v_cvt_pk_bf16_f32 v28, v28, v29
	v_cvt_pk_bf16_f32 v29, v30, v31
	v_cvt_pk_bf16_f32 v30, v24, v25
	v_add_u32_e32 v24, 0xa0, v148
	global_store_dwordx4 v[146:147], v[108:111], off offset:256
	v_cvt_pk_bf16_f32 v95, v90, v91
	v_mad_i64_i32 v[88:89], s[18:19], v88, s95, v[144:145]
	v_lshl_add_u64 v[108:109], v[104:105], 0, v[142:143]
	v_cvt_pk_bf16_f32 v76, v76, v77
	v_cvt_pk_bf16_f32 v77, v78, v79
	v_cvt_pk_bf16_f32 v78, v72, v73
	v_or_b32_e32 v72, 48, v148
	global_store_dwordx4 v[64:65], v[44:47], off offset:256
	v_cvt_pk_bf16_f32 v31, v26, v27
	v_mad_i64_i32 v[24:25], s[18:19], v24, s95, v[144:145]
	v_lshl_add_u64 v[44:45], v[40:41], 0, v[142:143]
	v_cvt_pk_bf16_f32 v12, v12, v13
	v_cvt_pk_bf16_f32 v13, v14, v15
	v_cvt_pk_bf16_f32 v14, v8, v9
	v_add_u32_e32 v8, 0xb0, v148
	global_store_dwordx4 v[108:109], v[92:95], off offset:256
	v_cvt_pk_bf16_f32 v79, v74, v75
	v_mad_i64_i32 v[72:73], s[18:19], v72, s95, v[144:145]
	v_lshl_add_u64 v[92:93], v[88:89], 0, v[142:143]
	global_store_dwordx4 v[44:45], v[28:31], off offset:256
	v_cvt_pk_bf16_f32 v15, v10, v11
	v_mad_i64_i32 v[8:9], s[18:19], v8, s95, v[144:145]
	v_lshl_add_u64 v[28:29], v[24:25], 0, v[142:143]
	v_cvt_pk_bf16_f32 v124, v124, v125
	v_cvt_pk_bf16_f32 v125, v126, v127
	v_cvt_pk_bf16_f32 v126, v120, v121
	v_cvt_pk_bf16_f32 v127, v122, v123
	v_cvt_pk_bf16_f32 v104, v116, v117
	v_cvt_pk_bf16_f32 v105, v118, v119
	v_cvt_pk_bf16_f32 v106, v112, v113
	v_cvt_pk_bf16_f32 v107, v114, v115
	v_cvt_pk_bf16_f32 v88, v100, v101
	v_cvt_pk_bf16_f32 v89, v102, v103
	v_cvt_pk_bf16_f32 v90, v96, v97
	v_cvt_pk_bf16_f32 v91, v98, v99
	global_store_dwordx4 v[92:93], v[76:79], off offset:256
	v_cvt_pk_bf16_f32 v74, v80, v81
	v_cvt_pk_bf16_f32 v75, v82, v83
	v_lshl_add_u64 v[76:77], v[72:73], 0, v[142:143]
	v_cvt_pk_bf16_f32 v72, v84, v85
	v_cvt_pk_bf16_f32 v73, v86, v87
	v_cvt_pk_bf16_f32 v71, v66, v67
	v_cvt_pk_bf16_f32 v60, v60, v61
	v_cvt_pk_bf16_f32 v61, v62, v63
	v_cvt_pk_bf16_f32 v62, v56, v57
	v_cvt_pk_bf16_f32 v63, v58, v59
	v_cvt_pk_bf16_f32 v40, v52, v53
	v_cvt_pk_bf16_f32 v41, v54, v55
	v_cvt_pk_bf16_f32 v42, v48, v49
	v_cvt_pk_bf16_f32 v43, v50, v51
	v_cvt_pk_bf16_f32 v24, v36, v37
	v_cvt_pk_bf16_f32 v25, v38, v39
	v_cvt_pk_bf16_f32 v26, v32, v33
	v_cvt_pk_bf16_f32 v27, v34, v35
	global_store_dwordx4 v[28:29], v[12:15], off offset:256
	v_cvt_pk_bf16_f32 v10, v16, v17
	v_cvt_pk_bf16_f32 v11, v18, v19
	v_lshl_add_u64 v[12:13], v[8:9], 0, v[142:143]
	v_cvt_pk_bf16_f32 v8, v20, v21
	v_cvt_pk_bf16_f32 v9, v22, v23
	v_cvt_pk_bf16_f32 v4, v4, v5
	v_cvt_pk_bf16_f32 v5, v6, v7
	v_cvt_pk_bf16_f32 v6, v0, v1
	v_cvt_pk_bf16_f32 v7, v2, v3
	s_andn2_b64 vcc, exec, s[4:5]
	s_mov_b64 s[4:5], -1
	global_store_dwordx4 v[146:147], v[124:127], off
	global_store_dwordx4 v[108:109], v[104:107], off
	global_store_dwordx4 v[92:93], v[88:91], off
	global_store_dwordx4 v[76:77], v[72:75], off
	global_store_dwordx4 v[76:77], v[68:71], off offset:256
	global_store_dwordx4 v[64:65], v[60:63], off
	global_store_dwordx4 v[44:45], v[40:43], off
	global_store_dwordx4 v[28:29], v[24:27], off
	global_store_dwordx4 v[12:13], v[8:11], off
	global_store_dwordx4 v[12:13], v[4:7], off offset:256
	s_cbranch_vccnz .LBB0_491
	s_andn2_b64 vcc, exec, s[0:1]
	s_cbranch_vccnz .LBB0_490
	s_barrier
	s_branch .LBB0_490
